# adds removal of compiler-inserted DMA-alias waits: LN residual pass-0 issue in last k-step, pool block-diagonal GEMM k-steps, DA-V transposed-store epilogue
# speedup vs baseline: 1.0446x; 1.0012x over previous
; DI f32x16 mfma(bf16x8 a, bf16x8 b, f32x16 c) { return __builtin_amdgcn_mfma_f32_32x32x16_bf16(a, b, c, 0, 0, 0); }
; template <int BK> DI int swz(int row) { constexpr int CPR = BK / 8; return (row / (16 / CPR)) % CPR; }
; DI void wait_vm0() { asm volatile("s_waitcnt vmcnt(0)" ::: "memory"); }
;   DI void pre(int grow0, int gcol0, int lane, int w, char* lds) { xpass(0, grow0, gcol0, lane, w, lds); }
;     ...
;   for (int kt = 0; kt < nk; ++kt) {
;     char* cur = lds + (kt & 1) * STG; char* nxt = lds + ((kt + 1) & 1) * STG;
;     const bool more = kt + 1 < nk;
;     const bf16_t* An = Ag + (kt + 1) * BK; const bf16_t* Bn = Bg + (kt + 1) * BK;
;     if (!more) epi.pre(row0 + wm * 64, col0 + wn * (32 * NTW), lane, w, lds);
;     bf16x8 fa[2][2], fb[2][NTW];
; #pragma unroll
;     for (int mt = 0; mt < 2; ++mt) { int row = wm * 64 + mt * 32 + l31; fa[0][mt] = *(const bf16x8*)(cur + row * (BK * 2) + ((hh ^ swz<BK>(row)) << 4)); }
; #pragma unroll
;     for (int nt = 0; nt < NTW; ++nt) { int row = wn * (32 * NTW) + nt * 32 + l31; fb[0][nt] = *(const bf16x8*)(cur + ABYTES + row * (BK * 2) + ((hh ^ swz<BK>(row)) << 4)); }
; #pragma unroll
;     for (int kk = 0; kk < NKK; ++kk) {
;       if (kk + 1 < NKK) {
;         const int ch = (kk + 1) * 2 + hh;
; #pragma unroll
;         for (int mt = 0; mt < 2; ++mt) { int row = wm * 64 + mt * 32 + l31; fa[(kk + 1) & 1][mt] = *(const bf16x8*)(cur + row * (BK * 2) + ((ch ^ swz<BK>(row)) << 4)); }
; #pragma unroll
;         for (int nt = 0; nt < NTW; ++nt) { int row = wn * (32 * NTW) + nt * 32 + l31; fb[(kk + 1) & 1][nt] = *(const bf16x8*)(cur + ABYTES + row * (BK * 2) + ((ch ^ swz<BK>(row)) << 4)); }
;       }
;       if (more) {
; #pragma unroll
;         for (int q = 0; q < PPK; ++q) {
;           const int pi = kk * PPK + q;
;           if (pi < NPA) stage_piece<BM, BK>(An, lda, nxt, tid, pi, wv);
;           else if (pi < NP) stage_piece<BN, BK>(Bn, ldb, nxt + ABYTES, tid, pi - NPA, wv);
;         }
;       }
;       __builtin_amdgcn_s_setprio(1);
; #pragma unroll
;       for (int mt = 0; mt < 2; ++mt)
; #pragma unroll
;         for (int nt = 0; nt < NTW; ++nt) acc[mt][nt] = mfma(fa[kk & 1][mt], fb[kk & 1][nt], acc[mt][nt]);
;       __builtin_amdgcn_s_setprio(0);
;       __builtin_amdgcn_sched_barrier(0);
;     }
;     wait_vm0();
;     __syncthreads();
;   }
.LBB0_173:
	s_and_b32 s30, s3, 0x10000
	s_xor_b32 s100, s30, 0x10000
	s_add_i32 s31, s30, s2
	v_add3_u32 v194, s100, v136, v166
	v_add3_u32 v198, s100, v144, v167
	ds_read_b128 v[194:197], v194
	v_add3_u32 v202, s100, v145, v161
	ds_read_b128 v[198:201], v198
	v_add3_u32 v206, s100, v152, v163
	ds_read_b128 v[202:205], v202 offset:32768
	v_add3_u32 v210, s100, v155, v159
	ds_read_b128 v[206:209], v206 offset:32768
	v_add3_u32 v226, s100, v158, v160
	ds_read_b128 v[210:213], v210 offset:32768
	ds_read_b128 v[226:229], v226 offset:32768
	v_lshl_add_u64 v[214:215], v[132:133], 0, s[6:7]
	v_lshl_add_u64 v[230:231], v[130:131], 0, s[6:7]
	s_mov_b32 m0, s31
	v_lshl_add_u64 v[232:233], v[214:215], 0, s[28:29]
	s_waitcnt lgkmcnt(6)
	v_mfma_f32_32x32x16_bf16 v[114:129], v[170:173], v[178:181], v[114:129]
	global_load_lds_dwordx4 v[232:233], off
	v_lshl_add_u64 v[232:233], v[214:215], 0, s[24:25]
	s_add_i32 m0, s31, 0x2000
	v_mfma_f32_32x32x16_bf16 v[98:113], v[170:173], v[182:185], v[98:113]
	global_load_lds_dwordx4 v[232:233], off
	v_lshl_add_u64 v[232:233], v[214:215], 0, s[26:27]
	s_add_i32 m0, s31, 0x4000
	v_mfma_f32_32x32x16_bf16 v[82:97], v[170:173], v[186:189], v[82:97]
	global_load_lds_dwordx4 v[232:233], off
	v_lshl_add_u64 v[232:233], v[214:215], 0, s[38:39]
	s_add_i32 m0, s31, 0x6000
	v_mfma_f32_32x32x16_bf16 v[66:81], v[170:173], v[190:193], v[66:81]
	global_load_lds_dwordx4 v[232:233], off
	v_lshl_add_u64 v[232:233], v[230:231], 0, s[28:29]
	s_add_i32 m0, s31, 0x8000
	v_mfma_f32_32x32x16_bf16 v[50:65], v[174:177], v[178:181], v[50:65]
	global_load_lds_dwordx4 v[232:233], off
	v_lshl_add_u64 v[232:233], v[230:231], 0, s[24:25]
	s_add_i32 m0, s31, 0xa000
	v_mfma_f32_32x32x16_bf16 v[34:49], v[174:177], v[182:185], v[34:49]
	global_load_lds_dwordx4 v[232:233], off
	v_lshl_add_u64 v[232:233], v[230:231], 0, s[26:27]
	s_add_i32 m0, s31, 0xc000
	v_mfma_f32_32x32x16_bf16 v[18:33], v[174:177], v[186:189], v[18:33]
	global_load_lds_dwordx4 v[232:233], off
	v_lshl_add_u64 v[232:233], v[230:231], 0, s[38:39]
	s_add_i32 m0, s31, 0xe000
	v_mfma_f32_32x32x16_bf16 v[2:17], v[174:177], v[190:193], v[2:17]
	global_load_lds_dwordx4 v[232:233], off
	v_add3_u32 v170, s100, v136, v153
	v_add3_u32 v174, s100, v144, v154
	ds_read_b128 v[170:173], v170
	v_add3_u32 v178, s100, v145, v149
	ds_read_b128 v[174:177], v174
	v_add3_u32 v182, s100, v152, v150
	ds_read_b128 v[178:181], v178 offset:32768
	v_add3_u32 v186, s100, v155, v147
	ds_read_b128 v[182:185], v182 offset:32768
	v_add3_u32 v190, s100, v158, v148
	ds_read_b128 v[186:189], v186 offset:32768
	ds_read_b128 v[190:193], v190 offset:32768
	s_waitcnt lgkmcnt(6)
	v_mfma_f32_32x32x16_bf16 v[114:129], v[194:197], v[202:205], v[114:129]
	v_mfma_f32_32x32x16_bf16 v[98:113], v[194:197], v[206:209], v[98:113]
	v_mfma_f32_32x32x16_bf16 v[82:97], v[194:197], v[210:213], v[82:97]
	v_mfma_f32_32x32x16_bf16 v[66:81], v[194:197], v[226:229], v[66:81]
	v_mfma_f32_32x32x16_bf16 v[50:65], v[198:201], v[202:205], v[50:65]
	v_mfma_f32_32x32x16_bf16 v[34:49], v[198:201], v[206:209], v[34:49]
	v_mfma_f32_32x32x16_bf16 v[18:33], v[198:201], v[210:213], v[18:33]
	v_mfma_f32_32x32x16_bf16 v[2:17], v[198:201], v[226:229], v[2:17]
	v_add3_u32 v194, s100, v136, v141
	v_add3_u32 v198, s100, v144, v142
	ds_read_b128 v[194:197], v194
	v_add3_u32 v202, s100, v145, v139
	ds_read_b128 v[198:201], v198
	v_add3_u32 v206, s100, v152, v140
	ds_read_b128 v[202:205], v202 offset:32768
	v_add3_u32 v210, s100, v155, v137
	ds_read_b128 v[206:209], v206 offset:32768
	v_add3_u32 v226, s100, v158, v138
	ds_read_b128 v[210:213], v210 offset:32768
	ds_read_b128 v[226:229], v226 offset:32768
	s_waitcnt lgkmcnt(6)
	v_mfma_f32_32x32x16_bf16 v[114:129], v[170:173], v[178:181], v[114:129]
	v_mfma_f32_32x32x16_bf16 v[98:113], v[170:173], v[182:185], v[98:113]
	v_mfma_f32_32x32x16_bf16 v[82:97], v[170:173], v[186:189], v[82:97]
	v_mfma_f32_32x32x16_bf16 v[66:81], v[170:173], v[190:193], v[66:81]
	v_mfma_f32_32x32x16_bf16 v[50:65], v[174:177], v[178:181], v[50:65]
	v_mfma_f32_32x32x16_bf16 v[34:49], v[174:177], v[182:185], v[34:49]
	v_mfma_f32_32x32x16_bf16 v[18:33], v[174:177], v[186:189], v[18:33]
	v_mfma_f32_32x32x16_bf16 v[2:17], v[174:177], v[190:193], v[2:17]
	s_add_u32 s6, s6, 0x80
	s_addc_u32 s7, s7, 0
	s_add_i32 s3, s3, 0x10000
	s_waitcnt vmcnt(0) lgkmcnt(0)
	s_barrier
	v_add3_u32 v170, s30, v136, v143
	v_add3_u32 v174, s30, v144, v146
	ds_read_b128 v[170:173], v170
	v_add3_u32 v178, s30, v145, v151
	ds_read_b128 v[174:177], v174
	v_add3_u32 v182, s30, v152, v156
	ds_read_b128 v[178:181], v178 offset:32768
	v_add3_u32 v186, s30, v155, v157
	ds_read_b128 v[182:185], v182 offset:32768
	v_add3_u32 v190, s30, v158, v168
	ds_read_b128 v[186:189], v186 offset:32768
	ds_read_b128 v[190:193], v190 offset:32768
	v_mfma_f32_32x32x16_bf16 v[114:129], v[194:197], v[202:205], v[114:129]
	v_mfma_f32_32x32x16_bf16 v[98:113], v[194:197], v[206:209], v[98:113]
	v_mfma_f32_32x32x16_bf16 v[82:97], v[194:197], v[210:213], v[82:97]
	v_mfma_f32_32x32x16_bf16 v[66:81], v[194:197], v[226:229], v[66:81]
	v_mfma_f32_32x32x16_bf16 v[50:65], v[198:201], v[202:205], v[50:65]
	v_mfma_f32_32x32x16_bf16 v[34:49], v[198:201], v[206:209], v[34:49]
	v_mfma_f32_32x32x16_bf16 v[18:33], v[198:201], v[210:213], v[18:33]
	v_mfma_f32_32x32x16_bf16 v[2:17], v[198:201], v[226:229], v[2:17]
	s_cmpk_lg_i32 s6, 0x780
	s_cbranch_scc1 .LBB0_173
; DI f32x16 mfma(bf16x8 a, bf16x8 b, f32x16 c) { return __builtin_amdgcn_mfma_f32_32x32x16_bf16(a, b, c, 0, 0, 0); }
; DI void wait_vm0() { asm volatile("s_waitcnt vmcnt(0)" ::: "memory"); }
;     ...
;     if (!more) epi.pre(row0 + wm * 64, col0 + wn * (32 * NTW), lane, w, lds);
;     bf16x8 fa[2][2], fb[2][NTW];
; #pragma unroll
;     for (int mt = 0; mt < 2; ++mt) { int row = wm * 64 + mt * 32 + l31; fa[0][mt] = *(const bf16x8*)(cur + row * (BK * 2) + ((hh ^ swz<BK>(row)) << 4)); }
; #pragma unroll
;     for (int nt = 0; nt < NTW; ++nt) { int row = wn * (32 * NTW) + nt * 32 + l31; fb[0][nt] = *(const bf16x8*)(cur + ABYTES + row * (BK * 2) + ((hh ^ swz<BK>(row)) << 4)); }
; #pragma unroll
;     for (int kk = 0; kk < NKK; ++kk) {
;       if (kk + 1 < NKK) {
;         const int ch = (kk + 1) * 2 + hh;
; #pragma unroll
;         for (int mt = 0; mt < 2; ++mt) { int row = wm * 64 + mt * 32 + l31; fa[(kk + 1) & 1][mt] = *(const bf16x8*)(cur + row * (BK * 2) + ((ch ^ swz<BK>(row)) << 4)); }
; #pragma unroll
;         for (int nt = 0; nt < NTW; ++nt) { int row = wn * (32 * NTW) + nt * 32 + l31; fb[(kk + 1) & 1][nt] = *(const bf16x8*)(cur + ABYTES + row * (BK * 2) + ((ch ^ swz<BK>(row)) << 4)); }
;       }
;       if (more) {
; #pragma unroll
;         for (int q = 0; q < PPK; ++q) {
;           const int pi = kk * PPK + q;
;           if (pi < NPA) stage_piece<BM, BK>(An, lda, nxt, tid, pi, wv);
;           else if (pi < NP) stage_piece<BN, BK>(Bn, ldb, nxt + ABYTES, tid, pi - NPA, wv);
;         }
;       }
;       __builtin_amdgcn_s_setprio(1);
; #pragma unroll
;       for (int mt = 0; mt < 2; ++mt)
; #pragma unroll
;         for (int nt = 0; nt < NTW; ++nt) acc[mt][nt] = mfma(fa[kk & 1][mt], fb[kk & 1][nt], acc[mt][nt]);
;       __builtin_amdgcn_s_setprio(0);
;       __builtin_amdgcn_sched_barrier(0);
;     }
;     wait_vm0();
;     __syncthreads();
;   DI void xpass(int ps, int grow0, int gcol0, int lane, int w, char* lds) const {
;     char* xs = lds + (ps & 1) * 65536 + __builtin_amdgcn_readfirstlane(w) * 8192;
;     const float* xsrc = Xin + (size_t)(grow0 + (ps >> 1) * 32 + (ps & 1) * 16 + (lane >> 5)) * D_ + gcol0 + (lane & 31) * 4;
; #pragma unroll
;     for (int pc = 0; pc < 8; ++pc)
;       __builtin_amdgcn_global_load_lds((const unsigned*)(xsrc + (size_t)(2 * pc) * D_), (__attribute__((address_space(3))) unsigned*)(xs + pc * 1024), 16, 0, 0);
;   }
	s_waitcnt lgkmcnt(0)
	v_readlane_b32 s3, v253, 9
	v_readlane_b32 s6, v253, 27
	v_readfirstlane_b32 s2, v134
	v_or_b32_e32 v130, s3, v135
	v_add_u32_e32 v130, v130, v169
	v_ashrrev_i32_e32 v131, 31, v130
	v_lshlrev_b64 v[130:131], 12, v[130:131]
	v_add_u32_e32 v132, s6, v164
	v_ashrrev_i32_e32 v133, 31, v132
	v_lshl_add_u64 v[130:131], s[10:11], 0, v[130:131]
	v_lshlrev_b32_e32 v0, 4, v0
	s_lshl_b32 s2, s2, 13
	v_lshl_add_u64 v[130:131], v[132:133], 2, v[130:131]
	v_and_b32_e32 v132, 0x1f0, v0
	v_mov_b32_e32 v133, v1
	v_lshl_add_u64 v[130:131], v[130:131], 0, v[132:133]
	s_mov_b32 m0, s2
	s_mov_b64 s[34:35], 0x2000
	global_load_lds_dwordx4 v[130:131], off
	v_lshl_add_u64 v[132:133], v[130:131], 0, s[34:35]
	s_or_b32 m0, s2, 0x400
	s_mov_b64 s[36:37], 0x4000
	global_load_lds_dwordx4 v[132:133], off
	v_lshl_add_u64 v[132:133], v[130:131], 0, s[36:37]
	s_or_b32 m0, s2, 0x800
	s_mov_b64 s[40:41], 0x6000
	global_load_lds_dwordx4 v[132:133], off
	v_lshl_add_u64 v[132:133], v[130:131], 0, s[40:41]
	s_or_b32 m0, s2, 0xc00
	s_mov_b64 s[44:45], 0x8000
	global_load_lds_dwordx4 v[132:133], off
	v_lshl_add_u64 v[132:133], v[130:131], 0, s[44:45]
	s_or_b32 m0, s2, 0x1000
	s_mov_b64 s[46:47], 0xa000
	global_load_lds_dwordx4 v[132:133], off
	v_lshl_add_u64 v[132:133], v[130:131], 0, s[46:47]
	s_or_b32 m0, s2, 0x1400
	s_mov_b64 s[52:53], 0xc000
	global_load_lds_dwordx4 v[132:133], off
	v_lshl_add_u64 v[132:133], v[130:131], 0, s[52:53]
	s_or_b32 m0, s2, 0x1800
	s_mov_b64 s[54:55], 0xe000
	global_load_lds_dwordx4 v[132:133], off
	v_lshl_add_u64 v[130:131], v[130:131], 0, s[54:55]
	s_or_b32 m0, s2, 0x1c00
	v_add_u32_e32 v0, s30, v136
	global_load_lds_dwordx4 v[130:131], off
	v_add_u32_e32 v134, s30, v144
	v_add_u32_e32 v130, v0, v143
	v_add_u32_e32 v135, v134, v146
	ds_read_b128 v[130:133], v130
	ds_read_b128 v[170:173], v135
	v_add_u32_e32 v135, s30, v145
	v_add_u32_e32 v136, v135, v151
	v_add_u32_e32 v143, s30, v152
	v_add_u32_e32 v144, v143, v156
	ds_read_b128 v[174:177], v136 offset:32768
	ds_read_b128 v[178:181], v144 offset:32768
	v_add_u32_e32 v136, s30, v155
	v_add_u32_e32 v144, v136, v157
	v_add_u32_e32 v164, s30, v158
	v_add_u32_e32 v145, v164, v168
	ds_read_b128 v[182:185], v144 offset:32768
	ds_read_b128 v[186:189], v145 offset:32768
	v_add_u32_e32 v144, v0, v166
	v_add_u32_e32 v145, v134, v167
	ds_read_b128 v[166:169], v144
	ds_read_b128 v[190:193], v145
	v_add_u32_e32 v144, v135, v161
	v_add_u32_e32 v145, v143, v163
	ds_read_b128 v[194:197], v144 offset:32768
	ds_read_b128 v[198:201], v145 offset:32768
	v_add_u32_e32 v144, v136, v159
	v_add_u32_e32 v145, v164, v160
	ds_read_b128 v[156:159], v144 offset:32768
	ds_read_b128 v[202:205], v145 offset:32768
	v_readlane_b32 s7, v253, 28
	s_setprio 1
	s_waitcnt lgkmcnt(0)
	v_mfma_f32_32x32x16_bf16 v[114:129], v[130:133], v[174:177], v[114:129]
	v_mfma_f32_32x32x16_bf16 v[98:113], v[130:133], v[178:181], v[98:113]
	v_mfma_f32_32x32x16_bf16 v[82:97], v[130:133], v[182:185], v[82:97]
	v_mfma_f32_32x32x16_bf16 v[66:81], v[130:133], v[186:189], v[66:81]
	v_mfma_f32_32x32x16_bf16 v[50:65], v[170:173], v[174:177], v[50:65]
	v_mfma_f32_32x32x16_bf16 v[34:49], v[170:173], v[178:181], v[34:49]
	v_mfma_f32_32x32x16_bf16 v[18:33], v[170:173], v[182:185], v[18:33]
	v_mfma_f32_32x32x16_bf16 v[2:17], v[170:173], v[186:189], v[2:17]
	s_setprio 0
	v_add_u32_e32 v130, v0, v153
	v_add_u32_e32 v144, v134, v154
	ds_read_b128 v[130:133], v130
	ds_read_b128 v[152:155], v144
	v_add_u32_e32 v144, v135, v149
	v_add_u32_e32 v145, v143, v150
	ds_read_b128 v[170:173], v144 offset:32768
	ds_read_b128 v[174:177], v145 offset:32768
	v_add_u32_e32 v144, v136, v147
	v_add_u32_e32 v148, v164, v148
	ds_read_b128 v[144:147], v144 offset:32768
	ds_read_b128 v[148:151], v148 offset:32768
	s_setprio 1
	v_mfma_f32_32x32x16_bf16 v[114:129], v[166:169], v[194:197], v[114:129]
	v_mfma_f32_32x32x16_bf16 v[98:113], v[166:169], v[198:201], v[98:113]
	v_mfma_f32_32x32x16_bf16 v[82:97], v[166:169], v[156:159], v[82:97]
	v_mfma_f32_32x32x16_bf16 v[66:81], v[166:169], v[202:205], v[66:81]
	v_mfma_f32_32x32x16_bf16 v[50:65], v[190:193], v[194:197], v[50:65]
	v_mfma_f32_32x32x16_bf16 v[34:49], v[190:193], v[198:201], v[34:49]
	v_mfma_f32_32x32x16_bf16 v[18:33], v[190:193], v[156:159], v[18:33]
	v_mfma_f32_32x32x16_bf16 v[2:17], v[190:193], v[202:205], v[2:17]
	s_setprio 0
	v_add_u32_e32 v0, v0, v141
	v_add_u32_e32 v134, v134, v142
	ds_read_b128 v[156:159], v0
	ds_read_b128 v[166:169], v134
	v_add_u32_e32 v0, v135, v139
	v_add_u32_e32 v134, v143, v140
	ds_read_b128 v[140:143], v0 offset:32768
	ds_read_b128 v[178:181], v134 offset:32768
	v_add_u32_e32 v0, v136, v137
	v_add_u32_e32 v138, v164, v138
	ds_read_b128 v[134:137], v0 offset:32768
	ds_read_b128 v[182:185], v138 offset:32768
	s_setprio 1
	s_waitcnt lgkmcnt(9)
	v_mfma_f32_32x32x16_bf16 v[114:129], v[130:133], v[170:173], v[114:129]
	s_waitcnt lgkmcnt(8)
	v_mfma_f32_32x32x16_bf16 v[98:113], v[130:133], v[174:177], v[98:113]
	s_waitcnt lgkmcnt(7)
	v_mfma_f32_32x32x16_bf16 v[82:97], v[130:133], v[144:147], v[82:97]
	s_waitcnt lgkmcnt(6)
	v_mfma_f32_32x32x16_bf16 v[66:81], v[130:133], v[148:151], v[66:81]
	v_mfma_f32_32x32x16_bf16 v[50:65], v[152:155], v[170:173], v[50:65]
	v_mfma_f32_32x32x16_bf16 v[34:49], v[152:155], v[174:177], v[34:49]
	v_mfma_f32_32x32x16_bf16 v[18:33], v[152:155], v[144:147], v[18:33]
	v_mfma_f32_32x32x16_bf16 v[2:17], v[152:155], v[148:151], v[2:17]
	s_setprio 0
	s_setprio 1
	s_waitcnt lgkmcnt(3)
	v_mfma_f32_32x32x16_bf16 v[114:129], v[156:159], v[140:143], v[114:129]
	s_waitcnt lgkmcnt(2)
	v_mfma_f32_32x32x16_bf16 v[98:113], v[156:159], v[178:181], v[98:113]
	s_waitcnt lgkmcnt(1)
	v_mfma_f32_32x32x16_bf16 v[82:97], v[156:159], v[134:137], v[82:97]
	s_waitcnt lgkmcnt(0)
	v_mfma_f32_32x32x16_bf16 v[66:81], v[156:159], v[182:185], v[66:81]
	v_mfma_f32_32x32x16_bf16 v[50:65], v[166:169], v[140:143], v[50:65]
	v_mfma_f32_32x32x16_bf16 v[34:49], v[166:169], v[178:181], v[34:49]
	v_mfma_f32_32x32x16_bf16 v[18:33], v[166:169], v[134:137], v[18:33]
	v_mfma_f32_32x32x16_bf16 v[2:17], v[166:169], v[182:185], v[2:17]
	s_setprio 0
	v_mov_b32_e32 v164, v216
	s_waitcnt vmcnt(0)
	s_barrier
;   DI void xpass(int ps, int grow0, int gcol0, int lane, int w, char* lds) const {
;     char* xs = lds + (ps & 1) * 65536 + __builtin_amdgcn_readfirstlane(w) * 8192;
;     const float* xsrc = Xin + (size_t)(grow0 + (ps >> 1) * 32 + (ps & 1) * 16 + (lane >> 5)) * D_ + gcol0 + (lane & 31) * 4;
; #pragma unroll
;     for (int pc = 0; pc < 8; ++pc)
;       __builtin_amdgcn_global_load_lds((const unsigned*)(xsrc + (size_t)(2 * pc) * D_), (__attribute__((address_space(3))) unsigned*)(xs + pc * 1024), 16, 0, 0);
;   }
;   DI void operator()(f32x16 (&acc)[2][4], int grow0, int gcol0, int lane, int w, char* lds) {
;     ...
;     for (int ps = 0; ps < 4; ++ps) {
;       const int mt = ps >> 1;
;       if (ps + 1 < 4) {
;         if (ps >= 1) asm volatile("s_waitcnt lgkmcnt(0)" ::: "memory");
;         xpass(ps + 1, grow0, gcol0, lane, w, lds);
;         if (ps >= 1) asm volatile("s_waitcnt vmcnt(8)" ::: "memory");
;       } else asm volatile("s_waitcnt vmcnt(0)" ::: "memory");
;       const char* xs = lds + (ps & 1) * 65536 + w * 8192;
; #pragma unroll
;       for (int qq = 0; qq < 2; ++qq)
; #pragma unroll
;         for (int e = 0; e < 4; ++e) {
;           const int i = 4 * (2 * (ps & 1) + qq) + e;
;           const float* xr = (const float*)(xs + (8 * qq + 4 * hh + e) * 512) + l31;
;           float s1 = 0.f, s2 = 0.f;
; #pragma unroll
;           for (int nt = 0; nt < 4; ++nt) {
;             float v = (acc[mt][nt][i] + bia[nt]) * csc[nt];
;             float z = ALPHA * xr[nt * 32] + hs * v;
;             acc[mt][nt][i] = z; s1 += z; s2 += z * z;
;           }
;           s1 = row16_sum(s1); s2 = row16_sum(s2);
;           if ((lane & 15) == 0) { f32x2 sv = {s1, s2}; *(f32x2*)(redw + (mt * 32 + (i & 3) + 8 * (i >> 2)) * 2) = sv; }
;         }
	v_mov_b32_e32 v133, v1
	v_ashrrev_i32_e32 v158, 6, v164
	v_lshrrev_b32_e32 v0, 30, v158
	v_add_u32_e32 v0, v158, v0
	v_ashrrev_i32_e32 v134, 2, v0
	v_mul_i32_i24_e32 v0, 4, v134
	v_sub_u32_e32 v0, v158, v0
	v_lshlrev_b32_e32 v135, 6, v0
	v_add_u32_e32 v163, s3, v135
	v_bfe_u32 v0, v164, 5, 1
	v_or_b32_e32 v159, v163, v0
	v_or_b32_e32 v130, 16, v159
	v_lshlrev_b32_e32 v200, 2, v164
	v_ashrrev_i32_e32 v131, 31, v130
	v_lshl_add_u32 v184, v134, 7, s6
	v_and_b32_e32 v0, 0x7c, v200
	v_lshlrev_b64 v[130:131], 12, v[130:131]
	v_ashrrev_i32_e32 v185, 31, v184
	v_readfirstlane_b32 s2, v158
	v_lshl_add_u64 v[130:131], s[10:11], 0, v[130:131]
	v_lshlrev_b32_e32 v0, 2, v0
	s_lshl_b32 s2, s2, 13
	v_lshl_add_u64 v[130:131], v[184:185], 2, v[130:131]
	v_mov_b32_e32 v132, v0
	s_add_i32 m0, s2, 0x10000
	v_lshl_add_u64 v[130:131], v[130:131], 0, v[132:133]
	global_load_lds_dwordx4 v[130:131], off
	v_lshl_add_u64 v[132:133], v[130:131], 0, s[34:35]
	s_add_i32 m0, s2, 0x10400
	v_and_b32_e32 v210, 0xc0, v135
	global_load_lds_dwordx4 v[132:133], off
	v_lshl_add_u64 v[132:133], v[130:131], 0, s[36:37]
	s_add_i32 m0, s2, 0x10800
	v_mov_b32_e32 v136, v114
	global_load_lds_dwordx4 v[132:133], off
	v_lshl_add_u64 v[132:133], v[130:131], 0, s[40:41]
	s_add_i32 m0, s2, 0x10c00
	v_mov_b32_e32 v137, v82
	global_load_lds_dwordx4 v[132:133], off
	v_lshl_add_u64 v[132:133], v[130:131], 0, s[44:45]
	s_add_i32 m0, s2, 0x11000
	v_mov_b32_e32 v140, v98
	global_load_lds_dwordx4 v[132:133], off
	v_lshl_add_u64 v[132:133], v[130:131], 0, s[46:47]
	s_add_i32 m0, s2, 0x11400
	v_mov_b32_e32 v141, v82
	global_load_lds_dwordx4 v[132:133], off
	v_lshl_add_u64 v[132:133], v[130:131], 0, s[52:53]
	s_add_i32 m0, s2, 0x11800
	v_lshl_add_u64 v[130:131], v[130:131], 0, s[54:55]
	global_load_lds_dwordx4 v[132:133], off
	s_add_i32 m0, s2, 0x11c00
	v_bfe_u32 v132, v164, 4, 1
	global_load_lds_dwordx4 v[130:131], off
	v_and_b32_e32 v130, 31, v164
	v_lshlrev_b32_e32 v131, 1, v134
	v_bfe_u32 v134, v164, 3, 3
	v_and_or_b32 v131, v131, 2, v132
	v_and_b32_e32 v132, 4, v134
	v_lshlrev_b32_e32 v130, 2, v130
	v_lshl_or_b32 v138, v158, 13, v130
	v_lshlrev_b32_e32 v154, 9, v132
	v_or_b32_e32 v133, v210, v132
	v_and_b32_e32 v130, 15, v164
	v_or_b32_e32 v132, v138, v154
	v_lshlrev_b32_e32 v135, 3, v133
	v_lshl_or_b32 v139, v131, 11, v221
	v_cmp_eq_u32_e32 vcc, 0, v130
	s_waitcnt vmcnt(8)
	ds_read2_b32 v[130:131], v132 offset1:32
	ds_read2_b32 v[132:133], v132 offset0:64 offset1:96
	v_pk_add_f32 v[136:137], v[136:137], 0 op_sel_hi:[1,0]
	v_pk_add_f32 v[140:141], v[140:141], 0 op_sel_hi:[1,0]
	s_mov_b32 s2, s67
	s_waitcnt lgkmcnt(0)
	v_mov_b32_e32 v142, v130
	v_mov_b32_e32 v143, v132
	v_mov_b32_e32 v130, v131
	v_mov_b32_e32 v131, v132
	v_pk_fma_f32 v[186:187], v[142:143], s[2:3], v[136:137] op_sel_hi:[1,0,1]
	v_pk_fma_f32 v[188:189], v[130:131], s[2:3], v[140:141] op_sel_hi:[1,0,1]
	v_pk_mul_f32 v[144:145], v[142:143], s[2:3] op_sel_hi:[1,0]
	v_pk_mul_f32 v[142:143], v[186:187], v[186:187]
	v_pk_mul_f32 v[130:131], v[188:189], v[188:189]
	v_pk_mov_b32 v[136:137], v[136:137], v[142:143] op_sel:[1,0]
	v_pk_mov_b32 v[130:131], v[144:145], v[130:131] op_sel:[1,0]
	v_add_f32_e32 v180, 0, v66
	v_pk_add_f32 v[130:131], v[136:137], v[130:131]
	v_pk_add_f32 v[136:137], v[186:187], v[188:189]
	v_pk_mul_f32 v[140:141], v[186:187], v[188:189]
	v_fmac_f32_e32 v180, 0x3fd744fd, v133
	v_mov_b32_e32 v137, v141
	v_pk_add_f32 v[130:131], v[136:137], v[130:131]
	v_mul_f32_e32 v181, v180, v180
	v_pk_add_f32 v[130:131], v[130:131], v[180:181]
	v_add_u32_e32 v181, v139, v135
	s_nop 0
	v_mov_b32_dpp v132, v130 quad_perm:[1,0,3,2] row_mask:0xf bank_mask:0xf bound_ctrl:1
	v_mov_b32_dpp v133, v131 quad_perm:[1,0,3,2] row_mask:0xf bank_mask:0xf bound_ctrl:1
	v_pk_add_f32 v[130:131], v[130:131], v[132:133]
	s_nop 1
	v_mov_b32_dpp v132, v130 quad_perm:[2,3,0,1] row_mask:0xf bank_mask:0xf bound_ctrl:1
	v_mov_b32_dpp v133, v131 quad_perm:[2,3,0,1] row_mask:0xf bank_mask:0xf bound_ctrl:1
	v_pk_add_f32 v[130:131], v[130:131], v[132:133]
	s_nop 1
	v_mov_b32_dpp v132, v130 row_half_mirror row_mask:0xf bank_mask:0xf bound_ctrl:1
	v_mov_b32_dpp v133, v131 row_half_mirror row_mask:0xf bank_mask:0xf bound_ctrl:1
	v_pk_add_f32 v[130:131], v[130:131], v[132:133]
	s_nop 1
	v_mov_b32_dpp v132, v130 row_mirror row_mask:0xf bank_mask:0xf bound_ctrl:1
	v_mov_b32_dpp v133, v131 row_mirror row_mask:0xf bank_mask:0xf bound_ctrl:1
	s_and_saveexec_b64 s[6:7], vcc
	v_pk_add_f32 v[130:131], v[130:131], v[132:133]
	ds_write_b64 v181, v[130:131]
	s_or_b64 exec, exec, s[6:7]
	v_add_u32_e32 v168, v138, v154
	ds_read2_b32 v[130:131], v168 offset0:128 offset1:160
	ds_read2_b32 v[132:133], v168 offset0:192 offset1:224
	v_mov_b32_e32 v82, v115
	v_add_f32_e32 v152, 0, v67
	v_pk_add_f32 v[66:67], v[82:83], 0 op_sel_hi:[1,0]
	v_mov_b32_e32 v82, v99
	v_pk_add_f32 v[82:83], v[82:83], 0 op_sel_hi:[1,0]
	s_waitcnt lgkmcnt(1)
	v_mov_b32_e32 v98, v130
	s_waitcnt lgkmcnt(0)
;   DI void operator()(f32x16 (&acc)[2][4], int grow0, int gcol0, int lane, int w, char* lds) {
;     ...
;       for (int qq = 0; qq < 2; ++qq)
; #pragma unroll
;         for (int e = 0; e < 4; ++e) {
;           const int i = 4 * (2 * (ps & 1) + qq) + e;
;           const float* xr = (const float*)(xs + (8 * qq + 4 * hh + e) * 512) + l31;
;           float s1 = 0.f, s2 = 0.f;
; #pragma unroll
;           for (int nt = 0; nt < 4; ++nt) {
;             float v = (acc[mt][nt][i] + bia[nt]) * csc[nt];
;             float z = ALPHA * xr[nt * 32] + hs * v;
;             acc[mt][nt][i] = z; s1 += z; s2 += z * z;
;           }
;           s1 = row16_sum(s1); s2 = row16_sum(s2);
;           if ((lane & 15) == 0) { f32x2 sv = {s1, s2}; *(f32x2*)(redw + (mt * 32 + (i & 3) + 8 * (i >> 2)) * 2) = sv; }
;         }
	v_mov_b32_e32 v99, v132
	s_mov_b32 s2, s67
	v_mov_b32_e32 v130, v131
	v_mov_b32_e32 v131, v132
	v_pk_fma_f32 v[166:167], v[98:99], s[2:3], v[66:67] op_sel_hi:[1,0,1]
	v_pk_fma_f32 v[172:173], v[130:131], s[2:3], v[82:83] op_sel_hi:[1,0,1]
	v_pk_mul_f32 v[114:115], v[98:99], s[2:3] op_sel_hi:[1,0]
	v_pk_mul_f32 v[98:99], v[166:167], v[166:167]
	v_pk_mul_f32 v[82:83], v[172:173], v[172:173]
	v_pk_mov_b32 v[66:67], v[66:67], v[98:99] op_sel:[1,0]
	v_pk_mov_b32 v[82:83], v[114:115], v[82:83] op_sel:[1,0]
	v_pk_mul_f32 v[98:99], v[166:167], v[172:173]
	v_pk_add_f32 v[66:67], v[66:67], v[82:83]
	v_pk_add_f32 v[82:83], v[166:167], v[172:173]
	v_fmac_f32_e32 v152, 0x3fd744fd, v133
	v_mov_b32_e32 v83, v99
	v_pk_add_f32 v[66:67], v[82:83], v[66:67]
	v_mul_f32_e32 v153, v152, v152
	v_pk_add_f32 v[66:67], v[66:67], v[152:153]
	s_nop 1
	v_mov_b32_dpp v82, v66 quad_perm:[1,0,3,2] row_mask:0xf bank_mask:0xf bound_ctrl:1
	v_mov_b32_dpp v83, v67 quad_perm:[1,0,3,2] row_mask:0xf bank_mask:0xf bound_ctrl:1
	v_pk_add_f32 v[66:67], v[66:67], v[82:83]
	s_nop 1
	v_mov_b32_dpp v82, v66 quad_perm:[2,3,0,1] row_mask:0xf bank_mask:0xf bound_ctrl:1
	v_mov_b32_dpp v83, v67 quad_perm:[2,3,0,1] row_mask:0xf bank_mask:0xf bound_ctrl:1
	v_pk_add_f32 v[66:67], v[66:67], v[82:83]
	s_nop 1
	v_mov_b32_dpp v82, v66 row_half_mirror row_mask:0xf bank_mask:0xf bound_ctrl:1
	v_mov_b32_dpp v83, v67 row_half_mirror row_mask:0xf bank_mask:0xf bound_ctrl:1
	v_pk_add_f32 v[66:67], v[66:67], v[82:83]
	s_nop 1
	v_mov_b32_dpp v82, v66 row_mirror row_mask:0xf bank_mask:0xf bound_ctrl:1
	v_mov_b32_dpp v83, v67 row_mirror row_mask:0xf bank_mask:0xf bound_ctrl:1
	s_and_saveexec_b64 s[6:7], vcc
	v_pk_add_f32 v[66:67], v[66:67], v[82:83]
	ds_write_b64 v181, v[66:67] offset:8
	s_or_b64 exec, exec, s[6:7]
	v_add_u32_e32 v153, 0x400, v168
	ds_read2_b32 v[82:83], v153 offset1:32
	ds_read2_b32 v[98:99], v153 offset0:64 offset1:96
	v_mov_b32_e32 v114, v116
	v_mov_b32_e32 v115, v84
	v_mov_b32_e32 v130, v100
	v_mov_b32_e32 v131, v84
	v_pk_add_f32 v[114:115], v[114:115], 0 op_sel_hi:[1,0]
	v_pk_add_f32 v[130:131], v[130:131], 0 op_sel_hi:[1,0]
	s_waitcnt lgkmcnt(1)
	v_mov_b32_e32 v132, v82
	s_waitcnt lgkmcnt(0)
	v_mov_b32_e32 v133, v98
	s_mov_b32 s2, s67
	v_mov_b32_e32 v140, v83
	v_mov_b32_e32 v141, v98
	v_pk_fma_f32 v[82:83], v[132:133], s[2:3], v[114:115] op_sel_hi:[1,0,1]
	v_pk_fma_f32 v[150:151], v[140:141], s[2:3], v[130:131] op_sel_hi:[1,0,1]
	v_pk_mul_f32 v[136:137], v[132:133], s[2:3] op_sel_hi:[1,0]
	v_pk_mul_f32 v[132:133], v[82:83], v[82:83]
	v_pk_mul_f32 v[130:131], v[150:151], v[150:151]
	v_pk_mov_b32 v[114:115], v[114:115], v[132:133] op_sel:[1,0]
	v_pk_mov_b32 v[130:131], v[136:137], v[130:131] op_sel:[1,0]
	v_add_f32_e32 v66, 0, v68
	v_pk_add_f32 v[114:115], v[114:115], v[130:131]
	v_pk_add_f32 v[130:131], v[82:83], v[150:151]
	v_pk_mul_f32 v[132:133], v[82:83], v[150:151]
	v_fmac_f32_e32 v66, 0x3fd744fd, v99
	v_mov_b32_e32 v131, v133
	v_pk_add_f32 v[114:115], v[130:131], v[114:115]
	v_mul_f32_e32 v67, v66, v66
	v_pk_add_f32 v[98:99], v[114:115], v[66:67]
	s_nop 1
	v_mov_b32_dpp v114, v98 quad_perm:[1,0,3,2] row_mask:0xf bank_mask:0xf bound_ctrl:1
	v_mov_b32_dpp v115, v99 quad_perm:[1,0,3,2] row_mask:0xf bank_mask:0xf bound_ctrl:1
	v_pk_add_f32 v[98:99], v[98:99], v[114:115]
	s_nop 1
	v_mov_b32_dpp v114, v98 quad_perm:[2,3,0,1] row_mask:0xf bank_mask:0xf bound_ctrl:1
	v_mov_b32_dpp v115, v99 quad_perm:[2,3,0,1] row_mask:0xf bank_mask:0xf bound_ctrl:1
	v_pk_add_f32 v[98:99], v[98:99], v[114:115]
	s_nop 1
	v_mov_b32_dpp v114, v98 row_half_mirror row_mask:0xf bank_mask:0xf bound_ctrl:1
	v_mov_b32_dpp v115, v99 row_half_mirror row_mask:0xf bank_mask:0xf bound_ctrl:1
	v_pk_add_f32 v[98:99], v[98:99], v[114:115]
	s_nop 1
	v_mov_b32_dpp v114, v98 row_mirror row_mask:0xf bank_mask:0xf bound_ctrl:1
	v_mov_b32_dpp v115, v99 row_mirror row_mask:0xf bank_mask:0xf bound_ctrl:1
	s_and_saveexec_b64 s[6:7], vcc
	v_pk_add_f32 v[98:99], v[98:99], v[114:115]
	ds_write_b64 v181, v[98:99] offset:16
	s_or_b64 exec, exec, s[6:7]
	v_lshlrev_b32_e32 v139, 9, v134
	v_or_b32_e32 v146, 0x600, v139
	v_add_u32_e32 v151, v138, v146
	ds_read2_b32 v[98:99], v151 offset1:32
	ds_read2_b32 v[114:115], v151 offset0:64 offset1:96
	v_mov_b32_e32 v84, v117
	v_pk_add_f32 v[116:117], v[84:85], 0 op_sel_hi:[1,0]
	v_mov_b32_e32 v84, v101
	v_pk_add_f32 v[84:85], v[84:85], 0 op_sel_hi:[1,0]
	s_waitcnt lgkmcnt(1)
	v_mov_b32_e32 v100, v98
	s_waitcnt lgkmcnt(0)
	v_mov_b32_e32 v101, v114
	s_mov_b32 s2, s67
	v_mov_b32_e32 v132, v99
	v_mov_b32_e32 v133, v114
	v_pk_mul_f32 v[130:131], v[100:101], s[2:3] op_sel_hi:[1,0]
	v_pk_fma_f32 v[98:99], v[100:101], s[2:3], v[116:117] op_sel_hi:[1,0,1]
	v_pk_fma_f32 v[100:101], v[132:133], s[2:3], v[84:85] op_sel_hi:[1,0,1]
	v_pk_mul_f32 v[134:135], v[98:99], v[98:99]
	v_pk_mul_f32 v[84:85], v[100:101], v[100:101]
	v_pk_mov_b32 v[116:117], v[116:117], v[134:135] op_sel:[1,0]
	v_pk_mov_b32 v[84:85], v[130:131], v[84:85] op_sel:[1,0]
	v_add_f32_e32 v68, 0, v69
	v_pk_add_f32 v[84:85], v[116:117], v[84:85]
	v_pk_add_f32 v[116:117], v[98:99], v[100:101]
	v_pk_mul_f32 v[130:131], v[98:99], v[100:101]
	v_fmac_f32_e32 v68, 0x3fd744fd, v115
	v_mov_b32_e32 v117, v131
	v_pk_add_f32 v[84:85], v[116:117], v[84:85]
	v_mul_f32_e32 v69, v68, v68
	v_pk_add_f32 v[84:85], v[84:85], v[68:69]
	s_nop 1
	v_mov_b32_dpp v114, v84 quad_perm:[1,0,3,2] row_mask:0xf bank_mask:0xf bound_ctrl:1
	v_mov_b32_dpp v115, v85 quad_perm:[1,0,3,2] row_mask:0xf bank_mask:0xf bound_ctrl:1
	v_pk_add_f32 v[84:85], v[84:85], v[114:115]
	s_nop 1
	v_mov_b32_dpp v114, v84 quad_perm:[2,3,0,1] row_mask:0xf bank_mask:0xf bound_ctrl:1
	v_mov_b32_dpp v115, v85 quad_perm:[2,3,0,1] row_mask:0xf bank_mask:0xf bound_ctrl:1
	v_pk_add_f32 v[84:85], v[84:85], v[114:115]
	s_nop 1
	v_mov_b32_dpp v114, v84 row_half_mirror row_mask:0xf bank_mask:0xf bound_ctrl:1
	v_mov_b32_dpp v115, v85 row_half_mirror row_mask:0xf bank_mask:0xf bound_ctrl:1
	v_pk_add_f32 v[84:85], v[84:85], v[114:115]
	s_nop 1
	v_mov_b32_dpp v114, v84 row_mirror row_mask:0xf bank_mask:0xf bound_ctrl:1
	v_mov_b32_dpp v115, v85 row_mirror row_mask:0xf bank_mask:0xf bound_ctrl:1
	s_and_saveexec_b64 s[6:7], vcc
	v_pk_add_f32 v[84:85], v[84:85], v[114:115]
	ds_write_b64 v181, v[84:85] offset:24
	s_or_b64 exec, exec, s[6:7]
	v_add_u32_e32 v67, 0x1000, v168
	ds_read2_b32 v[114:115], v67 offset1:32
	ds_read2_b32 v[130:131], v67 offset0:64 offset1:96
	v_mov_b32_e32 v116, v118
	v_mov_b32_e32 v117, v86
	v_pk_add_f32 v[132:133], v[116:117], 0 op_sel_hi:[1,0]
	v_mov_b32_e32 v116, v102
	v_pk_add_f32 v[116:117], v[116:117], 0 op_sel_hi:[1,0]
	s_waitcnt lgkmcnt(1)
;   DI void operator()(f32x16 (&acc)[2][4], int grow0, int gcol0, int lane, int w, char* lds) {
;     ...
;       for (int qq = 0; qq < 2; ++qq)
; #pragma unroll
;         for (int e = 0; e < 4; ++e) {
;           const int i = 4 * (2 * (ps & 1) + qq) + e;
;           const float* xr = (const float*)(xs + (8 * qq + 4 * hh + e) * 512) + l31;
;           float s1 = 0.f, s2 = 0.f;
; #pragma unroll
;           for (int nt = 0; nt < 4; ++nt) {
;             float v = (acc[mt][nt][i] + bia[nt]) * csc[nt];
;             float z = ALPHA * xr[nt * 32] + hs * v;
;             acc[mt][nt][i] = z; s1 += z; s2 += z * z;
;           }
;           s1 = row16_sum(s1); s2 = row16_sum(s2);
;           if ((lane & 15) == 0) { f32x2 sv = {s1, s2}; *(f32x2*)(redw + (mt * 32 + (i & 3) + 8 * (i >> 2)) * 2) = sv; }
;         }
	v_mov_b32_e32 v134, v114
	s_waitcnt lgkmcnt(0)
	v_mov_b32_e32 v135, v130
	s_mov_b32 s2, s67
	v_mov_b32_e32 v140, v115
	v_mov_b32_e32 v141, v130
	v_pk_fma_f32 v[114:115], v[134:135], s[2:3], v[132:133] op_sel_hi:[1,0,1]
	v_pk_fma_f32 v[116:117], v[140:141], s[2:3], v[116:117] op_sel_hi:[1,0,1]
	v_pk_mul_f32 v[136:137], v[134:135], s[2:3] op_sel_hi:[1,0]
	v_pk_mul_f32 v[134:135], v[114:115], v[114:115]
	v_pk_mul_f32 v[140:141], v[116:117], v[116:117]
	v_pk_mov_b32 v[132:133], v[132:133], v[134:135] op_sel:[1,0]
	v_pk_mov_b32 v[134:135], v[136:137], v[140:141] op_sel:[1,0]
	v_add_f32_e32 v84, 0, v70
	v_pk_add_f32 v[132:133], v[132:133], v[134:135]
	v_pk_add_f32 v[134:135], v[114:115], v[116:117]
	v_pk_mul_f32 v[136:137], v[114:115], v[116:117]
	v_fmac_f32_e32 v84, 0x3fd744fd, v131
	v_mov_b32_e32 v135, v137
	v_pk_add_f32 v[132:133], v[134:135], v[132:133]
	v_mul_f32_e32 v85, v84, v84
	v_pk_add_f32 v[130:131], v[132:133], v[84:85]
	s_nop 1
	v_mov_b32_dpp v132, v130 quad_perm:[1,0,3,2] row_mask:0xf bank_mask:0xf bound_ctrl:1
	v_mov_b32_dpp v133, v131 quad_perm:[1,0,3,2] row_mask:0xf bank_mask:0xf bound_ctrl:1
	v_pk_add_f32 v[130:131], v[130:131], v[132:133]
	s_nop 1
	v_mov_b32_dpp v132, v130 quad_perm:[2,3,0,1] row_mask:0xf bank_mask:0xf bound_ctrl:1
	v_mov_b32_dpp v133, v131 quad_perm:[2,3,0,1] row_mask:0xf bank_mask:0xf bound_ctrl:1
	v_pk_add_f32 v[130:131], v[130:131], v[132:133]
	s_nop 1
	v_mov_b32_dpp v132, v130 row_half_mirror row_mask:0xf bank_mask:0xf bound_ctrl:1
	v_mov_b32_dpp v133, v131 row_half_mirror row_mask:0xf bank_mask:0xf bound_ctrl:1
	v_pk_add_f32 v[130:131], v[130:131], v[132:133]
	s_nop 1
	v_mov_b32_dpp v132, v130 row_mirror row_mask:0xf bank_mask:0xf bound_ctrl:1
	v_mov_b32_dpp v133, v131 row_mirror row_mask:0xf bank_mask:0xf bound_ctrl:1
	s_and_saveexec_b64 s[6:7], vcc
	v_pk_add_f32 v[130:131], v[130:131], v[132:133]
	ds_write_b64 v181, v[130:131] offset:64
	s_or_b64 exec, exec, s[6:7]
	ds_read2_b32 v[130:131], v67 offset0:128 offset1:160
	ds_read2_b32 v[132:133], v67 offset0:192 offset1:224
	v_mov_b32_e32 v86, v119
	v_pk_add_f32 v[134:135], v[86:87], 0 op_sel_hi:[1,0]
	v_mov_b32_e32 v86, v103
	v_pk_add_f32 v[86:87], v[86:87], 0 op_sel_hi:[1,0]
	s_waitcnt lgkmcnt(1)
	v_mov_b32_e32 v102, v130
	s_waitcnt lgkmcnt(0)
	v_mov_b32_e32 v103, v132
	s_mov_b32 s2, s67
	v_mov_b32_e32 v118, v131
	v_mov_b32_e32 v119, v132
	v_pk_mul_f32 v[136:137], v[102:103], s[2:3] op_sel_hi:[1,0]
	v_pk_fma_f32 v[102:103], v[102:103], s[2:3], v[134:135] op_sel_hi:[1,0,1]
	v_pk_fma_f32 v[118:119], v[118:119], s[2:3], v[86:87] op_sel_hi:[1,0,1]
	v_pk_mul_f32 v[130:131], v[102:103], v[102:103]
	v_pk_mul_f32 v[86:87], v[118:119], v[118:119]
	v_pk_mov_b32 v[130:131], v[134:135], v[130:131] op_sel:[1,0]
	v_pk_mov_b32 v[86:87], v[136:137], v[86:87] op_sel:[1,0]
	v_add_f32_e32 v70, 0, v71
	v_pk_add_f32 v[86:87], v[130:131], v[86:87]
	v_pk_add_f32 v[130:131], v[102:103], v[118:119]
	v_pk_mul_f32 v[134:135], v[102:103], v[118:119]
	v_fmac_f32_e32 v70, 0x3fd744fd, v133
	v_mov_b32_e32 v131, v135
	v_pk_add_f32 v[86:87], v[130:131], v[86:87]
	v_mul_f32_e32 v71, v70, v70
	v_pk_add_f32 v[86:87], v[86:87], v[70:71]
	s_nop 1
	v_mov_b32_dpp v130, v86 quad_perm:[1,0,3,2] row_mask:0xf bank_mask:0xf bound_ctrl:1
	v_mov_b32_dpp v131, v87 quad_perm:[1,0,3,2] row_mask:0xf bank_mask:0xf bound_ctrl:1
	v_pk_add_f32 v[86:87], v[86:87], v[130:131]
	s_nop 1
	v_mov_b32_dpp v130, v86 quad_perm:[2,3,0,1] row_mask:0xf bank_mask:0xf bound_ctrl:1
	v_mov_b32_dpp v131, v87 quad_perm:[2,3,0,1] row_mask:0xf bank_mask:0xf bound_ctrl:1
	v_pk_add_f32 v[86:87], v[86:87], v[130:131]
	s_nop 1
	v_mov_b32_dpp v130, v86 row_half_mirror row_mask:0xf bank_mask:0xf bound_ctrl:1
	v_mov_b32_dpp v131, v87 row_half_mirror row_mask:0xf bank_mask:0xf bound_ctrl:1
	v_pk_add_f32 v[86:87], v[86:87], v[130:131]
	s_nop 1
	v_mov_b32_dpp v130, v86 row_mirror row_mask:0xf bank_mask:0xf bound_ctrl:1
	v_mov_b32_dpp v131, v87 row_mirror row_mask:0xf bank_mask:0xf bound_ctrl:1
	s_and_saveexec_b64 s[6:7], vcc
	v_pk_add_f32 v[86:87], v[86:87], v[130:131]
	ds_write_b64 v181, v[86:87] offset:72
	s_or_b64 exec, exec, s[6:7]
	v_add_u32_e32 v69, 0x1400, v168
	ds_read2_b32 v[130:131], v69 offset1:32
	ds_read2_b32 v[134:135], v69 offset0:64 offset1:96
	v_mov_b32_e32 v132, v120
	v_mov_b32_e32 v133, v88
	v_pk_add_f32 v[136:137], v[132:133], 0 op_sel_hi:[1,0]
	v_mov_b32_e32 v132, v104
	v_pk_add_f32 v[132:133], v[132:133], 0 op_sel_hi:[1,0]
	s_waitcnt lgkmcnt(1)
	v_mov_b32_e32 v140, v130
	s_waitcnt lgkmcnt(0)
	v_mov_b32_e32 v141, v134
	s_mov_b32 s2, s67
	v_mov_b32_e32 v144, v131
	v_mov_b32_e32 v145, v134
	v_pk_fma_f32 v[130:131], v[140:141], s[2:3], v[136:137] op_sel_hi:[1,0,1]
	v_pk_fma_f32 v[132:133], v[144:145], s[2:3], v[132:133] op_sel_hi:[1,0,1]
	v_pk_mul_f32 v[142:143], v[140:141], s[2:3] op_sel_hi:[1,0]
	v_pk_mul_f32 v[140:141], v[130:131], v[130:131]
	v_pk_mul_f32 v[144:145], v[132:133], v[132:133]
	v_pk_mov_b32 v[136:137], v[136:137], v[140:141] op_sel:[1,0]
	v_pk_mov_b32 v[140:141], v[142:143], v[144:145] op_sel:[1,0]
	v_add_f32_e32 v86, 0, v72
	v_pk_add_f32 v[136:137], v[136:137], v[140:141]
	v_pk_add_f32 v[140:141], v[130:131], v[132:133]
	v_pk_mul_f32 v[142:143], v[130:131], v[132:133]
	v_fmac_f32_e32 v86, 0x3fd744fd, v135
	v_mov_b32_e32 v141, v143
	v_pk_add_f32 v[136:137], v[140:141], v[136:137]
	v_mul_f32_e32 v87, v86, v86
	v_pk_add_f32 v[134:135], v[136:137], v[86:87]
	s_nop 1
	v_mov_b32_dpp v136, v134 quad_perm:[1,0,3,2] row_mask:0xf bank_mask:0xf bound_ctrl:1
	v_mov_b32_dpp v137, v135 quad_perm:[1,0,3,2] row_mask:0xf bank_mask:0xf bound_ctrl:1
	v_pk_add_f32 v[134:135], v[134:135], v[136:137]
	s_nop 1
	v_mov_b32_dpp v136, v134 quad_perm:[2,3,0,1] row_mask:0xf bank_mask:0xf bound_ctrl:1
	v_mov_b32_dpp v137, v135 quad_perm:[2,3,0,1] row_mask:0xf bank_mask:0xf bound_ctrl:1
	v_pk_add_f32 v[134:135], v[134:135], v[136:137]
	s_nop 1
	v_mov_b32_dpp v136, v134 row_half_mirror row_mask:0xf bank_mask:0xf bound_ctrl:1
	v_mov_b32_dpp v137, v135 row_half_mirror row_mask:0xf bank_mask:0xf bound_ctrl:1
	v_pk_add_f32 v[134:135], v[134:135], v[136:137]
	s_nop 1
	v_mov_b32_dpp v136, v134 row_mirror row_mask:0xf bank_mask:0xf bound_ctrl:1
	v_mov_b32_dpp v137, v135 row_mirror row_mask:0xf bank_mask:0xf bound_ctrl:1
	s_and_saveexec_b64 s[6:7], vcc
	v_pk_add_f32 v[134:135], v[134:135], v[136:137]
	ds_write_b64 v181, v[134:135] offset:80
	s_or_b64 exec, exec, s[6:7]
	v_or_b32_e32 v101, 0x1600, v139
	v_add_u32_e32 v71, v138, v101
	ds_read2_b32 v[134:135], v71 offset1:32
	ds_read2_b32 v[136:137], v71 offset0:64 offset1:96
	v_mov_b32_e32 v88, v121
	v_pk_add_f32 v[120:121], v[88:89], 0 op_sel_hi:[1,0]
	v_mov_b32_e32 v88, v105
	v_pk_add_f32 v[104:105], v[88:89], 0 op_sel_hi:[1,0]
	s_waitcnt lgkmcnt(1)
;   DI void xpass(int ps, int grow0, int gcol0, int lane, int w, char* lds) const {
;     char* xs = lds + (ps & 1) * 65536 + __builtin_amdgcn_readfirstlane(w) * 8192;
;     const float* xsrc = Xin + (size_t)(grow0 + (ps >> 1) * 32 + (ps & 1) * 16 + (lane >> 5)) * D_ + gcol0 + (lane & 31) * 4;
; #pragma unroll
;     for (int pc = 0; pc < 8; ++pc)
;       __builtin_amdgcn_global_load_lds((const unsigned*)(xsrc + (size_t)(2 * pc) * D_), (__attribute__((address_space(3))) unsigned*)(xs + pc * 1024), 16, 0, 0);
;   }
;   DI void operator()(f32x16 (&acc)[2][4], int grow0, int gcol0, int lane, int w, char* lds) {
;     ...
;       if (ps + 1 < 4) {
;         if (ps >= 1) asm volatile("s_waitcnt lgkmcnt(0)" ::: "memory");
;         xpass(ps + 1, grow0, gcol0, lane, w, lds);
;         if (ps >= 1) asm volatile("s_waitcnt vmcnt(8)" ::: "memory");
;       } else asm volatile("s_waitcnt vmcnt(0)" ::: "memory");
;       const char* xs = lds + (ps & 1) * 65536 + w * 8192;
; #pragma unroll
;       for (int qq = 0; qq < 2; ++qq)
; #pragma unroll
;         for (int e = 0; e < 4; ++e) {
;           const int i = 4 * (2 * (ps & 1) + qq) + e;
;           const float* xr = (const float*)(xs + (8 * qq + 4 * hh + e) * 512) + l31;
;           float s1 = 0.f, s2 = 0.f;
; #pragma unroll
;           for (int nt = 0; nt < 4; ++nt) {
;             float v = (acc[mt][nt][i] + bia[nt]) * csc[nt];
;             float z = ALPHA * xr[nt * 32] + hs * v;
;             acc[mt][nt][i] = z; s1 += z; s2 += z * z;
;           }
;           s1 = row16_sum(s1); s2 = row16_sum(s2);
;           if ((lane & 15) == 0) { f32x2 sv = {s1, s2}; *(f32x2*)(redw + (mt * 32 + (i & 3) + 8 * (i >> 2)) * 2) = sv; }
;         }
	v_mov_b32_e32 v88, v134
	s_waitcnt lgkmcnt(0)
	v_mov_b32_e32 v89, v136
	s_mov_b32 s2, s67
	v_mov_b32_e32 v134, v135
	v_mov_b32_e32 v135, v136
	v_pk_mul_f32 v[140:141], v[88:89], s[2:3] op_sel_hi:[1,0]
	v_pk_fma_f32 v[88:89], v[88:89], s[2:3], v[120:121] op_sel_hi:[1,0,1]
	v_pk_fma_f32 v[104:105], v[134:135], s[2:3], v[104:105] op_sel_hi:[1,0,1]
	v_pk_mul_f32 v[142:143], v[88:89], v[88:89]
	v_pk_mul_f32 v[134:135], v[104:105], v[104:105]
	v_pk_mov_b32 v[120:121], v[120:121], v[142:143] op_sel:[1,0]
	v_pk_mov_b32 v[134:135], v[140:141], v[134:135] op_sel:[1,0]
	v_add_f32_e32 v72, 0, v73
	v_pk_add_f32 v[120:121], v[120:121], v[134:135]
	v_pk_add_f32 v[134:135], v[88:89], v[104:105]
	v_pk_mul_f32 v[140:141], v[88:89], v[104:105]
	v_fmac_f32_e32 v72, 0x3fd744fd, v137
	v_mov_b32_e32 v135, v141
	v_pk_add_f32 v[120:121], v[134:135], v[120:121]
	v_mul_f32_e32 v73, v72, v72
	v_pk_add_f32 v[120:121], v[120:121], v[72:73]
	s_nop 1
	v_mov_b32_dpp v134, v120 quad_perm:[1,0,3,2] row_mask:0xf bank_mask:0xf bound_ctrl:1
	v_mov_b32_dpp v135, v121 quad_perm:[1,0,3,2] row_mask:0xf bank_mask:0xf bound_ctrl:1
	v_pk_add_f32 v[120:121], v[120:121], v[134:135]
	s_nop 1
	v_mov_b32_dpp v134, v120 quad_perm:[2,3,0,1] row_mask:0xf bank_mask:0xf bound_ctrl:1
	v_mov_b32_dpp v135, v121 quad_perm:[2,3,0,1] row_mask:0xf bank_mask:0xf bound_ctrl:1
	v_pk_add_f32 v[120:121], v[120:121], v[134:135]
	s_nop 1
	v_mov_b32_dpp v134, v120 row_half_mirror row_mask:0xf bank_mask:0xf bound_ctrl:1
	v_mov_b32_dpp v135, v121 row_half_mirror row_mask:0xf bank_mask:0xf bound_ctrl:1
	v_pk_add_f32 v[120:121], v[120:121], v[134:135]
	s_nop 1
	v_mov_b32_dpp v134, v120 row_mirror row_mask:0xf bank_mask:0xf bound_ctrl:1
	v_mov_b32_dpp v135, v121 row_mirror row_mask:0xf bank_mask:0xf bound_ctrl:1
	s_and_saveexec_b64 s[6:7], vcc
	v_pk_add_f32 v[120:121], v[120:121], v[134:135]
	ds_write_b64 v181, v[120:121] offset:88
	s_or_b64 exec, exec, s[6:7]
	v_or_b32_e32 v120, 32, v159
	v_ashrrev_i32_e32 v121, 31, v120
	v_lshlrev_b64 v[120:121], 12, v[120:121]
	v_readfirstlane_b32 s2, v158
	v_lshl_add_u64 v[120:121], s[10:11], 0, v[120:121]
	s_lshl_b32 s2, s2, 13
	v_lshl_add_u64 v[120:121], v[184:185], 2, v[120:121]
	s_waitcnt lgkmcnt(0)
	v_lshl_add_u64 v[120:121], v[120:121], 0, v[0:1]
	s_mov_b32 m0, s2
	s_mov_b64 s[6:7], 0x2000
	global_load_lds_dwordx4 v[120:121], off
	v_lshl_add_u64 v[134:135], v[120:121], 0, s[6:7]
	s_or_b32 m0, s2, 0x400
	s_mov_b64 s[6:7], 0x4000
	global_load_lds_dwordx4 v[134:135], off
	v_lshl_add_u64 v[134:135], v[120:121], 0, s[6:7]
	s_or_b32 m0, s2, 0x800
	s_mov_b64 s[6:7], 0x6000
	global_load_lds_dwordx4 v[134:135], off
	v_lshl_add_u64 v[134:135], v[120:121], 0, s[6:7]
	s_or_b32 m0, s2, 0xc00
	s_mov_b64 s[6:7], 0x8000
	global_load_lds_dwordx4 v[134:135], off
	v_lshl_add_u64 v[134:135], v[120:121], 0, s[6:7]
	s_or_b32 m0, s2, 0x1000
	s_mov_b64 s[6:7], 0xa000
	global_load_lds_dwordx4 v[134:135], off
	v_lshl_add_u64 v[134:135], v[120:121], 0, s[6:7]
	s_or_b32 m0, s2, 0x1400
	s_mov_b64 s[6:7], 0xc000
	global_load_lds_dwordx4 v[134:135], off
	v_lshl_add_u64 v[134:135], v[120:121], 0, s[6:7]
	s_or_b32 m0, s2, 0x1800
	s_mov_b64 s[6:7], 0xe000
	global_load_lds_dwordx4 v[134:135], off
	v_lshl_add_u64 v[120:121], v[120:121], 0, s[6:7]
	s_or_b32 m0, s2, 0x1c00
	v_add_u32_e32 v105, 0x10000, v138
	global_load_lds_dwordx4 v[120:121], off
	s_waitcnt vmcnt(8)
	v_add_u32_e32 v73, v105, v154
	ds_read2_b32 v[134:135], v73 offset1:32
	ds_read2_b32 v[138:139], v73 offset0:64 offset1:96
	v_mov_b32_e32 v136, v122
	v_mov_b32_e32 v137, v90
	v_pk_add_f32 v[140:141], v[136:137], 0 op_sel_hi:[1,0]
	v_mov_b32_e32 v136, v106
	v_pk_add_f32 v[136:137], v[136:137], 0 op_sel_hi:[1,0]
	s_waitcnt lgkmcnt(0)
	v_mov_b32_e32 v142, v134
	v_mov_b32_e32 v143, v138
	s_mov_b32 s2, s67
	v_mov_b32_e32 v148, v135
	v_mov_b32_e32 v149, v138
	v_pk_fma_f32 v[134:135], v[142:143], s[2:3], v[140:141] op_sel_hi:[1,0,1]
	v_pk_fma_f32 v[136:137], v[148:149], s[2:3], v[136:137] op_sel_hi:[1,0,1]
	v_pk_mul_f32 v[144:145], v[142:143], s[2:3] op_sel_hi:[1,0]
	v_pk_mul_f32 v[142:143], v[134:135], v[134:135]
	v_pk_mul_f32 v[148:149], v[136:137], v[136:137]
	v_pk_mov_b32 v[140:141], v[140:141], v[142:143] op_sel:[1,0]
	v_pk_mov_b32 v[142:143], v[144:145], v[148:149] op_sel:[1,0]
	v_add_f32_e32 v120, 0, v74
	v_pk_add_f32 v[140:141], v[140:141], v[142:143]
	v_pk_add_f32 v[142:143], v[134:135], v[136:137]
	v_pk_mul_f32 v[144:145], v[134:135], v[136:137]
	v_fmac_f32_e32 v120, 0x3fd744fd, v139
	v_mov_b32_e32 v143, v145
	v_pk_add_f32 v[140:141], v[142:143], v[140:141]
	v_mul_f32_e32 v121, v120, v120
	v_pk_add_f32 v[138:139], v[140:141], v[120:121]
	s_nop 1
	v_mov_b32_dpp v140, v138 quad_perm:[1,0,3,2] row_mask:0xf bank_mask:0xf bound_ctrl:1
	v_mov_b32_dpp v141, v139 quad_perm:[1,0,3,2] row_mask:0xf bank_mask:0xf bound_ctrl:1
	v_pk_add_f32 v[138:139], v[138:139], v[140:141]
	s_nop 1
	v_mov_b32_dpp v140, v138 quad_perm:[2,3,0,1] row_mask:0xf bank_mask:0xf bound_ctrl:1
	v_mov_b32_dpp v141, v139 quad_perm:[2,3,0,1] row_mask:0xf bank_mask:0xf bound_ctrl:1
	v_pk_add_f32 v[138:139], v[138:139], v[140:141]
	s_nop 1
	v_mov_b32_dpp v140, v138 row_half_mirror row_mask:0xf bank_mask:0xf bound_ctrl:1
	v_mov_b32_dpp v141, v139 row_half_mirror row_mask:0xf bank_mask:0xf bound_ctrl:1
	v_pk_add_f32 v[138:139], v[138:139], v[140:141]
	s_nop 1
	v_mov_b32_dpp v140, v138 row_mirror row_mask:0xf bank_mask:0xf bound_ctrl:1
	v_mov_b32_dpp v141, v139 row_mirror row_mask:0xf bank_mask:0xf bound_ctrl:1
	s_and_saveexec_b64 s[6:7], vcc
	v_pk_add_f32 v[138:139], v[138:139], v[140:141]
	ds_write_b64 v181, v[138:139] offset:128
	s_or_b64 exec, exec, s[6:7]
	v_or_b32_e32 v74, 0x200, v154
	v_add_u32_e32 v85, v105, v74
	ds_read2_b32 v[138:139], v85 offset1:32
	ds_read2_b32 v[140:141], v85 offset0:64 offset1:96
	v_mov_b32_e32 v90, v123
	v_pk_add_f32 v[142:143], v[90:91], 0 op_sel_hi:[1,0]
	v_mov_b32_e32 v90, v107
	v_pk_add_f32 v[90:91], v[90:91], 0 op_sel_hi:[1,0]
	s_waitcnt lgkmcnt(1)
;   DI void operator()(f32x16 (&acc)[2][4], int grow0, int gcol0, int lane, int w, char* lds) {
;     ...
;       for (int qq = 0; qq < 2; ++qq)
; #pragma unroll
;         for (int e = 0; e < 4; ++e) {
;           const int i = 4 * (2 * (ps & 1) + qq) + e;
;           const float* xr = (const float*)(xs + (8 * qq + 4 * hh + e) * 512) + l31;
;           float s1 = 0.f, s2 = 0.f;
; #pragma unroll
;           for (int nt = 0; nt < 4; ++nt) {
;             float v = (acc[mt][nt][i] + bia[nt]) * csc[nt];
;             float z = ALPHA * xr[nt * 32] + hs * v;
;             acc[mt][nt][i] = z; s1 += z; s2 += z * z;
;           }
;           s1 = row16_sum(s1); s2 = row16_sum(s2);
;           if ((lane & 15) == 0) { f32x2 sv = {s1, s2}; *(f32x2*)(redw + (mt * 32 + (i & 3) + 8 * (i >> 2)) * 2) = sv; }
;         }
	v_mov_b32_e32 v106, v138
	s_waitcnt lgkmcnt(0)
	v_mov_b32_e32 v107, v140
	s_mov_b32 s2, s67
	v_mov_b32_e32 v122, v139
	v_mov_b32_e32 v123, v140
	v_pk_mul_f32 v[144:145], v[106:107], s[2:3] op_sel_hi:[1,0]
	v_pk_fma_f32 v[106:107], v[106:107], s[2:3], v[142:143] op_sel_hi:[1,0,1]
	v_pk_fma_f32 v[122:123], v[122:123], s[2:3], v[90:91] op_sel_hi:[1,0,1]
	v_pk_mul_f32 v[138:139], v[106:107], v[106:107]
	v_pk_mul_f32 v[90:91], v[122:123], v[122:123]
	v_pk_mov_b32 v[138:139], v[142:143], v[138:139] op_sel:[1,0]
	v_pk_mov_b32 v[90:91], v[144:145], v[90:91] op_sel:[1,0]
	v_add_f32_e32 v74, 0, v75
	v_pk_add_f32 v[90:91], v[138:139], v[90:91]
	v_pk_add_f32 v[138:139], v[106:107], v[122:123]
	v_pk_mul_f32 v[142:143], v[106:107], v[122:123]
	v_fmac_f32_e32 v74, 0x3fd744fd, v141
	v_mov_b32_e32 v139, v143
	v_pk_add_f32 v[90:91], v[138:139], v[90:91]
	v_mul_f32_e32 v75, v74, v74
	v_pk_add_f32 v[90:91], v[90:91], v[74:75]
	s_nop 1
	v_mov_b32_dpp v138, v90 quad_perm:[1,0,3,2] row_mask:0xf bank_mask:0xf bound_ctrl:1
	v_mov_b32_dpp v139, v91 quad_perm:[1,0,3,2] row_mask:0xf bank_mask:0xf bound_ctrl:1
	v_pk_add_f32 v[90:91], v[90:91], v[138:139]
	s_nop 1
	v_mov_b32_dpp v138, v90 quad_perm:[2,3,0,1] row_mask:0xf bank_mask:0xf bound_ctrl:1
	v_mov_b32_dpp v139, v91 quad_perm:[2,3,0,1] row_mask:0xf bank_mask:0xf bound_ctrl:1
	v_pk_add_f32 v[90:91], v[90:91], v[138:139]
	s_nop 1
	v_mov_b32_dpp v138, v90 row_half_mirror row_mask:0xf bank_mask:0xf bound_ctrl:1
	v_mov_b32_dpp v139, v91 row_half_mirror row_mask:0xf bank_mask:0xf bound_ctrl:1
	v_pk_add_f32 v[90:91], v[90:91], v[138:139]
	s_nop 1
	v_mov_b32_dpp v138, v90 row_mirror row_mask:0xf bank_mask:0xf bound_ctrl:1
	v_mov_b32_dpp v139, v91 row_mirror row_mask:0xf bank_mask:0xf bound_ctrl:1
	s_and_saveexec_b64 s[6:7], vcc
	v_pk_add_f32 v[90:91], v[90:91], v[138:139]
	ds_write_b64 v181, v[90:91] offset:136
	s_or_b64 exec, exec, s[6:7]
	v_or_b32_e32 v75, 0x400, v154
	v_add_u32_e32 v75, v105, v75
	ds_read2_b32 v[138:139], v75 offset1:32
	ds_read2_b32 v[142:143], v75 offset0:64 offset1:96
	v_mov_b32_e32 v140, v124
	v_mov_b32_e32 v141, v92
	v_pk_add_f32 v[144:145], v[140:141], 0 op_sel_hi:[1,0]
	v_mov_b32_e32 v140, v108
	v_pk_add_f32 v[140:141], v[140:141], 0 op_sel_hi:[1,0]
	s_waitcnt lgkmcnt(1)
	v_mov_b32_e32 v148, v138
	s_waitcnt lgkmcnt(0)
	v_mov_b32_e32 v149, v142
	s_mov_b32 s2, s67
	v_mov_b32_e32 v160, v139
	v_mov_b32_e32 v161, v142
	v_pk_fma_f32 v[138:139], v[148:149], s[2:3], v[144:145] op_sel_hi:[1,0,1]
	v_pk_fma_f32 v[140:141], v[160:161], s[2:3], v[140:141] op_sel_hi:[1,0,1]
	v_pk_mul_f32 v[156:157], v[148:149], s[2:3] op_sel_hi:[1,0]
	v_pk_mul_f32 v[148:149], v[138:139], v[138:139]
	v_pk_mul_f32 v[160:161], v[140:141], v[140:141]
	v_pk_mov_b32 v[144:145], v[144:145], v[148:149] op_sel:[1,0]
	v_pk_mov_b32 v[148:149], v[156:157], v[160:161] op_sel:[1,0]
	v_add_f32_e32 v90, 0, v76
	v_pk_add_f32 v[144:145], v[144:145], v[148:149]
	v_pk_add_f32 v[148:149], v[138:139], v[140:141]
	v_pk_mul_f32 v[156:157], v[138:139], v[140:141]
	v_fmac_f32_e32 v90, 0x3fd744fd, v143
	v_mov_b32_e32 v149, v157
	v_pk_add_f32 v[144:145], v[148:149], v[144:145]
	v_mul_f32_e32 v91, v90, v90
	v_pk_add_f32 v[142:143], v[144:145], v[90:91]
	s_nop 1
	v_mov_b32_dpp v144, v142 quad_perm:[1,0,3,2] row_mask:0xf bank_mask:0xf bound_ctrl:1
	v_mov_b32_dpp v145, v143 quad_perm:[1,0,3,2] row_mask:0xf bank_mask:0xf bound_ctrl:1
	v_pk_add_f32 v[142:143], v[142:143], v[144:145]
	s_nop 1
	v_mov_b32_dpp v144, v142 quad_perm:[2,3,0,1] row_mask:0xf bank_mask:0xf bound_ctrl:1
	v_mov_b32_dpp v145, v143 quad_perm:[2,3,0,1] row_mask:0xf bank_mask:0xf bound_ctrl:1
	v_pk_add_f32 v[142:143], v[142:143], v[144:145]
	s_nop 1
	v_mov_b32_dpp v144, v142 row_half_mirror row_mask:0xf bank_mask:0xf bound_ctrl:1
	v_mov_b32_dpp v145, v143 row_half_mirror row_mask:0xf bank_mask:0xf bound_ctrl:1
	v_pk_add_f32 v[142:143], v[142:143], v[144:145]
	s_nop 1
	v_mov_b32_dpp v144, v142 row_mirror row_mask:0xf bank_mask:0xf bound_ctrl:1
	v_mov_b32_dpp v145, v143 row_mirror row_mask:0xf bank_mask:0xf bound_ctrl:1
	s_and_saveexec_b64 s[6:7], vcc
	v_pk_add_f32 v[142:143], v[142:143], v[144:145]
	ds_write_b64 v181, v[142:143] offset:144
	s_or_b64 exec, exec, s[6:7]
	v_add_u32_e32 v87, v105, v146
	ds_read2_b32 v[142:143], v87 offset1:32
	ds_read2_b32 v[144:145], v87 offset0:64 offset1:96
	v_mov_b32_e32 v92, v125
	v_pk_add_f32 v[146:147], v[92:93], 0 op_sel_hi:[1,0]
	v_mov_b32_e32 v92, v109
	v_pk_add_f32 v[92:93], v[92:93], 0 op_sel_hi:[1,0]
	s_waitcnt lgkmcnt(1)
	v_mov_b32_e32 v108, v142
	s_waitcnt lgkmcnt(0)
;   DI void operator()(f32x16 (&acc)[2][4], int grow0, int gcol0, int lane, int w, char* lds) {
;     ...
;       for (int qq = 0; qq < 2; ++qq)
; #pragma unroll
;         for (int e = 0; e < 4; ++e) {
;           const int i = 4 * (2 * (ps & 1) + qq) + e;
;           const float* xr = (const float*)(xs + (8 * qq + 4 * hh + e) * 512) + l31;
;           float s1 = 0.f, s2 = 0.f;
; #pragma unroll
;           for (int nt = 0; nt < 4; ++nt) {
;             float v = (acc[mt][nt][i] + bia[nt]) * csc[nt];
;             float z = ALPHA * xr[nt * 32] + hs * v;
;             acc[mt][nt][i] = z; s1 += z; s2 += z * z;
;           }
;           s1 = row16_sum(s1); s2 = row16_sum(s2);
;           if ((lane & 15) == 0) { f32x2 sv = {s1, s2}; *(f32x2*)(redw + (mt * 32 + (i & 3) + 8 * (i >> 2)) * 2) = sv; }
;         }
	v_mov_b32_e32 v109, v144
	s_mov_b32 s2, s67
	v_mov_b32_e32 v124, v143
	v_mov_b32_e32 v125, v144
	v_pk_mul_f32 v[148:149], v[108:109], s[2:3] op_sel_hi:[1,0]
	v_pk_fma_f32 v[108:109], v[108:109], s[2:3], v[146:147] op_sel_hi:[1,0,1]
	v_pk_fma_f32 v[124:125], v[124:125], s[2:3], v[92:93] op_sel_hi:[1,0,1]
	v_pk_mul_f32 v[142:143], v[108:109], v[108:109]
	v_pk_mul_f32 v[92:93], v[124:125], v[124:125]
	v_pk_mov_b32 v[142:143], v[146:147], v[142:143] op_sel:[1,0]
	v_pk_mov_b32 v[92:93], v[148:149], v[92:93] op_sel:[1,0]
	v_add_f32_e32 v76, 0, v77
	v_pk_add_f32 v[92:93], v[142:143], v[92:93]
	v_pk_add_f32 v[142:143], v[108:109], v[124:125]
	v_pk_mul_f32 v[146:147], v[108:109], v[124:125]
	v_fmac_f32_e32 v76, 0x3fd744fd, v145
	v_mov_b32_e32 v143, v147
	v_pk_add_f32 v[92:93], v[142:143], v[92:93]
	v_mul_f32_e32 v77, v76, v76
	v_pk_add_f32 v[92:93], v[92:93], v[76:77]
	s_nop 1
	v_mov_b32_dpp v142, v92 quad_perm:[1,0,3,2] row_mask:0xf bank_mask:0xf bound_ctrl:1
	v_mov_b32_dpp v143, v93 quad_perm:[1,0,3,2] row_mask:0xf bank_mask:0xf bound_ctrl:1
	v_pk_add_f32 v[92:93], v[92:93], v[142:143]
	s_nop 1
	v_mov_b32_dpp v142, v92 quad_perm:[2,3,0,1] row_mask:0xf bank_mask:0xf bound_ctrl:1
	v_mov_b32_dpp v143, v93 quad_perm:[2,3,0,1] row_mask:0xf bank_mask:0xf bound_ctrl:1
	v_pk_add_f32 v[92:93], v[92:93], v[142:143]
	s_nop 1
	v_mov_b32_dpp v142, v92 row_half_mirror row_mask:0xf bank_mask:0xf bound_ctrl:1
	v_mov_b32_dpp v143, v93 row_half_mirror row_mask:0xf bank_mask:0xf bound_ctrl:1
	v_pk_add_f32 v[92:93], v[92:93], v[142:143]
	s_nop 1
	v_mov_b32_dpp v142, v92 row_mirror row_mask:0xf bank_mask:0xf bound_ctrl:1
	v_mov_b32_dpp v143, v93 row_mirror row_mask:0xf bank_mask:0xf bound_ctrl:1
	s_and_saveexec_b64 s[6:7], vcc
	v_pk_add_f32 v[92:93], v[92:93], v[142:143]
	ds_write_b64 v181, v[92:93] offset:152
	s_or_b64 exec, exec, s[6:7]
	v_or_b32_e32 v77, 0x1000, v154
	v_add_u32_e32 v77, v105, v77
	ds_read2_b32 v[142:143], v77 offset1:32
	ds_read2_b32 v[146:147], v77 offset0:64 offset1:96
	v_mov_b32_e32 v144, v126
	v_mov_b32_e32 v145, v94
	v_pk_add_f32 v[148:149], v[144:145], 0 op_sel_hi:[1,0]
	v_mov_b32_e32 v144, v110
	v_pk_add_f32 v[144:145], v[144:145], 0 op_sel_hi:[1,0]
	s_waitcnt lgkmcnt(1)
	v_mov_b32_e32 v156, v142
	s_waitcnt lgkmcnt(0)
	v_mov_b32_e32 v157, v146
	s_mov_b32 s2, s67
	v_mov_b32_e32 v170, v143
	v_mov_b32_e32 v171, v146
	v_pk_fma_f32 v[142:143], v[156:157], s[2:3], v[148:149] op_sel_hi:[1,0,1]
	v_pk_fma_f32 v[144:145], v[170:171], s[2:3], v[144:145] op_sel_hi:[1,0,1]
	v_pk_mul_f32 v[160:161], v[156:157], s[2:3] op_sel_hi:[1,0]
	v_pk_mul_f32 v[156:157], v[142:143], v[142:143]
	v_pk_mul_f32 v[170:171], v[144:145], v[144:145]
	v_pk_mov_b32 v[148:149], v[148:149], v[156:157] op_sel:[1,0]
	v_pk_mov_b32 v[156:157], v[160:161], v[170:171] op_sel:[1,0]
	v_add_f32_e32 v92, 0, v78
	v_pk_add_f32 v[148:149], v[148:149], v[156:157]
	v_pk_add_f32 v[156:157], v[142:143], v[144:145]
	v_pk_mul_f32 v[160:161], v[142:143], v[144:145]
	v_fmac_f32_e32 v92, 0x3fd744fd, v147
	v_mov_b32_e32 v157, v161
	v_pk_add_f32 v[148:149], v[156:157], v[148:149]
	v_mul_f32_e32 v93, v92, v92
	v_pk_add_f32 v[146:147], v[148:149], v[92:93]
	s_nop 1
	v_mov_b32_dpp v148, v146 quad_perm:[1,0,3,2] row_mask:0xf bank_mask:0xf bound_ctrl:1
	v_mov_b32_dpp v149, v147 quad_perm:[1,0,3,2] row_mask:0xf bank_mask:0xf bound_ctrl:1
	v_pk_add_f32 v[146:147], v[146:147], v[148:149]
	s_nop 1
	v_mov_b32_dpp v148, v146 quad_perm:[2,3,0,1] row_mask:0xf bank_mask:0xf bound_ctrl:1
	v_mov_b32_dpp v149, v147 quad_perm:[2,3,0,1] row_mask:0xf bank_mask:0xf bound_ctrl:1
	v_pk_add_f32 v[146:147], v[146:147], v[148:149]
	s_nop 1
	v_mov_b32_dpp v148, v146 row_half_mirror row_mask:0xf bank_mask:0xf bound_ctrl:1
	v_mov_b32_dpp v149, v147 row_half_mirror row_mask:0xf bank_mask:0xf bound_ctrl:1
	v_pk_add_f32 v[146:147], v[146:147], v[148:149]
	s_nop 1
	v_mov_b32_dpp v148, v146 row_mirror row_mask:0xf bank_mask:0xf bound_ctrl:1
	v_mov_b32_dpp v149, v147 row_mirror row_mask:0xf bank_mask:0xf bound_ctrl:1
	s_and_saveexec_b64 s[6:7], vcc
	v_pk_add_f32 v[146:147], v[146:147], v[148:149]
	ds_write_b64 v181, v[146:147] offset:192
	s_or_b64 exec, exec, s[6:7]
	v_or_b32_e32 v78, 0x1200, v154
	v_add_u32_e32 v91, v105, v78
	ds_read2_b32 v[146:147], v91 offset1:32
	ds_read2_b32 v[148:149], v91 offset0:64 offset1:96
	v_mov_b32_e32 v94, v127
	v_pk_add_f32 v[156:157], v[94:95], 0 op_sel_hi:[1,0]
	v_mov_b32_e32 v94, v111
	v_pk_add_f32 v[94:95], v[94:95], 0 op_sel_hi:[1,0]
	s_waitcnt lgkmcnt(1)
	v_mov_b32_e32 v110, v146
	s_waitcnt lgkmcnt(0)
	v_mov_b32_e32 v111, v148
	s_mov_b32 s2, s67
	v_mov_b32_e32 v126, v147
	v_mov_b32_e32 v127, v148
	v_pk_mul_f32 v[160:161], v[110:111], s[2:3] op_sel_hi:[1,0]
	v_pk_fma_f32 v[110:111], v[110:111], s[2:3], v[156:157] op_sel_hi:[1,0,1]
	v_pk_fma_f32 v[126:127], v[126:127], s[2:3], v[94:95] op_sel_hi:[1,0,1]
	v_pk_mul_f32 v[146:147], v[110:111], v[110:111]
	v_pk_mul_f32 v[94:95], v[126:127], v[126:127]
	v_pk_mov_b32 v[146:147], v[156:157], v[146:147] op_sel:[1,0]
	v_pk_mov_b32 v[94:95], v[160:161], v[94:95] op_sel:[1,0]
	v_add_f32_e32 v78, 0, v79
	v_pk_add_f32 v[94:95], v[146:147], v[94:95]
	v_pk_add_f32 v[146:147], v[110:111], v[126:127]
	v_pk_mul_f32 v[156:157], v[110:111], v[126:127]
	v_fmac_f32_e32 v78, 0x3fd744fd, v149
	v_mov_b32_e32 v147, v157
	v_pk_add_f32 v[94:95], v[146:147], v[94:95]
	v_mul_f32_e32 v79, v78, v78
	v_pk_add_f32 v[94:95], v[94:95], v[78:79]
	s_nop 1
	v_mov_b32_dpp v146, v94 quad_perm:[1,0,3,2] row_mask:0xf bank_mask:0xf bound_ctrl:1
	v_mov_b32_dpp v147, v95 quad_perm:[1,0,3,2] row_mask:0xf bank_mask:0xf bound_ctrl:1
	v_pk_add_f32 v[94:95], v[94:95], v[146:147]
	s_nop 1
	v_mov_b32_dpp v146, v94 quad_perm:[2,3,0,1] row_mask:0xf bank_mask:0xf bound_ctrl:1
	v_mov_b32_dpp v147, v95 quad_perm:[2,3,0,1] row_mask:0xf bank_mask:0xf bound_ctrl:1
	v_pk_add_f32 v[94:95], v[94:95], v[146:147]
	s_nop 1
	v_mov_b32_dpp v146, v94 row_half_mirror row_mask:0xf bank_mask:0xf bound_ctrl:1
	v_mov_b32_dpp v147, v95 row_half_mirror row_mask:0xf bank_mask:0xf bound_ctrl:1
	v_pk_add_f32 v[94:95], v[94:95], v[146:147]
	s_nop 1
	v_mov_b32_dpp v146, v94 row_mirror row_mask:0xf bank_mask:0xf bound_ctrl:1
	v_mov_b32_dpp v147, v95 row_mirror row_mask:0xf bank_mask:0xf bound_ctrl:1
	s_and_saveexec_b64 s[6:7], vcc
	v_pk_add_f32 v[94:95], v[94:95], v[146:147]
	ds_write_b64 v181, v[94:95] offset:200
	s_or_b64 exec, exec, s[6:7]
	v_or_b32_e32 v79, 0x1400, v154
	v_add_u32_e32 v79, v105, v79
	ds_read2_b32 v[146:147], v79 offset1:32
	ds_read2_b32 v[154:155], v79 offset0:64 offset1:96
	v_mov_b32_e32 v148, v128
	v_mov_b32_e32 v149, v96
	v_pk_add_f32 v[156:157], v[148:149], 0 op_sel_hi:[1,0]
	v_mov_b32_e32 v148, v112
	v_pk_add_f32 v[148:149], v[148:149], 0 op_sel_hi:[1,0]
	s_waitcnt lgkmcnt(1)
;   DI void xpass(int ps, int grow0, int gcol0, int lane, int w, char* lds) const {
;     char* xs = lds + (ps & 1) * 65536 + __builtin_amdgcn_readfirstlane(w) * 8192;
;     const float* xsrc = Xin + (size_t)(grow0 + (ps >> 1) * 32 + (ps & 1) * 16 + (lane >> 5)) * D_ + gcol0 + (lane & 31) * 4;
; #pragma unroll
;     for (int pc = 0; pc < 8; ++pc)
;       __builtin_amdgcn_global_load_lds((const unsigned*)(xsrc + (size_t)(2 * pc) * D_), (__attribute__((address_space(3))) unsigned*)(xs + pc * 1024), 16, 0, 0);
;   }
;   DI void operator()(f32x16 (&acc)[2][4], int grow0, int gcol0, int lane, int w, char* lds) {
;     ...
;       if (ps + 1 < 4) {
;         if (ps >= 1) asm volatile("s_waitcnt lgkmcnt(0)" ::: "memory");
;         xpass(ps + 1, grow0, gcol0, lane, w, lds);
;         if (ps >= 1) asm volatile("s_waitcnt vmcnt(8)" ::: "memory");
;       } else asm volatile("s_waitcnt vmcnt(0)" ::: "memory");
;       const char* xs = lds + (ps & 1) * 65536 + w * 8192;
; #pragma unroll
;       for (int qq = 0; qq < 2; ++qq)
; #pragma unroll
;         for (int e = 0; e < 4; ++e) {
;           const int i = 4 * (2 * (ps & 1) + qq) + e;
;           const float* xr = (const float*)(xs + (8 * qq + 4 * hh + e) * 512) + l31;
;           float s1 = 0.f, s2 = 0.f;
; #pragma unroll
;           for (int nt = 0; nt < 4; ++nt) {
;             float v = (acc[mt][nt][i] + bia[nt]) * csc[nt];
;             float z = ALPHA * xr[nt * 32] + hs * v;
;             acc[mt][nt][i] = z; s1 += z; s2 += z * z;
;           }
;           s1 = row16_sum(s1); s2 = row16_sum(s2);
;           if ((lane & 15) == 0) { f32x2 sv = {s1, s2}; *(f32x2*)(redw + (mt * 32 + (i & 3) + 8 * (i >> 2)) * 2) = sv; }
;         }
	v_mov_b32_e32 v160, v146
	s_waitcnt lgkmcnt(0)
	v_mov_b32_e32 v161, v154
	s_mov_b32 s2, s67
	v_mov_b32_e32 v174, v147
	v_mov_b32_e32 v175, v154
	v_pk_fma_f32 v[146:147], v[160:161], s[2:3], v[156:157] op_sel_hi:[1,0,1]
	v_pk_fma_f32 v[148:149], v[174:175], s[2:3], v[148:149] op_sel_hi:[1,0,1]
	v_pk_mul_f32 v[170:171], v[160:161], s[2:3] op_sel_hi:[1,0]
	v_pk_mul_f32 v[160:161], v[146:147], v[146:147]
	v_pk_mul_f32 v[174:175], v[148:149], v[148:149]
	v_pk_mov_b32 v[156:157], v[156:157], v[160:161] op_sel:[1,0]
	v_pk_mov_b32 v[160:161], v[170:171], v[174:175] op_sel:[1,0]
	v_add_f32_e32 v94, 0, v80
	v_pk_add_f32 v[156:157], v[156:157], v[160:161]
	v_pk_add_f32 v[160:161], v[146:147], v[148:149]
	v_pk_mul_f32 v[170:171], v[146:147], v[148:149]
	v_fmac_f32_e32 v94, 0x3fd744fd, v155
	v_mov_b32_e32 v161, v171
	v_pk_add_f32 v[156:157], v[160:161], v[156:157]
	v_mul_f32_e32 v95, v94, v94
	v_pk_add_f32 v[154:155], v[156:157], v[94:95]
	s_nop 1
	v_mov_b32_dpp v156, v154 quad_perm:[1,0,3,2] row_mask:0xf bank_mask:0xf bound_ctrl:1
	v_mov_b32_dpp v157, v155 quad_perm:[1,0,3,2] row_mask:0xf bank_mask:0xf bound_ctrl:1
	v_pk_add_f32 v[154:155], v[154:155], v[156:157]
	s_nop 1
	v_mov_b32_dpp v156, v154 quad_perm:[2,3,0,1] row_mask:0xf bank_mask:0xf bound_ctrl:1
	v_mov_b32_dpp v157, v155 quad_perm:[2,3,0,1] row_mask:0xf bank_mask:0xf bound_ctrl:1
	v_pk_add_f32 v[154:155], v[154:155], v[156:157]
	s_nop 1
	v_mov_b32_dpp v156, v154 row_half_mirror row_mask:0xf bank_mask:0xf bound_ctrl:1
	v_mov_b32_dpp v157, v155 row_half_mirror row_mask:0xf bank_mask:0xf bound_ctrl:1
	v_pk_add_f32 v[154:155], v[154:155], v[156:157]
	s_nop 1
	v_mov_b32_dpp v156, v154 row_mirror row_mask:0xf bank_mask:0xf bound_ctrl:1
	v_mov_b32_dpp v157, v155 row_mirror row_mask:0xf bank_mask:0xf bound_ctrl:1
	s_and_saveexec_b64 s[6:7], vcc
	v_pk_add_f32 v[154:155], v[154:155], v[156:157]
	ds_write_b64 v181, v[154:155] offset:208
	s_or_b64 exec, exec, s[6:7]
	v_add_u32_e32 v93, v105, v101
	ds_read2_b32 v[154:155], v93 offset1:32
	ds_read2_b32 v[156:157], v93 offset0:64 offset1:96
	v_mov_b32_e32 v96, v129
	v_pk_add_f32 v[128:129], v[96:97], 0 op_sel_hi:[1,0]
	v_mov_b32_e32 v96, v113
	v_pk_add_f32 v[112:113], v[96:97], 0 op_sel_hi:[1,0]
	s_waitcnt lgkmcnt(1)
	v_mov_b32_e32 v96, v154
	s_waitcnt lgkmcnt(0)
	v_mov_b32_e32 v97, v156
	s_mov_b32 s2, s67
	v_mov_b32_e32 v154, v155
	v_mov_b32_e32 v155, v156
	v_pk_mul_f32 v[160:161], v[96:97], s[2:3] op_sel_hi:[1,0]
	v_pk_fma_f32 v[96:97], v[96:97], s[2:3], v[128:129] op_sel_hi:[1,0,1]
	v_pk_fma_f32 v[112:113], v[154:155], s[2:3], v[112:113] op_sel_hi:[1,0,1]
	v_pk_mul_f32 v[170:171], v[96:97], v[96:97]
	v_pk_mul_f32 v[154:155], v[112:113], v[112:113]
	v_pk_mov_b32 v[128:129], v[128:129], v[170:171] op_sel:[1,0]
	v_pk_mov_b32 v[154:155], v[160:161], v[154:155] op_sel:[1,0]
	v_add_f32_e32 v80, 0, v81
	v_pk_add_f32 v[128:129], v[128:129], v[154:155]
	v_pk_add_f32 v[154:155], v[96:97], v[112:113]
	v_pk_mul_f32 v[160:161], v[96:97], v[112:113]
	v_fmac_f32_e32 v80, 0x3fd744fd, v157
	v_mov_b32_e32 v155, v161
	v_pk_add_f32 v[128:129], v[154:155], v[128:129]
	v_mul_f32_e32 v81, v80, v80
	v_pk_add_f32 v[128:129], v[128:129], v[80:81]
	s_nop 1
	v_mov_b32_dpp v154, v128 quad_perm:[1,0,3,2] row_mask:0xf bank_mask:0xf bound_ctrl:1
	v_mov_b32_dpp v155, v129 quad_perm:[1,0,3,2] row_mask:0xf bank_mask:0xf bound_ctrl:1
	v_pk_add_f32 v[128:129], v[128:129], v[154:155]
	s_nop 1
	v_mov_b32_dpp v154, v128 quad_perm:[2,3,0,1] row_mask:0xf bank_mask:0xf bound_ctrl:1
	v_mov_b32_dpp v155, v129 quad_perm:[2,3,0,1] row_mask:0xf bank_mask:0xf bound_ctrl:1
	v_pk_add_f32 v[128:129], v[128:129], v[154:155]
	s_nop 1
	v_mov_b32_dpp v154, v128 row_half_mirror row_mask:0xf bank_mask:0xf bound_ctrl:1
	v_mov_b32_dpp v155, v129 row_half_mirror row_mask:0xf bank_mask:0xf bound_ctrl:1
	v_pk_add_f32 v[128:129], v[128:129], v[154:155]
	s_nop 1
	v_mov_b32_dpp v154, v128 row_mirror row_mask:0xf bank_mask:0xf bound_ctrl:1
	v_mov_b32_dpp v155, v129 row_mirror row_mask:0xf bank_mask:0xf bound_ctrl:1
	s_and_saveexec_b64 s[6:7], vcc
	v_pk_add_f32 v[128:129], v[128:129], v[154:155]
	ds_write_b64 v181, v[128:129] offset:216
	s_or_b64 exec, exec, s[6:7]
	v_or_b32_e32 v128, 48, v159
	v_ashrrev_i32_e32 v129, 31, v128
	v_lshlrev_b64 v[128:129], 12, v[128:129]
	v_readfirstlane_b32 s2, v158
	v_lshl_add_u64 v[128:129], s[10:11], 0, v[128:129]
	s_lshl_b32 s2, s2, 13
	v_lshl_add_u64 v[128:129], v[184:185], 2, v[128:129]
	s_waitcnt lgkmcnt(0)
	s_add_i32 m0, s2, 0x10000
	v_lshl_add_u64 v[128:129], v[128:129], 0, v[0:1]
	s_mov_b64 s[6:7], 0x2000
	global_load_lds_dwordx4 v[128:129], off
	v_lshl_add_u64 v[154:155], v[128:129], 0, s[6:7]
	s_add_i32 m0, s2, 0x10400
	s_mov_b64 s[6:7], 0x4000
	global_load_lds_dwordx4 v[154:155], off
	v_lshl_add_u64 v[154:155], v[128:129], 0, s[6:7]
	s_add_i32 m0, s2, 0x10800
	s_mov_b64 s[6:7], 0x6000
	global_load_lds_dwordx4 v[154:155], off
	v_lshl_add_u64 v[154:155], v[128:129], 0, s[6:7]
	s_add_i32 m0, s2, 0x10c00
	s_mov_b64 s[6:7], 0x8000
	global_load_lds_dwordx4 v[154:155], off
	v_lshl_add_u64 v[154:155], v[128:129], 0, s[6:7]
	s_add_i32 m0, s2, 0x11000
	s_mov_b64 s[6:7], 0xa000
	global_load_lds_dwordx4 v[154:155], off
	v_lshl_add_u64 v[154:155], v[128:129], 0, s[6:7]
	s_add_i32 m0, s2, 0x11400
	s_mov_b64 s[6:7], 0xc000
	global_load_lds_dwordx4 v[154:155], off
	v_lshl_add_u64 v[154:155], v[128:129], 0, s[6:7]
	s_add_i32 m0, s2, 0x11800
	s_mov_b64 s[6:7], 0xe000
	global_load_lds_dwordx4 v[154:155], off
	v_lshl_add_u64 v[128:129], v[128:129], 0, s[6:7]
	s_add_i32 m0, s2, 0x11c00
	v_mov_b32_e32 v156, v50
	global_load_lds_dwordx4 v[128:129], off
	s_waitcnt vmcnt(8)
;   DI void operator()(f32x16 (&acc)[2][4], int grow0, int gcol0, int lane, int w, char* lds) {
;     ...
;       for (int qq = 0; qq < 2; ++qq)
; #pragma unroll
;         for (int e = 0; e < 4; ++e) {
;           const int i = 4 * (2 * (ps & 1) + qq) + e;
;           const float* xr = (const float*)(xs + (8 * qq + 4 * hh + e) * 512) + l31;
;           float s1 = 0.f, s2 = 0.f;
; #pragma unroll
;           for (int nt = 0; nt < 4; ++nt) {
;             float v = (acc[mt][nt][i] + bia[nt]) * csc[nt];
;             float z = ALPHA * xr[nt * 32] + hs * v;
;             acc[mt][nt][i] = z; s1 += z; s2 += z * z;
;           }
;           s1 = row16_sum(s1); s2 = row16_sum(s2);
;           if ((lane & 15) == 0) { f32x2 sv = {s1, s2}; *(f32x2*)(redw + (mt * 32 + (i & 3) + 8 * (i >> 2)) * 2) = sv; }
;         }
	ds_read2_b32 v[154:155], v168 offset1:32
	ds_read2_b32 v[158:159], v168 offset0:64 offset1:96
	v_mov_b32_e32 v157, v18
	v_pk_add_f32 v[160:161], v[156:157], 0 op_sel_hi:[1,0]
	v_mov_b32_e32 v156, v34
	v_pk_add_f32 v[156:157], v[156:157], 0 op_sel_hi:[1,0]
	s_waitcnt lgkmcnt(0)
	v_mov_b32_e32 v170, v154
	v_mov_b32_e32 v171, v158
	s_mov_b32 s2, s67
	v_mov_b32_e32 v176, v155
	v_mov_b32_e32 v177, v158
	v_pk_fma_f32 v[154:155], v[170:171], s[2:3], v[160:161] op_sel_hi:[1,0,1]
	v_pk_fma_f32 v[156:157], v[176:177], s[2:3], v[156:157] op_sel_hi:[1,0,1]
	v_pk_mul_f32 v[174:175], v[170:171], s[2:3] op_sel_hi:[1,0]
	v_pk_mul_f32 v[170:171], v[154:155], v[154:155]
	v_pk_mul_f32 v[176:177], v[156:157], v[156:157]
	v_pk_mov_b32 v[160:161], v[160:161], v[170:171] op_sel:[1,0]
	v_pk_mov_b32 v[170:171], v[174:175], v[176:177] op_sel:[1,0]
	v_add_f32_e32 v128, 0, v2
	v_pk_add_f32 v[160:161], v[160:161], v[170:171]
	v_pk_add_f32 v[170:171], v[154:155], v[156:157]
	v_pk_mul_f32 v[174:175], v[154:155], v[156:157]
	v_fmac_f32_e32 v128, 0x3fd744fd, v159
	v_mov_b32_e32 v171, v175
	v_pk_add_f32 v[160:161], v[170:171], v[160:161]
	v_mul_f32_e32 v129, v128, v128
	v_pk_add_f32 v[158:159], v[160:161], v[128:129]
	s_nop 1
	v_mov_b32_dpp v160, v158 quad_perm:[1,0,3,2] row_mask:0xf bank_mask:0xf bound_ctrl:1
	v_mov_b32_dpp v161, v159 quad_perm:[1,0,3,2] row_mask:0xf bank_mask:0xf bound_ctrl:1
	v_pk_add_f32 v[158:159], v[158:159], v[160:161]
	s_nop 1
	v_mov_b32_dpp v160, v158 quad_perm:[2,3,0,1] row_mask:0xf bank_mask:0xf bound_ctrl:1
	v_mov_b32_dpp v161, v159 quad_perm:[2,3,0,1] row_mask:0xf bank_mask:0xf bound_ctrl:1
	v_pk_add_f32 v[158:159], v[158:159], v[160:161]
	s_nop 1
	v_mov_b32_dpp v160, v158 row_half_mirror row_mask:0xf bank_mask:0xf bound_ctrl:1
	v_mov_b32_dpp v161, v159 row_half_mirror row_mask:0xf bank_mask:0xf bound_ctrl:1
	v_pk_add_f32 v[158:159], v[158:159], v[160:161]
	s_nop 1
	v_mov_b32_dpp v160, v158 row_mirror row_mask:0xf bank_mask:0xf bound_ctrl:1
	v_mov_b32_dpp v161, v159 row_mirror row_mask:0xf bank_mask:0xf bound_ctrl:1
	s_and_saveexec_b64 s[6:7], vcc
	v_pk_add_f32 v[158:159], v[158:159], v[160:161]
	ds_write_b64 v181, v[158:159] offset:256
	s_or_b64 exec, exec, s[6:7]
	ds_read2_b32 v[158:159], v168 offset0:128 offset1:160
	ds_read2_b32 v[160:161], v168 offset0:192 offset1:224
	v_mov_b32_e32 v18, v51
	v_pk_add_f32 v[168:169], v[18:19], 0 op_sel_hi:[1,0]
	v_mov_b32_e32 v18, v35
	v_pk_add_f32 v[18:19], v[18:19], 0 op_sel_hi:[1,0]
	s_waitcnt lgkmcnt(1)
	v_mov_b32_e32 v34, v158
	s_waitcnt lgkmcnt(0)
	v_mov_b32_e32 v35, v160
	s_mov_b32 s2, s67
	v_mov_b32_e32 v50, v159
	v_mov_b32_e32 v51, v160
	v_pk_mul_f32 v[170:171], v[34:35], s[2:3] op_sel_hi:[1,0]
	v_pk_fma_f32 v[34:35], v[34:35], s[2:3], v[168:169] op_sel_hi:[1,0,1]
	v_pk_fma_f32 v[50:51], v[50:51], s[2:3], v[18:19] op_sel_hi:[1,0,1]
	v_pk_mul_f32 v[158:159], v[34:35], v[34:35]
	v_pk_mul_f32 v[18:19], v[50:51], v[50:51]
	v_pk_mov_b32 v[158:159], v[168:169], v[158:159] op_sel:[1,0]
	v_pk_mov_b32 v[18:19], v[170:171], v[18:19] op_sel:[1,0]
	v_add_f32_e32 v2, 0, v3
	v_pk_add_f32 v[18:19], v[158:159], v[18:19]
	v_pk_add_f32 v[158:159], v[34:35], v[50:51]
	v_pk_mul_f32 v[168:169], v[34:35], v[50:51]
	v_fmac_f32_e32 v2, 0x3fd744fd, v161
	v_mov_b32_e32 v159, v169
	v_pk_add_f32 v[18:19], v[158:159], v[18:19]
	v_mul_f32_e32 v3, v2, v2
	v_pk_add_f32 v[18:19], v[18:19], v[2:3]
	s_nop 1
	v_mov_b32_dpp v158, v18 quad_perm:[1,0,3,2] row_mask:0xf bank_mask:0xf bound_ctrl:1
	v_mov_b32_dpp v159, v19 quad_perm:[1,0,3,2] row_mask:0xf bank_mask:0xf bound_ctrl:1
	v_pk_add_f32 v[18:19], v[18:19], v[158:159]
	s_nop 1
	v_mov_b32_dpp v158, v18 quad_perm:[2,3,0,1] row_mask:0xf bank_mask:0xf bound_ctrl:1
	v_mov_b32_dpp v159, v19 quad_perm:[2,3,0,1] row_mask:0xf bank_mask:0xf bound_ctrl:1
	v_pk_add_f32 v[18:19], v[18:19], v[158:159]
	s_nop 1
	v_mov_b32_dpp v158, v18 row_half_mirror row_mask:0xf bank_mask:0xf bound_ctrl:1
	v_mov_b32_dpp v159, v19 row_half_mirror row_mask:0xf bank_mask:0xf bound_ctrl:1
	v_pk_add_f32 v[18:19], v[18:19], v[158:159]
	s_nop 1
	v_mov_b32_dpp v158, v18 row_mirror row_mask:0xf bank_mask:0xf bound_ctrl:1
	v_mov_b32_dpp v159, v19 row_mirror row_mask:0xf bank_mask:0xf bound_ctrl:1
	s_and_saveexec_b64 s[6:7], vcc
	v_pk_add_f32 v[18:19], v[18:19], v[158:159]
	ds_write_b64 v181, v[18:19] offset:264
	s_or_b64 exec, exec, s[6:7]
	ds_read2_b32 v[158:159], v153 offset1:32
	ds_read2_b32 v[168:169], v153 offset0:64 offset1:96
	v_mov_b32_e32 v160, v52
	v_mov_b32_e32 v161, v20
	v_pk_add_f32 v[170:171], v[160:161], 0 op_sel_hi:[1,0]
	v_mov_b32_e32 v160, v36
	v_pk_add_f32 v[160:161], v[160:161], 0 op_sel_hi:[1,0]
	s_waitcnt lgkmcnt(1)
	v_mov_b32_e32 v174, v158
	s_waitcnt lgkmcnt(0)
;   DI void operator()(f32x16 (&acc)[2][4], int grow0, int gcol0, int lane, int w, char* lds) {
;     ...
;       for (int qq = 0; qq < 2; ++qq)
; #pragma unroll
;         for (int e = 0; e < 4; ++e) {
;           const int i = 4 * (2 * (ps & 1) + qq) + e;
;           const float* xr = (const float*)(xs + (8 * qq + 4 * hh + e) * 512) + l31;
;           float s1 = 0.f, s2 = 0.f;
; #pragma unroll
;           for (int nt = 0; nt < 4; ++nt) {
;             float v = (acc[mt][nt][i] + bia[nt]) * csc[nt];
;             float z = ALPHA * xr[nt * 32] + hs * v;
;             acc[mt][nt][i] = z; s1 += z; s2 += z * z;
;           }
;           s1 = row16_sum(s1); s2 = row16_sum(s2);
;           if ((lane & 15) == 0) { f32x2 sv = {s1, s2}; *(f32x2*)(redw + (mt * 32 + (i & 3) + 8 * (i >> 2)) * 2) = sv; }
;         }
	v_mov_b32_e32 v175, v168
	s_mov_b32 s2, s67
	v_mov_b32_e32 v178, v159
	v_mov_b32_e32 v179, v168
	v_pk_fma_f32 v[158:159], v[174:175], s[2:3], v[170:171] op_sel_hi:[1,0,1]
	v_pk_fma_f32 v[160:161], v[178:179], s[2:3], v[160:161] op_sel_hi:[1,0,1]
	v_pk_mul_f32 v[176:177], v[174:175], s[2:3] op_sel_hi:[1,0]
	v_pk_mul_f32 v[174:175], v[158:159], v[158:159]
	v_pk_mul_f32 v[178:179], v[160:161], v[160:161]
	v_pk_mov_b32 v[170:171], v[170:171], v[174:175] op_sel:[1,0]
	v_pk_mov_b32 v[174:175], v[176:177], v[178:179] op_sel:[1,0]
	v_add_f32_e32 v18, 0, v4
	v_pk_add_f32 v[170:171], v[170:171], v[174:175]
	v_pk_add_f32 v[174:175], v[158:159], v[160:161]
	v_pk_mul_f32 v[176:177], v[158:159], v[160:161]
	v_fmac_f32_e32 v18, 0x3fd744fd, v169
	v_mov_b32_e32 v175, v177
	v_pk_add_f32 v[170:171], v[174:175], v[170:171]
	v_mul_f32_e32 v19, v18, v18
	v_pk_add_f32 v[168:169], v[170:171], v[18:19]
	s_nop 1
	v_mov_b32_dpp v170, v168 quad_perm:[1,0,3,2] row_mask:0xf bank_mask:0xf bound_ctrl:1
	v_mov_b32_dpp v171, v169 quad_perm:[1,0,3,2] row_mask:0xf bank_mask:0xf bound_ctrl:1
	v_pk_add_f32 v[168:169], v[168:169], v[170:171]
	s_nop 1
	v_mov_b32_dpp v170, v168 quad_perm:[2,3,0,1] row_mask:0xf bank_mask:0xf bound_ctrl:1
	v_mov_b32_dpp v171, v169 quad_perm:[2,3,0,1] row_mask:0xf bank_mask:0xf bound_ctrl:1
	v_pk_add_f32 v[168:169], v[168:169], v[170:171]
	s_nop 1
	v_mov_b32_dpp v170, v168 row_half_mirror row_mask:0xf bank_mask:0xf bound_ctrl:1
	v_mov_b32_dpp v171, v169 row_half_mirror row_mask:0xf bank_mask:0xf bound_ctrl:1
	v_pk_add_f32 v[168:169], v[168:169], v[170:171]
	s_nop 1
	v_mov_b32_dpp v170, v168 row_mirror row_mask:0xf bank_mask:0xf bound_ctrl:1
	v_mov_b32_dpp v171, v169 row_mirror row_mask:0xf bank_mask:0xf bound_ctrl:1
	s_and_saveexec_b64 s[6:7], vcc
	v_pk_add_f32 v[168:169], v[168:169], v[170:171]
	ds_write_b64 v181, v[168:169] offset:272
	s_or_b64 exec, exec, s[6:7]
	ds_read2_b32 v[168:169], v151 offset1:32
	ds_read2_b32 v[170:171], v151 offset0:64 offset1:96
	v_mov_b32_e32 v20, v53
	v_pk_add_f32 v[174:175], v[20:21], 0 op_sel_hi:[1,0]
	v_mov_b32_e32 v20, v37
	v_pk_add_f32 v[20:21], v[20:21], 0 op_sel_hi:[1,0]
	s_waitcnt lgkmcnt(1)
	v_mov_b32_e32 v36, v168
	s_waitcnt lgkmcnt(0)
	v_mov_b32_e32 v37, v170
	s_mov_b32 s2, s67
	v_mov_b32_e32 v52, v169
	v_mov_b32_e32 v53, v170
	v_pk_mul_f32 v[176:177], v[36:37], s[2:3] op_sel_hi:[1,0]
	v_pk_fma_f32 v[36:37], v[36:37], s[2:3], v[174:175] op_sel_hi:[1,0,1]
	v_pk_fma_f32 v[52:53], v[52:53], s[2:3], v[20:21] op_sel_hi:[1,0,1]
	v_pk_mul_f32 v[168:169], v[36:37], v[36:37]
	v_pk_mul_f32 v[20:21], v[52:53], v[52:53]
	v_pk_mov_b32 v[168:169], v[174:175], v[168:169] op_sel:[1,0]
	v_pk_mov_b32 v[20:21], v[176:177], v[20:21] op_sel:[1,0]
	v_add_f32_e32 v4, 0, v5
	v_pk_add_f32 v[20:21], v[168:169], v[20:21]
	v_pk_add_f32 v[168:169], v[36:37], v[52:53]
	v_pk_mul_f32 v[174:175], v[36:37], v[52:53]
	v_fmac_f32_e32 v4, 0x3fd744fd, v171
	v_mov_b32_e32 v169, v175
	v_pk_add_f32 v[20:21], v[168:169], v[20:21]
	v_mul_f32_e32 v5, v4, v4
	v_pk_add_f32 v[20:21], v[20:21], v[4:5]
	s_nop 1
	v_mov_b32_dpp v168, v20 quad_perm:[1,0,3,2] row_mask:0xf bank_mask:0xf bound_ctrl:1
	v_mov_b32_dpp v169, v21 quad_perm:[1,0,3,2] row_mask:0xf bank_mask:0xf bound_ctrl:1
	v_pk_add_f32 v[20:21], v[20:21], v[168:169]
	s_nop 1
	v_mov_b32_dpp v168, v20 quad_perm:[2,3,0,1] row_mask:0xf bank_mask:0xf bound_ctrl:1
	v_mov_b32_dpp v169, v21 quad_perm:[2,3,0,1] row_mask:0xf bank_mask:0xf bound_ctrl:1
	v_pk_add_f32 v[20:21], v[20:21], v[168:169]
	s_nop 1
	v_mov_b32_dpp v168, v20 row_half_mirror row_mask:0xf bank_mask:0xf bound_ctrl:1
	v_mov_b32_dpp v169, v21 row_half_mirror row_mask:0xf bank_mask:0xf bound_ctrl:1
	v_pk_add_f32 v[20:21], v[20:21], v[168:169]
	s_nop 1
	v_mov_b32_dpp v168, v20 row_mirror row_mask:0xf bank_mask:0xf bound_ctrl:1
	v_mov_b32_dpp v169, v21 row_mirror row_mask:0xf bank_mask:0xf bound_ctrl:1
	s_and_saveexec_b64 s[6:7], vcc
	v_pk_add_f32 v[20:21], v[20:21], v[168:169]
	ds_write_b64 v181, v[20:21] offset:280
	s_or_b64 exec, exec, s[6:7]
	ds_read2_b32 v[168:169], v67 offset1:32
	ds_read2_b32 v[174:175], v67 offset0:64 offset1:96
	v_mov_b32_e32 v170, v54
	v_mov_b32_e32 v171, v22
	v_pk_add_f32 v[176:177], v[170:171], 0 op_sel_hi:[1,0]
	v_mov_b32_e32 v170, v38
	v_pk_add_f32 v[170:171], v[170:171], 0 op_sel_hi:[1,0]
	s_waitcnt lgkmcnt(1)
	v_mov_b32_e32 v178, v168
	s_waitcnt lgkmcnt(0)
	v_mov_b32_e32 v179, v174
	s_mov_b32 s2, s67
	v_mov_b32_e32 v190, v169
	v_mov_b32_e32 v191, v174
	v_pk_fma_f32 v[168:169], v[178:179], s[2:3], v[176:177] op_sel_hi:[1,0,1]
	v_pk_fma_f32 v[170:171], v[190:191], s[2:3], v[170:171] op_sel_hi:[1,0,1]
	v_pk_mul_f32 v[182:183], v[178:179], s[2:3] op_sel_hi:[1,0]
	v_pk_mul_f32 v[178:179], v[168:169], v[168:169]
	v_pk_mul_f32 v[190:191], v[170:171], v[170:171]
	v_pk_mov_b32 v[176:177], v[176:177], v[178:179] op_sel:[1,0]
	v_pk_mov_b32 v[178:179], v[182:183], v[190:191] op_sel:[1,0]
	v_add_f32_e32 v20, 0, v6
	v_pk_add_f32 v[176:177], v[176:177], v[178:179]
	v_pk_add_f32 v[178:179], v[168:169], v[170:171]
	v_pk_mul_f32 v[182:183], v[168:169], v[170:171]
	v_fmac_f32_e32 v20, 0x3fd744fd, v175
	v_mov_b32_e32 v179, v183
	v_pk_add_f32 v[176:177], v[178:179], v[176:177]
	v_mul_f32_e32 v21, v20, v20
	v_pk_add_f32 v[174:175], v[176:177], v[20:21]
	s_nop 1
	v_mov_b32_dpp v176, v174 quad_perm:[1,0,3,2] row_mask:0xf bank_mask:0xf bound_ctrl:1
	v_mov_b32_dpp v177, v175 quad_perm:[1,0,3,2] row_mask:0xf bank_mask:0xf bound_ctrl:1
	v_pk_add_f32 v[174:175], v[174:175], v[176:177]
	s_nop 1
	v_mov_b32_dpp v176, v174 quad_perm:[2,3,0,1] row_mask:0xf bank_mask:0xf bound_ctrl:1
	v_mov_b32_dpp v177, v175 quad_perm:[2,3,0,1] row_mask:0xf bank_mask:0xf bound_ctrl:1
	v_pk_add_f32 v[174:175], v[174:175], v[176:177]
	s_nop 1
	v_mov_b32_dpp v176, v174 row_half_mirror row_mask:0xf bank_mask:0xf bound_ctrl:1
	v_mov_b32_dpp v177, v175 row_half_mirror row_mask:0xf bank_mask:0xf bound_ctrl:1
	v_pk_add_f32 v[174:175], v[174:175], v[176:177]
	s_nop 1
	v_mov_b32_dpp v176, v174 row_mirror row_mask:0xf bank_mask:0xf bound_ctrl:1
	v_mov_b32_dpp v177, v175 row_mirror row_mask:0xf bank_mask:0xf bound_ctrl:1
	s_and_saveexec_b64 s[6:7], vcc
	v_pk_add_f32 v[174:175], v[174:175], v[176:177]
	ds_write_b64 v181, v[174:175] offset:320
	s_or_b64 exec, exec, s[6:7]
	ds_read2_b32 v[174:175], v67 offset0:128 offset1:160
	ds_read2_b32 v[176:177], v67 offset0:192 offset1:224
	v_mov_b32_e32 v22, v55
	v_pk_add_f32 v[178:179], v[22:23], 0 op_sel_hi:[1,0]
	v_mov_b32_e32 v22, v39
	v_pk_add_f32 v[22:23], v[22:23], 0 op_sel_hi:[1,0]
	s_waitcnt lgkmcnt(1)
;   DI void operator()(f32x16 (&acc)[2][4], int grow0, int gcol0, int lane, int w, char* lds) {
;     ...
;       } else asm volatile("s_waitcnt vmcnt(0)" ::: "memory");
;       const char* xs = lds + (ps & 1) * 65536 + w * 8192;
; #pragma unroll
;       for (int qq = 0; qq < 2; ++qq)
; #pragma unroll
;         for (int e = 0; e < 4; ++e) {
;           const int i = 4 * (2 * (ps & 1) + qq) + e;
;           const float* xr = (const float*)(xs + (8 * qq + 4 * hh + e) * 512) + l31;
;           float s1 = 0.f, s2 = 0.f;
; #pragma unroll
;           for (int nt = 0; nt < 4; ++nt) {
;             float v = (acc[mt][nt][i] + bia[nt]) * csc[nt];
;             float z = ALPHA * xr[nt * 32] + hs * v;
;             acc[mt][nt][i] = z; s1 += z; s2 += z * z;
;           }
;           s1 = row16_sum(s1); s2 = row16_sum(s2);
;           if ((lane & 15) == 0) { f32x2 sv = {s1, s2}; *(f32x2*)(redw + (mt * 32 + (i & 3) + 8 * (i >> 2)) * 2) = sv; }
;         }
	v_mov_b32_e32 v38, v174
	s_waitcnt lgkmcnt(0)
	v_mov_b32_e32 v39, v176
	s_mov_b32 s2, s67
	v_mov_b32_e32 v54, v175
	v_mov_b32_e32 v55, v176
	v_pk_mul_f32 v[182:183], v[38:39], s[2:3] op_sel_hi:[1,0]
	v_pk_fma_f32 v[38:39], v[38:39], s[2:3], v[178:179] op_sel_hi:[1,0,1]
	v_pk_fma_f32 v[54:55], v[54:55], s[2:3], v[22:23] op_sel_hi:[1,0,1]
	v_pk_mul_f32 v[174:175], v[38:39], v[38:39]
	v_pk_mul_f32 v[22:23], v[54:55], v[54:55]
	v_pk_mov_b32 v[174:175], v[178:179], v[174:175] op_sel:[1,0]
	v_pk_mov_b32 v[22:23], v[182:183], v[22:23] op_sel:[1,0]
	v_add_f32_e32 v6, 0, v7
	v_pk_add_f32 v[22:23], v[174:175], v[22:23]
	v_pk_add_f32 v[174:175], v[38:39], v[54:55]
	v_pk_mul_f32 v[178:179], v[38:39], v[54:55]
	v_fmac_f32_e32 v6, 0x3fd744fd, v177
	v_mov_b32_e32 v175, v179
	v_pk_add_f32 v[22:23], v[174:175], v[22:23]
	v_mul_f32_e32 v7, v6, v6
	v_pk_add_f32 v[22:23], v[22:23], v[6:7]
	s_nop 1
	v_mov_b32_dpp v174, v22 quad_perm:[1,0,3,2] row_mask:0xf bank_mask:0xf bound_ctrl:1
	v_mov_b32_dpp v175, v23 quad_perm:[1,0,3,2] row_mask:0xf bank_mask:0xf bound_ctrl:1
	v_pk_add_f32 v[22:23], v[22:23], v[174:175]
	s_nop 1
	v_mov_b32_dpp v174, v22 quad_perm:[2,3,0,1] row_mask:0xf bank_mask:0xf bound_ctrl:1
	v_mov_b32_dpp v175, v23 quad_perm:[2,3,0,1] row_mask:0xf bank_mask:0xf bound_ctrl:1
	v_pk_add_f32 v[22:23], v[22:23], v[174:175]
	s_nop 1
	v_mov_b32_dpp v174, v22 row_half_mirror row_mask:0xf bank_mask:0xf bound_ctrl:1
	v_mov_b32_dpp v175, v23 row_half_mirror row_mask:0xf bank_mask:0xf bound_ctrl:1
	v_pk_add_f32 v[22:23], v[22:23], v[174:175]
	s_nop 1
	v_mov_b32_dpp v174, v22 row_mirror row_mask:0xf bank_mask:0xf bound_ctrl:1
	v_mov_b32_dpp v175, v23 row_mirror row_mask:0xf bank_mask:0xf bound_ctrl:1
	s_and_saveexec_b64 s[6:7], vcc
	v_pk_add_f32 v[22:23], v[22:23], v[174:175]
	ds_write_b64 v181, v[22:23] offset:328
	s_or_b64 exec, exec, s[6:7]
	ds_read2_b32 v[174:175], v69 offset1:32
	ds_read2_b32 v[178:179], v69 offset0:64 offset1:96
	v_mov_b32_e32 v176, v56
	v_mov_b32_e32 v177, v24
	v_pk_add_f32 v[182:183], v[176:177], 0 op_sel_hi:[1,0]
	v_mov_b32_e32 v176, v40
	v_pk_add_f32 v[176:177], v[176:177], 0 op_sel_hi:[1,0]
	s_waitcnt lgkmcnt(1)
	v_mov_b32_e32 v190, v174
	s_waitcnt lgkmcnt(0)
	v_mov_b32_e32 v191, v178
	s_mov_b32 s2, s67
	v_mov_b32_e32 v194, v175
	v_mov_b32_e32 v195, v178
	v_pk_fma_f32 v[174:175], v[190:191], s[2:3], v[182:183] op_sel_hi:[1,0,1]
	v_pk_fma_f32 v[176:177], v[194:195], s[2:3], v[176:177] op_sel_hi:[1,0,1]
	v_pk_mul_f32 v[192:193], v[190:191], s[2:3] op_sel_hi:[1,0]
	v_pk_mul_f32 v[190:191], v[174:175], v[174:175]
	v_pk_mul_f32 v[194:195], v[176:177], v[176:177]
	v_pk_mov_b32 v[182:183], v[182:183], v[190:191] op_sel:[1,0]
	v_pk_mov_b32 v[190:191], v[192:193], v[194:195] op_sel:[1,0]
	v_add_f32_e32 v22, 0, v8
	v_pk_add_f32 v[182:183], v[182:183], v[190:191]
	v_pk_add_f32 v[190:191], v[174:175], v[176:177]
	v_pk_mul_f32 v[192:193], v[174:175], v[176:177]
	v_fmac_f32_e32 v22, 0x3fd744fd, v179
	v_mov_b32_e32 v191, v193
	v_pk_add_f32 v[182:183], v[190:191], v[182:183]
	v_mul_f32_e32 v23, v22, v22
	v_pk_add_f32 v[178:179], v[182:183], v[22:23]
	s_nop 1
	v_mov_b32_dpp v182, v178 quad_perm:[1,0,3,2] row_mask:0xf bank_mask:0xf bound_ctrl:1
	v_mov_b32_dpp v183, v179 quad_perm:[1,0,3,2] row_mask:0xf bank_mask:0xf bound_ctrl:1
	v_pk_add_f32 v[178:179], v[178:179], v[182:183]
	s_nop 1
	v_mov_b32_dpp v182, v178 quad_perm:[2,3,0,1] row_mask:0xf bank_mask:0xf bound_ctrl:1
	v_mov_b32_dpp v183, v179 quad_perm:[2,3,0,1] row_mask:0xf bank_mask:0xf bound_ctrl:1
	v_pk_add_f32 v[178:179], v[178:179], v[182:183]
	s_nop 1
	v_mov_b32_dpp v182, v178 row_half_mirror row_mask:0xf bank_mask:0xf bound_ctrl:1
	v_mov_b32_dpp v183, v179 row_half_mirror row_mask:0xf bank_mask:0xf bound_ctrl:1
	v_pk_add_f32 v[178:179], v[178:179], v[182:183]
	s_nop 1
	v_mov_b32_dpp v182, v178 row_mirror row_mask:0xf bank_mask:0xf bound_ctrl:1
	v_mov_b32_dpp v183, v179 row_mirror row_mask:0xf bank_mask:0xf bound_ctrl:1
	s_and_saveexec_b64 s[6:7], vcc
	v_pk_add_f32 v[178:179], v[178:179], v[182:183]
	ds_write_b64 v181, v[178:179] offset:336
	s_or_b64 exec, exec, s[6:7]
	ds_read2_b32 v[178:179], v71 offset1:32
	ds_read2_b32 v[182:183], v71 offset0:64 offset1:96
	v_mov_b32_e32 v24, v57
	v_pk_add_f32 v[190:191], v[24:25], 0 op_sel_hi:[1,0]
	v_mov_b32_e32 v24, v41
	v_pk_add_f32 v[24:25], v[24:25], 0 op_sel_hi:[1,0]
	s_waitcnt lgkmcnt(1)
	v_mov_b32_e32 v40, v178
	s_waitcnt lgkmcnt(0)
	v_mov_b32_e32 v41, v182
	s_mov_b32 s2, s67
	v_mov_b32_e32 v56, v179
	v_mov_b32_e32 v57, v182
	v_pk_mul_f32 v[192:193], v[40:41], s[2:3] op_sel_hi:[1,0]
	v_pk_fma_f32 v[40:41], v[40:41], s[2:3], v[190:191] op_sel_hi:[1,0,1]
	v_pk_fma_f32 v[56:57], v[56:57], s[2:3], v[24:25] op_sel_hi:[1,0,1]
	v_pk_mul_f32 v[178:179], v[40:41], v[40:41]
	v_pk_mul_f32 v[24:25], v[56:57], v[56:57]
	v_pk_mov_b32 v[178:179], v[190:191], v[178:179] op_sel:[1,0]
	v_pk_mov_b32 v[24:25], v[192:193], v[24:25] op_sel:[1,0]
	v_add_f32_e32 v8, 0, v9
	v_pk_add_f32 v[24:25], v[178:179], v[24:25]
	v_pk_add_f32 v[178:179], v[40:41], v[56:57]
	v_pk_mul_f32 v[190:191], v[40:41], v[56:57]
	v_fmac_f32_e32 v8, 0x3fd744fd, v183
	v_mov_b32_e32 v179, v191
	v_pk_add_f32 v[24:25], v[178:179], v[24:25]
	v_mul_f32_e32 v9, v8, v8
	v_pk_add_f32 v[24:25], v[24:25], v[8:9]
	s_nop 1
	v_mov_b32_dpp v178, v24 quad_perm:[1,0,3,2] row_mask:0xf bank_mask:0xf bound_ctrl:1
	v_mov_b32_dpp v179, v25 quad_perm:[1,0,3,2] row_mask:0xf bank_mask:0xf bound_ctrl:1
	v_pk_add_f32 v[24:25], v[24:25], v[178:179]
	s_nop 1
	v_mov_b32_dpp v178, v24 quad_perm:[2,3,0,1] row_mask:0xf bank_mask:0xf bound_ctrl:1
	v_mov_b32_dpp v179, v25 quad_perm:[2,3,0,1] row_mask:0xf bank_mask:0xf bound_ctrl:1
	v_pk_add_f32 v[24:25], v[24:25], v[178:179]
	s_nop 1
	v_mov_b32_dpp v178, v24 row_half_mirror row_mask:0xf bank_mask:0xf bound_ctrl:1
	v_mov_b32_dpp v179, v25 row_half_mirror row_mask:0xf bank_mask:0xf bound_ctrl:1
	v_pk_add_f32 v[24:25], v[24:25], v[178:179]
	s_nop 1
	v_mov_b32_dpp v178, v24 row_mirror row_mask:0xf bank_mask:0xf bound_ctrl:1
	v_mov_b32_dpp v179, v25 row_mirror row_mask:0xf bank_mask:0xf bound_ctrl:1
	s_and_saveexec_b64 s[6:7], vcc
	v_pk_add_f32 v[24:25], v[24:25], v[178:179]
	ds_write_b64 v181, v[24:25] offset:344
	s_or_b64 exec, exec, s[6:7]
	s_waitcnt vmcnt(0)
;   DI void operator()(f32x16 (&acc)[2][4], int grow0, int gcol0, int lane, int w, char* lds) {
;     ...
;       for (int qq = 0; qq < 2; ++qq)
; #pragma unroll
;         for (int e = 0; e < 4; ++e) {
;           const int i = 4 * (2 * (ps & 1) + qq) + e;
;           const float* xr = (const float*)(xs + (8 * qq + 4 * hh + e) * 512) + l31;
;           float s1 = 0.f, s2 = 0.f;
; #pragma unroll
;           for (int nt = 0; nt < 4; ++nt) {
;             float v = (acc[mt][nt][i] + bia[nt]) * csc[nt];
;             float z = ALPHA * xr[nt * 32] + hs * v;
;             acc[mt][nt][i] = z; s1 += z; s2 += z * z;
;           }
;           s1 = row16_sum(s1); s2 = row16_sum(s2);
;           if ((lane & 15) == 0) { f32x2 sv = {s1, s2}; *(f32x2*)(redw + (mt * 32 + (i & 3) + 8 * (i >> 2)) * 2) = sv; }
;         }
	ds_read2_b32 v[182:183], v73 offset1:32
	ds_read2_b32 v[192:193], v73 offset0:64 offset1:96
	v_add_f32_e32 v179, 0, v42
	v_mov_b32_e32 v190, v58
	v_mov_b32_e32 v191, v26
	s_waitcnt lgkmcnt(1)
	v_fmac_f32_e32 v179, 0x3fd744fd, v183
	v_pk_add_f32 v[194:195], v[190:191], 0 op_sel_hi:[1,0]
	s_waitcnt lgkmcnt(0)
	v_mov_b32_e32 v183, v192
	s_mov_b32 s2, s67
	v_pk_fma_f32 v[190:191], v[182:183], s[2:3], v[194:195] op_sel_hi:[1,0,1]
	v_mov_b32_e32 v178, v192
	v_pk_mul_f32 v[182:183], v[190:191], v[190:191]
	v_mov_b32_e32 v196, v165
	v_mov_b32_e32 v197, v179
	v_pk_mov_b32 v[182:183], v[194:195], v[182:183] op_sel:[1,0]
	v_add_f32_e32 v24, 0, v10
	v_pk_fma_f32 v[182:183], v[178:179], v[196:197], v[182:183]
	v_fmac_f32_e32 v24, 0x3fd744fd, v193
	v_pk_mov_b32 v[194:195], v[178:179], v[182:183] op_sel:[1,0]
	v_mul_f32_e32 v25, v24, v24
	v_pk_add_f32 v[196:197], v[190:191], v[194:195]
	v_pk_mul_f32 v[194:195], v[190:191], v[194:195]
	s_nop 0
	v_mov_b32_e32 v197, v195
	v_pk_add_f32 v[194:195], v[182:183], v[196:197]
	s_nop 0
	v_pk_add_f32 v[192:193], v[194:195], v[24:25]
	s_nop 1
	v_mov_b32_dpp v194, v192 quad_perm:[1,0,3,2] row_mask:0xf bank_mask:0xf bound_ctrl:1
	v_mov_b32_dpp v195, v193 quad_perm:[1,0,3,2] row_mask:0xf bank_mask:0xf bound_ctrl:1
	v_pk_add_f32 v[192:193], v[192:193], v[194:195]
	s_nop 1
	v_mov_b32_dpp v194, v192 quad_perm:[2,3,0,1] row_mask:0xf bank_mask:0xf bound_ctrl:1
	v_mov_b32_dpp v195, v193 quad_perm:[2,3,0,1] row_mask:0xf bank_mask:0xf bound_ctrl:1
	v_pk_add_f32 v[192:193], v[192:193], v[194:195]
	s_nop 1
	v_mov_b32_dpp v194, v192 row_half_mirror row_mask:0xf bank_mask:0xf bound_ctrl:1
	v_mov_b32_dpp v195, v193 row_half_mirror row_mask:0xf bank_mask:0xf bound_ctrl:1
	v_pk_add_f32 v[192:193], v[192:193], v[194:195]
	s_nop 1
	v_mov_b32_dpp v194, v192 row_mirror row_mask:0xf bank_mask:0xf bound_ctrl:1
	v_mov_b32_dpp v195, v193 row_mirror row_mask:0xf bank_mask:0xf bound_ctrl:1
	s_and_saveexec_b64 s[6:7], vcc
	v_pk_add_f32 v[192:193], v[192:193], v[194:195]
	ds_write_b64 v181, v[192:193] offset:384
	s_or_b64 exec, exec, s[6:7]
	ds_read2_b32 v[192:193], v85 offset1:32
	ds_read2_b32 v[194:195], v85 offset0:64 offset1:96
	v_mov_b32_e32 v26, v59
	v_pk_add_f32 v[196:197], v[26:27], 0 op_sel_hi:[1,0]
	v_mov_b32_e32 v26, v43
	v_pk_add_f32 v[26:27], v[26:27], 0 op_sel_hi:[1,0]
	s_waitcnt lgkmcnt(1)
	v_mov_b32_e32 v42, v192
	s_waitcnt lgkmcnt(0)
	v_mov_b32_e32 v43, v194
	s_mov_b32 s2, s67
	v_mov_b32_e32 v58, v193
	v_mov_b32_e32 v59, v194
	v_pk_mul_f32 v[198:199], v[42:43], s[2:3] op_sel_hi:[1,0]
	v_pk_fma_f32 v[42:43], v[42:43], s[2:3], v[196:197] op_sel_hi:[1,0,1]
	v_pk_fma_f32 v[58:59], v[58:59], s[2:3], v[26:27] op_sel_hi:[1,0,1]
	v_pk_mul_f32 v[192:193], v[42:43], v[42:43]
	v_pk_mul_f32 v[26:27], v[58:59], v[58:59]
	v_pk_mov_b32 v[192:193], v[196:197], v[192:193] op_sel:[1,0]
	v_pk_mov_b32 v[26:27], v[198:199], v[26:27] op_sel:[1,0]
	v_add_f32_e32 v10, 0, v11
	v_pk_add_f32 v[26:27], v[192:193], v[26:27]
	v_pk_add_f32 v[192:193], v[42:43], v[58:59]
	v_pk_mul_f32 v[196:197], v[42:43], v[58:59]
	v_fmac_f32_e32 v10, 0x3fd744fd, v195
	v_mov_b32_e32 v193, v197
	v_pk_add_f32 v[26:27], v[192:193], v[26:27]
	v_mul_f32_e32 v11, v10, v10
	v_pk_add_f32 v[26:27], v[26:27], v[10:11]
	s_nop 1
	v_mov_b32_dpp v192, v26 quad_perm:[1,0,3,2] row_mask:0xf bank_mask:0xf bound_ctrl:1
	v_mov_b32_dpp v193, v27 quad_perm:[1,0,3,2] row_mask:0xf bank_mask:0xf bound_ctrl:1
	v_pk_add_f32 v[26:27], v[26:27], v[192:193]
	s_nop 1
	v_mov_b32_dpp v192, v26 quad_perm:[2,3,0,1] row_mask:0xf bank_mask:0xf bound_ctrl:1
	v_mov_b32_dpp v193, v27 quad_perm:[2,3,0,1] row_mask:0xf bank_mask:0xf bound_ctrl:1
	v_pk_add_f32 v[26:27], v[26:27], v[192:193]
	s_nop 1
	v_mov_b32_dpp v192, v26 row_half_mirror row_mask:0xf bank_mask:0xf bound_ctrl:1
	v_mov_b32_dpp v193, v27 row_half_mirror row_mask:0xf bank_mask:0xf bound_ctrl:1
	v_pk_add_f32 v[26:27], v[26:27], v[192:193]
	s_nop 1
	v_mov_b32_dpp v192, v26 row_mirror row_mask:0xf bank_mask:0xf bound_ctrl:1
	v_mov_b32_dpp v193, v27 row_mirror row_mask:0xf bank_mask:0xf bound_ctrl:1
	s_and_saveexec_b64 s[6:7], vcc
	v_pk_add_f32 v[26:27], v[26:27], v[192:193]
	ds_write_b64 v181, v[26:27] offset:392
	s_or_b64 exec, exec, s[6:7]
	ds_read2_b32 v[192:193], v75 offset1:32
	ds_read2_b32 v[196:197], v75 offset0:64 offset1:96
	v_mov_b32_e32 v194, v60
	v_mov_b32_e32 v195, v28
	v_pk_add_f32 v[198:199], v[194:195], 0 op_sel_hi:[1,0]
	v_mov_b32_e32 v194, v44
	v_pk_add_f32 v[194:195], v[194:195], 0 op_sel_hi:[1,0]
	s_waitcnt lgkmcnt(1)
	v_mov_b32_e32 v202, v192
	s_waitcnt lgkmcnt(0)
	v_mov_b32_e32 v203, v196
	s_mov_b32 s2, s67
	v_mov_b32_e32 v206, v193
	v_mov_b32_e32 v207, v196
	v_pk_fma_f32 v[192:193], v[202:203], s[2:3], v[198:199] op_sel_hi:[1,0,1]
	v_pk_fma_f32 v[194:195], v[206:207], s[2:3], v[194:195] op_sel_hi:[1,0,1]
	v_pk_mul_f32 v[204:205], v[202:203], s[2:3] op_sel_hi:[1,0]
	v_pk_mul_f32 v[202:203], v[192:193], v[192:193]
	v_pk_mul_f32 v[206:207], v[194:195], v[194:195]
	v_pk_mov_b32 v[198:199], v[198:199], v[202:203] op_sel:[1,0]
	v_pk_mov_b32 v[202:203], v[204:205], v[206:207] op_sel:[1,0]
	v_add_f32_e32 v26, 0, v12
	v_pk_add_f32 v[198:199], v[198:199], v[202:203]
	v_pk_add_f32 v[202:203], v[192:193], v[194:195]
	v_pk_mul_f32 v[204:205], v[192:193], v[194:195]
	v_fmac_f32_e32 v26, 0x3fd744fd, v197
	v_mov_b32_e32 v203, v205
	v_pk_add_f32 v[198:199], v[202:203], v[198:199]
	v_mul_f32_e32 v27, v26, v26
	v_pk_add_f32 v[196:197], v[198:199], v[26:27]
	s_nop 1
	v_mov_b32_dpp v198, v196 quad_perm:[1,0,3,2] row_mask:0xf bank_mask:0xf bound_ctrl:1
	v_mov_b32_dpp v199, v197 quad_perm:[1,0,3,2] row_mask:0xf bank_mask:0xf bound_ctrl:1
	v_pk_add_f32 v[196:197], v[196:197], v[198:199]
	s_nop 1
	v_mov_b32_dpp v198, v196 quad_perm:[2,3,0,1] row_mask:0xf bank_mask:0xf bound_ctrl:1
	v_mov_b32_dpp v199, v197 quad_perm:[2,3,0,1] row_mask:0xf bank_mask:0xf bound_ctrl:1
	v_pk_add_f32 v[196:197], v[196:197], v[198:199]
	s_nop 1
	v_mov_b32_dpp v198, v196 row_half_mirror row_mask:0xf bank_mask:0xf bound_ctrl:1
	v_mov_b32_dpp v199, v197 row_half_mirror row_mask:0xf bank_mask:0xf bound_ctrl:1
	v_pk_add_f32 v[196:197], v[196:197], v[198:199]
	s_nop 1
	v_mov_b32_dpp v198, v196 row_mirror row_mask:0xf bank_mask:0xf bound_ctrl:1
	v_mov_b32_dpp v199, v197 row_mirror row_mask:0xf bank_mask:0xf bound_ctrl:1
	s_and_saveexec_b64 s[6:7], vcc
	v_pk_add_f32 v[196:197], v[196:197], v[198:199]
	ds_write_b64 v181, v[196:197] offset:400
	s_or_b64 exec, exec, s[6:7]
	ds_read2_b32 v[196:197], v87 offset1:32
	ds_read2_b32 v[198:199], v87 offset0:64 offset1:96
	v_mov_b32_e32 v28, v61
	v_pk_add_f32 v[202:203], v[28:29], 0 op_sel_hi:[1,0]
	v_mov_b32_e32 v28, v45
	v_pk_add_f32 v[28:29], v[28:29], 0 op_sel_hi:[1,0]
	s_waitcnt lgkmcnt(1)
;   DI void operator()(f32x16 (&acc)[2][4], int grow0, int gcol0, int lane, int w, char* lds) {
;     ...
;       for (int qq = 0; qq < 2; ++qq)
; #pragma unroll
;         for (int e = 0; e < 4; ++e) {
;           const int i = 4 * (2 * (ps & 1) + qq) + e;
;           const float* xr = (const float*)(xs + (8 * qq + 4 * hh + e) * 512) + l31;
;           float s1 = 0.f, s2 = 0.f;
; #pragma unroll
;           for (int nt = 0; nt < 4; ++nt) {
;             float v = (acc[mt][nt][i] + bia[nt]) * csc[nt];
;             float z = ALPHA * xr[nt * 32] + hs * v;
;             acc[mt][nt][i] = z; s1 += z; s2 += z * z;
;           }
;           s1 = row16_sum(s1); s2 = row16_sum(s2);
;           if ((lane & 15) == 0) { f32x2 sv = {s1, s2}; *(f32x2*)(redw + (mt * 32 + (i & 3) + 8 * (i >> 2)) * 2) = sv; }
;         }
	v_mov_b32_e32 v44, v196
	s_waitcnt lgkmcnt(0)
	v_mov_b32_e32 v45, v198
	s_mov_b32 s2, s67
	v_mov_b32_e32 v60, v197
	v_mov_b32_e32 v61, v198
	v_pk_mul_f32 v[204:205], v[44:45], s[2:3] op_sel_hi:[1,0]
	v_pk_fma_f32 v[44:45], v[44:45], s[2:3], v[202:203] op_sel_hi:[1,0,1]
	v_pk_fma_f32 v[60:61], v[60:61], s[2:3], v[28:29] op_sel_hi:[1,0,1]
	v_pk_mul_f32 v[196:197], v[44:45], v[44:45]
	v_pk_mul_f32 v[28:29], v[60:61], v[60:61]
	v_pk_mov_b32 v[196:197], v[202:203], v[196:197] op_sel:[1,0]
	v_pk_mov_b32 v[28:29], v[204:205], v[28:29] op_sel:[1,0]
	v_add_f32_e32 v12, 0, v13
	v_pk_add_f32 v[28:29], v[196:197], v[28:29]
	v_pk_add_f32 v[196:197], v[44:45], v[60:61]
	v_pk_mul_f32 v[202:203], v[44:45], v[60:61]
	v_fmac_f32_e32 v12, 0x3fd744fd, v199
	v_mov_b32_e32 v197, v203
	v_pk_add_f32 v[28:29], v[196:197], v[28:29]
	v_mul_f32_e32 v13, v12, v12
	v_pk_add_f32 v[28:29], v[28:29], v[12:13]
	s_nop 1
	v_mov_b32_dpp v196, v28 quad_perm:[1,0,3,2] row_mask:0xf bank_mask:0xf bound_ctrl:1
	v_mov_b32_dpp v197, v29 quad_perm:[1,0,3,2] row_mask:0xf bank_mask:0xf bound_ctrl:1
	v_pk_add_f32 v[28:29], v[28:29], v[196:197]
	s_nop 1
	v_mov_b32_dpp v196, v28 quad_perm:[2,3,0,1] row_mask:0xf bank_mask:0xf bound_ctrl:1
	v_mov_b32_dpp v197, v29 quad_perm:[2,3,0,1] row_mask:0xf bank_mask:0xf bound_ctrl:1
	v_pk_add_f32 v[28:29], v[28:29], v[196:197]
	s_nop 1
	v_mov_b32_dpp v196, v28 row_half_mirror row_mask:0xf bank_mask:0xf bound_ctrl:1
	v_mov_b32_dpp v197, v29 row_half_mirror row_mask:0xf bank_mask:0xf bound_ctrl:1
	v_pk_add_f32 v[28:29], v[28:29], v[196:197]
	s_nop 1
	v_mov_b32_dpp v196, v28 row_mirror row_mask:0xf bank_mask:0xf bound_ctrl:1
	v_mov_b32_dpp v197, v29 row_mirror row_mask:0xf bank_mask:0xf bound_ctrl:1
	s_and_saveexec_b64 s[6:7], vcc
	v_pk_add_f32 v[28:29], v[28:29], v[196:197]
	ds_write_b64 v181, v[28:29] offset:408
	s_or_b64 exec, exec, s[6:7]
	ds_read2_b32 v[196:197], v77 offset1:32
	ds_read2_b32 v[202:203], v77 offset0:64 offset1:96
	v_mov_b32_e32 v198, v62
	v_mov_b32_e32 v199, v30
	v_pk_add_f32 v[204:205], v[198:199], 0 op_sel_hi:[1,0]
	v_mov_b32_e32 v198, v46
	v_pk_add_f32 v[198:199], v[198:199], 0 op_sel_hi:[1,0]
	s_waitcnt lgkmcnt(1)
	v_mov_b32_e32 v206, v196
	s_waitcnt lgkmcnt(0)
	v_mov_b32_e32 v207, v202
	s_mov_b32 s2, s67
	v_mov_b32_e32 v212, v197
	v_mov_b32_e32 v213, v202
	v_pk_fma_f32 v[196:197], v[206:207], s[2:3], v[204:205] op_sel_hi:[1,0,1]
	v_pk_fma_f32 v[198:199], v[212:213], s[2:3], v[198:199] op_sel_hi:[1,0,1]
	v_pk_mul_f32 v[208:209], v[206:207], s[2:3] op_sel_hi:[1,0]
	v_pk_mul_f32 v[206:207], v[196:197], v[196:197]
	v_pk_mul_f32 v[212:213], v[198:199], v[198:199]
	v_pk_mov_b32 v[204:205], v[204:205], v[206:207] op_sel:[1,0]
	v_pk_mov_b32 v[206:207], v[208:209], v[212:213] op_sel:[1,0]
	v_add_f32_e32 v28, 0, v14
	v_pk_add_f32 v[204:205], v[204:205], v[206:207]
	v_pk_add_f32 v[206:207], v[196:197], v[198:199]
	v_pk_mul_f32 v[208:209], v[196:197], v[198:199]
	v_fmac_f32_e32 v28, 0x3fd744fd, v203
	v_mov_b32_e32 v207, v209
	v_pk_add_f32 v[204:205], v[206:207], v[204:205]
	v_mul_f32_e32 v29, v28, v28
	v_pk_add_f32 v[202:203], v[204:205], v[28:29]
	s_nop 1
	v_mov_b32_dpp v204, v202 quad_perm:[1,0,3,2] row_mask:0xf bank_mask:0xf bound_ctrl:1
	v_mov_b32_dpp v205, v203 quad_perm:[1,0,3,2] row_mask:0xf bank_mask:0xf bound_ctrl:1
	v_pk_add_f32 v[202:203], v[202:203], v[204:205]
	s_nop 1
	v_mov_b32_dpp v204, v202 quad_perm:[2,3,0,1] row_mask:0xf bank_mask:0xf bound_ctrl:1
	v_mov_b32_dpp v205, v203 quad_perm:[2,3,0,1] row_mask:0xf bank_mask:0xf bound_ctrl:1
	v_pk_add_f32 v[202:203], v[202:203], v[204:205]
	s_nop 1
	v_mov_b32_dpp v204, v202 row_half_mirror row_mask:0xf bank_mask:0xf bound_ctrl:1
	v_mov_b32_dpp v205, v203 row_half_mirror row_mask:0xf bank_mask:0xf bound_ctrl:1
	v_pk_add_f32 v[202:203], v[202:203], v[204:205]
	s_nop 1
	v_mov_b32_dpp v204, v202 row_mirror row_mask:0xf bank_mask:0xf bound_ctrl:1
	v_mov_b32_dpp v205, v203 row_mirror row_mask:0xf bank_mask:0xf bound_ctrl:1
	s_and_saveexec_b64 s[6:7], vcc
	v_pk_add_f32 v[202:203], v[202:203], v[204:205]
	ds_write_b64 v181, v[202:203] offset:448
	s_or_b64 exec, exec, s[6:7]
	ds_read2_b32 v[202:203], v91 offset1:32
	ds_read2_b32 v[204:205], v91 offset0:64 offset1:96
	v_mov_b32_e32 v30, v63
	v_pk_add_f32 v[206:207], v[30:31], 0 op_sel_hi:[1,0]
	v_mov_b32_e32 v30, v47
	v_pk_add_f32 v[30:31], v[30:31], 0 op_sel_hi:[1,0]
	s_waitcnt lgkmcnt(1)
	v_mov_b32_e32 v46, v202
	s_waitcnt lgkmcnt(0)
	v_mov_b32_e32 v47, v204
	s_mov_b32 s2, s67
	v_mov_b32_e32 v62, v203
	v_mov_b32_e32 v63, v204
	v_pk_mul_f32 v[208:209], v[46:47], s[2:3] op_sel_hi:[1,0]
	v_pk_fma_f32 v[46:47], v[46:47], s[2:3], v[206:207] op_sel_hi:[1,0,1]
	v_pk_fma_f32 v[62:63], v[62:63], s[2:3], v[30:31] op_sel_hi:[1,0,1]
	v_pk_mul_f32 v[202:203], v[46:47], v[46:47]
	v_pk_mul_f32 v[30:31], v[62:63], v[62:63]
	v_pk_mov_b32 v[202:203], v[206:207], v[202:203] op_sel:[1,0]
	v_pk_mov_b32 v[30:31], v[208:209], v[30:31] op_sel:[1,0]
	v_add_f32_e32 v14, 0, v15
	v_pk_add_f32 v[30:31], v[202:203], v[30:31]
	v_pk_add_f32 v[202:203], v[46:47], v[62:63]
	v_pk_mul_f32 v[206:207], v[46:47], v[62:63]
	v_fmac_f32_e32 v14, 0x3fd744fd, v205
	v_mov_b32_e32 v203, v207
	v_pk_add_f32 v[30:31], v[202:203], v[30:31]
	v_mul_f32_e32 v15, v14, v14
	v_pk_add_f32 v[30:31], v[30:31], v[14:15]
	s_nop 1
	v_mov_b32_dpp v202, v30 quad_perm:[1,0,3,2] row_mask:0xf bank_mask:0xf bound_ctrl:1
	v_mov_b32_dpp v203, v31 quad_perm:[1,0,3,2] row_mask:0xf bank_mask:0xf bound_ctrl:1
	v_pk_add_f32 v[30:31], v[30:31], v[202:203]
	s_nop 1
	v_mov_b32_dpp v202, v30 quad_perm:[2,3,0,1] row_mask:0xf bank_mask:0xf bound_ctrl:1
	v_mov_b32_dpp v203, v31 quad_perm:[2,3,0,1] row_mask:0xf bank_mask:0xf bound_ctrl:1
	v_pk_add_f32 v[30:31], v[30:31], v[202:203]
	s_nop 1
	v_mov_b32_dpp v202, v30 row_half_mirror row_mask:0xf bank_mask:0xf bound_ctrl:1
	v_mov_b32_dpp v203, v31 row_half_mirror row_mask:0xf bank_mask:0xf bound_ctrl:1
	v_pk_add_f32 v[30:31], v[30:31], v[202:203]
	s_nop 1
	v_mov_b32_dpp v202, v30 row_mirror row_mask:0xf bank_mask:0xf bound_ctrl:1
	v_mov_b32_dpp v203, v31 row_mirror row_mask:0xf bank_mask:0xf bound_ctrl:1
	s_and_saveexec_b64 s[6:7], vcc
	v_pk_add_f32 v[30:31], v[30:31], v[202:203]
	ds_write_b64 v181, v[30:31] offset:456
	s_or_b64 exec, exec, s[6:7]
	ds_read2_b32 v[202:203], v79 offset1:32
	ds_read2_b32 v[206:207], v79 offset0:64 offset1:96
	v_mov_b32_e32 v204, v64
	v_mov_b32_e32 v205, v32
	v_pk_add_f32 v[208:209], v[204:205], 0 op_sel_hi:[1,0]
	v_mov_b32_e32 v204, v48
	v_pk_add_f32 v[204:205], v[204:205], 0 op_sel_hi:[1,0]
	s_waitcnt lgkmcnt(1)
; DI void ag_st64(u64_t* p, u64_t v) { __hip_atomic_store(p, v, __ATOMIC_RELAXED, __HIP_MEMORY_SCOPE_AGENT); }
;   DI void operator()(f32x16 (&acc)[2][4], int grow0, int gcol0, int lane, int w, char* lds) {
;     ...
;           for (int nt = 0; nt < 4; ++nt) {
;             float v = (acc[mt][nt][i] + bia[nt]) * csc[nt];
;             float z = ALPHA * xr[nt * 32] + hs * v;
;             acc[mt][nt][i] = z; s1 += z; s2 += z * z;
;           }
;           s1 = row16_sum(s1); s2 = row16_sum(s2);
;           if ((lane & 15) == 0) { f32x2 sv = {s1, s2}; *(f32x2*)(redw + (mt * 32 + (i & 3) + 8 * (i >> 2)) * 2) = sv; }
;         }
;     }
;     __syncthreads();
;     u64_t* myslots = xstat + ((size_t)pm * 256) * 4;
;     if (tid < 256) {
;       float s1 = (red[tid * 2] + red[(256 + tid) * 2]) + (red[(512 + tid) * 2] + red[(768 + tid) * 2]);
;       float s2 = (red[tid * 2 + 1] + red[(256 + tid) * 2 + 1]) + (red[(512 + tid) * 2 + 1] + red[(768 + tid) * 2 + 1]);
;       ag_st64(myslots + tid * 4 + pn, ((u64_t)__float_as_uint(s2) << 32) | (u64_t)__float_as_uint(s1));
	v_mov_b32_e32 v212, v202
	s_waitcnt lgkmcnt(0)
	v_mov_b32_e32 v213, v206
	s_mov_b32 s2, s67
	v_mov_b32_e32 v226, v203
	v_mov_b32_e32 v227, v206
	v_pk_fma_f32 v[202:203], v[212:213], s[2:3], v[208:209] op_sel_hi:[1,0,1]
	v_pk_fma_f32 v[204:205], v[226:227], s[2:3], v[204:205] op_sel_hi:[1,0,1]
	v_pk_mul_f32 v[214:215], v[212:213], s[2:3] op_sel_hi:[1,0]
	v_pk_mul_f32 v[212:213], v[202:203], v[202:203]
	v_pk_mul_f32 v[226:227], v[204:205], v[204:205]
	v_pk_mov_b32 v[208:209], v[208:209], v[212:213] op_sel:[1,0]
	v_pk_mov_b32 v[212:213], v[214:215], v[226:227] op_sel:[1,0]
	v_add_f32_e32 v30, 0, v16
	v_pk_add_f32 v[208:209], v[208:209], v[212:213]
	v_pk_add_f32 v[212:213], v[202:203], v[204:205]
	v_pk_mul_f32 v[214:215], v[202:203], v[204:205]
	v_fmac_f32_e32 v30, 0x3fd744fd, v207
	v_mov_b32_e32 v213, v215
	v_pk_add_f32 v[208:209], v[212:213], v[208:209]
	v_mul_f32_e32 v31, v30, v30
	v_pk_add_f32 v[206:207], v[208:209], v[30:31]
	s_nop 1
	v_mov_b32_dpp v208, v206 quad_perm:[1,0,3,2] row_mask:0xf bank_mask:0xf bound_ctrl:1
	v_mov_b32_dpp v209, v207 quad_perm:[1,0,3,2] row_mask:0xf bank_mask:0xf bound_ctrl:1
	v_pk_add_f32 v[206:207], v[206:207], v[208:209]
	s_nop 1
	v_mov_b32_dpp v208, v206 quad_perm:[2,3,0,1] row_mask:0xf bank_mask:0xf bound_ctrl:1
	v_mov_b32_dpp v209, v207 quad_perm:[2,3,0,1] row_mask:0xf bank_mask:0xf bound_ctrl:1
	v_pk_add_f32 v[206:207], v[206:207], v[208:209]
	s_nop 1
	v_mov_b32_dpp v208, v206 row_half_mirror row_mask:0xf bank_mask:0xf bound_ctrl:1
	v_mov_b32_dpp v209, v207 row_half_mirror row_mask:0xf bank_mask:0xf bound_ctrl:1
	v_pk_add_f32 v[206:207], v[206:207], v[208:209]
	s_nop 1
	v_mov_b32_dpp v208, v206 row_mirror row_mask:0xf bank_mask:0xf bound_ctrl:1
	v_mov_b32_dpp v209, v207 row_mirror row_mask:0xf bank_mask:0xf bound_ctrl:1
	s_and_saveexec_b64 s[6:7], vcc
	v_pk_add_f32 v[206:207], v[206:207], v[208:209]
	ds_write_b64 v181, v[206:207] offset:464
	s_or_b64 exec, exec, s[6:7]
	ds_read2_b32 v[206:207], v93 offset1:32
	ds_read2_b32 v[208:209], v93 offset0:64 offset1:96
	v_mov_b32_e32 v32, v65
	v_pk_add_f32 v[64:65], v[32:33], 0 op_sel_hi:[1,0]
	v_mov_b32_e32 v32, v49
	v_pk_add_f32 v[48:49], v[32:33], 0 op_sel_hi:[1,0]
	s_waitcnt lgkmcnt(1)
	v_mov_b32_e32 v32, v206
	s_waitcnt lgkmcnt(0)
	v_mov_b32_e32 v33, v208
	s_mov_b32 s2, s67
	v_mov_b32_e32 v206, v207
	v_mov_b32_e32 v207, v208
	v_pk_mul_f32 v[212:213], v[32:33], s[2:3] op_sel_hi:[1,0]
	v_pk_fma_f32 v[32:33], v[32:33], s[2:3], v[64:65] op_sel_hi:[1,0,1]
	v_pk_fma_f32 v[48:49], v[206:207], s[2:3], v[48:49] op_sel_hi:[1,0,1]
	v_pk_mul_f32 v[214:215], v[32:33], v[32:33]
	v_pk_mul_f32 v[206:207], v[48:49], v[48:49]
	v_pk_mov_b32 v[64:65], v[64:65], v[214:215] op_sel:[1,0]
	v_pk_mov_b32 v[206:207], v[212:213], v[206:207] op_sel:[1,0]
	v_add_f32_e32 v16, 0, v17
	v_pk_add_f32 v[64:65], v[64:65], v[206:207]
	v_pk_add_f32 v[206:207], v[32:33], v[48:49]
	v_pk_mul_f32 v[212:213], v[32:33], v[48:49]
	v_fmac_f32_e32 v16, 0x3fd744fd, v209
	v_mov_b32_e32 v207, v213
	v_pk_add_f32 v[64:65], v[206:207], v[64:65]
	v_mul_f32_e32 v17, v16, v16
	v_pk_add_f32 v[64:65], v[64:65], v[16:17]
	s_nop 1
	v_mov_b32_dpp v206, v64 quad_perm:[1,0,3,2] row_mask:0xf bank_mask:0xf bound_ctrl:1
	v_mov_b32_dpp v207, v65 quad_perm:[1,0,3,2] row_mask:0xf bank_mask:0xf bound_ctrl:1
	v_pk_add_f32 v[64:65], v[64:65], v[206:207]
	s_nop 1
	v_mov_b32_dpp v206, v64 quad_perm:[2,3,0,1] row_mask:0xf bank_mask:0xf bound_ctrl:1
	v_mov_b32_dpp v207, v65 quad_perm:[2,3,0,1] row_mask:0xf bank_mask:0xf bound_ctrl:1
	v_pk_add_f32 v[64:65], v[64:65], v[206:207]
	s_nop 1
	v_mov_b32_dpp v206, v64 row_half_mirror row_mask:0xf bank_mask:0xf bound_ctrl:1
	v_mov_b32_dpp v207, v65 row_half_mirror row_mask:0xf bank_mask:0xf bound_ctrl:1
	v_pk_add_f32 v[64:65], v[64:65], v[206:207]
	s_nop 1
	v_mov_b32_dpp v206, v64 row_mirror row_mask:0xf bank_mask:0xf bound_ctrl:1
	v_mov_b32_dpp v207, v65 row_mirror row_mask:0xf bank_mask:0xf bound_ctrl:1
	s_and_saveexec_b64 s[6:7], vcc
	v_pk_add_f32 v[64:65], v[64:65], v[206:207]
	ds_write_b64 v181, v[64:65] offset:472
	s_or_b64 exec, exec, s[6:7]
	v_ashrrev_i32_e32 v206, 8, v163
	v_ashrrev_i32_e32 v207, 31, v206
	v_lshlrev_b64 v[64:65], 13, v[206:207]
	v_lshl_add_u64 v[64:65], s[8:9], 0, v[64:65]
	v_cmp_gt_i32_e64 s[40:41], s60, v164
	v_ashrrev_i32_e32 v201, 31, v200
	s_waitcnt lgkmcnt(0)
	s_barrier
	s_and_saveexec_b64 s[6:7], s[40:41]
	s_cbranch_execz .LBB0_240
	v_lshl_add_u32 v0, v164, 3, v221
	ds_read2st64_b64 v[212:215], v0 offset1:4
	ds_read2st64_b64 v[226:229], v0 offset0:8 offset1:12
	v_ashrrev_i32_e32 v208, 8, v184
	v_ashrrev_i32_e32 v209, 31, v208
	s_waitcnt lgkmcnt(1)
	v_mov_b32_e32 v230, v212
	s_waitcnt lgkmcnt(0)
	v_mov_b32_e32 v231, v226
	v_mov_b32_e32 v232, v214
	v_mov_b32_e32 v233, v228
	v_mov_b32_e32 v226, v213
	v_mov_b32_e32 v228, v215
	v_pk_add_f32 v[230:231], v[230:231], v[232:233]
	v_pk_add_f32 v[212:213], v[226:227], v[228:229]
	v_pk_add_f32 v[230:231], v[230:231], v[230:231] op_sel:[0,1] op_sel_hi:[1,0]
	v_pk_add_f32 v[212:213], v[212:213], v[212:213] op_sel:[0,1] op_sel_hi:[1,0]
	v_lshl_add_u64 v[214:215], v[200:201], 3, v[64:65]
	v_lshl_add_u64 v[208:209], v[208:209], 3, v[214:215]
	v_mov_b32_e32 v231, v212
	global_store_dwordx2 v[208:209], v[230:231], off sc1

; DI f32x16 mfma(bf16x8 a, bf16x8 b, f32x16 c) { return __builtin_amdgcn_mfma_f32_32x32x16_bf16(a, b, c, 0, 0, 0); }
; template <int BK> DI int swz(int row) { constexpr int CPR = BK / 8; return (row / (16 / CPR)) % CPR; }
; DI void wait_vm0() { asm volatile("s_waitcnt vmcnt(0)" ::: "memory"); }
;   DI void pre(int grow0, int gcol0, int lane, int w, char* lds) { xpass(0, grow0, gcol0, lane, w, lds); }
;     ...
;   for (int kt = 0; kt < nk; ++kt) {
;     char* cur = lds + (kt & 1) * STG; char* nxt = lds + ((kt + 1) & 1) * STG;
;     const bool more = kt + 1 < nk;
;     const bf16_t* An = Ag + (kt + 1) * BK; const bf16_t* Bn = Bg + (kt + 1) * BK;
;     if (!more) epi.pre(row0 + wm * 64, col0 + wn * (32 * NTW), lane, w, lds);
;     bf16x8 fa[2][2], fb[2][NTW];
; #pragma unroll
;     for (int mt = 0; mt < 2; ++mt) { int row = wm * 64 + mt * 32 + l31; fa[0][mt] = *(const bf16x8*)(cur + row * (BK * 2) + ((hh ^ swz<BK>(row)) << 4)); }
; #pragma unroll
;     for (int nt = 0; nt < NTW; ++nt) { int row = wn * (32 * NTW) + nt * 32 + l31; fb[0][nt] = *(const bf16x8*)(cur + ABYTES + row * (BK * 2) + ((hh ^ swz<BK>(row)) << 4)); }
; #pragma unroll
;     for (int kk = 0; kk < NKK; ++kk) {
;       if (kk + 1 < NKK) {
;         const int ch = (kk + 1) * 2 + hh;
; #pragma unroll
;         for (int mt = 0; mt < 2; ++mt) { int row = wm * 64 + mt * 32 + l31; fa[(kk + 1) & 1][mt] = *(const bf16x8*)(cur + row * (BK * 2) + ((ch ^ swz<BK>(row)) << 4)); }
; #pragma unroll
;         for (int nt = 0; nt < NTW; ++nt) { int row = wn * (32 * NTW) + nt * 32 + l31; fb[(kk + 1) & 1][nt] = *(const bf16x8*)(cur + ABYTES + row * (BK * 2) + ((ch ^ swz<BK>(row)) << 4)); }
;       }
;       if (more) {
; #pragma unroll
;         for (int q = 0; q < PPK; ++q) {
;           const int pi = kk * PPK + q;
;           if (pi < NPA) stage_piece<BM, BK>(An, lda, nxt, tid, pi, wv);
;           else if (pi < NP) stage_piece<BN, BK>(Bn, ldb, nxt + ABYTES, tid, pi - NPA, wv);
;         }
;       }
;       __builtin_amdgcn_s_setprio(1);
; #pragma unroll
;       for (int mt = 0; mt < 2; ++mt)
; #pragma unroll
;         for (int nt = 0; nt < NTW; ++nt) acc[mt][nt] = mfma(fa[kk & 1][mt], fb[kk & 1][nt], acc[mt][nt]);
;       __builtin_amdgcn_s_setprio(0);
;       __builtin_amdgcn_sched_barrier(0);
;     }
;     wait_vm0();
;     __syncthreads();
;   }
.LBB0_292:
	s_and_b32 s30, s3, 0x10000
	s_xor_b32 s100, s30, 0x10000
	s_add_i32 s31, s30, s2
	v_add3_u32 v194, s100, v136, v164
	v_add3_u32 v198, s100, v144, v166
	ds_read_b128 v[194:197], v194
	v_add3_u32 v202, s100, v145, v161
	ds_read_b128 v[198:201], v198
	v_add3_u32 v206, s100, v152, v163
	ds_read_b128 v[202:205], v202 offset:32768
	v_add3_u32 v210, s100, v155, v159
	ds_read_b128 v[206:209], v206 offset:32768
	v_add3_u32 v226, s100, v158, v160
	ds_read_b128 v[210:213], v210 offset:32768
	ds_read_b128 v[226:229], v226 offset:32768
	v_lshl_add_u64 v[214:215], v[132:133], 0, s[6:7]
	v_lshl_add_u64 v[230:231], v[130:131], 0, s[6:7]
	s_mov_b32 m0, s31
	v_lshl_add_u64 v[232:233], v[214:215], 0, s[28:29]
	s_waitcnt lgkmcnt(6)
	v_mfma_f32_32x32x16_bf16 v[114:129], v[170:173], v[178:181], v[114:129]
	global_load_lds_dwordx4 v[232:233], off
	v_lshl_add_u64 v[232:233], v[214:215], 0, s[36:37]
	s_add_i32 m0, s31, 0x2000
	v_mfma_f32_32x32x16_bf16 v[98:113], v[170:173], v[182:185], v[98:113]
	global_load_lds_dwordx4 v[232:233], off
	v_lshl_add_u64 v[232:233], v[214:215], 0, s[40:41]
	s_add_i32 m0, s31, 0x4000
	v_mfma_f32_32x32x16_bf16 v[82:97], v[170:173], v[186:189], v[82:97]
	global_load_lds_dwordx4 v[232:233], off
	v_lshl_add_u64 v[232:233], v[214:215], 0, s[42:43]
	s_add_i32 m0, s31, 0x6000
	v_mfma_f32_32x32x16_bf16 v[66:81], v[170:173], v[190:193], v[66:81]
	global_load_lds_dwordx4 v[232:233], off
	v_lshl_add_u64 v[232:233], v[230:231], 0, s[28:29]
	s_add_i32 m0, s31, 0x8000
	v_mfma_f32_32x32x16_bf16 v[50:65], v[174:177], v[178:181], v[50:65]
	global_load_lds_dwordx4 v[232:233], off
	v_lshl_add_u64 v[232:233], v[230:231], 0, s[36:37]
	s_add_i32 m0, s31, 0xa000
	v_mfma_f32_32x32x16_bf16 v[34:49], v[174:177], v[182:185], v[34:49]
	global_load_lds_dwordx4 v[232:233], off
	v_lshl_add_u64 v[232:233], v[230:231], 0, s[40:41]
	s_add_i32 m0, s31, 0xc000
	v_mfma_f32_32x32x16_bf16 v[18:33], v[174:177], v[186:189], v[18:33]
	global_load_lds_dwordx4 v[232:233], off
	v_lshl_add_u64 v[232:233], v[230:231], 0, s[42:43]
	s_add_i32 m0, s31, 0xe000
	v_mfma_f32_32x32x16_bf16 v[2:17], v[174:177], v[190:193], v[2:17]
	global_load_lds_dwordx4 v[232:233], off
	v_add3_u32 v170, s100, v136, v153
	v_add3_u32 v174, s100, v144, v154
	ds_read_b128 v[170:173], v170
	v_add3_u32 v178, s100, v145, v149
	ds_read_b128 v[174:177], v174
	v_add3_u32 v182, s100, v152, v150
	ds_read_b128 v[178:181], v178 offset:32768
	v_add3_u32 v186, s100, v155, v147
	ds_read_b128 v[182:185], v182 offset:32768
	v_add3_u32 v190, s100, v158, v148
	ds_read_b128 v[186:189], v186 offset:32768
	ds_read_b128 v[190:193], v190 offset:32768
	s_waitcnt lgkmcnt(6)
	v_mfma_f32_32x32x16_bf16 v[114:129], v[194:197], v[202:205], v[114:129]
	v_mfma_f32_32x32x16_bf16 v[98:113], v[194:197], v[206:209], v[98:113]
	v_mfma_f32_32x32x16_bf16 v[82:97], v[194:197], v[210:213], v[82:97]
	v_mfma_f32_32x32x16_bf16 v[66:81], v[194:197], v[226:229], v[66:81]
	v_mfma_f32_32x32x16_bf16 v[50:65], v[198:201], v[202:205], v[50:65]
	v_mfma_f32_32x32x16_bf16 v[34:49], v[198:201], v[206:209], v[34:49]
	v_mfma_f32_32x32x16_bf16 v[18:33], v[198:201], v[210:213], v[18:33]
	v_mfma_f32_32x32x16_bf16 v[2:17], v[198:201], v[226:229], v[2:17]
	v_add3_u32 v194, s100, v136, v141
	v_add3_u32 v198, s100, v144, v142
	ds_read_b128 v[194:197], v194
	v_add3_u32 v202, s100, v145, v139
	ds_read_b128 v[198:201], v198
	v_add3_u32 v206, s100, v152, v140
	ds_read_b128 v[202:205], v202 offset:32768
	v_add3_u32 v210, s100, v155, v137
	ds_read_b128 v[206:209], v206 offset:32768
	v_add3_u32 v226, s100, v158, v138
	ds_read_b128 v[210:213], v210 offset:32768
	ds_read_b128 v[226:229], v226 offset:32768
	s_waitcnt lgkmcnt(6)
	v_mfma_f32_32x32x16_bf16 v[114:129], v[170:173], v[178:181], v[114:129]
	v_mfma_f32_32x32x16_bf16 v[98:113], v[170:173], v[182:185], v[98:113]
	v_mfma_f32_32x32x16_bf16 v[82:97], v[170:173], v[186:189], v[82:97]
	v_mfma_f32_32x32x16_bf16 v[66:81], v[170:173], v[190:193], v[66:81]
	v_mfma_f32_32x32x16_bf16 v[50:65], v[174:177], v[178:181], v[50:65]
	v_mfma_f32_32x32x16_bf16 v[34:49], v[174:177], v[182:185], v[34:49]
	v_mfma_f32_32x32x16_bf16 v[18:33], v[174:177], v[186:189], v[18:33]
	v_mfma_f32_32x32x16_bf16 v[2:17], v[174:177], v[190:193], v[2:17]
	s_add_u32 s6, s6, 0x80
	s_addc_u32 s7, s7, 0
	s_add_i32 s3, s3, 0x10000
	s_waitcnt vmcnt(0) lgkmcnt(0)
	s_barrier
	v_add3_u32 v170, s30, v136, v143
	v_add3_u32 v174, s30, v144, v146
	ds_read_b128 v[170:173], v170
	v_add3_u32 v178, s30, v145, v151
	ds_read_b128 v[174:177], v174
	v_add3_u32 v182, s30, v152, v156
	ds_read_b128 v[178:181], v178 offset:32768
	v_add3_u32 v186, s30, v155, v157
	ds_read_b128 v[182:185], v182 offset:32768
	v_add3_u32 v190, s30, v158, v167
	ds_read_b128 v[186:189], v186 offset:32768
	ds_read_b128 v[190:193], v190 offset:32768
	v_mfma_f32_32x32x16_bf16 v[114:129], v[194:197], v[202:205], v[114:129]
	v_mfma_f32_32x32x16_bf16 v[98:113], v[194:197], v[206:209], v[98:113]
	v_mfma_f32_32x32x16_bf16 v[82:97], v[194:197], v[210:213], v[82:97]
	v_mfma_f32_32x32x16_bf16 v[66:81], v[194:197], v[226:229], v[66:81]
	v_mfma_f32_32x32x16_bf16 v[50:65], v[198:201], v[202:205], v[50:65]
	v_mfma_f32_32x32x16_bf16 v[34:49], v[198:201], v[206:209], v[34:49]
	v_mfma_f32_32x32x16_bf16 v[18:33], v[198:201], v[210:213], v[18:33]
	v_mfma_f32_32x32x16_bf16 v[2:17], v[198:201], v[226:229], v[2:17]
	s_cmpk_lg_i32 s6, 0x1580
	s_cbranch_scc1 .LBB0_292
; DI f32x16 mfma(bf16x8 a, bf16x8 b, f32x16 c) { return __builtin_amdgcn_mfma_f32_32x32x16_bf16(a, b, c, 0, 0, 0); }
; DI void wait_vm0() { asm volatile("s_waitcnt vmcnt(0)" ::: "memory"); }
;     ...
;     if (!more) epi.pre(row0 + wm * 64, col0 + wn * (32 * NTW), lane, w, lds);
;     bf16x8 fa[2][2], fb[2][NTW];
; #pragma unroll
;     for (int mt = 0; mt < 2; ++mt) { int row = wm * 64 + mt * 32 + l31; fa[0][mt] = *(const bf16x8*)(cur + row * (BK * 2) + ((hh ^ swz<BK>(row)) << 4)); }
; #pragma unroll
;     for (int nt = 0; nt < NTW; ++nt) { int row = wn * (32 * NTW) + nt * 32 + l31; fb[0][nt] = *(const bf16x8*)(cur + ABYTES + row * (BK * 2) + ((hh ^ swz<BK>(row)) << 4)); }
; #pragma unroll
;     for (int kk = 0; kk < NKK; ++kk) {
;       if (kk + 1 < NKK) {
;         const int ch = (kk + 1) * 2 + hh;
; #pragma unroll
;         for (int mt = 0; mt < 2; ++mt) { int row = wm * 64 + mt * 32 + l31; fa[(kk + 1) & 1][mt] = *(const bf16x8*)(cur + row * (BK * 2) + ((ch ^ swz<BK>(row)) << 4)); }
; #pragma unroll
;         for (int nt = 0; nt < NTW; ++nt) { int row = wn * (32 * NTW) + nt * 32 + l31; fb[(kk + 1) & 1][nt] = *(const bf16x8*)(cur + ABYTES + row * (BK * 2) + ((ch ^ swz<BK>(row)) << 4)); }
;       }
;       if (more) {
; #pragma unroll
;         for (int q = 0; q < PPK; ++q) {
;           const int pi = kk * PPK + q;
;           if (pi < NPA) stage_piece<BM, BK>(An, lda, nxt, tid, pi, wv);
;           else if (pi < NP) stage_piece<BN, BK>(Bn, ldb, nxt + ABYTES, tid, pi - NPA, wv);
;         }
;       }
;       __builtin_amdgcn_s_setprio(1);
; #pragma unroll
;       for (int mt = 0; mt < 2; ++mt)
; #pragma unroll
;         for (int nt = 0; nt < NTW; ++nt) acc[mt][nt] = mfma(fa[kk & 1][mt], fb[kk & 1][nt], acc[mt][nt]);
;       __builtin_amdgcn_s_setprio(0);
;       __builtin_amdgcn_sched_barrier(0);
;     }
;     wait_vm0();
;     __syncthreads();
;   DI void xpass(int ps, int grow0, int gcol0, int lane, int w, char* lds) const {
;     char* xs = lds + (ps & 1) * 65536 + __builtin_amdgcn_readfirstlane(w) * 8192;
;     const float* xsrc = Xin + (size_t)(grow0 + (ps >> 1) * 32 + (ps & 1) * 16 + (lane >> 5)) * D_ + gcol0 + (lane & 31) * 4;
; #pragma unroll
;     for (int pc = 0; pc < 8; ++pc)
;       __builtin_amdgcn_global_load_lds((const unsigned*)(xsrc + (size_t)(2 * pc) * D_), (__attribute__((address_space(3))) unsigned*)(xs + pc * 1024), 16, 0, 0);
;   }
	s_waitcnt lgkmcnt(0)
	v_readlane_b32 s3, v253, 9
	v_readlane_b32 s6, v253, 27
	v_readlane_b32 s54, v255, 29
	v_or_b32_e32 v130, s3, v135
	v_add_u32_e32 v130, v130, v169
	v_ashrrev_i32_e32 v131, 31, v130
	v_lshlrev_b64 v[130:131], 12, v[130:131]
	v_add_u32_e32 v132, s6, v168
	v_readlane_b32 s55, v255, 30
	v_ashrrev_i32_e32 v133, 31, v132
	v_readfirstlane_b32 s2, v134
	v_lshl_add_u64 v[130:131], s[54:55], 0, v[130:131]
	v_lshlrev_b32_e32 v0, 4, v0
	s_lshl_b32 s2, s2, 13
	v_lshl_add_u64 v[130:131], v[132:133], 2, v[130:131]
	v_and_b32_e32 v0, 0x1f0, v0
	v_lshl_add_u64 v[130:131], v[130:131], 0, v[0:1]
	s_mov_b32 m0, s2
	s_mov_b64 s[34:35], 0x2000
	global_load_lds_dwordx4 v[130:131], off
	v_lshl_add_u64 v[132:133], v[130:131], 0, s[34:35]
	s_or_b32 m0, s2, 0x400
	s_mov_b64 s[36:37], 0x4000
	global_load_lds_dwordx4 v[132:133], off
	v_lshl_add_u64 v[132:133], v[130:131], 0, s[36:37]
	s_or_b32 m0, s2, 0x800
	s_mov_b64 s[40:41], 0x6000
	global_load_lds_dwordx4 v[132:133], off
	v_lshl_add_u64 v[132:133], v[130:131], 0, s[40:41]
	s_or_b32 m0, s2, 0xc00
	s_mov_b64 s[42:43], 0x8000
	global_load_lds_dwordx4 v[132:133], off
	v_lshl_add_u64 v[132:133], v[130:131], 0, s[42:43]
	s_or_b32 m0, s2, 0x1000
	s_mov_b64 s[44:45], 0xa000
	global_load_lds_dwordx4 v[132:133], off
	v_lshl_add_u64 v[132:133], v[130:131], 0, s[44:45]
	s_or_b32 m0, s2, 0x1400
	s_mov_b64 s[46:47], 0xc000
	global_load_lds_dwordx4 v[132:133], off
	v_lshl_add_u64 v[132:133], v[130:131], 0, s[46:47]
	s_or_b32 m0, s2, 0x1800
	s_mov_b64 s[52:53], 0xe000
	global_load_lds_dwordx4 v[132:133], off
	v_lshl_add_u64 v[130:131], v[130:131], 0, s[52:53]
	s_or_b32 m0, s2, 0x1c00
	v_add_u32_e32 v0, s30, v136
	global_load_lds_dwordx4 v[130:131], off
	v_add_u32_e32 v134, s30, v144
	v_add_u32_e32 v130, v0, v143
	v_add_u32_e32 v135, v134, v146
	ds_read_b128 v[130:133], v130
	ds_read_b128 v[168:171], v135
	v_add_u32_e32 v135, s30, v145
	v_add_u32_e32 v136, v135, v151
	v_add_u32_e32 v143, s30, v152
	v_add_u32_e32 v144, v143, v156
	ds_read_b128 v[172:175], v136 offset:32768
	ds_read_b128 v[176:179], v144 offset:32768
	v_add_u32_e32 v136, s30, v155
	v_add_u32_e32 v144, v136, v157
	v_add_u32_e32 v208, s30, v158
	v_add_u32_e32 v145, v208, v167
	ds_read_b128 v[180:183], v144 offset:32768
	ds_read_b128 v[184:187], v145 offset:32768
	v_add_u32_e32 v144, v0, v164
	v_add_u32_e32 v145, v134, v166
	ds_read_b128 v[188:191], v144
	ds_read_b128 v[192:195], v145
	v_add_u32_e32 v144, v135, v161
	v_add_u32_e32 v145, v143, v163
	ds_read_b128 v[196:199], v144 offset:32768
	ds_read_b128 v[200:203], v145 offset:32768
	v_add_u32_e32 v144, v136, v159
	v_add_u32_e32 v145, v208, v160
	ds_read_b128 v[156:159], v144 offset:32768
	ds_read_b128 v[204:207], v145 offset:32768
	v_readlane_b32 s7, v253, 28
	s_setprio 1
	s_waitcnt lgkmcnt(0)
	v_mfma_f32_32x32x16_bf16 v[114:129], v[130:133], v[172:175], v[114:129]
	v_mfma_f32_32x32x16_bf16 v[98:113], v[130:133], v[176:179], v[98:113]
	v_mfma_f32_32x32x16_bf16 v[82:97], v[130:133], v[180:183], v[82:97]
	v_mfma_f32_32x32x16_bf16 v[66:81], v[130:133], v[184:187], v[66:81]
	v_mfma_f32_32x32x16_bf16 v[50:65], v[168:171], v[172:175], v[50:65]
	v_mfma_f32_32x32x16_bf16 v[34:49], v[168:171], v[176:179], v[34:49]
	v_mfma_f32_32x32x16_bf16 v[18:33], v[168:171], v[180:183], v[18:33]
	v_mfma_f32_32x32x16_bf16 v[2:17], v[168:171], v[184:187], v[2:17]
	s_setprio 0
	v_add_u32_e32 v130, v0, v153
	v_add_u32_e32 v144, v134, v154
	ds_read_b128 v[130:133], v130
	ds_read_b128 v[152:155], v144
	v_add_u32_e32 v144, v135, v149
	v_add_u32_e32 v145, v143, v150
	ds_read_b128 v[166:169], v144 offset:32768
	ds_read_b128 v[170:173], v145 offset:32768
	v_add_u32_e32 v144, v136, v147
	v_add_u32_e32 v148, v208, v148
	ds_read_b128 v[144:147], v144 offset:32768
	ds_read_b128 v[148:151], v148 offset:32768
	s_setprio 1
	v_mfma_f32_32x32x16_bf16 v[114:129], v[188:191], v[196:199], v[114:129]
	v_mfma_f32_32x32x16_bf16 v[98:113], v[188:191], v[200:203], v[98:113]
	v_mfma_f32_32x32x16_bf16 v[82:97], v[188:191], v[156:159], v[82:97]
	v_mfma_f32_32x32x16_bf16 v[66:81], v[188:191], v[204:207], v[66:81]
	v_mfma_f32_32x32x16_bf16 v[50:65], v[192:195], v[196:199], v[50:65]
	v_mfma_f32_32x32x16_bf16 v[34:49], v[192:195], v[200:203], v[34:49]
	v_mfma_f32_32x32x16_bf16 v[18:33], v[192:195], v[156:159], v[18:33]
	v_mfma_f32_32x32x16_bf16 v[2:17], v[192:195], v[204:207], v[2:17]
	s_setprio 0
	v_add_u32_e32 v0, v0, v141
	v_add_u32_e32 v134, v134, v142
	ds_read_b128 v[156:159], v0
	ds_read_b128 v[174:177], v134
	v_add_u32_e32 v0, v135, v139
	v_add_u32_e32 v134, v143, v140
	ds_read_b128 v[140:143], v0 offset:32768
	ds_read_b128 v[178:181], v134 offset:32768
	v_add_u32_e32 v0, v136, v137
	v_add_u32_e32 v138, v208, v138
	ds_read_b128 v[134:137], v0 offset:32768
	ds_read_b128 v[182:185], v138 offset:32768
	s_setprio 1
	s_waitcnt lgkmcnt(9)
	v_mfma_f32_32x32x16_bf16 v[114:129], v[130:133], v[166:169], v[114:129]
	s_waitcnt lgkmcnt(8)
	v_mfma_f32_32x32x16_bf16 v[98:113], v[130:133], v[170:173], v[98:113]
	s_waitcnt lgkmcnt(7)
	v_mfma_f32_32x32x16_bf16 v[82:97], v[130:133], v[144:147], v[82:97]
	s_waitcnt lgkmcnt(6)
	v_mfma_f32_32x32x16_bf16 v[66:81], v[130:133], v[148:151], v[66:81]
	v_mfma_f32_32x32x16_bf16 v[50:65], v[152:155], v[166:169], v[50:65]
	v_mfma_f32_32x32x16_bf16 v[34:49], v[152:155], v[170:173], v[34:49]
	v_mfma_f32_32x32x16_bf16 v[18:33], v[152:155], v[144:147], v[18:33]
	v_mfma_f32_32x32x16_bf16 v[2:17], v[152:155], v[148:151], v[2:17]
	s_setprio 0
	s_setprio 1
	s_waitcnt lgkmcnt(3)
	v_mfma_f32_32x32x16_bf16 v[114:129], v[156:159], v[140:143], v[114:129]
	s_waitcnt lgkmcnt(2)
	v_mfma_f32_32x32x16_bf16 v[98:113], v[156:159], v[178:181], v[98:113]
	s_waitcnt lgkmcnt(1)
	v_mfma_f32_32x32x16_bf16 v[82:97], v[156:159], v[134:137], v[82:97]
	s_waitcnt lgkmcnt(0)
	v_mfma_f32_32x32x16_bf16 v[66:81], v[156:159], v[182:185], v[66:81]
	v_mfma_f32_32x32x16_bf16 v[50:65], v[174:177], v[140:143], v[50:65]
	v_mfma_f32_32x32x16_bf16 v[34:49], v[174:177], v[178:181], v[34:49]
	v_mfma_f32_32x32x16_bf16 v[18:33], v[174:177], v[134:137], v[18:33]
	v_mfma_f32_32x32x16_bf16 v[2:17], v[174:177], v[182:185], v[2:17]
	s_setprio 0
	v_mov_b32_e32 v210, v216
	s_waitcnt vmcnt(0)
	s_barrier
;   DI void xpass(int ps, int grow0, int gcol0, int lane, int w, char* lds) const {
;     char* xs = lds + (ps & 1) * 65536 + __builtin_amdgcn_readfirstlane(w) * 8192;
;     const float* xsrc = Xin + (size_t)(grow0 + (ps >> 1) * 32 + (ps & 1) * 16 + (lane >> 5)) * D_ + gcol0 + (lane & 31) * 4;
; #pragma unroll
;     for (int pc = 0; pc < 8; ++pc)
;       __builtin_amdgcn_global_load_lds((const unsigned*)(xsrc + (size_t)(2 * pc) * D_), (__attribute__((address_space(3))) unsigned*)(xs + pc * 1024), 16, 0, 0);
;   }
;   DI void operator()(f32x16 (&acc)[2][4], int grow0, int gcol0, int lane, int w, char* lds) {
;     ...
;     for (int ps = 0; ps < 4; ++ps) {
;       const int mt = ps >> 1;
;       if (ps + 1 < 4) {
;         if (ps >= 1) asm volatile("s_waitcnt lgkmcnt(0)" ::: "memory");
;         xpass(ps + 1, grow0, gcol0, lane, w, lds);
;         if (ps >= 1) asm volatile("s_waitcnt vmcnt(8)" ::: "memory");
;       } else asm volatile("s_waitcnt vmcnt(0)" ::: "memory");
;       const char* xs = lds + (ps & 1) * 65536 + w * 8192;
; #pragma unroll
;       for (int qq = 0; qq < 2; ++qq)
; #pragma unroll
;         for (int e = 0; e < 4; ++e) {
;           const int i = 4 * (2 * (ps & 1) + qq) + e;
;           const float* xr = (const float*)(xs + (8 * qq + 4 * hh + e) * 512) + l31;
;           float s1 = 0.f, s2 = 0.f;
; #pragma unroll
;           for (int nt = 0; nt < 4; ++nt) {
;             float v = (acc[mt][nt][i] + bia[nt]) * csc[nt];
;             float z = ALPHA * xr[nt * 32] + hs * v;
;             acc[mt][nt][i] = z; s1 += z; s2 += z * z;
;           }
;           s1 = row16_sum(s1); s2 = row16_sum(s2);
;           if ((lane & 15) == 0) { f32x2 sv = {s1, s2}; *(f32x2*)(redw + (mt * 32 + (i & 3) + 8 * (i >> 2)) * 2) = sv; }
;         }
	v_add_f32_e32 v114, 0, v114
	v_ashrrev_i32_e32 v169, 6, v210
	v_lshrrev_b32_e32 v0, 30, v169
	v_add_u32_e32 v0, v169, v0
	v_ashrrev_i32_e32 v134, 2, v0
	v_mul_i32_i24_e32 v0, 4, v134
	v_sub_u32_e32 v0, v169, v0
	v_lshlrev_b32_e32 v135, 6, v0
	v_add_u32_e32 v164, s3, v135
	v_bfe_u32 v0, v210, 5, 1
	v_or_b32_e32 v176, v164, v0
	v_or_b32_e32 v130, 16, v176
	v_ashrrev_i32_e32 v131, 31, v130
	v_lshl_add_u32 v154, v134, 7, s6
	v_lshlrev_b32_e32 v168, 2, v210
	v_lshlrev_b64 v[130:131], 12, v[130:131]
	v_ashrrev_i32_e32 v155, 31, v154
	v_and_b32_e32 v0, 0x7c, v168
	v_readfirstlane_b32 s2, v169
	v_lshl_add_u64 v[130:131], s[54:55], 0, v[130:131]
	s_lshl_b32 s2, s2, 13
	v_lshl_add_u64 v[130:131], v[154:155], 2, v[130:131]
	v_lshlrev_b32_e32 v0, 2, v0
	s_add_i32 m0, s2, 0x10000
	v_lshl_add_u64 v[130:131], v[130:131], 0, v[0:1]
	global_load_lds_dwordx4 v[130:131], off
	v_lshl_add_u64 v[132:133], v[130:131], 0, s[34:35]
	s_add_i32 m0, s2, 0x10400
	v_and_b32_e32 v211, 0xc0, v135
	global_load_lds_dwordx4 v[132:133], off
	v_lshl_add_u64 v[132:133], v[130:131], 0, s[36:37]
	s_add_i32 m0, s2, 0x10800
	v_mov_b32_e32 v144, v98
	global_load_lds_dwordx4 v[132:133], off
	v_lshl_add_u64 v[132:133], v[130:131], 0, s[40:41]
	s_add_i32 m0, s2, 0x10c00
	v_mov_b32_e32 v145, v82
	global_load_lds_dwordx4 v[132:133], off
	v_lshl_add_u64 v[132:133], v[130:131], 0, s[42:43]
	s_add_i32 m0, s2, 0x11000
	v_mul_f32_e32 v141, 0.5, v114
	global_load_lds_dwordx4 v[132:133], off
	v_lshl_add_u64 v[132:133], v[130:131], 0, s[44:45]
	s_add_i32 m0, s2, 0x11400
	v_pk_add_f32 v[144:145], v[144:145], 0 op_sel_hi:[1,0]
	global_load_lds_dwordx4 v[132:133], off
	v_lshl_add_u64 v[132:133], v[130:131], 0, s[46:47]
	s_add_i32 m0, s2, 0x11800
	v_lshl_add_u64 v[130:131], v[130:131], 0, s[52:53]
	global_load_lds_dwordx4 v[132:133], off
	s_add_i32 m0, s2, 0x11c00
	v_bfe_u32 v132, v210, 4, 1
	global_load_lds_dwordx4 v[130:131], off
	v_and_b32_e32 v130, 31, v210
	v_lshlrev_b32_e32 v131, 1, v134
	v_bfe_u32 v134, v210, 3, 3
	v_and_or_b32 v131, v131, 2, v132
	v_and_b32_e32 v132, 4, v134
	v_lshlrev_b32_e32 v130, 2, v130
	v_or_b32_e32 v133, v211, v132
	v_lshl_or_b32 v138, v169, 13, v130
	v_lshlrev_b32_e32 v172, 9, v132
	v_lshlrev_b32_e32 v135, 3, v133
	v_or_b32_e32 v132, v138, v172
	v_and_b32_e32 v133, 15, v210
	v_lshl_or_b32 v139, v131, 11, v221
	s_waitcnt vmcnt(8)
	ds_read2_b32 v[130:131], v132 offset1:32
	v_cmp_eq_u32_e32 vcc, 0, v133
	ds_read2_b32 v[132:133], v132 offset0:64 offset1:96
	v_mov_b32_e32 v140, v82
	v_mov_b32_e32 v136, v1
	s_waitcnt lgkmcnt(0)
	v_mul_f32_e32 v137, 0x3fd744fd, v130
	v_mov_b32_e32 v130, v131
	v_mov_b32_e32 v131, v132
	s_mov_b32 s2, s67
	v_pk_add_f32 v[160:161], v[140:141], v[136:137]
	v_pk_mul_f32 v[130:131], v[130:131], s[2:3] op_sel_hi:[1,0]
	v_pk_mul_f32 v[136:137], v[144:145], 0.5 op_sel_hi:[1,0]
	v_pk_fma_f32 v[158:159], v[144:145], 0.5, v[130:131] op_sel_hi:[1,0,1]
	v_mov_b32_e32 v136, v161
	v_mov_b32_e32 v144, v1
	v_mov_b32_e32 v145, v131
	v_add_f32_e32 v142, 0, v66
	v_mov_b32_e32 v143, v133
	v_pk_mul_f32 v[140:141], v[158:159], v[158:159]
	v_pk_add_f32 v[136:137], v[136:137], v[144:145]
	v_mul_f32_e32 v66, 0x3fd744fd, v133
	v_mov_b32_e32 v163, v161
	v_pk_mov_b32 v[130:131], v[130:131], v[140:141] op_sel:[1,0]
	v_pk_add_f32 v[140:141], v[158:159], v[136:137]
	v_pk_mul_f32 v[136:137], v[158:159], v[136:137]
	v_pk_fma_f32 v[166:167], v[142:143], s[66:67], v[66:67] op_sel_hi:[1,1,0]
	v_pk_fma_f32 v[130:131], v[160:161], v[162:163], v[130:131]
	v_mov_b32_e32 v141, v137
	v_pk_mul_f32 v[132:133], v[166:167], v[166:167]
	v_pk_add_f32 v[130:131], v[140:141], v[130:131]
	v_mov_b32_e32 v167, v132
	v_pk_add_f32 v[130:131], v[130:131], v[166:167]
	v_add_u32_e32 v160, v139, v135
	s_nop 0
	v_mov_b32_dpp v132, v130 quad_perm:[1,0,3,2] row_mask:0xf bank_mask:0xf bound_ctrl:1
	v_mov_b32_dpp v133, v131 quad_perm:[1,0,3,2] row_mask:0xf bank_mask:0xf bound_ctrl:1
	v_pk_add_f32 v[130:131], v[130:131], v[132:133]
	s_nop 1
	v_mov_b32_dpp v132, v130 quad_perm:[2,3,0,1] row_mask:0xf bank_mask:0xf bound_ctrl:1
	v_mov_b32_dpp v133, v131 quad_perm:[2,3,0,1] row_mask:0xf bank_mask:0xf bound_ctrl:1
	v_pk_add_f32 v[130:131], v[130:131], v[132:133]
	s_nop 1
	v_mov_b32_dpp v132, v130 row_half_mirror row_mask:0xf bank_mask:0xf bound_ctrl:1
	v_mov_b32_dpp v133, v131 row_half_mirror row_mask:0xf bank_mask:0xf bound_ctrl:1
	v_pk_add_f32 v[130:131], v[130:131], v[132:133]
	s_nop 1
	v_mov_b32_dpp v132, v130 row_mirror row_mask:0xf bank_mask:0xf bound_ctrl:1
	v_mov_b32_dpp v133, v131 row_mirror row_mask:0xf bank_mask:0xf bound_ctrl:1
	s_and_saveexec_b64 s[6:7], vcc
	v_pk_add_f32 v[130:131], v[130:131], v[132:133]
	ds_write_b64 v160, v[130:131]
	s_or_b64 exec, exec, s[6:7]
	v_add_u32_e32 v167, v138, v172
	ds_read2_b32 v[130:131], v167 offset0:128 offset1:160
	ds_read2_b32 v[132:133], v167 offset0:192 offset1:224
	v_add_f32_e32 v82, 0, v115
	v_mul_f32_e32 v115, 0.5, v82
	v_mov_b32_e32 v82, v99
	s_waitcnt lgkmcnt(1)
	v_mul_f32_e32 v137, 0x3fd744fd, v130
	v_pk_add_f32 v[98:99], v[82:83], 0 op_sel_hi:[1,0]
	v_mov_b32_e32 v114, v83
	v_mov_b32_e32 v136, v1
	v_mov_b32_e32 v82, v131
	s_waitcnt lgkmcnt(0)
;   DI void operator()(f32x16 (&acc)[2][4], int grow0, int gcol0, int lane, int w, char* lds) {
;     ...
;       for (int qq = 0; qq < 2; ++qq)
; #pragma unroll
;         for (int e = 0; e < 4; ++e) {
;           const int i = 4 * (2 * (ps & 1) + qq) + e;
;           const float* xr = (const float*)(xs + (8 * qq + 4 * hh + e) * 512) + l31;
;           float s1 = 0.f, s2 = 0.f;
; #pragma unroll
;           for (int nt = 0; nt < 4; ++nt) {
;             float v = (acc[mt][nt][i] + bia[nt]) * csc[nt];
;             float z = ALPHA * xr[nt * 32] + hs * v;
;             acc[mt][nt][i] = z; s1 += z; s2 += z * z;
;           }
;           s1 = row16_sum(s1); s2 = row16_sum(s2);
;           if ((lane & 15) == 0) { f32x2 sv = {s1, s2}; *(f32x2*)(redw + (mt * 32 + (i & 3) + 8 * (i >> 2)) * 2) = sv; }
;         }
	v_mov_b32_e32 v83, v132
	s_mov_b32 s2, s67
	v_pk_add_f32 v[170:171], v[114:115], v[136:137]
	v_pk_mul_f32 v[82:83], v[82:83], s[2:3] op_sel_hi:[1,0]
	v_pk_mul_f32 v[114:115], v[98:99], 0.5 op_sel_hi:[1,0]
	v_pk_fma_f32 v[148:149], v[98:99], 0.5, v[82:83] op_sel_hi:[1,0,1]
	v_mov_b32_e32 v114, v171
	v_mov_b32_e32 v130, v1
	v_mov_b32_e32 v131, v83
	v_pk_mul_f32 v[98:99], v[148:149], v[148:149]
	v_pk_add_f32 v[114:115], v[114:115], v[130:131]
	v_mov_b32_e32 v163, v171
	v_pk_mov_b32 v[82:83], v[82:83], v[98:99] op_sel:[1,0]
	v_pk_add_f32 v[98:99], v[148:149], v[114:115]
	v_pk_mul_f32 v[114:115], v[148:149], v[114:115]
	v_pk_fma_f32 v[82:83], v[170:171], v[162:163], v[82:83]
	v_mov_b32_e32 v99, v115
	v_add_f32_e32 v66, 0, v67
	v_mov_b32_e32 v67, v133
	v_pk_add_f32 v[82:83], v[98:99], v[82:83]
	v_mul_f32_e32 v98, 0x3fd744fd, v133
	v_pk_fma_f32 v[142:143], v[66:67], s[66:67], v[98:99] op_sel_hi:[1,1,0]
	s_nop 0
	v_pk_mul_f32 v[66:67], v[142:143], v[142:143]
	s_nop 0
	v_mov_b32_e32 v143, v66
	v_pk_add_f32 v[66:67], v[82:83], v[142:143]
	s_nop 1
	v_mov_b32_dpp v82, v66 quad_perm:[1,0,3,2] row_mask:0xf bank_mask:0xf bound_ctrl:1
	v_mov_b32_dpp v83, v67 quad_perm:[1,0,3,2] row_mask:0xf bank_mask:0xf bound_ctrl:1
	v_pk_add_f32 v[66:67], v[66:67], v[82:83]
	s_nop 1
	v_mov_b32_dpp v82, v66 quad_perm:[2,3,0,1] row_mask:0xf bank_mask:0xf bound_ctrl:1
	v_mov_b32_dpp v83, v67 quad_perm:[2,3,0,1] row_mask:0xf bank_mask:0xf bound_ctrl:1
	v_pk_add_f32 v[66:67], v[66:67], v[82:83]
	s_nop 1
	v_mov_b32_dpp v82, v66 row_half_mirror row_mask:0xf bank_mask:0xf bound_ctrl:1
	v_mov_b32_dpp v83, v67 row_half_mirror row_mask:0xf bank_mask:0xf bound_ctrl:1
	v_pk_add_f32 v[66:67], v[66:67], v[82:83]
	s_nop 1
	v_mov_b32_dpp v82, v66 row_mirror row_mask:0xf bank_mask:0xf bound_ctrl:1
	v_mov_b32_dpp v83, v67 row_mirror row_mask:0xf bank_mask:0xf bound_ctrl:1
	s_and_saveexec_b64 s[6:7], vcc
	v_pk_add_f32 v[66:67], v[66:67], v[82:83]
	ds_write_b64 v160, v[66:67] offset:8
	s_or_b64 exec, exec, s[6:7]
	v_add_u32_e32 v143, 0x400, v167
	ds_read2_b32 v[66:67], v143 offset1:32
	ds_read2_b32 v[82:83], v143 offset0:64 offset1:96
	v_add_f32_e32 v99, 0, v116
	v_mov_b32_e32 v132, v100
	v_mov_b32_e32 v133, v84
	v_mul_f32_e32 v115, 0.5, v99
	s_waitcnt lgkmcnt(1)
	v_mul_f32_e32 v131, 0x3fd744fd, v66
	v_pk_add_f32 v[132:133], v[132:133], 0 op_sel_hi:[1,0]
	v_mov_b32_e32 v114, v84
	v_mov_b32_e32 v130, v1
	v_mov_b32_e32 v66, v67
	s_waitcnt lgkmcnt(0)
	v_mov_b32_e32 v67, v82
	s_mov_b32 s2, s67
	v_pk_add_f32 v[144:145], v[114:115], v[130:131]
	v_pk_mul_f32 v[114:115], v[66:67], s[2:3] op_sel_hi:[1,0]
	v_pk_mul_f32 v[130:131], v[132:133], 0.5 op_sel_hi:[1,0]
	v_pk_fma_f32 v[66:67], v[132:133], 0.5, v[114:115] op_sel_hi:[1,0,1]
	v_mov_b32_e32 v130, v145
	v_mov_b32_e32 v136, v1
	v_mov_b32_e32 v137, v115
	v_add_f32_e32 v98, 0, v68
	v_mov_b32_e32 v99, v83
	v_pk_mul_f32 v[132:133], v[66:67], v[66:67]
	v_pk_add_f32 v[130:131], v[130:131], v[136:137]
	v_mul_f32_e32 v68, 0x3fd744fd, v83
	v_mov_b32_e32 v163, v145
	v_pk_mov_b32 v[114:115], v[114:115], v[132:133] op_sel:[1,0]
	v_pk_add_f32 v[132:133], v[66:67], v[130:131]
	v_pk_mul_f32 v[130:131], v[66:67], v[130:131]
	v_pk_fma_f32 v[82:83], v[98:99], s[66:67], v[68:69] op_sel_hi:[1,1,0]
	v_pk_fma_f32 v[114:115], v[144:145], v[162:163], v[114:115]
	v_mov_b32_e32 v133, v131
	v_pk_mul_f32 v[98:99], v[82:83], v[82:83]
	v_pk_add_f32 v[114:115], v[132:133], v[114:115]
	v_mov_b32_e32 v83, v98
	v_pk_add_f32 v[98:99], v[114:115], v[82:83]
	s_nop 1
	v_mov_b32_dpp v114, v98 quad_perm:[1,0,3,2] row_mask:0xf bank_mask:0xf bound_ctrl:1
	v_mov_b32_dpp v115, v99 quad_perm:[1,0,3,2] row_mask:0xf bank_mask:0xf bound_ctrl:1
	v_pk_add_f32 v[98:99], v[98:99], v[114:115]
	s_nop 1
	v_mov_b32_dpp v114, v98 quad_perm:[2,3,0,1] row_mask:0xf bank_mask:0xf bound_ctrl:1
	v_mov_b32_dpp v115, v99 quad_perm:[2,3,0,1] row_mask:0xf bank_mask:0xf bound_ctrl:1
	v_pk_add_f32 v[98:99], v[98:99], v[114:115]
	s_nop 1
	v_mov_b32_dpp v114, v98 row_half_mirror row_mask:0xf bank_mask:0xf bound_ctrl:1
	v_mov_b32_dpp v115, v99 row_half_mirror row_mask:0xf bank_mask:0xf bound_ctrl:1
	v_pk_add_f32 v[98:99], v[98:99], v[114:115]
	s_nop 1
	v_mov_b32_dpp v114, v98 row_mirror row_mask:0xf bank_mask:0xf bound_ctrl:1
	v_mov_b32_dpp v115, v99 row_mirror row_mask:0xf bank_mask:0xf bound_ctrl:1
	s_and_saveexec_b64 s[6:7], vcc
	v_pk_add_f32 v[98:99], v[98:99], v[114:115]
	ds_write_b64 v160, v[98:99] offset:16
	s_or_b64 exec, exec, s[6:7]
	v_lshlrev_b32_e32 v139, 9, v134
	v_or_b32_e32 v152, 0x600, v139
	v_add_u32_e32 v144, v138, v152
	ds_read2_b32 v[114:115], v144 offset1:32
	ds_read2_b32 v[130:131], v144 offset0:64 offset1:96
	v_add_f32_e32 v68, 0, v117
	v_add_f32_e32 v116, 0, v69
	v_mul_f32_e32 v69, 0.5, v68
	s_waitcnt lgkmcnt(1)
	v_mul_f32_e32 v99, 0x3fd744fd, v114
	v_mov_b32_e32 v84, v101
	v_mov_b32_e32 v68, v85
	v_mov_b32_e32 v98, v1
	v_pk_add_f32 v[100:101], v[84:85], 0 op_sel_hi:[1,0]
	v_pk_add_f32 v[98:99], v[68:69], v[98:99]
	v_mov_b32_e32 v68, v115
	s_waitcnt lgkmcnt(0)
;   DI void operator()(f32x16 (&acc)[2][4], int grow0, int gcol0, int lane, int w, char* lds) {
;     ...
;       for (int qq = 0; qq < 2; ++qq)
; #pragma unroll
;         for (int e = 0; e < 4; ++e) {
;           const int i = 4 * (2 * (ps & 1) + qq) + e;
;           const float* xr = (const float*)(xs + (8 * qq + 4 * hh + e) * 512) + l31;
;           float s1 = 0.f, s2 = 0.f;
; #pragma unroll
;           for (int nt = 0; nt < 4; ++nt) {
;             float v = (acc[mt][nt][i] + bia[nt]) * csc[nt];
;             float z = ALPHA * xr[nt * 32] + hs * v;
;             acc[mt][nt][i] = z; s1 += z; s2 += z * z;
;           }
;           s1 = row16_sum(s1); s2 = row16_sum(s2);
;           if ((lane & 15) == 0) { f32x2 sv = {s1, s2}; *(f32x2*)(redw + (mt * 32 + (i & 3) + 8 * (i >> 2)) * 2) = sv; }
;         }
	v_mov_b32_e32 v69, v130
	s_mov_b32 s2, s67
	v_pk_mul_f32 v[84:85], v[68:69], s[2:3] op_sel_hi:[1,0]
	v_pk_mul_f32 v[114:115], v[100:101], 0.5 op_sel_hi:[1,0]
	v_pk_fma_f32 v[68:69], v[100:101], 0.5, v[84:85] op_sel_hi:[1,0,1]
	v_mov_b32_e32 v114, v99
	v_mov_b32_e32 v132, v1
	v_mov_b32_e32 v133, v85
	v_pk_mul_f32 v[100:101], v[68:69], v[68:69]
	v_pk_add_f32 v[114:115], v[114:115], v[132:133]
	v_mov_b32_e32 v163, v99
	v_pk_mov_b32 v[84:85], v[84:85], v[100:101] op_sel:[1,0]
	v_pk_add_f32 v[100:101], v[68:69], v[114:115]
	v_pk_mul_f32 v[114:115], v[68:69], v[114:115]
	v_pk_fma_f32 v[84:85], v[98:99], v[162:163], v[84:85]
	v_mov_b32_e32 v101, v115
	v_mov_b32_e32 v117, v131
	v_pk_add_f32 v[100:101], v[100:101], v[84:85]
	v_mul_f32_e32 v84, 0x3fd744fd, v131
	v_pk_fma_f32 v[84:85], v[116:117], s[66:67], v[84:85] op_sel_hi:[1,1,0]
	s_nop 0
	v_pk_mul_f32 v[114:115], v[84:85], v[84:85]
	s_nop 0
	v_mov_b32_e32 v85, v114
	v_pk_add_f32 v[100:101], v[100:101], v[84:85]
	s_nop 1
	v_mov_b32_dpp v114, v100 quad_perm:[1,0,3,2] row_mask:0xf bank_mask:0xf bound_ctrl:1
	v_mov_b32_dpp v115, v101 quad_perm:[1,0,3,2] row_mask:0xf bank_mask:0xf bound_ctrl:1
	v_pk_add_f32 v[100:101], v[100:101], v[114:115]
	s_nop 1
	v_mov_b32_dpp v114, v100 quad_perm:[2,3,0,1] row_mask:0xf bank_mask:0xf bound_ctrl:1
	v_mov_b32_dpp v115, v101 quad_perm:[2,3,0,1] row_mask:0xf bank_mask:0xf bound_ctrl:1
	v_pk_add_f32 v[100:101], v[100:101], v[114:115]
	s_nop 1
	v_mov_b32_dpp v114, v100 row_half_mirror row_mask:0xf bank_mask:0xf bound_ctrl:1
	v_mov_b32_dpp v115, v101 row_half_mirror row_mask:0xf bank_mask:0xf bound_ctrl:1
	v_pk_add_f32 v[100:101], v[100:101], v[114:115]
	s_nop 1
	v_mov_b32_dpp v114, v100 row_mirror row_mask:0xf bank_mask:0xf bound_ctrl:1
	v_mov_b32_dpp v115, v101 row_mirror row_mask:0xf bank_mask:0xf bound_ctrl:1
	s_and_saveexec_b64 s[6:7], vcc
	v_pk_add_f32 v[100:101], v[100:101], v[114:115]
	ds_write_b64 v160, v[100:101] offset:24
	s_or_b64 exec, exec, s[6:7]
	v_add_u32_e32 v83, 0x1000, v167
	ds_read2_b32 v[100:101], v83 offset1:32
	ds_read2_b32 v[114:115], v83 offset0:64 offset1:96
	v_add_f32_e32 v85, 0, v118
	v_mov_b32_e32 v134, v102
	v_mov_b32_e32 v135, v86
	v_mul_f32_e32 v117, 0.5, v85
	s_waitcnt lgkmcnt(1)
	v_mul_f32_e32 v133, 0x3fd744fd, v100
	v_pk_add_f32 v[134:135], v[134:135], 0 op_sel_hi:[1,0]
	v_mov_b32_e32 v116, v86
	v_mov_b32_e32 v132, v1
	v_mov_b32_e32 v100, v101
	s_waitcnt lgkmcnt(0)
	v_mov_b32_e32 v101, v114
	s_mov_b32 s2, s67
	v_pk_add_f32 v[116:117], v[116:117], v[132:133]
	v_pk_mul_f32 v[132:133], v[100:101], s[2:3] op_sel_hi:[1,0]
	v_pk_mul_f32 v[136:137], v[134:135], 0.5 op_sel_hi:[1,0]
	v_pk_fma_f32 v[100:101], v[134:135], 0.5, v[132:133] op_sel_hi:[1,0,1]
	v_mov_b32_e32 v136, v117
	v_mov_b32_e32 v140, v1
	v_mov_b32_e32 v141, v133
	v_add_f32_e32 v130, 0, v70
	v_mov_b32_e32 v131, v115
	v_pk_mul_f32 v[134:135], v[100:101], v[100:101]
	v_pk_add_f32 v[136:137], v[136:137], v[140:141]
	v_mul_f32_e32 v70, 0x3fd744fd, v115
	v_mov_b32_e32 v163, v117
	v_pk_mov_b32 v[132:133], v[132:133], v[134:135] op_sel:[1,0]
	v_pk_add_f32 v[134:135], v[100:101], v[136:137]
	v_pk_mul_f32 v[136:137], v[100:101], v[136:137]
	v_pk_fma_f32 v[114:115], v[130:131], s[66:67], v[70:71] op_sel_hi:[1,1,0]
	v_pk_fma_f32 v[132:133], v[116:117], v[162:163], v[132:133]
	v_mov_b32_e32 v135, v137
	v_pk_mul_f32 v[130:131], v[114:115], v[114:115]
	v_pk_add_f32 v[132:133], v[134:135], v[132:133]
	v_mov_b32_e32 v115, v130
	v_pk_add_f32 v[130:131], v[132:133], v[114:115]
	s_nop 1
	v_mov_b32_dpp v132, v130 quad_perm:[1,0,3,2] row_mask:0xf bank_mask:0xf bound_ctrl:1
	v_mov_b32_dpp v133, v131 quad_perm:[1,0,3,2] row_mask:0xf bank_mask:0xf bound_ctrl:1
	v_pk_add_f32 v[130:131], v[130:131], v[132:133]
	s_nop 1
	v_mov_b32_dpp v132, v130 quad_perm:[2,3,0,1] row_mask:0xf bank_mask:0xf bound_ctrl:1
	v_mov_b32_dpp v133, v131 quad_perm:[2,3,0,1] row_mask:0xf bank_mask:0xf bound_ctrl:1
	v_pk_add_f32 v[130:131], v[130:131], v[132:133]
	s_nop 1
	v_mov_b32_dpp v132, v130 row_half_mirror row_mask:0xf bank_mask:0xf bound_ctrl:1
	v_mov_b32_dpp v133, v131 row_half_mirror row_mask:0xf bank_mask:0xf bound_ctrl:1
	v_pk_add_f32 v[130:131], v[130:131], v[132:133]
	s_nop 1
	v_mov_b32_dpp v132, v130 row_mirror row_mask:0xf bank_mask:0xf bound_ctrl:1
	v_mov_b32_dpp v133, v131 row_mirror row_mask:0xf bank_mask:0xf bound_ctrl:1
	s_and_saveexec_b64 s[6:7], vcc
	v_pk_add_f32 v[130:131], v[130:131], v[132:133]
	ds_write_b64 v160, v[130:131] offset:64
	s_or_b64 exec, exec, s[6:7]
	ds_read2_b32 v[130:131], v83 offset0:128 offset1:160
	ds_read2_b32 v[132:133], v83 offset0:192 offset1:224
	v_add_f32_e32 v70, 0, v119
	v_add_f32_e32 v118, 0, v71
	v_mul_f32_e32 v71, 0.5, v70
	s_waitcnt lgkmcnt(1)
	v_mul_f32_e32 v135, 0x3fd744fd, v130
	v_mov_b32_e32 v86, v103
	v_mov_b32_e32 v70, v87
	v_mov_b32_e32 v134, v1
	v_pk_add_f32 v[136:137], v[86:87], 0 op_sel_hi:[1,0]
	v_pk_add_f32 v[102:103], v[70:71], v[134:135]
	v_mov_b32_e32 v70, v131
	s_waitcnt lgkmcnt(0)
;   DI void operator()(f32x16 (&acc)[2][4], int grow0, int gcol0, int lane, int w, char* lds) {
;     ...
; #pragma unroll
;       for (int qq = 0; qq < 2; ++qq)
; #pragma unroll
;         for (int e = 0; e < 4; ++e) {
;           const int i = 4 * (2 * (ps & 1) + qq) + e;
;           const float* xr = (const float*)(xs + (8 * qq + 4 * hh + e) * 512) + l31;
;           float s1 = 0.f, s2 = 0.f;
; #pragma unroll
;           for (int nt = 0; nt < 4; ++nt) {
;             float v = (acc[mt][nt][i] + bia[nt]) * csc[nt];
;             float z = ALPHA * xr[nt * 32] + hs * v;
;             acc[mt][nt][i] = z; s1 += z; s2 += z * z;
;           }
;           s1 = row16_sum(s1); s2 = row16_sum(s2);
;           if ((lane & 15) == 0) { f32x2 sv = {s1, s2}; *(f32x2*)(redw + (mt * 32 + (i & 3) + 8 * (i >> 2)) * 2) = sv; }
;         }
	v_mov_b32_e32 v71, v132
	s_mov_b32 s2, s67
	v_pk_mul_f32 v[86:87], v[70:71], s[2:3] op_sel_hi:[1,0]
	v_pk_mul_f32 v[130:131], v[136:137], 0.5 op_sel_hi:[1,0]
	v_pk_fma_f32 v[70:71], v[136:137], 0.5, v[86:87] op_sel_hi:[1,0,1]
	v_mov_b32_e32 v130, v103
	v_mov_b32_e32 v136, v1
	v_mov_b32_e32 v137, v87
	v_pk_mul_f32 v[134:135], v[70:71], v[70:71]
	v_pk_add_f32 v[130:131], v[130:131], v[136:137]
	v_mov_b32_e32 v163, v103
	v_pk_mov_b32 v[86:87], v[86:87], v[134:135] op_sel:[1,0]
	v_pk_add_f32 v[134:135], v[70:71], v[130:131]
	v_pk_mul_f32 v[130:131], v[70:71], v[130:131]
	v_pk_fma_f32 v[86:87], v[102:103], v[162:163], v[86:87]
	v_mov_b32_e32 v135, v131
	v_mov_b32_e32 v119, v133
	v_pk_add_f32 v[130:131], v[134:135], v[86:87]
	v_mul_f32_e32 v86, 0x3fd744fd, v133
	v_pk_fma_f32 v[86:87], v[118:119], s[66:67], v[86:87] op_sel_hi:[1,1,0]
	s_nop 0
	v_pk_mul_f32 v[118:119], v[86:87], v[86:87]
	s_nop 0
	v_mov_b32_e32 v87, v118
	v_pk_add_f32 v[118:119], v[130:131], v[86:87]
	s_nop 1
	v_mov_b32_dpp v130, v118 quad_perm:[1,0,3,2] row_mask:0xf bank_mask:0xf bound_ctrl:1
	v_mov_b32_dpp v131, v119 quad_perm:[1,0,3,2] row_mask:0xf bank_mask:0xf bound_ctrl:1
	v_pk_add_f32 v[118:119], v[118:119], v[130:131]
	s_nop 1
	v_mov_b32_dpp v130, v118 quad_perm:[2,3,0,1] row_mask:0xf bank_mask:0xf bound_ctrl:1
	v_mov_b32_dpp v131, v119 quad_perm:[2,3,0,1] row_mask:0xf bank_mask:0xf bound_ctrl:1
	v_pk_add_f32 v[118:119], v[118:119], v[130:131]
	s_nop 1
	v_mov_b32_dpp v130, v118 row_half_mirror row_mask:0xf bank_mask:0xf bound_ctrl:1
	v_mov_b32_dpp v131, v119 row_half_mirror row_mask:0xf bank_mask:0xf bound_ctrl:1
	v_pk_add_f32 v[118:119], v[118:119], v[130:131]
	s_nop 1
	v_mov_b32_dpp v130, v118 row_mirror row_mask:0xf bank_mask:0xf bound_ctrl:1
	v_mov_b32_dpp v131, v119 row_mirror row_mask:0xf bank_mask:0xf bound_ctrl:1
	s_and_saveexec_b64 s[6:7], vcc
	v_pk_add_f32 v[118:119], v[118:119], v[130:131]
	ds_write_b64 v160, v[118:119] offset:72
	s_or_b64 exec, exec, s[6:7]
	v_add_u32_e32 v85, 0x1400, v167
	ds_read2_b32 v[118:119], v85 offset1:32
	ds_read2_b32 v[130:131], v85 offset0:64 offset1:96
	v_add_f32_e32 v87, 0, v120
	v_mov_b32_e32 v140, v104
	v_mov_b32_e32 v141, v88
	v_mul_f32_e32 v133, 0.5, v87
	s_waitcnt lgkmcnt(1)
	v_mul_f32_e32 v137, 0x3fd744fd, v118
	v_pk_add_f32 v[140:141], v[140:141], 0 op_sel_hi:[1,0]
	v_mov_b32_e32 v132, v88
	v_mov_b32_e32 v136, v1
	v_mov_b32_e32 v118, v119
	s_waitcnt lgkmcnt(0)
	v_mov_b32_e32 v119, v130
	s_mov_b32 s2, s67
	v_pk_add_f32 v[132:133], v[132:133], v[136:137]
	v_pk_mul_f32 v[136:137], v[118:119], s[2:3] op_sel_hi:[1,0]
	v_pk_mul_f32 v[146:147], v[140:141], 0.5 op_sel_hi:[1,0]
	v_pk_fma_f32 v[118:119], v[140:141], 0.5, v[136:137] op_sel_hi:[1,0,1]
	v_mov_b32_e32 v146, v133
	v_mov_b32_e32 v150, v1
	v_mov_b32_e32 v151, v137
	v_add_f32_e32 v134, 0, v72
	v_mov_b32_e32 v135, v131
	v_pk_mul_f32 v[140:141], v[118:119], v[118:119]
	v_pk_add_f32 v[146:147], v[146:147], v[150:151]
	v_mul_f32_e32 v72, 0x3fd744fd, v131
	v_mov_b32_e32 v163, v133
	v_pk_mov_b32 v[136:137], v[136:137], v[140:141] op_sel:[1,0]
	v_pk_add_f32 v[140:141], v[118:119], v[146:147]
	v_pk_mul_f32 v[146:147], v[118:119], v[146:147]
	v_pk_fma_f32 v[130:131], v[134:135], s[66:67], v[72:73] op_sel_hi:[1,1,0]
	v_pk_fma_f32 v[136:137], v[132:133], v[162:163], v[136:137]
	v_mov_b32_e32 v141, v147
	v_pk_mul_f32 v[134:135], v[130:131], v[130:131]
	v_pk_add_f32 v[136:137], v[140:141], v[136:137]
	v_mov_b32_e32 v131, v134
	v_pk_add_f32 v[134:135], v[136:137], v[130:131]
	s_nop 1
	v_mov_b32_dpp v136, v134 quad_perm:[1,0,3,2] row_mask:0xf bank_mask:0xf bound_ctrl:1
	v_mov_b32_dpp v137, v135 quad_perm:[1,0,3,2] row_mask:0xf bank_mask:0xf bound_ctrl:1
	v_pk_add_f32 v[134:135], v[134:135], v[136:137]
	s_nop 1
	v_mov_b32_dpp v136, v134 quad_perm:[2,3,0,1] row_mask:0xf bank_mask:0xf bound_ctrl:1
	v_mov_b32_dpp v137, v135 quad_perm:[2,3,0,1] row_mask:0xf bank_mask:0xf bound_ctrl:1
	v_pk_add_f32 v[134:135], v[134:135], v[136:137]
	s_nop 1
	v_mov_b32_dpp v136, v134 row_half_mirror row_mask:0xf bank_mask:0xf bound_ctrl:1
	v_mov_b32_dpp v137, v135 row_half_mirror row_mask:0xf bank_mask:0xf bound_ctrl:1
	v_pk_add_f32 v[134:135], v[134:135], v[136:137]
	s_nop 1
	v_mov_b32_dpp v136, v134 row_mirror row_mask:0xf bank_mask:0xf bound_ctrl:1
	v_mov_b32_dpp v137, v135 row_mirror row_mask:0xf bank_mask:0xf bound_ctrl:1
	s_and_saveexec_b64 s[6:7], vcc
	v_pk_add_f32 v[134:135], v[134:135], v[136:137]
	ds_write_b64 v160, v[134:135] offset:80
	s_or_b64 exec, exec, s[6:7]
	v_or_b32_e32 v115, 0x1600, v139
	v_add_u32_e32 v87, v138, v115
	ds_read2_b32 v[134:135], v87 offset1:32
	ds_read2_b32 v[136:137], v87 offset0:64 offset1:96
	v_add_f32_e32 v72, 0, v121
	v_add_f32_e32 v120, 0, v73
	v_mul_f32_e32 v73, 0.5, v72
	s_waitcnt lgkmcnt(1)
	v_mul_f32_e32 v141, 0x3fd744fd, v134
	v_mov_b32_e32 v88, v105
	v_mov_b32_e32 v72, v89
	v_mov_b32_e32 v140, v1
	v_pk_add_f32 v[146:147], v[88:89], 0 op_sel_hi:[1,0]
	v_pk_add_f32 v[104:105], v[72:73], v[140:141]
	v_mov_b32_e32 v72, v135
	s_waitcnt lgkmcnt(0)
;   DI void xpass(int ps, int grow0, int gcol0, int lane, int w, char* lds) const {
;     char* xs = lds + (ps & 1) * 65536 + __builtin_amdgcn_readfirstlane(w) * 8192;
;     const float* xsrc = Xin + (size_t)(grow0 + (ps >> 1) * 32 + (ps & 1) * 16 + (lane >> 5)) * D_ + gcol0 + (lane & 31) * 4;
; #pragma unroll
;     for (int pc = 0; pc < 8; ++pc)
;       __builtin_amdgcn_global_load_lds((const unsigned*)(xsrc + (size_t)(2 * pc) * D_), (__attribute__((address_space(3))) unsigned*)(xs + pc * 1024), 16, 0, 0);
;   }
;   DI void operator()(f32x16 (&acc)[2][4], int grow0, int gcol0, int lane, int w, char* lds) {
;     ...
;     for (int ps = 0; ps < 4; ++ps) {
;       const int mt = ps >> 1;
;       if (ps + 1 < 4) {
;         if (ps >= 1) asm volatile("s_waitcnt lgkmcnt(0)" ::: "memory");
;         xpass(ps + 1, grow0, gcol0, lane, w, lds);
;         if (ps >= 1) asm volatile("s_waitcnt vmcnt(8)" ::: "memory");
;       } else asm volatile("s_waitcnt vmcnt(0)" ::: "memory");
;       const char* xs = lds + (ps & 1) * 65536 + w * 8192;
; #pragma unroll
;       for (int qq = 0; qq < 2; ++qq)
; #pragma unroll
;         for (int e = 0; e < 4; ++e) {
;           const int i = 4 * (2 * (ps & 1) + qq) + e;
;           const float* xr = (const float*)(xs + (8 * qq + 4 * hh + e) * 512) + l31;
;           float s1 = 0.f, s2 = 0.f;
; #pragma unroll
;           for (int nt = 0; nt < 4; ++nt) {
;             float v = (acc[mt][nt][i] + bia[nt]) * csc[nt];
;             float z = ALPHA * xr[nt * 32] + hs * v;
;             acc[mt][nt][i] = z; s1 += z; s2 += z * z;
;           }
;           s1 = row16_sum(s1); s2 = row16_sum(s2);
;           if ((lane & 15) == 0) { f32x2 sv = {s1, s2}; *(f32x2*)(redw + (mt * 32 + (i & 3) + 8 * (i >> 2)) * 2) = sv; }
;         }
	v_mov_b32_e32 v73, v136
	s_mov_b32 s2, s67
	v_pk_mul_f32 v[88:89], v[72:73], s[2:3] op_sel_hi:[1,0]
	v_pk_mul_f32 v[134:135], v[146:147], 0.5 op_sel_hi:[1,0]
	v_pk_fma_f32 v[72:73], v[146:147], 0.5, v[88:89] op_sel_hi:[1,0,1]
	v_mov_b32_e32 v134, v105
	v_mov_b32_e32 v146, v1
	v_mov_b32_e32 v147, v89
	v_pk_mul_f32 v[140:141], v[72:73], v[72:73]
	v_pk_add_f32 v[134:135], v[134:135], v[146:147]
	v_mov_b32_e32 v163, v105
	v_pk_mov_b32 v[88:89], v[88:89], v[140:141] op_sel:[1,0]
	v_pk_add_f32 v[140:141], v[72:73], v[134:135]
	v_pk_mul_f32 v[134:135], v[72:73], v[134:135]
	v_pk_fma_f32 v[88:89], v[104:105], v[162:163], v[88:89]
	v_mov_b32_e32 v141, v135
	v_mov_b32_e32 v121, v137
	v_pk_add_f32 v[134:135], v[140:141], v[88:89]
	v_mul_f32_e32 v88, 0x3fd744fd, v137
	v_pk_fma_f32 v[88:89], v[120:121], s[66:67], v[88:89] op_sel_hi:[1,1,0]
	s_nop 0
	v_pk_mul_f32 v[120:121], v[88:89], v[88:89]
	s_nop 0
	v_mov_b32_e32 v89, v120
	v_pk_add_f32 v[120:121], v[134:135], v[88:89]
	s_nop 1
	v_mov_b32_dpp v134, v120 quad_perm:[1,0,3,2] row_mask:0xf bank_mask:0xf bound_ctrl:1
	v_mov_b32_dpp v135, v121 quad_perm:[1,0,3,2] row_mask:0xf bank_mask:0xf bound_ctrl:1
	v_pk_add_f32 v[120:121], v[120:121], v[134:135]
	s_nop 1
	v_mov_b32_dpp v134, v120 quad_perm:[2,3,0,1] row_mask:0xf bank_mask:0xf bound_ctrl:1
	v_mov_b32_dpp v135, v121 quad_perm:[2,3,0,1] row_mask:0xf bank_mask:0xf bound_ctrl:1
	v_pk_add_f32 v[120:121], v[120:121], v[134:135]
	s_nop 1
	v_mov_b32_dpp v134, v120 row_half_mirror row_mask:0xf bank_mask:0xf bound_ctrl:1
	v_mov_b32_dpp v135, v121 row_half_mirror row_mask:0xf bank_mask:0xf bound_ctrl:1
	v_pk_add_f32 v[120:121], v[120:121], v[134:135]
	s_nop 1
	v_mov_b32_dpp v134, v120 row_mirror row_mask:0xf bank_mask:0xf bound_ctrl:1
	v_mov_b32_dpp v135, v121 row_mirror row_mask:0xf bank_mask:0xf bound_ctrl:1
	s_and_saveexec_b64 s[6:7], vcc
	v_pk_add_f32 v[120:121], v[120:121], v[134:135]
	ds_write_b64 v160, v[120:121] offset:88
	s_or_b64 exec, exec, s[6:7]
	v_or_b32_e32 v120, 32, v176
	v_ashrrev_i32_e32 v121, 31, v120
	v_readlane_b32 s6, v255, 29
	v_lshlrev_b64 v[120:121], 12, v[120:121]
	v_readlane_b32 s7, v255, 30
	v_readfirstlane_b32 s2, v169
	s_lshl_b32 s2, s2, 13
	v_lshl_add_u64 v[120:121], s[6:7], 0, v[120:121]
	v_lshl_add_u64 v[120:121], v[154:155], 2, v[120:121]
	s_waitcnt lgkmcnt(0)
	v_lshl_add_u64 v[120:121], v[120:121], 0, v[0:1]
	s_mov_b32 m0, s2
	s_mov_b64 s[6:7], 0x2000
	global_load_lds_dwordx4 v[120:121], off
	v_lshl_add_u64 v[134:135], v[120:121], 0, s[6:7]
	s_or_b32 m0, s2, 0x400
	s_mov_b64 s[6:7], 0x4000
	global_load_lds_dwordx4 v[134:135], off
	v_lshl_add_u64 v[134:135], v[120:121], 0, s[6:7]
	s_or_b32 m0, s2, 0x800
	s_mov_b64 s[6:7], 0x6000
	global_load_lds_dwordx4 v[134:135], off
	v_lshl_add_u64 v[134:135], v[120:121], 0, s[6:7]
	s_or_b32 m0, s2, 0xc00
	s_mov_b64 s[6:7], 0x8000
	global_load_lds_dwordx4 v[134:135], off
	v_lshl_add_u64 v[134:135], v[120:121], 0, s[6:7]
	s_or_b32 m0, s2, 0x1000
	s_mov_b64 s[6:7], 0xa000
	global_load_lds_dwordx4 v[134:135], off
	v_lshl_add_u64 v[134:135], v[120:121], 0, s[6:7]
	s_or_b32 m0, s2, 0x1400
	s_mov_b64 s[6:7], 0xc000
	global_load_lds_dwordx4 v[134:135], off
	v_lshl_add_u64 v[134:135], v[120:121], 0, s[6:7]
	s_or_b32 m0, s2, 0x1800
	s_mov_b64 s[6:7], 0xe000
	global_load_lds_dwordx4 v[134:135], off
	v_lshl_add_u64 v[120:121], v[120:121], 0, s[6:7]
	s_or_b32 m0, s2, 0x1c00
	v_add_u32_e32 v116, 0x10000, v138
	global_load_lds_dwordx4 v[120:121], off
	s_waitcnt vmcnt(8)
	v_add_u32_e32 v89, v116, v172
	ds_read2_b32 v[120:121], v89 offset1:32
	ds_read2_b32 v[134:135], v89 offset0:64 offset1:96
	v_add_f32_e32 v98, 0, v122
	v_mov_b32_e32 v146, v106
	v_mov_b32_e32 v147, v90
	s_waitcnt lgkmcnt(0)
	v_mul_f32_e32 v137, 0x3fd744fd, v120
	v_mul_f32_e32 v139, 0.5, v98
	v_pk_add_f32 v[146:147], v[146:147], 0 op_sel_hi:[1,0]
	v_mov_b32_e32 v138, v90
	v_mov_b32_e32 v136, v1
	v_mov_b32_e32 v120, v121
	v_mov_b32_e32 v121, v134
	s_mov_b32 s2, s67
	v_pk_add_f32 v[136:137], v[138:139], v[136:137]
	v_pk_mul_f32 v[138:139], v[120:121], s[2:3] op_sel_hi:[1,0]
	v_pk_mul_f32 v[150:151], v[146:147], 0.5 op_sel_hi:[1,0]
	v_pk_fma_f32 v[120:121], v[146:147], 0.5, v[138:139] op_sel_hi:[1,0,1]
	v_mov_b32_e32 v150, v137
	v_mov_b32_e32 v156, v1
	v_mov_b32_e32 v157, v139
	v_add_f32_e32 v140, 0, v74
	v_mov_b32_e32 v141, v135
	v_pk_mul_f32 v[146:147], v[120:121], v[120:121]
	v_pk_add_f32 v[150:151], v[150:151], v[156:157]
	v_mul_f32_e32 v74, 0x3fd744fd, v135
	v_mov_b32_e32 v163, v137
	v_pk_mov_b32 v[138:139], v[138:139], v[146:147] op_sel:[1,0]
	v_pk_add_f32 v[146:147], v[120:121], v[150:151]
	v_pk_mul_f32 v[150:151], v[120:121], v[150:151]
	v_pk_fma_f32 v[134:135], v[140:141], s[66:67], v[74:75] op_sel_hi:[1,1,0]
	v_pk_fma_f32 v[138:139], v[136:137], v[162:163], v[138:139]
	v_mov_b32_e32 v147, v151
	v_pk_mul_f32 v[140:141], v[134:135], v[134:135]
	v_pk_add_f32 v[138:139], v[146:147], v[138:139]
	v_mov_b32_e32 v135, v140
	v_pk_add_f32 v[138:139], v[138:139], v[134:135]
	s_nop 1
	v_mov_b32_dpp v140, v138 quad_perm:[1,0,3,2] row_mask:0xf bank_mask:0xf bound_ctrl:1
	v_mov_b32_dpp v141, v139 quad_perm:[1,0,3,2] row_mask:0xf bank_mask:0xf bound_ctrl:1
	v_pk_add_f32 v[138:139], v[138:139], v[140:141]
	s_nop 1
	v_mov_b32_dpp v140, v138 quad_perm:[2,3,0,1] row_mask:0xf bank_mask:0xf bound_ctrl:1
	v_mov_b32_dpp v141, v139 quad_perm:[2,3,0,1] row_mask:0xf bank_mask:0xf bound_ctrl:1
	v_pk_add_f32 v[138:139], v[138:139], v[140:141]
	s_nop 1
	v_mov_b32_dpp v140, v138 row_half_mirror row_mask:0xf bank_mask:0xf bound_ctrl:1
	v_mov_b32_dpp v141, v139 row_half_mirror row_mask:0xf bank_mask:0xf bound_ctrl:1
	v_pk_add_f32 v[138:139], v[138:139], v[140:141]
	s_nop 1
	v_mov_b32_dpp v140, v138 row_mirror row_mask:0xf bank_mask:0xf bound_ctrl:1
	v_mov_b32_dpp v141, v139 row_mirror row_mask:0xf bank_mask:0xf bound_ctrl:1
	s_and_saveexec_b64 s[6:7], vcc
	v_pk_add_f32 v[138:139], v[138:139], v[140:141]
	ds_write_b64 v160, v[138:139] offset:128
	s_or_b64 exec, exec, s[6:7]
	v_or_b32_e32 v74, 0x200, v172
	v_add_u32_e32 v98, v116, v74
	ds_read2_b32 v[138:139], v98 offset1:32
	ds_read2_b32 v[140:141], v98 offset0:64 offset1:96
	v_add_f32_e32 v74, 0, v123
	v_add_f32_e32 v122, 0, v75
	v_mul_f32_e32 v75, 0.5, v74
	s_waitcnt lgkmcnt(1)
;   DI void operator()(f32x16 (&acc)[2][4], int grow0, int gcol0, int lane, int w, char* lds) {
;     ...
; #pragma unroll
;       for (int qq = 0; qq < 2; ++qq)
; #pragma unroll
;         for (int e = 0; e < 4; ++e) {
;           const int i = 4 * (2 * (ps & 1) + qq) + e;
;           const float* xr = (const float*)(xs + (8 * qq + 4 * hh + e) * 512) + l31;
;           float s1 = 0.f, s2 = 0.f;
; #pragma unroll
;           for (int nt = 0; nt < 4; ++nt) {
;             float v = (acc[mt][nt][i] + bia[nt]) * csc[nt];
;             float z = ALPHA * xr[nt * 32] + hs * v;
;             acc[mt][nt][i] = z; s1 += z; s2 += z * z;
;           }
;           s1 = row16_sum(s1); s2 = row16_sum(s2);
;           if ((lane & 15) == 0) { f32x2 sv = {s1, s2}; *(f32x2*)(redw + (mt * 32 + (i & 3) + 8 * (i >> 2)) * 2) = sv; }
;         }
	v_mul_f32_e32 v147, 0x3fd744fd, v138
	v_mov_b32_e32 v90, v107
	v_mov_b32_e32 v74, v91
	v_mov_b32_e32 v146, v1
	v_pk_add_f32 v[150:151], v[90:91], 0 op_sel_hi:[1,0]
	v_pk_add_f32 v[106:107], v[74:75], v[146:147]
	v_mov_b32_e32 v74, v139
	s_waitcnt lgkmcnt(0)
	v_mov_b32_e32 v75, v140
	s_mov_b32 s2, s67
	v_pk_mul_f32 v[90:91], v[74:75], s[2:3] op_sel_hi:[1,0]
	v_pk_mul_f32 v[138:139], v[150:151], 0.5 op_sel_hi:[1,0]
	v_pk_fma_f32 v[74:75], v[150:151], 0.5, v[90:91] op_sel_hi:[1,0,1]
	v_mov_b32_e32 v138, v107
	v_mov_b32_e32 v150, v1
	v_mov_b32_e32 v151, v91
	v_pk_mul_f32 v[146:147], v[74:75], v[74:75]
	v_pk_add_f32 v[138:139], v[138:139], v[150:151]
	v_mov_b32_e32 v163, v107
	v_pk_mov_b32 v[90:91], v[90:91], v[146:147] op_sel:[1,0]
	v_pk_add_f32 v[146:147], v[74:75], v[138:139]
	v_pk_mul_f32 v[138:139], v[74:75], v[138:139]
	v_pk_fma_f32 v[90:91], v[106:107], v[162:163], v[90:91]
	v_mov_b32_e32 v147, v139
	v_mov_b32_e32 v123, v141
	v_pk_add_f32 v[138:139], v[146:147], v[90:91]
	v_mul_f32_e32 v90, 0x3fd744fd, v141
	v_pk_fma_f32 v[90:91], v[122:123], s[66:67], v[90:91] op_sel_hi:[1,1,0]
	s_nop 0
	v_pk_mul_f32 v[122:123], v[90:91], v[90:91]
	s_nop 0
	v_mov_b32_e32 v91, v122
	v_pk_add_f32 v[122:123], v[138:139], v[90:91]
	s_nop 1
	v_mov_b32_dpp v138, v122 quad_perm:[1,0,3,2] row_mask:0xf bank_mask:0xf bound_ctrl:1
	v_mov_b32_dpp v139, v123 quad_perm:[1,0,3,2] row_mask:0xf bank_mask:0xf bound_ctrl:1
	v_pk_add_f32 v[122:123], v[122:123], v[138:139]
	s_nop 1
	v_mov_b32_dpp v138, v122 quad_perm:[2,3,0,1] row_mask:0xf bank_mask:0xf bound_ctrl:1
	v_mov_b32_dpp v139, v123 quad_perm:[2,3,0,1] row_mask:0xf bank_mask:0xf bound_ctrl:1
	v_pk_add_f32 v[122:123], v[122:123], v[138:139]
	s_nop 1
	v_mov_b32_dpp v138, v122 row_half_mirror row_mask:0xf bank_mask:0xf bound_ctrl:1
	v_mov_b32_dpp v139, v123 row_half_mirror row_mask:0xf bank_mask:0xf bound_ctrl:1
	v_pk_add_f32 v[122:123], v[122:123], v[138:139]
	s_nop 1
	v_mov_b32_dpp v138, v122 row_mirror row_mask:0xf bank_mask:0xf bound_ctrl:1
	v_mov_b32_dpp v139, v123 row_mirror row_mask:0xf bank_mask:0xf bound_ctrl:1
	s_and_saveexec_b64 s[6:7], vcc
	v_pk_add_f32 v[122:123], v[122:123], v[138:139]
	ds_write_b64 v160, v[122:123] offset:136
	s_or_b64 exec, exec, s[6:7]
	v_or_b32_e32 v91, 0x400, v172
	v_add_u32_e32 v102, v116, v91
	ds_read2_b32 v[122:123], v102 offset1:32
	ds_read2_b32 v[138:139], v102 offset0:64 offset1:96
	v_add_f32_e32 v91, 0, v124
	v_mov_b32_e32 v156, v108
	v_mov_b32_e32 v157, v92
	v_mul_f32_e32 v141, 0.5, v91
	s_waitcnt lgkmcnt(1)
	v_mul_f32_e32 v151, 0x3fd744fd, v122
	v_pk_add_f32 v[156:157], v[156:157], 0 op_sel_hi:[1,0]
	v_mov_b32_e32 v140, v92
	v_mov_b32_e32 v150, v1
	v_mov_b32_e32 v122, v123
	s_waitcnt lgkmcnt(0)
	v_mov_b32_e32 v123, v138
	s_mov_b32 s2, s67
	v_pk_add_f32 v[140:141], v[140:141], v[150:151]
	v_pk_mul_f32 v[150:151], v[122:123], s[2:3] op_sel_hi:[1,0]
	v_pk_mul_f32 v[174:175], v[156:157], 0.5 op_sel_hi:[1,0]
	v_pk_fma_f32 v[122:123], v[156:157], 0.5, v[150:151] op_sel_hi:[1,0,1]
	v_mov_b32_e32 v174, v141
	v_mov_b32_e32 v178, v1
	v_mov_b32_e32 v179, v151
	v_add_f32_e32 v146, 0, v76
	v_mov_b32_e32 v147, v139
	v_pk_mul_f32 v[156:157], v[122:123], v[122:123]
	v_pk_add_f32 v[174:175], v[174:175], v[178:179]
	v_mul_f32_e32 v76, 0x3fd744fd, v139
	v_mov_b32_e32 v163, v141
	v_pk_mov_b32 v[150:151], v[150:151], v[156:157] op_sel:[1,0]
	v_pk_add_f32 v[156:157], v[122:123], v[174:175]
	v_pk_mul_f32 v[174:175], v[122:123], v[174:175]
	v_pk_fma_f32 v[138:139], v[146:147], s[66:67], v[76:77] op_sel_hi:[1,1,0]
	v_pk_fma_f32 v[150:151], v[140:141], v[162:163], v[150:151]
	v_mov_b32_e32 v157, v175
	v_pk_mul_f32 v[146:147], v[138:139], v[138:139]
	v_pk_add_f32 v[150:151], v[156:157], v[150:151]
	v_mov_b32_e32 v139, v146
	v_pk_add_f32 v[146:147], v[150:151], v[138:139]
	s_nop 1
	v_mov_b32_dpp v150, v146 quad_perm:[1,0,3,2] row_mask:0xf bank_mask:0xf bound_ctrl:1
	v_mov_b32_dpp v151, v147 quad_perm:[1,0,3,2] row_mask:0xf bank_mask:0xf bound_ctrl:1
	v_pk_add_f32 v[146:147], v[146:147], v[150:151]
	s_nop 1
	v_mov_b32_dpp v150, v146 quad_perm:[2,3,0,1] row_mask:0xf bank_mask:0xf bound_ctrl:1
	v_mov_b32_dpp v151, v147 quad_perm:[2,3,0,1] row_mask:0xf bank_mask:0xf bound_ctrl:1
	v_pk_add_f32 v[146:147], v[146:147], v[150:151]
	s_nop 1
	v_mov_b32_dpp v150, v146 row_half_mirror row_mask:0xf bank_mask:0xf bound_ctrl:1
	v_mov_b32_dpp v151, v147 row_half_mirror row_mask:0xf bank_mask:0xf bound_ctrl:1
	v_pk_add_f32 v[146:147], v[146:147], v[150:151]
	s_nop 1
	v_mov_b32_dpp v150, v146 row_mirror row_mask:0xf bank_mask:0xf bound_ctrl:1
	v_mov_b32_dpp v151, v147 row_mirror row_mask:0xf bank_mask:0xf bound_ctrl:1
	s_and_saveexec_b64 s[6:7], vcc
	v_pk_add_f32 v[146:147], v[146:147], v[150:151]
	ds_write_b64 v160, v[146:147] offset:144
	s_or_b64 exec, exec, s[6:7]
	v_add_u32_e32 v104, v116, v152
	ds_read2_b32 v[146:147], v104 offset1:32
	ds_read2_b32 v[150:151], v104 offset0:64 offset1:96
	v_add_f32_e32 v76, 0, v125
	v_add_f32_e32 v124, 0, v77
	v_mul_f32_e32 v77, 0.5, v76
	s_waitcnt lgkmcnt(1)
	v_mul_f32_e32 v153, 0x3fd744fd, v146
	v_mov_b32_e32 v92, v109
	v_mov_b32_e32 v76, v93
	v_mov_b32_e32 v152, v1
	v_pk_add_f32 v[156:157], v[92:93], 0 op_sel_hi:[1,0]
	v_pk_add_f32 v[108:109], v[76:77], v[152:153]
	v_mov_b32_e32 v76, v147
	s_waitcnt lgkmcnt(0)
;   DI void operator()(f32x16 (&acc)[2][4], int grow0, int gcol0, int lane, int w, char* lds) {
;     ...
; #pragma unroll
;       for (int qq = 0; qq < 2; ++qq)
; #pragma unroll
;         for (int e = 0; e < 4; ++e) {
;           const int i = 4 * (2 * (ps & 1) + qq) + e;
;           const float* xr = (const float*)(xs + (8 * qq + 4 * hh + e) * 512) + l31;
;           float s1 = 0.f, s2 = 0.f;
; #pragma unroll
;           for (int nt = 0; nt < 4; ++nt) {
;             float v = (acc[mt][nt][i] + bia[nt]) * csc[nt];
;             float z = ALPHA * xr[nt * 32] + hs * v;
;             acc[mt][nt][i] = z; s1 += z; s2 += z * z;
;           }
;           s1 = row16_sum(s1); s2 = row16_sum(s2);
;           if ((lane & 15) == 0) { f32x2 sv = {s1, s2}; *(f32x2*)(redw + (mt * 32 + (i & 3) + 8 * (i >> 2)) * 2) = sv; }
;         }
	v_mov_b32_e32 v77, v150
	s_mov_b32 s2, s67
	v_pk_mul_f32 v[92:93], v[76:77], s[2:3] op_sel_hi:[1,0]
	v_pk_mul_f32 v[146:147], v[156:157], 0.5 op_sel_hi:[1,0]
	v_pk_fma_f32 v[76:77], v[156:157], 0.5, v[92:93] op_sel_hi:[1,0,1]
	v_mov_b32_e32 v146, v109
	v_mov_b32_e32 v156, v1
	v_mov_b32_e32 v157, v93
	v_pk_mul_f32 v[152:153], v[76:77], v[76:77]
	v_pk_add_f32 v[146:147], v[146:147], v[156:157]
	v_mov_b32_e32 v163, v109
	v_pk_mov_b32 v[92:93], v[92:93], v[152:153] op_sel:[1,0]
	v_pk_add_f32 v[152:153], v[76:77], v[146:147]
	v_pk_mul_f32 v[146:147], v[76:77], v[146:147]
	v_pk_fma_f32 v[92:93], v[108:109], v[162:163], v[92:93]
	v_mov_b32_e32 v153, v147
	v_mov_b32_e32 v125, v151
	v_pk_add_f32 v[146:147], v[152:153], v[92:93]
	v_mul_f32_e32 v92, 0x3fd744fd, v151
	v_pk_fma_f32 v[92:93], v[124:125], s[66:67], v[92:93] op_sel_hi:[1,1,0]
	s_nop 0
	v_pk_mul_f32 v[124:125], v[92:93], v[92:93]
	s_nop 0
	v_mov_b32_e32 v93, v124
	v_pk_add_f32 v[124:125], v[146:147], v[92:93]
	s_nop 1
	v_mov_b32_dpp v146, v124 quad_perm:[1,0,3,2] row_mask:0xf bank_mask:0xf bound_ctrl:1
	v_mov_b32_dpp v147, v125 quad_perm:[1,0,3,2] row_mask:0xf bank_mask:0xf bound_ctrl:1
	v_pk_add_f32 v[124:125], v[124:125], v[146:147]
	s_nop 1
	v_mov_b32_dpp v146, v124 quad_perm:[2,3,0,1] row_mask:0xf bank_mask:0xf bound_ctrl:1
	v_mov_b32_dpp v147, v125 quad_perm:[2,3,0,1] row_mask:0xf bank_mask:0xf bound_ctrl:1
	v_pk_add_f32 v[124:125], v[124:125], v[146:147]
	s_nop 1
	v_mov_b32_dpp v146, v124 row_half_mirror row_mask:0xf bank_mask:0xf bound_ctrl:1
	v_mov_b32_dpp v147, v125 row_half_mirror row_mask:0xf bank_mask:0xf bound_ctrl:1
	v_pk_add_f32 v[124:125], v[124:125], v[146:147]
	s_nop 1
	v_mov_b32_dpp v146, v124 row_mirror row_mask:0xf bank_mask:0xf bound_ctrl:1
	v_mov_b32_dpp v147, v125 row_mirror row_mask:0xf bank_mask:0xf bound_ctrl:1
	s_and_saveexec_b64 s[6:7], vcc
	v_pk_add_f32 v[124:125], v[124:125], v[146:147]
	ds_write_b64 v160, v[124:125] offset:152
	s_or_b64 exec, exec, s[6:7]
	v_or_b32_e32 v91, 0x1000, v172
	v_add_u32_e32 v93, v116, v91
	ds_read2_b32 v[124:125], v93 offset1:32
	ds_read2_b32 v[146:147], v93 offset0:64 offset1:96
	v_add_f32_e32 v91, 0, v126
	v_mov_b32_e32 v174, v110
	v_mov_b32_e32 v175, v94
	v_mul_f32_e32 v151, 0.5, v91
	s_waitcnt lgkmcnt(1)
	v_mul_f32_e32 v157, 0x3fd744fd, v124
	v_pk_add_f32 v[174:175], v[174:175], 0 op_sel_hi:[1,0]
	v_mov_b32_e32 v150, v94
	v_mov_b32_e32 v156, v1
	v_mov_b32_e32 v124, v125
	s_waitcnt lgkmcnt(0)
	v_mov_b32_e32 v125, v146
	s_mov_b32 s2, s67
	v_pk_add_f32 v[150:151], v[150:151], v[156:157]
	v_pk_mul_f32 v[156:157], v[124:125], s[2:3] op_sel_hi:[1,0]
	v_pk_mul_f32 v[178:179], v[174:175], 0.5 op_sel_hi:[1,0]
	v_pk_fma_f32 v[124:125], v[174:175], 0.5, v[156:157] op_sel_hi:[1,0,1]
	v_mov_b32_e32 v178, v151
	v_mov_b32_e32 v180, v1
	v_mov_b32_e32 v181, v157
	v_add_f32_e32 v152, 0, v78
	v_mov_b32_e32 v153, v147
	v_pk_mul_f32 v[174:175], v[124:125], v[124:125]
	v_pk_add_f32 v[178:179], v[178:179], v[180:181]
	v_mul_f32_e32 v78, 0x3fd744fd, v147
	v_mov_b32_e32 v163, v151
	v_pk_mov_b32 v[156:157], v[156:157], v[174:175] op_sel:[1,0]
	v_pk_add_f32 v[174:175], v[124:125], v[178:179]
	v_pk_mul_f32 v[178:179], v[124:125], v[178:179]
	v_pk_fma_f32 v[146:147], v[152:153], s[66:67], v[78:79] op_sel_hi:[1,1,0]
	v_pk_fma_f32 v[156:157], v[150:151], v[162:163], v[156:157]
	v_mov_b32_e32 v175, v179
	v_pk_mul_f32 v[152:153], v[146:147], v[146:147]
	v_pk_add_f32 v[156:157], v[174:175], v[156:157]
	v_mov_b32_e32 v147, v152
	v_pk_add_f32 v[152:153], v[156:157], v[146:147]
	s_nop 1
	v_mov_b32_dpp v156, v152 quad_perm:[1,0,3,2] row_mask:0xf bank_mask:0xf bound_ctrl:1
	v_mov_b32_dpp v157, v153 quad_perm:[1,0,3,2] row_mask:0xf bank_mask:0xf bound_ctrl:1
	v_pk_add_f32 v[152:153], v[152:153], v[156:157]
	s_nop 1
	v_mov_b32_dpp v156, v152 quad_perm:[2,3,0,1] row_mask:0xf bank_mask:0xf bound_ctrl:1
	v_mov_b32_dpp v157, v153 quad_perm:[2,3,0,1] row_mask:0xf bank_mask:0xf bound_ctrl:1
	v_pk_add_f32 v[152:153], v[152:153], v[156:157]
	s_nop 1
	v_mov_b32_dpp v156, v152 row_half_mirror row_mask:0xf bank_mask:0xf bound_ctrl:1
	v_mov_b32_dpp v157, v153 row_half_mirror row_mask:0xf bank_mask:0xf bound_ctrl:1
	v_pk_add_f32 v[152:153], v[152:153], v[156:157]
	s_nop 1
	v_mov_b32_dpp v156, v152 row_mirror row_mask:0xf bank_mask:0xf bound_ctrl:1
	v_mov_b32_dpp v157, v153 row_mirror row_mask:0xf bank_mask:0xf bound_ctrl:1
	s_and_saveexec_b64 s[6:7], vcc
	v_pk_add_f32 v[152:153], v[152:153], v[156:157]
	ds_write_b64 v160, v[152:153] offset:192
	s_or_b64 exec, exec, s[6:7]
	v_or_b32_e32 v78, 0x1200, v172
	v_add_u32_e32 v106, v116, v78
	ds_read2_b32 v[152:153], v106 offset1:32
	ds_read2_b32 v[156:157], v106 offset0:64 offset1:96
	v_add_f32_e32 v78, 0, v127
	v_add_f32_e32 v126, 0, v79
	v_mul_f32_e32 v79, 0.5, v78
	s_waitcnt lgkmcnt(1)
	v_mul_f32_e32 v175, 0x3fd744fd, v152
	v_mov_b32_e32 v94, v111
	v_mov_b32_e32 v78, v95
	v_mov_b32_e32 v174, v1
	v_pk_add_f32 v[178:179], v[94:95], 0 op_sel_hi:[1,0]
	v_pk_add_f32 v[110:111], v[78:79], v[174:175]
	v_mov_b32_e32 v78, v153
	s_waitcnt lgkmcnt(0)
;   DI void operator()(f32x16 (&acc)[2][4], int grow0, int gcol0, int lane, int w, char* lds) {
;     ...
; #pragma unroll
;       for (int qq = 0; qq < 2; ++qq)
; #pragma unroll
;         for (int e = 0; e < 4; ++e) {
;           const int i = 4 * (2 * (ps & 1) + qq) + e;
;           const float* xr = (const float*)(xs + (8 * qq + 4 * hh + e) * 512) + l31;
;           float s1 = 0.f, s2 = 0.f;
; #pragma unroll
;           for (int nt = 0; nt < 4; ++nt) {
;             float v = (acc[mt][nt][i] + bia[nt]) * csc[nt];
;             float z = ALPHA * xr[nt * 32] + hs * v;
;             acc[mt][nt][i] = z; s1 += z; s2 += z * z;
;           }
;           s1 = row16_sum(s1); s2 = row16_sum(s2);
;           if ((lane & 15) == 0) { f32x2 sv = {s1, s2}; *(f32x2*)(redw + (mt * 32 + (i & 3) + 8 * (i >> 2)) * 2) = sv; }
;         }
	v_mov_b32_e32 v79, v156
	s_mov_b32 s2, s67
	v_pk_mul_f32 v[94:95], v[78:79], s[2:3] op_sel_hi:[1,0]
	v_pk_mul_f32 v[152:153], v[178:179], 0.5 op_sel_hi:[1,0]
	v_pk_fma_f32 v[78:79], v[178:179], 0.5, v[94:95] op_sel_hi:[1,0,1]
	v_mov_b32_e32 v152, v111
	v_mov_b32_e32 v178, v1
	v_mov_b32_e32 v179, v95
	v_pk_mul_f32 v[174:175], v[78:79], v[78:79]
	v_pk_add_f32 v[152:153], v[152:153], v[178:179]
	v_mov_b32_e32 v163, v111
	v_pk_mov_b32 v[94:95], v[94:95], v[174:175] op_sel:[1,0]
	v_pk_add_f32 v[174:175], v[78:79], v[152:153]
	v_pk_mul_f32 v[152:153], v[78:79], v[152:153]
	v_pk_fma_f32 v[94:95], v[110:111], v[162:163], v[94:95]
	v_mov_b32_e32 v175, v153
	v_mov_b32_e32 v127, v157
	v_pk_add_f32 v[152:153], v[174:175], v[94:95]
	v_mul_f32_e32 v94, 0x3fd744fd, v157
	v_pk_fma_f32 v[94:95], v[126:127], s[66:67], v[94:95] op_sel_hi:[1,1,0]
	s_nop 0
	v_pk_mul_f32 v[126:127], v[94:95], v[94:95]
	s_nop 0
	v_mov_b32_e32 v95, v126
	v_pk_add_f32 v[126:127], v[152:153], v[94:95]
	s_nop 1
	v_mov_b32_dpp v152, v126 quad_perm:[1,0,3,2] row_mask:0xf bank_mask:0xf bound_ctrl:1
	v_mov_b32_dpp v153, v127 quad_perm:[1,0,3,2] row_mask:0xf bank_mask:0xf bound_ctrl:1
	v_pk_add_f32 v[126:127], v[126:127], v[152:153]
	s_nop 1
	v_mov_b32_dpp v152, v126 quad_perm:[2,3,0,1] row_mask:0xf bank_mask:0xf bound_ctrl:1
	v_mov_b32_dpp v153, v127 quad_perm:[2,3,0,1] row_mask:0xf bank_mask:0xf bound_ctrl:1
	v_pk_add_f32 v[126:127], v[126:127], v[152:153]
	s_nop 1
	v_mov_b32_dpp v152, v126 row_half_mirror row_mask:0xf bank_mask:0xf bound_ctrl:1
	v_mov_b32_dpp v153, v127 row_half_mirror row_mask:0xf bank_mask:0xf bound_ctrl:1
	v_pk_add_f32 v[126:127], v[126:127], v[152:153]
	s_nop 1
	v_mov_b32_dpp v152, v126 row_mirror row_mask:0xf bank_mask:0xf bound_ctrl:1
	v_mov_b32_dpp v153, v127 row_mirror row_mask:0xf bank_mask:0xf bound_ctrl:1
	s_and_saveexec_b64 s[6:7], vcc
	v_pk_add_f32 v[126:127], v[126:127], v[152:153]
	ds_write_b64 v160, v[126:127] offset:200
	s_or_b64 exec, exec, s[6:7]
	v_or_b32_e32 v91, 0x1400, v172
	v_add_u32_e32 v95, v116, v91
	ds_read2_b32 v[126:127], v95 offset1:32
	ds_read2_b32 v[152:153], v95 offset0:64 offset1:96
	v_add_f32_e32 v91, 0, v128
	v_mov_b32_e32 v178, v112
	v_mov_b32_e32 v179, v96
	v_mul_f32_e32 v157, 0.5, v91
	s_waitcnt lgkmcnt(1)
	v_mul_f32_e32 v175, 0x3fd744fd, v126
	v_pk_add_f32 v[178:179], v[178:179], 0 op_sel_hi:[1,0]
	v_mov_b32_e32 v156, v96
	v_mov_b32_e32 v174, v1
	v_mov_b32_e32 v126, v127
	s_waitcnt lgkmcnt(0)
	v_mov_b32_e32 v127, v152
	s_mov_b32 s2, s67
	v_pk_add_f32 v[156:157], v[156:157], v[174:175]
	v_pk_mul_f32 v[174:175], v[126:127], s[2:3] op_sel_hi:[1,0]
	v_pk_mul_f32 v[180:181], v[178:179], 0.5 op_sel_hi:[1,0]
	v_pk_fma_f32 v[126:127], v[178:179], 0.5, v[174:175] op_sel_hi:[1,0,1]
	v_mov_b32_e32 v180, v157
	v_mov_b32_e32 v182, v1
	v_mov_b32_e32 v183, v175
	v_add_f32_e32 v172, 0, v80
	v_mov_b32_e32 v173, v153
	v_pk_mul_f32 v[178:179], v[126:127], v[126:127]
	v_pk_add_f32 v[180:181], v[180:181], v[182:183]
	v_mul_f32_e32 v80, 0x3fd744fd, v153
	v_mov_b32_e32 v163, v157
	v_pk_mov_b32 v[174:175], v[174:175], v[178:179] op_sel:[1,0]
	v_pk_add_f32 v[178:179], v[126:127], v[180:181]
	v_pk_mul_f32 v[180:181], v[126:127], v[180:181]
	v_pk_fma_f32 v[152:153], v[172:173], s[66:67], v[80:81] op_sel_hi:[1,1,0]
	v_pk_fma_f32 v[174:175], v[156:157], v[162:163], v[174:175]
	v_mov_b32_e32 v179, v181
	v_pk_mul_f32 v[172:173], v[152:153], v[152:153]
	v_pk_add_f32 v[174:175], v[178:179], v[174:175]
	v_mov_b32_e32 v153, v172
	v_pk_add_f32 v[172:173], v[174:175], v[152:153]
	s_nop 1
	v_mov_b32_dpp v174, v172 quad_perm:[1,0,3,2] row_mask:0xf bank_mask:0xf bound_ctrl:1
	v_mov_b32_dpp v175, v173 quad_perm:[1,0,3,2] row_mask:0xf bank_mask:0xf bound_ctrl:1
	v_pk_add_f32 v[172:173], v[172:173], v[174:175]
	s_nop 1
	v_mov_b32_dpp v174, v172 quad_perm:[2,3,0,1] row_mask:0xf bank_mask:0xf bound_ctrl:1
	v_mov_b32_dpp v175, v173 quad_perm:[2,3,0,1] row_mask:0xf bank_mask:0xf bound_ctrl:1
	v_pk_add_f32 v[172:173], v[172:173], v[174:175]
	s_nop 1
	v_mov_b32_dpp v174, v172 row_half_mirror row_mask:0xf bank_mask:0xf bound_ctrl:1
	v_mov_b32_dpp v175, v173 row_half_mirror row_mask:0xf bank_mask:0xf bound_ctrl:1
	v_pk_add_f32 v[172:173], v[172:173], v[174:175]
	s_nop 1
	v_mov_b32_dpp v174, v172 row_mirror row_mask:0xf bank_mask:0xf bound_ctrl:1
	v_mov_b32_dpp v175, v173 row_mirror row_mask:0xf bank_mask:0xf bound_ctrl:1
	s_and_saveexec_b64 s[6:7], vcc
	v_pk_add_f32 v[172:173], v[172:173], v[174:175]
	ds_write_b64 v160, v[172:173] offset:208
	s_or_b64 exec, exec, s[6:7]
	v_add_u32_e32 v91, v116, v115
	v_add_f32_e32 v80, 0, v129
	ds_read2_b32 v[128:129], v91 offset1:32
	ds_read2_b32 v[178:179], v91 offset0:64 offset1:96
	v_mov_b32_e32 v96, v113
	v_mul_f32_e32 v175, 0.5, v80
	v_add_f32_e32 v180, 0, v81
	s_waitcnt lgkmcnt(1)
	v_mul_f32_e32 v173, 0x3fd744fd, v128
	v_pk_add_f32 v[80:81], v[96:97], 0 op_sel_hi:[1,0]
	v_mov_b32_e32 v174, v97
	v_mov_b32_e32 v172, v1
	v_mov_b32_e32 v96, v129
	s_waitcnt lgkmcnt(0)
;   DI void xpass(int ps, int grow0, int gcol0, int lane, int w, char* lds) const {
;     char* xs = lds + (ps & 1) * 65536 + __builtin_amdgcn_readfirstlane(w) * 8192;
;     const float* xsrc = Xin + (size_t)(grow0 + (ps >> 1) * 32 + (ps & 1) * 16 + (lane >> 5)) * D_ + gcol0 + (lane & 31) * 4;
; #pragma unroll
;     for (int pc = 0; pc < 8; ++pc)
;       __builtin_amdgcn_global_load_lds((const unsigned*)(xsrc + (size_t)(2 * pc) * D_), (__attribute__((address_space(3))) unsigned*)(xs + pc * 1024), 16, 0, 0);
;   }
;   DI void operator()(f32x16 (&acc)[2][4], int grow0, int gcol0, int lane, int w, char* lds) {
;     ...
;     for (int ps = 0; ps < 4; ++ps) {
;       const int mt = ps >> 1;
;       if (ps + 1 < 4) {
;         if (ps >= 1) asm volatile("s_waitcnt lgkmcnt(0)" ::: "memory");
;         xpass(ps + 1, grow0, gcol0, lane, w, lds);
;         if (ps >= 1) asm volatile("s_waitcnt vmcnt(8)" ::: "memory");
;       } else asm volatile("s_waitcnt vmcnt(0)" ::: "memory");
;       const char* xs = lds + (ps & 1) * 65536 + w * 8192;
; #pragma unroll
;       for (int qq = 0; qq < 2; ++qq)
; #pragma unroll
;         for (int e = 0; e < 4; ++e) {
;           const int i = 4 * (2 * (ps & 1) + qq) + e;
;           const float* xr = (const float*)(xs + (8 * qq + 4 * hh + e) * 512) + l31;
;           float s1 = 0.f, s2 = 0.f;
; #pragma unroll
;           for (int nt = 0; nt < 4; ++nt) {
;             float v = (acc[mt][nt][i] + bia[nt]) * csc[nt];
;             float z = ALPHA * xr[nt * 32] + hs * v;
;             acc[mt][nt][i] = z; s1 += z; s2 += z * z;
;           }
;           s1 = row16_sum(s1); s2 = row16_sum(s2);
;           if ((lane & 15) == 0) { f32x2 sv = {s1, s2}; *(f32x2*)(redw + (mt * 32 + (i & 3) + 8 * (i >> 2)) * 2) = sv; }
;         }
	v_mov_b32_e32 v97, v178
	s_mov_b32 s2, s67
	v_pk_add_f32 v[112:113], v[174:175], v[172:173]
	v_pk_mul_f32 v[96:97], v[96:97], s[2:3] op_sel_hi:[1,0]
	v_pk_mul_f32 v[128:129], v[80:81], 0.5 op_sel_hi:[1,0]
	v_pk_fma_f32 v[80:81], v[80:81], 0.5, v[96:97] op_sel_hi:[1,0,1]
	v_mov_b32_e32 v128, v113
	v_mov_b32_e32 v174, v1
	v_mov_b32_e32 v175, v97
	v_pk_mul_f32 v[172:173], v[80:81], v[80:81]
	v_pk_add_f32 v[128:129], v[128:129], v[174:175]
	v_mov_b32_e32 v163, v113
	v_pk_mov_b32 v[96:97], v[96:97], v[172:173] op_sel:[1,0]
	v_pk_add_f32 v[172:173], v[80:81], v[128:129]
	v_pk_mul_f32 v[128:129], v[80:81], v[128:129]
	v_pk_fma_f32 v[96:97], v[112:113], v[162:163], v[96:97]
	v_mov_b32_e32 v173, v129
	v_mov_b32_e32 v181, v179
	v_pk_add_f32 v[128:129], v[172:173], v[96:97]
	v_mul_f32_e32 v96, 0x3fd744fd, v179
	v_pk_fma_f32 v[96:97], v[180:181], s[66:67], v[96:97] op_sel_hi:[1,1,0]
	s_nop 0
	v_pk_mul_f32 v[172:173], v[96:97], v[96:97]
	s_nop 0
	v_mov_b32_e32 v97, v172
	v_pk_add_f32 v[128:129], v[128:129], v[96:97]
	s_nop 1
	v_mov_b32_dpp v172, v128 quad_perm:[1,0,3,2] row_mask:0xf bank_mask:0xf bound_ctrl:1
	v_mov_b32_dpp v173, v129 quad_perm:[1,0,3,2] row_mask:0xf bank_mask:0xf bound_ctrl:1
	v_pk_add_f32 v[128:129], v[128:129], v[172:173]
	s_nop 1
	v_mov_b32_dpp v172, v128 quad_perm:[2,3,0,1] row_mask:0xf bank_mask:0xf bound_ctrl:1
	v_mov_b32_dpp v173, v129 quad_perm:[2,3,0,1] row_mask:0xf bank_mask:0xf bound_ctrl:1
	v_pk_add_f32 v[128:129], v[128:129], v[172:173]
	s_nop 1
	v_mov_b32_dpp v172, v128 row_half_mirror row_mask:0xf bank_mask:0xf bound_ctrl:1
	v_mov_b32_dpp v173, v129 row_half_mirror row_mask:0xf bank_mask:0xf bound_ctrl:1
	v_pk_add_f32 v[128:129], v[128:129], v[172:173]
	s_nop 1
	v_mov_b32_dpp v172, v128 row_mirror row_mask:0xf bank_mask:0xf bound_ctrl:1
	v_mov_b32_dpp v173, v129 row_mirror row_mask:0xf bank_mask:0xf bound_ctrl:1
	s_and_saveexec_b64 s[6:7], vcc
	v_pk_add_f32 v[128:129], v[128:129], v[172:173]
	ds_write_b64 v160, v[128:129] offset:216
	s_or_b64 exec, exec, s[6:7]
	v_or_b32_e32 v128, 48, v176
	v_ashrrev_i32_e32 v129, 31, v128
	v_readlane_b32 s6, v255, 29
	v_lshlrev_b64 v[128:129], 12, v[128:129]
	v_readlane_b32 s7, v255, 30
	v_readfirstlane_b32 s2, v169
	s_lshl_b32 s2, s2, 13
	v_lshl_add_u64 v[128:129], s[6:7], 0, v[128:129]
	v_lshl_add_u64 v[128:129], v[154:155], 2, v[128:129]
	s_waitcnt lgkmcnt(0)
	s_add_i32 m0, s2, 0x10000
	v_lshl_add_u64 v[128:129], v[128:129], 0, v[0:1]
	s_mov_b64 s[6:7], 0x2000
	global_load_lds_dwordx4 v[128:129], off
	v_lshl_add_u64 v[172:173], v[128:129], 0, s[6:7]
	s_add_i32 m0, s2, 0x10400
	s_mov_b64 s[6:7], 0x4000
	global_load_lds_dwordx4 v[172:173], off
	v_lshl_add_u64 v[172:173], v[128:129], 0, s[6:7]
	s_add_i32 m0, s2, 0x10800
	s_mov_b64 s[6:7], 0x6000
	global_load_lds_dwordx4 v[172:173], off
	v_lshl_add_u64 v[172:173], v[128:129], 0, s[6:7]
	s_add_i32 m0, s2, 0x10c00
	s_mov_b64 s[6:7], 0x8000
	global_load_lds_dwordx4 v[172:173], off
	v_lshl_add_u64 v[172:173], v[128:129], 0, s[6:7]
	s_add_i32 m0, s2, 0x11000
	s_mov_b64 s[6:7], 0xa000
	global_load_lds_dwordx4 v[172:173], off
	v_lshl_add_u64 v[172:173], v[128:129], 0, s[6:7]
	s_add_i32 m0, s2, 0x11400
	s_mov_b64 s[6:7], 0xc000
	global_load_lds_dwordx4 v[172:173], off
	v_lshl_add_u64 v[172:173], v[128:129], 0, s[6:7]
	s_add_i32 m0, s2, 0x11800
	s_mov_b64 s[6:7], 0xe000
	global_load_lds_dwordx4 v[172:173], off
	v_lshl_add_u64 v[128:129], v[128:129], 0, s[6:7]
	s_add_i32 m0, s2, 0x11c00
	v_add_f32_e32 v0, 0, v50
	global_load_lds_dwordx4 v[128:129], off
	s_waitcnt vmcnt(8)
	ds_read2_b32 v[128:129], v167 offset1:32
	ds_read2_b32 v[172:173], v167 offset0:64 offset1:96
	v_mov_b32_e32 v180, v34
	v_mov_b32_e32 v181, v18
	v_mul_f32_e32 v177, 0.5, v0
	s_waitcnt lgkmcnt(0)
	v_mul_f32_e32 v175, 0x3fd744fd, v128
	v_pk_add_f32 v[180:181], v[180:181], 0 op_sel_hi:[1,0]
	v_mov_b32_e32 v176, v18
	v_mov_b32_e32 v174, v1
	v_mov_b32_e32 v128, v129
	v_mov_b32_e32 v129, v172
	s_mov_b32 s2, s67
	v_pk_add_f32 v[174:175], v[176:177], v[174:175]
	v_pk_mul_f32 v[176:177], v[128:129], s[2:3] op_sel_hi:[1,0]
	v_pk_mul_f32 v[182:183], v[180:181], 0.5 op_sel_hi:[1,0]
	v_pk_fma_f32 v[128:129], v[180:181], 0.5, v[176:177] op_sel_hi:[1,0,1]
	v_mov_b32_e32 v182, v175
	v_mov_b32_e32 v184, v1
	v_mov_b32_e32 v185, v177
	v_add_f32_e32 v178, 0, v2
	v_mov_b32_e32 v179, v173
	v_pk_mul_f32 v[180:181], v[128:129], v[128:129]
	v_pk_add_f32 v[182:183], v[182:183], v[184:185]
	v_mul_f32_e32 v0, 0x3fd744fd, v173
	v_mov_b32_e32 v163, v175
	v_pk_mov_b32 v[176:177], v[176:177], v[180:181] op_sel:[1,0]
	v_pk_add_f32 v[180:181], v[128:129], v[182:183]
	v_pk_mul_f32 v[182:183], v[128:129], v[182:183]
	v_pk_fma_f32 v[172:173], v[178:179], s[66:67], v[0:1] op_sel_hi:[1,1,0]
	v_pk_fma_f32 v[176:177], v[174:175], v[162:163], v[176:177]
	v_mov_b32_e32 v181, v183
	v_pk_mul_f32 v[178:179], v[172:173], v[172:173]
	v_pk_add_f32 v[176:177], v[180:181], v[176:177]
	v_mov_b32_e32 v173, v178
	v_pk_add_f32 v[176:177], v[176:177], v[172:173]
	s_nop 1
	v_mov_b32_dpp v178, v176 quad_perm:[1,0,3,2] row_mask:0xf bank_mask:0xf bound_ctrl:1
	v_mov_b32_dpp v179, v177 quad_perm:[1,0,3,2] row_mask:0xf bank_mask:0xf bound_ctrl:1
	v_pk_add_f32 v[176:177], v[176:177], v[178:179]
	s_nop 1
	v_mov_b32_dpp v178, v176 quad_perm:[2,3,0,1] row_mask:0xf bank_mask:0xf bound_ctrl:1
	v_mov_b32_dpp v179, v177 quad_perm:[2,3,0,1] row_mask:0xf bank_mask:0xf bound_ctrl:1
	v_pk_add_f32 v[176:177], v[176:177], v[178:179]
	s_nop 1
	v_mov_b32_dpp v178, v176 row_half_mirror row_mask:0xf bank_mask:0xf bound_ctrl:1
	v_mov_b32_dpp v179, v177 row_half_mirror row_mask:0xf bank_mask:0xf bound_ctrl:1
	v_pk_add_f32 v[176:177], v[176:177], v[178:179]
	s_nop 1
	v_mov_b32_dpp v178, v176 row_mirror row_mask:0xf bank_mask:0xf bound_ctrl:1
	v_mov_b32_dpp v179, v177 row_mirror row_mask:0xf bank_mask:0xf bound_ctrl:1
	s_and_saveexec_b64 s[6:7], vcc
	v_pk_add_f32 v[176:177], v[176:177], v[178:179]
	ds_write_b64 v160, v[176:177] offset:256
	s_or_b64 exec, exec, s[6:7]
	ds_read2_b32 v[176:177], v167 offset0:128 offset1:160
	ds_read2_b32 v[178:179], v167 offset0:192 offset1:224
	v_add_f32_e32 v0, 0, v51
	v_add_f32_e32 v50, 0, v3
	v_mul_f32_e32 v3, 0.5, v0
	s_waitcnt lgkmcnt(1)
;   DI void operator()(f32x16 (&acc)[2][4], int grow0, int gcol0, int lane, int w, char* lds) {
;     ...
; #pragma unroll
;       for (int qq = 0; qq < 2; ++qq)
; #pragma unroll
;         for (int e = 0; e < 4; ++e) {
;           const int i = 4 * (2 * (ps & 1) + qq) + e;
;           const float* xr = (const float*)(xs + (8 * qq + 4 * hh + e) * 512) + l31;
;           float s1 = 0.f, s2 = 0.f;
; #pragma unroll
;           for (int nt = 0; nt < 4; ++nt) {
;             float v = (acc[mt][nt][i] + bia[nt]) * csc[nt];
;             float z = ALPHA * xr[nt * 32] + hs * v;
;             acc[mt][nt][i] = z; s1 += z; s2 += z * z;
;           }
;           s1 = row16_sum(s1); s2 = row16_sum(s2);
;           if ((lane & 15) == 0) { f32x2 sv = {s1, s2}; *(f32x2*)(redw + (mt * 32 + (i & 3) + 8 * (i >> 2)) * 2) = sv; }
;         }
	v_mul_f32_e32 v181, 0x3fd744fd, v176
	v_mov_b32_e32 v18, v35
	v_mov_b32_e32 v2, v19
	v_mov_b32_e32 v180, v1
	v_pk_add_f32 v[182:183], v[18:19], 0 op_sel_hi:[1,0]
	v_pk_add_f32 v[34:35], v[2:3], v[180:181]
	v_mov_b32_e32 v2, v177
	s_waitcnt lgkmcnt(0)
	v_mov_b32_e32 v3, v178
	s_mov_b32 s2, s67
	v_pk_mul_f32 v[18:19], v[2:3], s[2:3] op_sel_hi:[1,0]
	v_pk_mul_f32 v[176:177], v[182:183], 0.5 op_sel_hi:[1,0]
	v_pk_fma_f32 v[2:3], v[182:183], 0.5, v[18:19] op_sel_hi:[1,0,1]
	v_mov_b32_e32 v176, v35
	v_mov_b32_e32 v182, v1
	v_mov_b32_e32 v183, v19
	v_pk_mul_f32 v[180:181], v[2:3], v[2:3]
	v_pk_add_f32 v[176:177], v[176:177], v[182:183]
	v_mov_b32_e32 v163, v35
	v_pk_mov_b32 v[18:19], v[18:19], v[180:181] op_sel:[1,0]
	v_pk_add_f32 v[180:181], v[2:3], v[176:177]
	v_pk_mul_f32 v[176:177], v[2:3], v[176:177]
	v_mov_b32_e32 v51, v179
	v_pk_fma_f32 v[18:19], v[34:35], v[162:163], v[18:19]
	v_mov_b32_e32 v181, v177
	v_mul_f32_e32 v0, 0x3fd744fd, v179
	v_pk_add_f32 v[176:177], v[180:181], v[18:19]
	v_pk_fma_f32 v[18:19], v[50:51], s[66:67], v[0:1] op_sel_hi:[1,1,0]
	s_nop 0
	v_pk_mul_f32 v[50:51], v[18:19], v[18:19]
	s_nop 0
	v_mov_b32_e32 v19, v50
	v_pk_add_f32 v[50:51], v[176:177], v[18:19]
	s_nop 1
	v_mov_b32_dpp v176, v50 quad_perm:[1,0,3,2] row_mask:0xf bank_mask:0xf bound_ctrl:1
	v_mov_b32_dpp v177, v51 quad_perm:[1,0,3,2] row_mask:0xf bank_mask:0xf bound_ctrl:1
	v_pk_add_f32 v[50:51], v[50:51], v[176:177]
	s_nop 1
	v_mov_b32_dpp v176, v50 quad_perm:[2,3,0,1] row_mask:0xf bank_mask:0xf bound_ctrl:1
	v_mov_b32_dpp v177, v51 quad_perm:[2,3,0,1] row_mask:0xf bank_mask:0xf bound_ctrl:1
	v_pk_add_f32 v[50:51], v[50:51], v[176:177]
	s_nop 1
	v_mov_b32_dpp v176, v50 row_half_mirror row_mask:0xf bank_mask:0xf bound_ctrl:1
	v_mov_b32_dpp v177, v51 row_half_mirror row_mask:0xf bank_mask:0xf bound_ctrl:1
	v_pk_add_f32 v[50:51], v[50:51], v[176:177]
	s_nop 1
	v_mov_b32_dpp v176, v50 row_mirror row_mask:0xf bank_mask:0xf bound_ctrl:1
	v_mov_b32_dpp v177, v51 row_mirror row_mask:0xf bank_mask:0xf bound_ctrl:1
	s_and_saveexec_b64 s[6:7], vcc
	v_pk_add_f32 v[50:51], v[50:51], v[176:177]
	ds_write_b64 v160, v[50:51] offset:264
	s_or_b64 exec, exec, s[6:7]
	ds_read2_b32 v[50:51], v143 offset1:32
	ds_read2_b32 v[176:177], v143 offset0:64 offset1:96
	v_add_f32_e32 v0, 0, v52
	v_mov_b32_e32 v184, v36
	v_mov_b32_e32 v185, v20
	v_mul_f32_e32 v179, 0.5, v0
	s_waitcnt lgkmcnt(1)
	v_mul_f32_e32 v183, 0x3fd744fd, v50
	v_pk_add_f32 v[184:185], v[184:185], 0 op_sel_hi:[1,0]
	v_mov_b32_e32 v178, v20
	v_mov_b32_e32 v182, v1
	v_mov_b32_e32 v50, v51
	s_waitcnt lgkmcnt(0)
	v_mov_b32_e32 v51, v176
	s_mov_b32 s2, s67
	v_pk_add_f32 v[178:179], v[178:179], v[182:183]
	v_pk_mul_f32 v[182:183], v[50:51], s[2:3] op_sel_hi:[1,0]
	v_pk_mul_f32 v[186:187], v[184:185], 0.5 op_sel_hi:[1,0]
	v_pk_fma_f32 v[50:51], v[184:185], 0.5, v[182:183] op_sel_hi:[1,0,1]
	v_mov_b32_e32 v186, v179
	v_mov_b32_e32 v188, v1
	v_mov_b32_e32 v189, v183
	v_add_f32_e32 v180, 0, v4
	v_mov_b32_e32 v181, v177
	v_pk_mul_f32 v[184:185], v[50:51], v[50:51]
	v_pk_add_f32 v[186:187], v[186:187], v[188:189]
	v_mul_f32_e32 v0, 0x3fd744fd, v177
	v_mov_b32_e32 v163, v179
	v_pk_mov_b32 v[182:183], v[182:183], v[184:185] op_sel:[1,0]
	v_pk_add_f32 v[184:185], v[50:51], v[186:187]
	v_pk_mul_f32 v[186:187], v[50:51], v[186:187]
	v_pk_fma_f32 v[176:177], v[180:181], s[66:67], v[0:1] op_sel_hi:[1,1,0]
	v_pk_fma_f32 v[182:183], v[178:179], v[162:163], v[182:183]
	v_mov_b32_e32 v185, v187
	v_pk_mul_f32 v[180:181], v[176:177], v[176:177]
	v_pk_add_f32 v[182:183], v[184:185], v[182:183]
	v_mov_b32_e32 v177, v180
	v_pk_add_f32 v[180:181], v[182:183], v[176:177]
	s_nop 1
	v_mov_b32_dpp v182, v180 quad_perm:[1,0,3,2] row_mask:0xf bank_mask:0xf bound_ctrl:1
	v_mov_b32_dpp v183, v181 quad_perm:[1,0,3,2] row_mask:0xf bank_mask:0xf bound_ctrl:1
	v_pk_add_f32 v[180:181], v[180:181], v[182:183]
	s_nop 1
	v_mov_b32_dpp v182, v180 quad_perm:[2,3,0,1] row_mask:0xf bank_mask:0xf bound_ctrl:1
	v_mov_b32_dpp v183, v181 quad_perm:[2,3,0,1] row_mask:0xf bank_mask:0xf bound_ctrl:1
	v_pk_add_f32 v[180:181], v[180:181], v[182:183]
	s_nop 1
	v_mov_b32_dpp v182, v180 row_half_mirror row_mask:0xf bank_mask:0xf bound_ctrl:1
	v_mov_b32_dpp v183, v181 row_half_mirror row_mask:0xf bank_mask:0xf bound_ctrl:1
	v_pk_add_f32 v[180:181], v[180:181], v[182:183]
	s_nop 1
	v_mov_b32_dpp v182, v180 row_mirror row_mask:0xf bank_mask:0xf bound_ctrl:1
	v_mov_b32_dpp v183, v181 row_mirror row_mask:0xf bank_mask:0xf bound_ctrl:1
	s_and_saveexec_b64 s[6:7], vcc
	v_pk_add_f32 v[180:181], v[180:181], v[182:183]
	ds_write_b64 v160, v[180:181] offset:272
	s_or_b64 exec, exec, s[6:7]
	ds_read2_b32 v[180:181], v144 offset1:32
	ds_read2_b32 v[182:183], v144 offset0:64 offset1:96
	v_add_f32_e32 v0, 0, v53
	v_add_f32_e32 v52, 0, v5
	v_mul_f32_e32 v5, 0.5, v0
	s_waitcnt lgkmcnt(1)
	v_mul_f32_e32 v185, 0x3fd744fd, v180
	v_mov_b32_e32 v20, v37
	v_mov_b32_e32 v4, v21
	v_mov_b32_e32 v184, v1
	v_pk_add_f32 v[186:187], v[20:21], 0 op_sel_hi:[1,0]
	v_pk_add_f32 v[36:37], v[4:5], v[184:185]
	v_mov_b32_e32 v4, v181
	s_waitcnt lgkmcnt(0)
;   DI void operator()(f32x16 (&acc)[2][4], int grow0, int gcol0, int lane, int w, char* lds) {
;     ...
; #pragma unroll
;       for (int qq = 0; qq < 2; ++qq)
; #pragma unroll
;         for (int e = 0; e < 4; ++e) {
;           const int i = 4 * (2 * (ps & 1) + qq) + e;
;           const float* xr = (const float*)(xs + (8 * qq + 4 * hh + e) * 512) + l31;
;           float s1 = 0.f, s2 = 0.f;
; #pragma unroll
;           for (int nt = 0; nt < 4; ++nt) {
;             float v = (acc[mt][nt][i] + bia[nt]) * csc[nt];
;             float z = ALPHA * xr[nt * 32] + hs * v;
;             acc[mt][nt][i] = z; s1 += z; s2 += z * z;
;           }
;           s1 = row16_sum(s1); s2 = row16_sum(s2);
;           if ((lane & 15) == 0) { f32x2 sv = {s1, s2}; *(f32x2*)(redw + (mt * 32 + (i & 3) + 8 * (i >> 2)) * 2) = sv; }
;         }
	v_mov_b32_e32 v5, v182
	s_mov_b32 s2, s67
	v_pk_mul_f32 v[20:21], v[4:5], s[2:3] op_sel_hi:[1,0]
	v_pk_mul_f32 v[180:181], v[186:187], 0.5 op_sel_hi:[1,0]
	v_pk_fma_f32 v[4:5], v[186:187], 0.5, v[20:21] op_sel_hi:[1,0,1]
	v_mov_b32_e32 v180, v37
	v_mov_b32_e32 v186, v1
	v_mov_b32_e32 v187, v21
	v_pk_mul_f32 v[184:185], v[4:5], v[4:5]
	v_pk_add_f32 v[180:181], v[180:181], v[186:187]
	v_mov_b32_e32 v163, v37
	v_pk_mov_b32 v[20:21], v[20:21], v[184:185] op_sel:[1,0]
	v_pk_add_f32 v[184:185], v[4:5], v[180:181]
	v_pk_mul_f32 v[180:181], v[4:5], v[180:181]
	v_mov_b32_e32 v53, v183
	v_pk_fma_f32 v[20:21], v[36:37], v[162:163], v[20:21]
	v_mov_b32_e32 v185, v181
	v_mul_f32_e32 v0, 0x3fd744fd, v183
	v_pk_add_f32 v[180:181], v[184:185], v[20:21]
	v_pk_fma_f32 v[20:21], v[52:53], s[66:67], v[0:1] op_sel_hi:[1,1,0]
	s_nop 0
	v_pk_mul_f32 v[52:53], v[20:21], v[20:21]
	s_nop 0
	v_mov_b32_e32 v21, v52
	v_pk_add_f32 v[52:53], v[180:181], v[20:21]
	s_nop 1
	v_mov_b32_dpp v180, v52 quad_perm:[1,0,3,2] row_mask:0xf bank_mask:0xf bound_ctrl:1
	v_mov_b32_dpp v181, v53 quad_perm:[1,0,3,2] row_mask:0xf bank_mask:0xf bound_ctrl:1
	v_pk_add_f32 v[52:53], v[52:53], v[180:181]
	s_nop 1
	v_mov_b32_dpp v180, v52 quad_perm:[2,3,0,1] row_mask:0xf bank_mask:0xf bound_ctrl:1
	v_mov_b32_dpp v181, v53 quad_perm:[2,3,0,1] row_mask:0xf bank_mask:0xf bound_ctrl:1
	v_pk_add_f32 v[52:53], v[52:53], v[180:181]
	s_nop 1
	v_mov_b32_dpp v180, v52 row_half_mirror row_mask:0xf bank_mask:0xf bound_ctrl:1
	v_mov_b32_dpp v181, v53 row_half_mirror row_mask:0xf bank_mask:0xf bound_ctrl:1
	v_pk_add_f32 v[52:53], v[52:53], v[180:181]
	s_nop 1
	v_mov_b32_dpp v180, v52 row_mirror row_mask:0xf bank_mask:0xf bound_ctrl:1
	v_mov_b32_dpp v181, v53 row_mirror row_mask:0xf bank_mask:0xf bound_ctrl:1
	s_and_saveexec_b64 s[6:7], vcc
	v_pk_add_f32 v[52:53], v[52:53], v[180:181]
	ds_write_b64 v160, v[52:53] offset:280
	s_or_b64 exec, exec, s[6:7]
	ds_read2_b32 v[52:53], v83 offset1:32
	ds_read2_b32 v[180:181], v83 offset0:64 offset1:96
	v_add_f32_e32 v0, 0, v54
	v_mov_b32_e32 v188, v38
	v_mov_b32_e32 v189, v22
	v_mul_f32_e32 v183, 0.5, v0
	s_waitcnt lgkmcnt(1)
	v_mul_f32_e32 v187, 0x3fd744fd, v52
	v_pk_add_f32 v[188:189], v[188:189], 0 op_sel_hi:[1,0]
	v_mov_b32_e32 v182, v22
	v_mov_b32_e32 v186, v1
	v_mov_b32_e32 v52, v53
	s_waitcnt lgkmcnt(0)
	v_mov_b32_e32 v53, v180
	s_mov_b32 s2, s67
	v_pk_add_f32 v[182:183], v[182:183], v[186:187]
	v_pk_mul_f32 v[186:187], v[52:53], s[2:3] op_sel_hi:[1,0]
	v_pk_mul_f32 v[190:191], v[188:189], 0.5 op_sel_hi:[1,0]
	v_pk_fma_f32 v[52:53], v[188:189], 0.5, v[186:187] op_sel_hi:[1,0,1]
	v_mov_b32_e32 v190, v183
	v_mov_b32_e32 v192, v1
	v_mov_b32_e32 v193, v187
	v_add_f32_e32 v184, 0, v6
	v_mov_b32_e32 v185, v181
	v_pk_mul_f32 v[188:189], v[52:53], v[52:53]
	v_pk_add_f32 v[190:191], v[190:191], v[192:193]
	v_mul_f32_e32 v0, 0x3fd744fd, v181
	v_mov_b32_e32 v163, v183
	v_pk_mov_b32 v[186:187], v[186:187], v[188:189] op_sel:[1,0]
	v_pk_add_f32 v[188:189], v[52:53], v[190:191]
	v_pk_mul_f32 v[190:191], v[52:53], v[190:191]
	v_pk_fma_f32 v[180:181], v[184:185], s[66:67], v[0:1] op_sel_hi:[1,1,0]
	v_pk_fma_f32 v[186:187], v[182:183], v[162:163], v[186:187]
	v_mov_b32_e32 v189, v191
	v_pk_mul_f32 v[184:185], v[180:181], v[180:181]
	v_pk_add_f32 v[186:187], v[188:189], v[186:187]
	v_mov_b32_e32 v181, v184
	v_pk_add_f32 v[184:185], v[186:187], v[180:181]
	s_nop 1
	v_mov_b32_dpp v186, v184 quad_perm:[1,0,3,2] row_mask:0xf bank_mask:0xf bound_ctrl:1
	v_mov_b32_dpp v187, v185 quad_perm:[1,0,3,2] row_mask:0xf bank_mask:0xf bound_ctrl:1
	v_pk_add_f32 v[184:185], v[184:185], v[186:187]
	s_nop 1
	v_mov_b32_dpp v186, v184 quad_perm:[2,3,0,1] row_mask:0xf bank_mask:0xf bound_ctrl:1
	v_mov_b32_dpp v187, v185 quad_perm:[2,3,0,1] row_mask:0xf bank_mask:0xf bound_ctrl:1
	v_pk_add_f32 v[184:185], v[184:185], v[186:187]
	s_nop 1
	v_mov_b32_dpp v186, v184 row_half_mirror row_mask:0xf bank_mask:0xf bound_ctrl:1
	v_mov_b32_dpp v187, v185 row_half_mirror row_mask:0xf bank_mask:0xf bound_ctrl:1
	v_pk_add_f32 v[184:185], v[184:185], v[186:187]
	s_nop 1
	v_mov_b32_dpp v186, v184 row_mirror row_mask:0xf bank_mask:0xf bound_ctrl:1
	v_mov_b32_dpp v187, v185 row_mirror row_mask:0xf bank_mask:0xf bound_ctrl:1
	s_and_saveexec_b64 s[6:7], vcc
	v_pk_add_f32 v[184:185], v[184:185], v[186:187]
	ds_write_b64 v160, v[184:185] offset:320
	s_or_b64 exec, exec, s[6:7]
	ds_read2_b32 v[184:185], v83 offset0:128 offset1:160
	ds_read2_b32 v[186:187], v83 offset0:192 offset1:224
	v_add_f32_e32 v0, 0, v55
	v_add_f32_e32 v54, 0, v7
	v_mul_f32_e32 v7, 0.5, v0
	s_waitcnt lgkmcnt(1)
	v_mul_f32_e32 v189, 0x3fd744fd, v184
	v_mov_b32_e32 v22, v39
	v_mov_b32_e32 v6, v23
	v_mov_b32_e32 v188, v1
	v_pk_add_f32 v[190:191], v[22:23], 0 op_sel_hi:[1,0]
	v_pk_add_f32 v[38:39], v[6:7], v[188:189]
	v_mov_b32_e32 v6, v185
	s_waitcnt lgkmcnt(0)
;   DI void operator()(f32x16 (&acc)[2][4], int grow0, int gcol0, int lane, int w, char* lds) {
;     ...
; #pragma unroll
;       for (int qq = 0; qq < 2; ++qq)
; #pragma unroll
;         for (int e = 0; e < 4; ++e) {
;           const int i = 4 * (2 * (ps & 1) + qq) + e;
;           const float* xr = (const float*)(xs + (8 * qq + 4 * hh + e) * 512) + l31;
;           float s1 = 0.f, s2 = 0.f;
; #pragma unroll
;           for (int nt = 0; nt < 4; ++nt) {
;             float v = (acc[mt][nt][i] + bia[nt]) * csc[nt];
;             float z = ALPHA * xr[nt * 32] + hs * v;
;             acc[mt][nt][i] = z; s1 += z; s2 += z * z;
;           }
;           s1 = row16_sum(s1); s2 = row16_sum(s2);
;           if ((lane & 15) == 0) { f32x2 sv = {s1, s2}; *(f32x2*)(redw + (mt * 32 + (i & 3) + 8 * (i >> 2)) * 2) = sv; }
;         }
	v_mov_b32_e32 v7, v186
	s_mov_b32 s2, s67
	v_pk_mul_f32 v[22:23], v[6:7], s[2:3] op_sel_hi:[1,0]
	v_pk_mul_f32 v[184:185], v[190:191], 0.5 op_sel_hi:[1,0]
	v_pk_fma_f32 v[6:7], v[190:191], 0.5, v[22:23] op_sel_hi:[1,0,1]
	v_mov_b32_e32 v184, v39
	v_mov_b32_e32 v190, v1
	v_mov_b32_e32 v191, v23
	v_pk_mul_f32 v[188:189], v[6:7], v[6:7]
	v_pk_add_f32 v[184:185], v[184:185], v[190:191]
	v_mov_b32_e32 v163, v39
	v_pk_mov_b32 v[22:23], v[22:23], v[188:189] op_sel:[1,0]
	v_pk_add_f32 v[188:189], v[6:7], v[184:185]
	v_pk_mul_f32 v[184:185], v[6:7], v[184:185]
	v_mov_b32_e32 v55, v187
	v_pk_fma_f32 v[22:23], v[38:39], v[162:163], v[22:23]
	v_mov_b32_e32 v189, v185
	v_mul_f32_e32 v0, 0x3fd744fd, v187
	v_pk_add_f32 v[184:185], v[188:189], v[22:23]
	v_pk_fma_f32 v[22:23], v[54:55], s[66:67], v[0:1] op_sel_hi:[1,1,0]
	s_nop 0
	v_pk_mul_f32 v[54:55], v[22:23], v[22:23]
	s_nop 0
	v_mov_b32_e32 v23, v54
	v_pk_add_f32 v[54:55], v[184:185], v[22:23]
	s_nop 1
	v_mov_b32_dpp v184, v54 quad_perm:[1,0,3,2] row_mask:0xf bank_mask:0xf bound_ctrl:1
	v_mov_b32_dpp v185, v55 quad_perm:[1,0,3,2] row_mask:0xf bank_mask:0xf bound_ctrl:1
	v_pk_add_f32 v[54:55], v[54:55], v[184:185]
	s_nop 1
	v_mov_b32_dpp v184, v54 quad_perm:[2,3,0,1] row_mask:0xf bank_mask:0xf bound_ctrl:1
	v_mov_b32_dpp v185, v55 quad_perm:[2,3,0,1] row_mask:0xf bank_mask:0xf bound_ctrl:1
	v_pk_add_f32 v[54:55], v[54:55], v[184:185]
	s_nop 1
	v_mov_b32_dpp v184, v54 row_half_mirror row_mask:0xf bank_mask:0xf bound_ctrl:1
	v_mov_b32_dpp v185, v55 row_half_mirror row_mask:0xf bank_mask:0xf bound_ctrl:1
	v_pk_add_f32 v[54:55], v[54:55], v[184:185]
	s_nop 1
	v_mov_b32_dpp v184, v54 row_mirror row_mask:0xf bank_mask:0xf bound_ctrl:1
	v_mov_b32_dpp v185, v55 row_mirror row_mask:0xf bank_mask:0xf bound_ctrl:1
	s_and_saveexec_b64 s[6:7], vcc
	v_pk_add_f32 v[54:55], v[54:55], v[184:185]
	ds_write_b64 v160, v[54:55] offset:328
	s_or_b64 exec, exec, s[6:7]
	ds_read2_b32 v[54:55], v85 offset1:32
	ds_read2_b32 v[184:185], v85 offset0:64 offset1:96
	v_add_f32_e32 v0, 0, v56
	v_mov_b32_e32 v192, v40
	v_mov_b32_e32 v193, v24
	v_mul_f32_e32 v187, 0.5, v0
	s_waitcnt lgkmcnt(1)
	v_mul_f32_e32 v191, 0x3fd744fd, v54
	v_pk_add_f32 v[192:193], v[192:193], 0 op_sel_hi:[1,0]
	v_mov_b32_e32 v186, v24
	v_mov_b32_e32 v190, v1
	v_mov_b32_e32 v54, v55
	s_waitcnt lgkmcnt(0)
	v_mov_b32_e32 v55, v184
	s_mov_b32 s2, s67
	v_pk_add_f32 v[186:187], v[186:187], v[190:191]
	v_pk_mul_f32 v[190:191], v[54:55], s[2:3] op_sel_hi:[1,0]
	v_pk_mul_f32 v[194:195], v[192:193], 0.5 op_sel_hi:[1,0]
	v_pk_fma_f32 v[54:55], v[192:193], 0.5, v[190:191] op_sel_hi:[1,0,1]
	v_mov_b32_e32 v194, v187
	v_mov_b32_e32 v196, v1
	v_mov_b32_e32 v197, v191
	v_add_f32_e32 v188, 0, v8
	v_mov_b32_e32 v189, v185
	v_pk_mul_f32 v[192:193], v[54:55], v[54:55]
	v_pk_add_f32 v[194:195], v[194:195], v[196:197]
	v_mul_f32_e32 v0, 0x3fd744fd, v185
	v_mov_b32_e32 v163, v187
	v_pk_mov_b32 v[190:191], v[190:191], v[192:193] op_sel:[1,0]
	v_pk_add_f32 v[192:193], v[54:55], v[194:195]
	v_pk_mul_f32 v[194:195], v[54:55], v[194:195]
	v_pk_fma_f32 v[184:185], v[188:189], s[66:67], v[0:1] op_sel_hi:[1,1,0]
	v_pk_fma_f32 v[190:191], v[186:187], v[162:163], v[190:191]
	v_mov_b32_e32 v193, v195
	v_pk_mul_f32 v[188:189], v[184:185], v[184:185]
	v_pk_add_f32 v[190:191], v[192:193], v[190:191]
	v_mov_b32_e32 v185, v188
	v_pk_add_f32 v[188:189], v[190:191], v[184:185]
	s_nop 1
	v_mov_b32_dpp v190, v188 quad_perm:[1,0,3,2] row_mask:0xf bank_mask:0xf bound_ctrl:1
	v_mov_b32_dpp v191, v189 quad_perm:[1,0,3,2] row_mask:0xf bank_mask:0xf bound_ctrl:1
	v_pk_add_f32 v[188:189], v[188:189], v[190:191]
	s_nop 1
	v_mov_b32_dpp v190, v188 quad_perm:[2,3,0,1] row_mask:0xf bank_mask:0xf bound_ctrl:1
	v_mov_b32_dpp v191, v189 quad_perm:[2,3,0,1] row_mask:0xf bank_mask:0xf bound_ctrl:1
	v_pk_add_f32 v[188:189], v[188:189], v[190:191]
	s_nop 1
	v_mov_b32_dpp v190, v188 row_half_mirror row_mask:0xf bank_mask:0xf bound_ctrl:1
	v_mov_b32_dpp v191, v189 row_half_mirror row_mask:0xf bank_mask:0xf bound_ctrl:1
	v_pk_add_f32 v[188:189], v[188:189], v[190:191]
	s_nop 1
	v_mov_b32_dpp v190, v188 row_mirror row_mask:0xf bank_mask:0xf bound_ctrl:1
	v_mov_b32_dpp v191, v189 row_mirror row_mask:0xf bank_mask:0xf bound_ctrl:1
	s_and_saveexec_b64 s[6:7], vcc
	v_pk_add_f32 v[188:189], v[188:189], v[190:191]
	ds_write_b64 v160, v[188:189] offset:336
	s_or_b64 exec, exec, s[6:7]
	ds_read2_b32 v[188:189], v87 offset1:32
	ds_read2_b32 v[190:191], v87 offset0:64 offset1:96
	v_add_f32_e32 v0, 0, v57
	v_add_f32_e32 v56, 0, v9
	v_mul_f32_e32 v9, 0.5, v0
	s_waitcnt lgkmcnt(1)
	v_mul_f32_e32 v193, 0x3fd744fd, v188
	v_mov_b32_e32 v24, v41
	v_mov_b32_e32 v8, v25
	v_mov_b32_e32 v192, v1
	v_pk_add_f32 v[194:195], v[24:25], 0 op_sel_hi:[1,0]
	v_pk_add_f32 v[40:41], v[8:9], v[192:193]
	v_mov_b32_e32 v8, v189
	s_waitcnt lgkmcnt(0)
;   DI void operator()(f32x16 (&acc)[2][4], int grow0, int gcol0, int lane, int w, char* lds) {
;     ...
;       } else asm volatile("s_waitcnt vmcnt(0)" ::: "memory");
;       const char* xs = lds + (ps & 1) * 65536 + w * 8192;
; #pragma unroll
;       for (int qq = 0; qq < 2; ++qq)
; #pragma unroll
;         for (int e = 0; e < 4; ++e) {
;           const int i = 4 * (2 * (ps & 1) + qq) + e;
;           const float* xr = (const float*)(xs + (8 * qq + 4 * hh + e) * 512) + l31;
;           float s1 = 0.f, s2 = 0.f;
; #pragma unroll
;           for (int nt = 0; nt < 4; ++nt) {
;             float v = (acc[mt][nt][i] + bia[nt]) * csc[nt];
;             float z = ALPHA * xr[nt * 32] + hs * v;
;             acc[mt][nt][i] = z; s1 += z; s2 += z * z;
;           }
;           s1 = row16_sum(s1); s2 = row16_sum(s2);
;           if ((lane & 15) == 0) { f32x2 sv = {s1, s2}; *(f32x2*)(redw + (mt * 32 + (i & 3) + 8 * (i >> 2)) * 2) = sv; }
;         }
	v_mov_b32_e32 v9, v190
	s_mov_b32 s2, s67
	v_pk_mul_f32 v[24:25], v[8:9], s[2:3] op_sel_hi:[1,0]
	v_pk_mul_f32 v[188:189], v[194:195], 0.5 op_sel_hi:[1,0]
	v_pk_fma_f32 v[8:9], v[194:195], 0.5, v[24:25] op_sel_hi:[1,0,1]
	v_mov_b32_e32 v188, v41
	v_mov_b32_e32 v194, v1
	v_mov_b32_e32 v195, v25
	v_pk_mul_f32 v[192:193], v[8:9], v[8:9]
	v_pk_add_f32 v[188:189], v[188:189], v[194:195]
	v_mov_b32_e32 v163, v41
	v_pk_mov_b32 v[24:25], v[24:25], v[192:193] op_sel:[1,0]
	v_pk_add_f32 v[192:193], v[8:9], v[188:189]
	v_pk_mul_f32 v[188:189], v[8:9], v[188:189]
	v_mov_b32_e32 v57, v191
	v_pk_fma_f32 v[24:25], v[40:41], v[162:163], v[24:25]
	v_mov_b32_e32 v193, v189
	v_mul_f32_e32 v0, 0x3fd744fd, v191
	v_pk_add_f32 v[188:189], v[192:193], v[24:25]
	v_pk_fma_f32 v[24:25], v[56:57], s[66:67], v[0:1] op_sel_hi:[1,1,0]
	s_nop 0
	v_pk_mul_f32 v[56:57], v[24:25], v[24:25]
	s_nop 0
	v_mov_b32_e32 v25, v56
	v_pk_add_f32 v[56:57], v[188:189], v[24:25]
	s_nop 1
	v_mov_b32_dpp v188, v56 quad_perm:[1,0,3,2] row_mask:0xf bank_mask:0xf bound_ctrl:1
	v_mov_b32_dpp v189, v57 quad_perm:[1,0,3,2] row_mask:0xf bank_mask:0xf bound_ctrl:1
	v_pk_add_f32 v[56:57], v[56:57], v[188:189]
	s_nop 1
	v_mov_b32_dpp v188, v56 quad_perm:[2,3,0,1] row_mask:0xf bank_mask:0xf bound_ctrl:1
	v_mov_b32_dpp v189, v57 quad_perm:[2,3,0,1] row_mask:0xf bank_mask:0xf bound_ctrl:1
	v_pk_add_f32 v[56:57], v[56:57], v[188:189]
	s_nop 1
	v_mov_b32_dpp v188, v56 row_half_mirror row_mask:0xf bank_mask:0xf bound_ctrl:1
	v_mov_b32_dpp v189, v57 row_half_mirror row_mask:0xf bank_mask:0xf bound_ctrl:1
	v_pk_add_f32 v[56:57], v[56:57], v[188:189]
	s_nop 1
	v_mov_b32_dpp v188, v56 row_mirror row_mask:0xf bank_mask:0xf bound_ctrl:1
	v_mov_b32_dpp v189, v57 row_mirror row_mask:0xf bank_mask:0xf bound_ctrl:1
	s_and_saveexec_b64 s[6:7], vcc
	v_pk_add_f32 v[56:57], v[56:57], v[188:189]
	ds_write_b64 v160, v[56:57] offset:344
	s_or_b64 exec, exec, s[6:7]
	s_waitcnt vmcnt(0)
	ds_read2_b32 v[56:57], v89 offset1:32
	ds_read2_b32 v[190:191], v89 offset0:64 offset1:96
	v_add_f32_e32 v0, 0, v58
	v_mul_f32_e32 v189, 0.5, v0
	v_mov_b32_e32 v188, v26
	s_waitcnt lgkmcnt(1)
	v_mul_f32_e32 v193, 0x3fd744fd, v56
	v_add_f32_e32 v56, 0, v42
	v_mul_f32_e32 v0, 0x3fd744fd, v57
	v_mov_b32_e32 v192, v1
	v_pk_fma_f32 v[56:57], v[56:57], s[66:67], v[0:1] op_sel_hi:[1,1,0]
	v_pk_add_f32 v[192:193], v[188:189], v[192:193]
	s_waitcnt lgkmcnt(0)
	v_mov_b32_e32 v188, v190
	v_mov_b32_e32 v189, v56
	v_mov_b32_e32 v196, v165
	v_mov_b32_e32 v197, v56
	v_mov_b32_e32 v163, v193
	v_pk_mul_f32 v[196:197], v[188:189], v[196:197]
	v_pk_mul_f32 v[198:199], v[192:193], v[162:163]
	v_mov_b32_e32 v200, v1
	v_pk_mov_b32 v[198:199], v[192:193], v[198:199] op_sel:[1,0]
	v_mov_b32_e32 v201, v196
	v_add_f32_e32 v194, 0, v10
	v_mov_b32_e32 v195, v191
	v_pk_fma_f32 v[188:189], v[192:193], v[162:163], v[196:197]
	v_pk_add_f32 v[196:197], v[198:199], v[200:201]
	v_mul_f32_e32 v0, 0x3fd744fd, v191
	v_pk_add_f32 v[198:199], v[56:57], v[196:197]
	v_pk_mul_f32 v[196:197], v[188:189], v[196:197] op_sel_hi:[0,1]
	v_pk_fma_f32 v[190:191], v[194:195], s[66:67], v[0:1] op_sel_hi:[1,1,0]
	v_mov_b32_e32 v199, v197
	v_pk_mul_f32 v[194:195], v[190:191], v[190:191]
	v_pk_add_f32 v[196:197], v[188:189], v[198:199]
	v_mov_b32_e32 v191, v194
	v_pk_add_f32 v[194:195], v[196:197], v[190:191]
	s_nop 1
	v_mov_b32_dpp v196, v194 quad_perm:[1,0,3,2] row_mask:0xf bank_mask:0xf bound_ctrl:1
	v_mov_b32_dpp v197, v195 quad_perm:[1,0,3,2] row_mask:0xf bank_mask:0xf bound_ctrl:1
	v_pk_add_f32 v[194:195], v[194:195], v[196:197]
	s_nop 1
	v_mov_b32_dpp v196, v194 quad_perm:[2,3,0,1] row_mask:0xf bank_mask:0xf bound_ctrl:1
	v_mov_b32_dpp v197, v195 quad_perm:[2,3,0,1] row_mask:0xf bank_mask:0xf bound_ctrl:1
	v_pk_add_f32 v[194:195], v[194:195], v[196:197]
	s_nop 1
	v_mov_b32_dpp v196, v194 row_half_mirror row_mask:0xf bank_mask:0xf bound_ctrl:1
	v_mov_b32_dpp v197, v195 row_half_mirror row_mask:0xf bank_mask:0xf bound_ctrl:1
	v_pk_add_f32 v[194:195], v[194:195], v[196:197]
	s_nop 1
	v_mov_b32_dpp v196, v194 row_mirror row_mask:0xf bank_mask:0xf bound_ctrl:1
	v_mov_b32_dpp v197, v195 row_mirror row_mask:0xf bank_mask:0xf bound_ctrl:1
	s_and_saveexec_b64 s[6:7], vcc
	v_pk_add_f32 v[194:195], v[194:195], v[196:197]
	ds_write_b64 v160, v[194:195] offset:384
	s_or_b64 exec, exec, s[6:7]
	ds_read2_b32 v[194:195], v98 offset1:32
	ds_read2_b32 v[196:197], v98 offset0:64 offset1:96
	v_add_f32_e32 v0, 0, v59
	v_add_f32_e32 v58, 0, v11
	v_mul_f32_e32 v11, 0.5, v0
	s_waitcnt lgkmcnt(1)
	v_mul_f32_e32 v199, 0x3fd744fd, v194
	v_mov_b32_e32 v26, v43
	v_mov_b32_e32 v10, v27
	v_mov_b32_e32 v198, v1
	v_pk_add_f32 v[200:201], v[26:27], 0 op_sel_hi:[1,0]
	v_pk_add_f32 v[42:43], v[10:11], v[198:199]
	v_mov_b32_e32 v10, v195
	s_waitcnt lgkmcnt(0)
;   DI void operator()(f32x16 (&acc)[2][4], int grow0, int gcol0, int lane, int w, char* lds) {
;     ...
; #pragma unroll
;       for (int qq = 0; qq < 2; ++qq)
; #pragma unroll
;         for (int e = 0; e < 4; ++e) {
;           const int i = 4 * (2 * (ps & 1) + qq) + e;
;           const float* xr = (const float*)(xs + (8 * qq + 4 * hh + e) * 512) + l31;
;           float s1 = 0.f, s2 = 0.f;
; #pragma unroll
;           for (int nt = 0; nt < 4; ++nt) {
;             float v = (acc[mt][nt][i] + bia[nt]) * csc[nt];
;             float z = ALPHA * xr[nt * 32] + hs * v;
;             acc[mt][nt][i] = z; s1 += z; s2 += z * z;
;           }
;           s1 = row16_sum(s1); s2 = row16_sum(s2);
;           if ((lane & 15) == 0) { f32x2 sv = {s1, s2}; *(f32x2*)(redw + (mt * 32 + (i & 3) + 8 * (i >> 2)) * 2) = sv; }
;         }
	v_mov_b32_e32 v11, v196
	s_mov_b32 s2, s67
	v_pk_mul_f32 v[26:27], v[10:11], s[2:3] op_sel_hi:[1,0]
	v_pk_mul_f32 v[194:195], v[200:201], 0.5 op_sel_hi:[1,0]
	v_pk_fma_f32 v[10:11], v[200:201], 0.5, v[26:27] op_sel_hi:[1,0,1]
	v_mov_b32_e32 v194, v43
	v_mov_b32_e32 v200, v1
	v_mov_b32_e32 v201, v27
	v_pk_mul_f32 v[198:199], v[10:11], v[10:11]
	v_pk_add_f32 v[194:195], v[194:195], v[200:201]
	v_mov_b32_e32 v163, v43
	v_pk_mov_b32 v[26:27], v[26:27], v[198:199] op_sel:[1,0]
	v_pk_add_f32 v[198:199], v[10:11], v[194:195]
	v_pk_mul_f32 v[194:195], v[10:11], v[194:195]
	v_mov_b32_e32 v59, v197
	v_pk_fma_f32 v[26:27], v[42:43], v[162:163], v[26:27]
	v_mov_b32_e32 v199, v195
	v_mul_f32_e32 v0, 0x3fd744fd, v197
	v_pk_add_f32 v[194:195], v[198:199], v[26:27]
	v_pk_fma_f32 v[26:27], v[58:59], s[66:67], v[0:1] op_sel_hi:[1,1,0]
	s_nop 0
	v_pk_mul_f32 v[58:59], v[26:27], v[26:27]
	s_nop 0
	v_mov_b32_e32 v27, v58
	v_pk_add_f32 v[58:59], v[194:195], v[26:27]
	s_nop 1
	v_mov_b32_dpp v194, v58 quad_perm:[1,0,3,2] row_mask:0xf bank_mask:0xf bound_ctrl:1
	v_mov_b32_dpp v195, v59 quad_perm:[1,0,3,2] row_mask:0xf bank_mask:0xf bound_ctrl:1
	v_pk_add_f32 v[58:59], v[58:59], v[194:195]
	s_nop 1
	v_mov_b32_dpp v194, v58 quad_perm:[2,3,0,1] row_mask:0xf bank_mask:0xf bound_ctrl:1
	v_mov_b32_dpp v195, v59 quad_perm:[2,3,0,1] row_mask:0xf bank_mask:0xf bound_ctrl:1
	v_pk_add_f32 v[58:59], v[58:59], v[194:195]
	s_nop 1
	v_mov_b32_dpp v194, v58 row_half_mirror row_mask:0xf bank_mask:0xf bound_ctrl:1
	v_mov_b32_dpp v195, v59 row_half_mirror row_mask:0xf bank_mask:0xf bound_ctrl:1
	v_pk_add_f32 v[58:59], v[58:59], v[194:195]
	s_nop 1
	v_mov_b32_dpp v194, v58 row_mirror row_mask:0xf bank_mask:0xf bound_ctrl:1
	v_mov_b32_dpp v195, v59 row_mirror row_mask:0xf bank_mask:0xf bound_ctrl:1
	s_and_saveexec_b64 s[6:7], vcc
	v_pk_add_f32 v[58:59], v[58:59], v[194:195]
	ds_write_b64 v160, v[58:59] offset:392
	s_or_b64 exec, exec, s[6:7]
	ds_read2_b32 v[58:59], v102 offset1:32
	ds_read2_b32 v[194:195], v102 offset0:64 offset1:96
	v_add_f32_e32 v0, 0, v60
	v_mov_b32_e32 v202, v44
	v_mov_b32_e32 v203, v28
	v_mul_f32_e32 v197, 0.5, v0
	s_waitcnt lgkmcnt(1)
	v_mul_f32_e32 v201, 0x3fd744fd, v58
	v_pk_add_f32 v[202:203], v[202:203], 0 op_sel_hi:[1,0]
	v_mov_b32_e32 v196, v28
	v_mov_b32_e32 v200, v1
	v_mov_b32_e32 v58, v59
	s_waitcnt lgkmcnt(0)
	v_mov_b32_e32 v59, v194
	s_mov_b32 s2, s67
	v_pk_add_f32 v[196:197], v[196:197], v[200:201]
	v_pk_mul_f32 v[200:201], v[58:59], s[2:3] op_sel_hi:[1,0]
	v_pk_mul_f32 v[204:205], v[202:203], 0.5 op_sel_hi:[1,0]
	v_pk_fma_f32 v[58:59], v[202:203], 0.5, v[200:201] op_sel_hi:[1,0,1]
	v_mov_b32_e32 v204, v197
	v_mov_b32_e32 v206, v1
	v_mov_b32_e32 v207, v201
	v_add_f32_e32 v198, 0, v12
	v_mov_b32_e32 v199, v195
	v_pk_mul_f32 v[202:203], v[58:59], v[58:59]
	v_pk_add_f32 v[204:205], v[204:205], v[206:207]
	v_mul_f32_e32 v0, 0x3fd744fd, v195
	v_mov_b32_e32 v163, v197
	v_pk_mov_b32 v[200:201], v[200:201], v[202:203] op_sel:[1,0]
	v_pk_add_f32 v[202:203], v[58:59], v[204:205]
	v_pk_mul_f32 v[204:205], v[58:59], v[204:205]
	v_pk_fma_f32 v[194:195], v[198:199], s[66:67], v[0:1] op_sel_hi:[1,1,0]
	v_pk_fma_f32 v[200:201], v[196:197], v[162:163], v[200:201]
	v_mov_b32_e32 v203, v205
	v_pk_mul_f32 v[198:199], v[194:195], v[194:195]
	v_pk_add_f32 v[200:201], v[202:203], v[200:201]
	v_mov_b32_e32 v195, v198
	v_pk_add_f32 v[198:199], v[200:201], v[194:195]
	s_nop 1
	v_mov_b32_dpp v200, v198 quad_perm:[1,0,3,2] row_mask:0xf bank_mask:0xf bound_ctrl:1
	v_mov_b32_dpp v201, v199 quad_perm:[1,0,3,2] row_mask:0xf bank_mask:0xf bound_ctrl:1
	v_pk_add_f32 v[198:199], v[198:199], v[200:201]
	s_nop 1
	v_mov_b32_dpp v200, v198 quad_perm:[2,3,0,1] row_mask:0xf bank_mask:0xf bound_ctrl:1
	v_mov_b32_dpp v201, v199 quad_perm:[2,3,0,1] row_mask:0xf bank_mask:0xf bound_ctrl:1
	v_pk_add_f32 v[198:199], v[198:199], v[200:201]
	s_nop 1
	v_mov_b32_dpp v200, v198 row_half_mirror row_mask:0xf bank_mask:0xf bound_ctrl:1
	v_mov_b32_dpp v201, v199 row_half_mirror row_mask:0xf bank_mask:0xf bound_ctrl:1
	v_pk_add_f32 v[198:199], v[198:199], v[200:201]
	s_nop 1
	v_mov_b32_dpp v200, v198 row_mirror row_mask:0xf bank_mask:0xf bound_ctrl:1
	v_mov_b32_dpp v201, v199 row_mirror row_mask:0xf bank_mask:0xf bound_ctrl:1
	s_and_saveexec_b64 s[6:7], vcc
	v_pk_add_f32 v[198:199], v[198:199], v[200:201]
	ds_write_b64 v160, v[198:199] offset:400
	s_or_b64 exec, exec, s[6:7]
	ds_read2_b32 v[198:199], v104 offset1:32
	ds_read2_b32 v[200:201], v104 offset0:64 offset1:96
	v_add_f32_e32 v0, 0, v61
	v_add_f32_e32 v60, 0, v13
	v_mul_f32_e32 v13, 0.5, v0
	s_waitcnt lgkmcnt(1)
	v_mul_f32_e32 v203, 0x3fd744fd, v198
	v_mov_b32_e32 v28, v45
	v_mov_b32_e32 v12, v29
	v_mov_b32_e32 v202, v1
	v_pk_add_f32 v[204:205], v[28:29], 0 op_sel_hi:[1,0]
	v_pk_add_f32 v[44:45], v[12:13], v[202:203]
	v_mov_b32_e32 v12, v199
	s_waitcnt lgkmcnt(0)
;   DI void operator()(f32x16 (&acc)[2][4], int grow0, int gcol0, int lane, int w, char* lds) {
;     ...
; #pragma unroll
;       for (int qq = 0; qq < 2; ++qq)
; #pragma unroll
;         for (int e = 0; e < 4; ++e) {
;           const int i = 4 * (2 * (ps & 1) + qq) + e;
;           const float* xr = (const float*)(xs + (8 * qq + 4 * hh + e) * 512) + l31;
;           float s1 = 0.f, s2 = 0.f;
; #pragma unroll
;           for (int nt = 0; nt < 4; ++nt) {
;             float v = (acc[mt][nt][i] + bia[nt]) * csc[nt];
;             float z = ALPHA * xr[nt * 32] + hs * v;
;             acc[mt][nt][i] = z; s1 += z; s2 += z * z;
;           }
;           s1 = row16_sum(s1); s2 = row16_sum(s2);
;           if ((lane & 15) == 0) { f32x2 sv = {s1, s2}; *(f32x2*)(redw + (mt * 32 + (i & 3) + 8 * (i >> 2)) * 2) = sv; }
;         }
	v_mov_b32_e32 v13, v200
	s_mov_b32 s2, s67
	v_pk_mul_f32 v[28:29], v[12:13], s[2:3] op_sel_hi:[1,0]
	v_pk_mul_f32 v[198:199], v[204:205], 0.5 op_sel_hi:[1,0]
	v_pk_fma_f32 v[12:13], v[204:205], 0.5, v[28:29] op_sel_hi:[1,0,1]
	v_mov_b32_e32 v198, v45
	v_mov_b32_e32 v204, v1
	v_mov_b32_e32 v205, v29
	v_pk_mul_f32 v[202:203], v[12:13], v[12:13]
	v_pk_add_f32 v[198:199], v[198:199], v[204:205]
	v_mov_b32_e32 v163, v45
	v_pk_mov_b32 v[28:29], v[28:29], v[202:203] op_sel:[1,0]
	v_pk_add_f32 v[202:203], v[12:13], v[198:199]
	v_pk_mul_f32 v[198:199], v[12:13], v[198:199]
	v_mov_b32_e32 v61, v201
	v_pk_fma_f32 v[28:29], v[44:45], v[162:163], v[28:29]
	v_mov_b32_e32 v203, v199
	v_mul_f32_e32 v0, 0x3fd744fd, v201
	v_pk_add_f32 v[198:199], v[202:203], v[28:29]
	v_pk_fma_f32 v[28:29], v[60:61], s[66:67], v[0:1] op_sel_hi:[1,1,0]
	s_nop 0
	v_pk_mul_f32 v[60:61], v[28:29], v[28:29]
	s_nop 0
	v_mov_b32_e32 v29, v60
	v_pk_add_f32 v[60:61], v[198:199], v[28:29]
	s_nop 1
	v_mov_b32_dpp v198, v60 quad_perm:[1,0,3,2] row_mask:0xf bank_mask:0xf bound_ctrl:1
	v_mov_b32_dpp v199, v61 quad_perm:[1,0,3,2] row_mask:0xf bank_mask:0xf bound_ctrl:1
	v_pk_add_f32 v[60:61], v[60:61], v[198:199]
	s_nop 1
	v_mov_b32_dpp v198, v60 quad_perm:[2,3,0,1] row_mask:0xf bank_mask:0xf bound_ctrl:1
	v_mov_b32_dpp v199, v61 quad_perm:[2,3,0,1] row_mask:0xf bank_mask:0xf bound_ctrl:1
	v_pk_add_f32 v[60:61], v[60:61], v[198:199]
	s_nop 1
	v_mov_b32_dpp v198, v60 row_half_mirror row_mask:0xf bank_mask:0xf bound_ctrl:1
	v_mov_b32_dpp v199, v61 row_half_mirror row_mask:0xf bank_mask:0xf bound_ctrl:1
	v_pk_add_f32 v[60:61], v[60:61], v[198:199]
	s_nop 1
	v_mov_b32_dpp v198, v60 row_mirror row_mask:0xf bank_mask:0xf bound_ctrl:1
	v_mov_b32_dpp v199, v61 row_mirror row_mask:0xf bank_mask:0xf bound_ctrl:1
	s_and_saveexec_b64 s[6:7], vcc
	v_pk_add_f32 v[60:61], v[60:61], v[198:199]
	ds_write_b64 v160, v[60:61] offset:408
	s_or_b64 exec, exec, s[6:7]
	ds_read2_b32 v[60:61], v93 offset1:32
	ds_read2_b32 v[198:199], v93 offset0:64 offset1:96
	v_add_f32_e32 v0, 0, v62
	v_mov_b32_e32 v206, v46
	v_mov_b32_e32 v207, v30
	v_mul_f32_e32 v201, 0.5, v0
	s_waitcnt lgkmcnt(1)
	v_mul_f32_e32 v205, 0x3fd744fd, v60
	v_pk_add_f32 v[206:207], v[206:207], 0 op_sel_hi:[1,0]
	v_mov_b32_e32 v200, v30
	v_mov_b32_e32 v204, v1
	v_mov_b32_e32 v60, v61
	s_waitcnt lgkmcnt(0)
	v_mov_b32_e32 v61, v198
	s_mov_b32 s2, s67
	v_pk_add_f32 v[200:201], v[200:201], v[204:205]
	v_pk_mul_f32 v[204:205], v[60:61], s[2:3] op_sel_hi:[1,0]
	v_pk_mul_f32 v[208:209], v[206:207], 0.5 op_sel_hi:[1,0]
	v_pk_fma_f32 v[60:61], v[206:207], 0.5, v[204:205] op_sel_hi:[1,0,1]
	v_mov_b32_e32 v208, v201
	v_mov_b32_e32 v212, v1
	v_mov_b32_e32 v213, v205
	v_add_f32_e32 v202, 0, v14
	v_mov_b32_e32 v203, v199
	v_pk_mul_f32 v[206:207], v[60:61], v[60:61]
	v_pk_add_f32 v[208:209], v[208:209], v[212:213]
	v_mul_f32_e32 v0, 0x3fd744fd, v199
	v_mov_b32_e32 v163, v201
	v_pk_mov_b32 v[204:205], v[204:205], v[206:207] op_sel:[1,0]
	v_pk_add_f32 v[206:207], v[60:61], v[208:209]
	v_pk_mul_f32 v[208:209], v[60:61], v[208:209]
	v_pk_fma_f32 v[198:199], v[202:203], s[66:67], v[0:1] op_sel_hi:[1,1,0]
	v_pk_fma_f32 v[204:205], v[200:201], v[162:163], v[204:205]
	v_mov_b32_e32 v207, v209
	v_pk_mul_f32 v[202:203], v[198:199], v[198:199]
	v_pk_add_f32 v[204:205], v[206:207], v[204:205]
	v_mov_b32_e32 v199, v202
	v_pk_add_f32 v[202:203], v[204:205], v[198:199]
	s_nop 1
	v_mov_b32_dpp v204, v202 quad_perm:[1,0,3,2] row_mask:0xf bank_mask:0xf bound_ctrl:1
	v_mov_b32_dpp v205, v203 quad_perm:[1,0,3,2] row_mask:0xf bank_mask:0xf bound_ctrl:1
	v_pk_add_f32 v[202:203], v[202:203], v[204:205]
	s_nop 1
	v_mov_b32_dpp v204, v202 quad_perm:[2,3,0,1] row_mask:0xf bank_mask:0xf bound_ctrl:1
	v_mov_b32_dpp v205, v203 quad_perm:[2,3,0,1] row_mask:0xf bank_mask:0xf bound_ctrl:1
	v_pk_add_f32 v[202:203], v[202:203], v[204:205]
	s_nop 1
	v_mov_b32_dpp v204, v202 row_half_mirror row_mask:0xf bank_mask:0xf bound_ctrl:1
	v_mov_b32_dpp v205, v203 row_half_mirror row_mask:0xf bank_mask:0xf bound_ctrl:1
	v_pk_add_f32 v[202:203], v[202:203], v[204:205]
	s_nop 1
	v_mov_b32_dpp v204, v202 row_mirror row_mask:0xf bank_mask:0xf bound_ctrl:1
	v_mov_b32_dpp v205, v203 row_mirror row_mask:0xf bank_mask:0xf bound_ctrl:1
	s_and_saveexec_b64 s[6:7], vcc
	v_pk_add_f32 v[202:203], v[202:203], v[204:205]
	ds_write_b64 v160, v[202:203] offset:448
	s_or_b64 exec, exec, s[6:7]
	ds_read2_b32 v[202:203], v106 offset1:32
	ds_read2_b32 v[204:205], v106 offset0:64 offset1:96
	v_add_f32_e32 v0, 0, v63
	v_add_f32_e32 v62, 0, v15
	v_mul_f32_e32 v15, 0.5, v0
	s_waitcnt lgkmcnt(1)
	v_mul_f32_e32 v207, 0x3fd744fd, v202
	v_mov_b32_e32 v30, v47
	v_mov_b32_e32 v14, v31
	v_mov_b32_e32 v206, v1
	v_pk_add_f32 v[208:209], v[30:31], 0 op_sel_hi:[1,0]
	v_pk_add_f32 v[46:47], v[14:15], v[206:207]
	v_mov_b32_e32 v14, v203
	s_waitcnt lgkmcnt(0)
;   DI void operator()(f32x16 (&acc)[2][4], int grow0, int gcol0, int lane, int w, char* lds) {
;     ...
; #pragma unroll
;       for (int qq = 0; qq < 2; ++qq)
; #pragma unroll
;         for (int e = 0; e < 4; ++e) {
;           const int i = 4 * (2 * (ps & 1) + qq) + e;
;           const float* xr = (const float*)(xs + (8 * qq + 4 * hh + e) * 512) + l31;
;           float s1 = 0.f, s2 = 0.f;
; #pragma unroll
;           for (int nt = 0; nt < 4; ++nt) {
;             float v = (acc[mt][nt][i] + bia[nt]) * csc[nt];
;             float z = ALPHA * xr[nt * 32] + hs * v;
;             acc[mt][nt][i] = z; s1 += z; s2 += z * z;
;           }
;           s1 = row16_sum(s1); s2 = row16_sum(s2);
;           if ((lane & 15) == 0) { f32x2 sv = {s1, s2}; *(f32x2*)(redw + (mt * 32 + (i & 3) + 8 * (i >> 2)) * 2) = sv; }
;         }
;     }
;     __syncthreads();
;     u64_t* myslots = xstat + ((size_t)pm * 256) * 4;
	v_mov_b32_e32 v15, v204
	s_mov_b32 s2, s67
	v_pk_mul_f32 v[30:31], v[14:15], s[2:3] op_sel_hi:[1,0]
	v_pk_mul_f32 v[202:203], v[208:209], 0.5 op_sel_hi:[1,0]
	v_pk_fma_f32 v[14:15], v[208:209], 0.5, v[30:31] op_sel_hi:[1,0,1]
	v_mov_b32_e32 v202, v47
	v_mov_b32_e32 v208, v1
	v_mov_b32_e32 v209, v31
	v_pk_mul_f32 v[206:207], v[14:15], v[14:15]
	v_pk_add_f32 v[202:203], v[202:203], v[208:209]
	v_mov_b32_e32 v163, v47
	v_pk_mov_b32 v[30:31], v[30:31], v[206:207] op_sel:[1,0]
	v_pk_add_f32 v[206:207], v[14:15], v[202:203]
	v_pk_mul_f32 v[202:203], v[14:15], v[202:203]
	v_mov_b32_e32 v63, v205
	v_pk_fma_f32 v[30:31], v[46:47], v[162:163], v[30:31]
	v_mov_b32_e32 v207, v203
	v_mul_f32_e32 v0, 0x3fd744fd, v205
	v_pk_add_f32 v[202:203], v[206:207], v[30:31]
	v_pk_fma_f32 v[30:31], v[62:63], s[66:67], v[0:1] op_sel_hi:[1,1,0]
	s_nop 0
	v_pk_mul_f32 v[62:63], v[30:31], v[30:31]
	s_nop 0
	v_mov_b32_e32 v31, v62
	v_pk_add_f32 v[62:63], v[202:203], v[30:31]
	s_nop 1
	v_mov_b32_dpp v202, v62 quad_perm:[1,0,3,2] row_mask:0xf bank_mask:0xf bound_ctrl:1
	v_mov_b32_dpp v203, v63 quad_perm:[1,0,3,2] row_mask:0xf bank_mask:0xf bound_ctrl:1
	v_pk_add_f32 v[62:63], v[62:63], v[202:203]
	s_nop 1
	v_mov_b32_dpp v202, v62 quad_perm:[2,3,0,1] row_mask:0xf bank_mask:0xf bound_ctrl:1
	v_mov_b32_dpp v203, v63 quad_perm:[2,3,0,1] row_mask:0xf bank_mask:0xf bound_ctrl:1
	v_pk_add_f32 v[62:63], v[62:63], v[202:203]
	s_nop 1
	v_mov_b32_dpp v202, v62 row_half_mirror row_mask:0xf bank_mask:0xf bound_ctrl:1
	v_mov_b32_dpp v203, v63 row_half_mirror row_mask:0xf bank_mask:0xf bound_ctrl:1
	v_pk_add_f32 v[62:63], v[62:63], v[202:203]
	s_nop 1
	v_mov_b32_dpp v202, v62 row_mirror row_mask:0xf bank_mask:0xf bound_ctrl:1
	v_mov_b32_dpp v203, v63 row_mirror row_mask:0xf bank_mask:0xf bound_ctrl:1
	s_and_saveexec_b64 s[6:7], vcc
	v_pk_add_f32 v[62:63], v[62:63], v[202:203]
	ds_write_b64 v160, v[62:63] offset:456
	s_or_b64 exec, exec, s[6:7]
	ds_read2_b32 v[62:63], v95 offset1:32
	ds_read2_b32 v[202:203], v95 offset0:64 offset1:96
	v_add_f32_e32 v0, 0, v64
	v_mov_b32_e32 v212, v48
	v_mov_b32_e32 v213, v32
	v_mul_f32_e32 v205, 0.5, v0
	s_waitcnt lgkmcnt(1)
	v_mul_f32_e32 v209, 0x3fd744fd, v62
	v_pk_add_f32 v[212:213], v[212:213], 0 op_sel_hi:[1,0]
	v_mov_b32_e32 v204, v32
	v_mov_b32_e32 v208, v1
	v_mov_b32_e32 v62, v63
	s_waitcnt lgkmcnt(0)
	v_mov_b32_e32 v63, v202
	s_mov_b32 s2, s67
	v_pk_add_f32 v[204:205], v[204:205], v[208:209]
	v_pk_mul_f32 v[208:209], v[62:63], s[2:3] op_sel_hi:[1,0]
	v_pk_mul_f32 v[214:215], v[212:213], 0.5 op_sel_hi:[1,0]
	v_pk_fma_f32 v[62:63], v[212:213], 0.5, v[208:209] op_sel_hi:[1,0,1]
	v_mov_b32_e32 v214, v205
	v_mov_b32_e32 v226, v1
	v_mov_b32_e32 v227, v209
	v_add_f32_e32 v206, 0, v16
	v_mov_b32_e32 v207, v203
	v_pk_mul_f32 v[212:213], v[62:63], v[62:63]
	v_pk_add_f32 v[214:215], v[214:215], v[226:227]
	v_mul_f32_e32 v0, 0x3fd744fd, v203
	v_mov_b32_e32 v163, v205
	v_pk_mov_b32 v[208:209], v[208:209], v[212:213] op_sel:[1,0]
	v_pk_add_f32 v[212:213], v[62:63], v[214:215]
	v_pk_mul_f32 v[214:215], v[62:63], v[214:215]
	v_pk_fma_f32 v[202:203], v[206:207], s[66:67], v[0:1] op_sel_hi:[1,1,0]
	v_pk_fma_f32 v[208:209], v[204:205], v[162:163], v[208:209]
	v_mov_b32_e32 v213, v215
	v_pk_mul_f32 v[206:207], v[202:203], v[202:203]
	v_pk_add_f32 v[208:209], v[212:213], v[208:209]
	v_mov_b32_e32 v203, v206
	v_pk_add_f32 v[206:207], v[208:209], v[202:203]
	s_nop 1
	v_mov_b32_dpp v208, v206 quad_perm:[1,0,3,2] row_mask:0xf bank_mask:0xf bound_ctrl:1
	v_mov_b32_dpp v209, v207 quad_perm:[1,0,3,2] row_mask:0xf bank_mask:0xf bound_ctrl:1
	v_pk_add_f32 v[206:207], v[206:207], v[208:209]
	s_nop 1
	v_mov_b32_dpp v208, v206 quad_perm:[2,3,0,1] row_mask:0xf bank_mask:0xf bound_ctrl:1
	v_mov_b32_dpp v209, v207 quad_perm:[2,3,0,1] row_mask:0xf bank_mask:0xf bound_ctrl:1
	v_pk_add_f32 v[206:207], v[206:207], v[208:209]
	s_nop 1
	v_mov_b32_dpp v208, v206 row_half_mirror row_mask:0xf bank_mask:0xf bound_ctrl:1
	v_mov_b32_dpp v209, v207 row_half_mirror row_mask:0xf bank_mask:0xf bound_ctrl:1
	v_pk_add_f32 v[206:207], v[206:207], v[208:209]
	s_nop 1
	v_mov_b32_dpp v208, v206 row_mirror row_mask:0xf bank_mask:0xf bound_ctrl:1
	v_mov_b32_dpp v209, v207 row_mirror row_mask:0xf bank_mask:0xf bound_ctrl:1
	s_and_saveexec_b64 s[6:7], vcc
	v_pk_add_f32 v[206:207], v[206:207], v[208:209]
	ds_write_b64 v160, v[206:207] offset:464
	s_or_b64 exec, exec, s[6:7]
	v_add_f32_e32 v0, 0, v65
	ds_read2_b32 v[64:65], v91 offset1:32
	ds_read2_b32 v[212:213], v91 offset0:64 offset1:96
	v_mov_b32_e32 v32, v49
	v_mul_f32_e32 v209, 0.5, v0
	v_add_f32_e32 v214, 0, v17
	s_waitcnt lgkmcnt(1)
	v_mul_f32_e32 v207, 0x3fd744fd, v64
	v_pk_add_f32 v[16:17], v[32:33], 0 op_sel_hi:[1,0]
	v_mov_b32_e32 v208, v33
	v_mov_b32_e32 v206, v1
	v_mov_b32_e32 v32, v65
	s_waitcnt lgkmcnt(0)
	v_mov_b32_e32 v33, v212
	s_mov_b32 s2, s67
	v_pk_add_f32 v[48:49], v[208:209], v[206:207]
	v_pk_mul_f32 v[32:33], v[32:33], s[2:3] op_sel_hi:[1,0]
	v_pk_mul_f32 v[64:65], v[16:17], 0.5 op_sel_hi:[1,0]
	v_pk_fma_f32 v[16:17], v[16:17], 0.5, v[32:33] op_sel_hi:[1,0,1]
	v_mov_b32_e32 v64, v49
	v_mov_b32_e32 v208, v1
	v_mov_b32_e32 v209, v33
	v_pk_mul_f32 v[206:207], v[16:17], v[16:17]
	v_pk_add_f32 v[64:65], v[64:65], v[208:209]
	v_mov_b32_e32 v163, v49
	v_pk_mov_b32 v[32:33], v[32:33], v[206:207] op_sel:[1,0]
	v_pk_add_f32 v[206:207], v[16:17], v[64:65]
	v_pk_mul_f32 v[64:65], v[16:17], v[64:65]
	v_mov_b32_e32 v215, v213
	v_pk_fma_f32 v[32:33], v[48:49], v[162:163], v[32:33]
	v_mov_b32_e32 v207, v65
	v_mul_f32_e32 v0, 0x3fd744fd, v213
	v_pk_add_f32 v[64:65], v[206:207], v[32:33]
	v_pk_fma_f32 v[32:33], v[214:215], s[66:67], v[0:1] op_sel_hi:[1,1,0]
	s_nop 0
	v_pk_mul_f32 v[206:207], v[32:33], v[32:33]
	s_nop 0
	v_mov_b32_e32 v33, v206
	v_pk_add_f32 v[64:65], v[64:65], v[32:33]
	s_nop 1
	v_mov_b32_dpp v206, v64 quad_perm:[1,0,3,2] row_mask:0xf bank_mask:0xf bound_ctrl:1
	v_mov_b32_dpp v207, v65 quad_perm:[1,0,3,2] row_mask:0xf bank_mask:0xf bound_ctrl:1
	v_pk_add_f32 v[64:65], v[64:65], v[206:207]
	s_nop 1
	v_mov_b32_dpp v206, v64 quad_perm:[2,3,0,1] row_mask:0xf bank_mask:0xf bound_ctrl:1
	v_mov_b32_dpp v207, v65 quad_perm:[2,3,0,1] row_mask:0xf bank_mask:0xf bound_ctrl:1
	v_pk_add_f32 v[64:65], v[64:65], v[206:207]
	s_nop 1
	v_mov_b32_dpp v206, v64 row_half_mirror row_mask:0xf bank_mask:0xf bound_ctrl:1
	v_mov_b32_dpp v207, v65 row_half_mirror row_mask:0xf bank_mask:0xf bound_ctrl:1
	v_pk_add_f32 v[64:65], v[64:65], v[206:207]
	s_nop 1
	v_mov_b32_dpp v206, v64 row_mirror row_mask:0xf bank_mask:0xf bound_ctrl:1
	v_mov_b32_dpp v207, v65 row_mirror row_mask:0xf bank_mask:0xf bound_ctrl:1
	s_and_saveexec_b64 s[6:7], vcc
	v_pk_add_f32 v[64:65], v[64:65], v[206:207]
	ds_write_b64 v160, v[64:65] offset:472
	s_or_b64 exec, exec, s[6:7]
	v_ashrrev_i32_e32 v206, 8, v164
	v_ashrrev_i32_e32 v207, 31, v206
	v_lshlrev_b64 v[64:65], 13, v[206:207]
	v_lshl_add_u64 v[64:65], s[8:9], 0, v[64:65]
	v_cmp_gt_i32_e64 s[40:41], s60, v210
	v_ashrrev_i32_e32 v169, 31, v168
	s_waitcnt lgkmcnt(0)
	s_barrier
; DI void ag_st64(u64_t* p, u64_t v) { __hip_atomic_store(p, v, __ATOMIC_RELAXED, __HIP_MEMORY_SCOPE_AGENT); }
;   DI void operator()(f32x16 (&acc)[2][4], int grow0, int gcol0, int lane, int w, char* lds) {
;     ...
;     if (tid < 256) {
;       float s1 = (red[tid * 2] + red[(256 + tid) * 2]) + (red[(512 + tid) * 2] + red[(768 + tid) * 2]);
;       float s2 = (red[tid * 2 + 1] + red[(256 + tid) * 2 + 1]) + (red[(512 + tid) * 2 + 1] + red[(768 + tid) * 2 + 1]);
;       ag_st64(myslots + tid * 4 + pn, ((u64_t)__float_as_uint(s2) << 32) | (u64_t)__float_as_uint(s1));
;     }
	s_and_saveexec_b64 s[6:7], s[40:41]
	s_cbranch_execz .LBB0_359
	v_lshl_add_u32 v0, v210, 3, v221
	ds_read2st64_b64 v[212:215], v0 offset1:4
	ds_read2st64_b64 v[226:229], v0 offset0:8 offset1:12
	v_ashrrev_i32_e32 v208, 8, v154
	v_ashrrev_i32_e32 v209, 31, v208
	s_waitcnt lgkmcnt(1)
	v_mov_b32_e32 v230, v212
	s_waitcnt lgkmcnt(0)
	v_mov_b32_e32 v231, v226
	v_mov_b32_e32 v232, v214
	v_mov_b32_e32 v233, v228
	v_mov_b32_e32 v226, v213
	v_mov_b32_e32 v228, v215
	v_pk_add_f32 v[230:231], v[230:231], v[232:233]
	v_pk_add_f32 v[212:213], v[226:227], v[228:229]
	v_pk_add_f32 v[230:231], v[230:231], v[230:231] op_sel:[0,1] op_sel_hi:[1,0]
	v_pk_add_f32 v[212:213], v[212:213], v[212:213] op_sel:[0,1] op_sel_hi:[1,0]
	v_lshl_add_u64 v[214:215], v[168:169], 3, v[64:65]
	v_lshl_add_u64 v[208:209], v[208:209], 3, v[214:215]
	v_mov_b32_e32 v231, v212
	global_store_dwordx2 v[208:209], v[230:231], off sc1

; DI int launder(int x) { asm volatile("" : "+v"(x)); return x; }
;     ...
;   { const int tid2 = launder(threadIdx.x); epi(acc, row0 + (((tid2 >> 6) % WM) * 64), col0 + (((tid2 >> 6) / WM) * (32 * NTW)), tid2 & 63, tid2 >> 6, lds); }
;   DI void operator()(f32x16 (&acc)[2][4], int grow0, int gcol0, int lane, int w, char* lds) {
;     const int l31 = lane & 31, hh = lane >> 5;
;     const int part = gcol0 >> 10, cin = gcol0 & 1023;
;     if (part < 2) {
.LBB0_522:
	v_mov_b32_e32 v134, v216
	s_lshl_b32 s2, s2, 8
	v_ashrrev_i32_e32 v133, 6, v134
	v_lshrrev_b32_e32 v0, 30, v133
	v_add_u32_e32 v0, v133, v0
	v_ashrrev_i32_e32 v130, 2, v0
	v_mul_i32_i24_e32 v0, 4, v130
	v_sub_u32_e32 v0, v133, v0
	v_lshl_add_u32 v0, v0, 6, s2
	v_lshl_add_u32 v132, v130, 7, s6
	s_movk_i32 s2, 0x7ff
	v_and_b32_e32 v138, 31, v134
	v_bfe_u32 v130, v134, 5, 1
	v_and_b32_e32 v131, 0x380, v132
	v_cmp_lt_i32_e32 vcc, s2, v132
	s_and_saveexec_b64 s[2:3], vcc
	s_xor_b64 s[6:7], exec, s[2:3]
	s_cbranch_execz .LBB0_524
; DI unsigned pack2(float lo, float hi) { f32x2 v = {lo, hi}; bf2_t r = __builtin_convertvector(v, bf2_t); return __builtin_bit_cast(unsigned, r); }
; DI void tr_put(char* stg, int erow, const f32x16& v, int hh, float mul) {
; #pragma unroll
;   for (int qd = 0; qd < 4; ++qd) {
;     u32x2 pk; pk.x = pack2(v[4 * qd] * mul, v[4 * qd + 1] * mul); pk.y = pack2(v[4 * qd + 2] * mul, v[4 * qd + 3] * mul);
;     *(u32x2*)(stg + erow * 64 + (8 * qd + 4 * hh) * 2) = pk;
;   }
; }
; template <int R>
; DI void tr_flush(const char* stg, int row0, bf16_t* g, size_t grs, int lane) {
;   const int r0 = lane >> 2, ch = lane & 3;
; #pragma unroll
;   for (int it = 0; it < R / 16; ++it) {
;     const int r = it * 16 + r0;
;     u32x4 v = *(const u32x4*)(stg + (row0 + r) * 64 + ch * 16);
;     *(u32x4*)((char*)(g + (size_t)r * grs) + ch * 16) = v;
;   }
; }
;   DI void operator()(f32x16 (&acc)[2][4], int grow0, int gcol0, int lane, int w, char* lds) {
;     ...
;     } else {
;       const int b = grow0 >> 11, s0 = grow0 & 2047, h = cin >> 7;
;       char* stg = tr_stage(lds, w);
; #pragma unroll
;       for (int mt = 0; mt < 2; ++mt) {
; #pragma unroll
;         for (int nt = 0; nt < 4; ++nt) tr_put(stg, nt * 32 + l31, acc[mt][nt], hh, 1.f);
;         tr_flush<128>(stg, 0, Vt + ((size_t)(b * 8 + h) * 128) * S_ + s0 + mt * 32, S_, lane);
;       }
;     }
	v_lshl_add_u32 v133, v133, 13, v224
	v_lshlrev_b32_e32 v135, 6, v138
	v_lshlrev_b32_e32 v130, 3, v130
	v_and_b32_e32 v132, 63, v134
	v_and_b32_e32 v134, 0x7c0, v0
	v_lshrrev_b32_e32 v131, 7, v131
	v_or3_b32 v135, v133, v135, v130
	v_ashrrev_i32_e32 v0, 8, v0
	v_cvt_pk_bf16_f32 v66, v66, v67
	v_cvt_pk_bf16_f32 v67, v68, v69
	v_and_or_b32 v130, v0, -8, v131
	v_cvt_pk_bf16_f32 v114, v114, v115
	v_cvt_pk_bf16_f32 v115, v116, v117
	ds_write_b64 v135, v[66:67] offset:6144
	v_cvt_pk_bf16_f32 v66, v70, v71
	v_cvt_pk_bf16_f32 v67, v72, v73
	v_ashrrev_i32_e32 v131, 31, v130
	v_lshlrev_b32_e32 v0, 4, v132
	ds_write_b64 v135, v[114:115]
	v_cvt_pk_bf16_f32 v114, v118, v119
	v_cvt_pk_bf16_f32 v115, v120, v121
	ds_write_b64 v135, v[66:67] offset:6160
	v_cvt_pk_bf16_f32 v66, v74, v75
	v_cvt_pk_bf16_f32 v67, v76, v77
	v_lshlrev_b64 v[130:131], 19, v[130:131]
	v_lshrrev_b32_e32 v136, 2, v132
	v_and_b32_e32 v0, 48, v0
	ds_write_b64 v135, v[114:115] offset:16
	v_cvt_pk_bf16_f32 v114, v122, v123
	v_cvt_pk_bf16_f32 v115, v124, v125
	ds_write_b64 v135, v[66:67] offset:6176
	v_cvt_pk_bf16_f32 v66, v78, v79
	v_cvt_pk_bf16_f32 v67, v80, v81
	v_or_b32_e32 v132, v133, v0
	v_or_b32_e32 v137, 16, v136
	ds_write_b64 v135, v[114:115] offset:32
	v_cvt_pk_bf16_f32 v114, v126, v127
	v_cvt_pk_bf16_f32 v115, v128, v129
	ds_write_b64 v135, v[66:67] offset:6192
	v_lshl_add_u64 v[66:67], s[82:83], 0, v[130:131]
	v_lshlrev_b32_e32 v68, 1, v134
	v_mov_b32_e32 v69, v1
	v_lshl_or_b32 v138, v137, 6, v132
	ds_write_b64 v135, v[114:115] offset:48
	v_lshl_add_u64 v[70:71], v[66:67], 0, v[68:69]
	v_cvt_pk_bf16_f32 v98, v98, v99
	v_cvt_pk_bf16_f32 v99, v100, v101
	v_lshl_add_u64 v[74:75], v[70:71], 0, v[0:1]
	ds_read_b128 v[70:73], v138
	ds_write_b64 v135, v[98:99] offset:2048
	v_cvt_pk_bf16_f32 v98, v102, v103
	v_cvt_pk_bf16_f32 v99, v104, v105
	ds_write_b64 v135, v[98:99] offset:2064
	v_cvt_pk_bf16_f32 v98, v106, v107
	v_cvt_pk_bf16_f32 v99, v108, v109
	v_lshlrev_b32_e32 v0, 12, v136
	v_or_b32_e32 v141, 48, v136
	ds_write_b64 v135, v[98:99] offset:2080
	v_cvt_pk_bf16_f32 v98, v110, v111
	v_cvt_pk_bf16_f32 v99, v112, v113
	v_lshl_add_u64 v[76:77], v[74:75], 0, v[0:1]
	v_lshlrev_b32_e32 v0, 12, v137
	v_lshl_or_b32 v142, v141, 6, v132
	ds_write_b64 v135, v[98:99] offset:2096
	v_lshl_add_u64 v[78:79], v[74:75], 0, v[0:1]
	v_cvt_pk_bf16_f32 v82, v82, v83
	v_cvt_pk_bf16_f32 v83, v84, v85
	s_waitcnt lgkmcnt(0)
	global_store_dwordx4 v[78:79], v[70:73], off
	ds_read_b128 v[70:73], v142
	v_or_b32_e32 v139, 32, v136
	ds_write_b64 v135, v[82:83] offset:4096
	v_cvt_pk_bf16_f32 v82, v86, v87
	v_cvt_pk_bf16_f32 v83, v88, v89
	ds_write_b64 v135, v[82:83] offset:4112
	v_cvt_pk_bf16_f32 v82, v90, v91
	v_cvt_pk_bf16_f32 v83, v92, v93
	v_lshlrev_b32_e32 v0, 12, v139
	v_or_b32_e32 v145, 0x50, v136
	ds_write_b64 v135, v[82:83] offset:4128
	v_cvt_pk_bf16_f32 v82, v94, v95
	v_cvt_pk_bf16_f32 v83, v96, v97
	v_lshl_add_u64 v[80:81], v[74:75], 0, v[0:1]
	v_lshlrev_b32_e32 v0, 12, v141
	v_lshl_or_b32 v133, v136, 6, v132
	v_lshl_or_b32 v146, v145, 6, v132
	ds_write_b64 v135, v[82:83] offset:4144
	v_lshl_add_u64 v[82:83], v[74:75], 0, v[0:1]
	ds_read_b128 v[66:69], v133
	s_waitcnt lgkmcnt(5)
	global_store_dwordx4 v[82:83], v[70:73], off
	ds_read_b128 v[70:73], v146
	v_or_b32_e32 v143, 64, v136
	v_lshlrev_b32_e32 v0, 12, v143
	v_or_b32_e32 v147, 0x60, v136
	v_or_b32_e32 v149, 0x70, v136
	v_lshl_add_u64 v[84:85], v[74:75], 0, v[0:1]
	v_lshlrev_b32_e32 v0, 12, v145
	v_lshl_or_b32 v140, v139, 6, v132
	v_lshl_or_b32 v144, v143, 6, v132
	v_lshl_or_b32 v148, v147, 6, v132
	v_lshl_or_b32 v132, v149, 6, v132
	v_lshl_add_u64 v[86:87], v[74:75], 0, v[0:1]
	s_waitcnt lgkmcnt(0)
	global_store_dwordx4 v[86:87], v[70:73], off
	ds_read_b128 v[70:73], v132
	global_store_dwordx4 v[76:77], v[66:69], off
	ds_read_b128 v[66:69], v140
	v_cvt_pk_bf16_f32 v50, v50, v51
	v_cvt_pk_bf16_f32 v51, v52, v53
	v_cvt_pk_bf16_f32 v34, v34, v35
	v_cvt_pk_bf16_f32 v35, v36, v37
	s_waitcnt lgkmcnt(0)
	global_store_dwordx4 v[80:81], v[66:69], off
	ds_read_b128 v[66:69], v144
	v_cvt_pk_bf16_f32 v18, v18, v19
	v_cvt_pk_bf16_f32 v19, v20, v21
	v_lshlrev_b32_e32 v0, 12, v147
	ds_write_b64 v135, v[50:51]
	s_waitcnt lgkmcnt(1)
	global_store_dwordx4 v[84:85], v[66:69], off
	ds_read_b128 v[66:69], v148
	v_cvt_pk_bf16_f32 v50, v54, v55
	v_cvt_pk_bf16_f32 v51, v56, v57
	ds_write_b64 v135, v[34:35] offset:2048
	v_cvt_pk_bf16_f32 v34, v38, v39
	v_cvt_pk_bf16_f32 v35, v40, v41
	ds_write_b64 v135, v[18:19] offset:4096
	v_cvt_pk_bf16_f32 v18, v22, v23
	v_cvt_pk_bf16_f32 v19, v24, v25
	v_cvt_pk_bf16_f32 v2, v2, v3
	v_cvt_pk_bf16_f32 v3, v4, v5
	v_lshl_add_u64 v[88:89], v[74:75], 0, v[0:1]
	v_lshlrev_b32_e32 v0, 12, v149
	ds_write_b64 v135, v[50:51] offset:16
	v_cvt_pk_bf16_f32 v50, v58, v59
	v_cvt_pk_bf16_f32 v51, v60, v61
	ds_write_b64 v135, v[34:35] offset:2064
	v_cvt_pk_bf16_f32 v34, v42, v43
	v_cvt_pk_bf16_f32 v35, v44, v45
	ds_write_b64 v135, v[18:19] offset:4112
	v_cvt_pk_bf16_f32 v18, v26, v27
	v_cvt_pk_bf16_f32 v19, v28, v29
	ds_write_b64 v135, v[2:3] offset:6144
	v_cvt_pk_bf16_f32 v2, v6, v7
	v_cvt_pk_bf16_f32 v3, v8, v9
	s_waitcnt lgkmcnt(6)
	global_store_dwordx4 v[88:89], v[66:69], off
	ds_write_b64 v135, v[50:51] offset:32
	v_cvt_pk_bf16_f32 v50, v62, v63
	v_lshl_add_u64 v[66:67], v[74:75], 0, v[0:1]
	v_cvt_pk_bf16_f32 v51, v64, v65
	ds_write_b64 v135, v[34:35] offset:2080
	v_cvt_pk_bf16_f32 v34, v46, v47
	v_cvt_pk_bf16_f32 v35, v48, v49
	ds_write_b64 v135, v[18:19] offset:4128
	v_cvt_pk_bf16_f32 v18, v30, v31
	v_cvt_pk_bf16_f32 v19, v32, v33
	ds_write_b64 v135, v[2:3] offset:6160
	v_cvt_pk_bf16_f32 v2, v10, v11
	v_cvt_pk_bf16_f32 v3, v12, v13
	global_store_dwordx4 v[66:67], v[70:73], off
	ds_write_b64 v135, v[50:51] offset:48
	ds_write_b64 v135, v[34:35] offset:2096
	ds_write_b64 v135, v[18:19] offset:4144
	ds_write_b64 v135, v[2:3] offset:6176
	ds_read_b128 v[2:5], v133
	ds_read_b128 v[6:9], v138
	ds_read_b128 v[10:13], v140
	v_cvt_pk_bf16_f32 v14, v14, v15
	v_cvt_pk_bf16_f32 v15, v16, v17
	ds_write_b64 v135, v[14:15] offset:6192
	s_waitcnt lgkmcnt(3)
	global_store_dwordx4 v[76:77], v[2:5], off offset:64
	s_waitcnt lgkmcnt(2)
	global_store_dwordx4 v[78:79], v[6:9], off offset:64
	s_waitcnt lgkmcnt(1)
	global_store_dwordx4 v[80:81], v[10:13], off offset:64
	ds_read_b128 v[2:5], v142
	ds_read_b128 v[6:9], v144
	ds_read_b128 v[10:13], v146
	ds_read_b128 v[14:17], v148
	ds_read_b128 v[18:21], v132
	s_waitcnt lgkmcnt(4)
	global_store_dwordx4 v[82:83], v[2:5], off offset:64
	s_waitcnt lgkmcnt(3)
	global_store_dwordx4 v[84:85], v[6:9], off offset:64
	s_waitcnt lgkmcnt(2)
	global_store_dwordx4 v[86:87], v[10:13], off offset:64
	s_waitcnt lgkmcnt(1)
	global_store_dwordx4 v[88:89], v[14:17], off offset:64
	s_waitcnt lgkmcnt(0)
	global_store_dwordx4 v[66:67], v[18:21], off offset:64

; DI f32x16 mfma(bf16x8 a, bf16x8 b, f32x16 c) { return __builtin_amdgcn_mfma_f32_32x32x16_bf16(a, b, c, 0, 0, 0); }
; template <int BK> DI int swz(int row) { constexpr int CPR = BK / 8; return (row / (16 / CPR)) % CPR; }
; DI void wait_vm0() { asm volatile("s_waitcnt vmcnt(0)" ::: "memory"); }
;   DI void pre(int grow0, int gcol0, int lane, int w, char* lds) { xpass(0, grow0, gcol0, lane, w, lds); }
;     ...
;   for (int kt = 0; kt < nk; ++kt) {
;     char* cur = lds + (kt & 1) * STG; char* nxt = lds + ((kt + 1) & 1) * STG;
;     const bool more = kt + 1 < nk;
;     const bf16_t* An = Ag + (kt + 1) * BK; const bf16_t* Bn = Bg + (kt + 1) * BK;
;     if (!more) epi.pre(row0 + wm * 64, col0 + wn * (32 * NTW), lane, w, lds);
;     bf16x8 fa[2][2], fb[2][NTW];
; #pragma unroll
;     for (int mt = 0; mt < 2; ++mt) { int row = wm * 64 + mt * 32 + l31; fa[0][mt] = *(const bf16x8*)(cur + row * (BK * 2) + ((hh ^ swz<BK>(row)) << 4)); }
; #pragma unroll
;     for (int nt = 0; nt < NTW; ++nt) { int row = wn * (32 * NTW) + nt * 32 + l31; fb[0][nt] = *(const bf16x8*)(cur + ABYTES + row * (BK * 2) + ((hh ^ swz<BK>(row)) << 4)); }
; #pragma unroll
;     for (int kk = 0; kk < NKK; ++kk) {
;       if (kk + 1 < NKK) {
;         const int ch = (kk + 1) * 2 + hh;
; #pragma unroll
;         for (int mt = 0; mt < 2; ++mt) { int row = wm * 64 + mt * 32 + l31; fa[(kk + 1) & 1][mt] = *(const bf16x8*)(cur + row * (BK * 2) + ((ch ^ swz<BK>(row)) << 4)); }
; #pragma unroll
;         for (int nt = 0; nt < NTW; ++nt) { int row = wn * (32 * NTW) + nt * 32 + l31; fb[(kk + 1) & 1][nt] = *(const bf16x8*)(cur + ABYTES + row * (BK * 2) + ((ch ^ swz<BK>(row)) << 4)); }
;       }
;       if (more) {
; #pragma unroll
;         for (int q = 0; q < PPK; ++q) {
;           const int pi = kk * PPK + q;
;           if (pi < NPA) stage_piece<BM, BK>(An, lda, nxt, tid, pi, wv);
;           else if (pi < NP) stage_piece<BN, BK>(Bn, ldb, nxt + ABYTES, tid, pi - NPA, wv);
;         }
;       }
;       __builtin_amdgcn_s_setprio(1);
; #pragma unroll
;       for (int mt = 0; mt < 2; ++mt)
; #pragma unroll
;         for (int nt = 0; nt < NTW; ++nt) acc[mt][nt] = mfma(fa[kk & 1][mt], fb[kk & 1][nt], acc[mt][nt]);
;       __builtin_amdgcn_s_setprio(0);
;       __builtin_amdgcn_sched_barrier(0);
;     }
;     wait_vm0();
;     __syncthreads();
.LBB0_532:
	s_add_i32 s7, s3, 0xffff0000
	s_and_b32 s30, s7, 0x10000
	s_and_b32 s7, s3, 0x10000
	v_add_u32_e32 v217, s30, v136
	v_add_u32_e32 v219, s30, v144
	v_add_u32_e32 v234, s30, v145
	v_add_u32_e32 v235, s30, v150
	v_add_u32_e32 v236, s30, v156
	v_add_u32_e32 v237, s30, v158
	s_lshl_b64 s[30:31], s[92:93], 1
	v_lshl_add_u64 v[214:215], v[132:133], 0, s[30:31]
	v_lshl_add_u64 v[230:231], v[130:131], 0, s[30:31]
	s_add_i32 s30, s7, s2
	v_add_u32_e32 v170, v217, v143
	v_add_u32_e32 v174, v219, v146
	v_add_u32_e32 v178, v234, v149
	v_add_u32_e32 v182, v235, v155
	v_add_u32_e32 v186, v236, v157
	v_add_u32_e32 v190, v237, v168
	v_add_u32_e32 v194, v217, v166
	v_add_u32_e32 v198, v219, v167
	v_add_u32_e32 v202, v234, v163
	v_add_u32_e32 v206, v235, v164
	v_add_u32_e32 v210, v236, v159
	v_add_u32_e32 v226, v237, v160
	s_mov_b32 m0, s30
	ds_read_b128 v[170:173], v170
	ds_read_b128 v[174:177], v174
	ds_read_b128 v[178:181], v178 offset:32768
	ds_read_b128 v[182:185], v182 offset:32768
	ds_read_b128 v[186:189], v186 offset:32768
	ds_read_b128 v[190:193], v190 offset:32768
	ds_read_b128 v[194:197], v194
	ds_read_b128 v[198:201], v198
	ds_read_b128 v[202:205], v202 offset:32768
	ds_read_b128 v[206:209], v206 offset:32768
	ds_read_b128 v[210:213], v210 offset:32768
	ds_read_b128 v[226:229], v226 offset:32768
	global_load_lds_dwordx4 v[230:231], off
	v_lshl_add_u64 v[232:233], v[230:231], 0, s[36:37]
	s_add_i32 m0, s30, 0x2000
	s_add_i32 s31, s30, 0x8000
	global_load_lds_dwordx4 v[232:233], off
	s_setprio 1
	s_waitcnt lgkmcnt(0)
	v_mfma_f32_32x32x16_bf16 v[114:129], v[170:173], v[178:181], v[114:129]
	v_mfma_f32_32x32x16_bf16 v[98:113], v[170:173], v[182:185], v[98:113]
	v_mfma_f32_32x32x16_bf16 v[82:97], v[170:173], v[186:189], v[82:97]
	v_mfma_f32_32x32x16_bf16 v[66:81], v[170:173], v[190:193], v[66:81]
	v_mfma_f32_32x32x16_bf16 v[50:65], v[174:177], v[178:181], v[50:65]
	v_mfma_f32_32x32x16_bf16 v[34:49], v[174:177], v[182:185], v[34:49]
	v_mfma_f32_32x32x16_bf16 v[18:33], v[174:177], v[186:189], v[18:33]
	v_mfma_f32_32x32x16_bf16 v[2:17], v[174:177], v[190:193], v[2:17]
	s_setprio 0
	v_add_u32_e32 v170, v217, v153
	v_add_u32_e32 v174, v219, v154
	v_add_u32_e32 v178, v234, v151
	v_add_u32_e32 v182, v235, v152
	v_add_u32_e32 v186, v236, v147
	v_add_u32_e32 v190, v237, v148
	v_lshl_add_u64 v[232:233], v[230:231], 0, s[40:41]
	s_add_i32 m0, s30, 0x4000
	ds_read_b128 v[170:173], v170
	ds_read_b128 v[174:177], v174
	ds_read_b128 v[178:181], v178 offset:32768
	ds_read_b128 v[182:185], v182 offset:32768
	ds_read_b128 v[186:189], v186 offset:32768
	ds_read_b128 v[190:193], v190 offset:32768
	global_load_lds_dwordx4 v[232:233], off
	v_lshl_add_u64 v[230:231], v[230:231], 0, s[34:35]
	s_add_i32 m0, s30, 0x6000
	s_nop 0
	global_load_lds_dwordx4 v[230:231], off
	s_setprio 1
	v_mfma_f32_32x32x16_bf16 v[114:129], v[194:197], v[202:205], v[114:129]
	v_mfma_f32_32x32x16_bf16 v[98:113], v[194:197], v[206:209], v[98:113]
	v_mfma_f32_32x32x16_bf16 v[82:97], v[194:197], v[210:213], v[82:97]
	v_mfma_f32_32x32x16_bf16 v[66:81], v[194:197], v[226:229], v[66:81]
	v_mfma_f32_32x32x16_bf16 v[50:65], v[198:201], v[202:205], v[50:65]
	v_mfma_f32_32x32x16_bf16 v[34:49], v[198:201], v[206:209], v[34:49]
	v_mfma_f32_32x32x16_bf16 v[18:33], v[198:201], v[210:213], v[18:33]
	v_mfma_f32_32x32x16_bf16 v[2:17], v[198:201], v[226:229], v[2:17]
	s_setprio 0
	s_mov_b32 m0, s31
	v_add_u32_e32 v194, v217, v141
	v_add_u32_e32 v198, v219, v142
	v_add_u32_e32 v202, v234, v139
	v_add_u32_e32 v206, v235, v140
	v_add_u32_e32 v210, v236, v137
	ds_read_b128 v[194:197], v194
	ds_read_b128 v[198:201], v198
	ds_read_b128 v[202:205], v202 offset:32768
	ds_read_b128 v[206:209], v206 offset:32768
	v_add_u32_e32 v217, v237, v138
	ds_read_b128 v[210:213], v210 offset:32768
	ds_read_b128 v[226:229], v217 offset:32768
	global_load_lds_dwordx4 v[214:215], off
	v_lshl_add_u64 v[230:231], v[214:215], 0, s[36:37]
	s_add_i32 m0, s30, 0xa000
	s_nop 0
	global_load_lds_dwordx4 v[230:231], off
	s_setprio 1
	s_waitcnt lgkmcnt(0)
	v_mfma_f32_32x32x16_bf16 v[114:129], v[170:173], v[178:181], v[114:129]
	v_mfma_f32_32x32x16_bf16 v[98:113], v[170:173], v[182:185], v[98:113]
	v_mfma_f32_32x32x16_bf16 v[82:97], v[170:173], v[186:189], v[82:97]
	v_mfma_f32_32x32x16_bf16 v[66:81], v[170:173], v[190:193], v[66:81]
	v_mfma_f32_32x32x16_bf16 v[50:65], v[174:177], v[178:181], v[50:65]
	v_mfma_f32_32x32x16_bf16 v[34:49], v[174:177], v[182:185], v[34:49]
	v_mfma_f32_32x32x16_bf16 v[18:33], v[174:177], v[186:189], v[18:33]
	v_mfma_f32_32x32x16_bf16 v[2:17], v[174:177], v[190:193], v[2:17]
	s_setprio 0
	v_lshl_add_u64 v[170:171], v[230:231], 0, s[36:37]
	s_add_i32 m0, s30, 0xc000
	s_nop 0
	global_load_lds_dwordx4 v[170:171], off
	v_lshl_add_u64 v[170:171], v[214:215], 0, s[34:35]
	s_add_i32 m0, s30, 0xe000
	s_nop 0
	global_load_lds_dwordx4 v[170:171], off
	s_setprio 1
	v_mfma_f32_32x32x16_bf16 v[114:129], v[194:197], v[202:205], v[114:129]
	v_mfma_f32_32x32x16_bf16 v[98:113], v[194:197], v[206:209], v[98:113]
	v_mfma_f32_32x32x16_bf16 v[82:97], v[194:197], v[210:213], v[82:97]
	v_mfma_f32_32x32x16_bf16 v[66:81], v[194:197], v[226:229], v[66:81]
	v_mfma_f32_32x32x16_bf16 v[50:65], v[198:201], v[202:205], v[50:65]
	v_mfma_f32_32x32x16_bf16 v[34:49], v[198:201], v[206:209], v[34:49]
	v_mfma_f32_32x32x16_bf16 v[18:33], v[198:201], v[210:213], v[18:33]
	v_mfma_f32_32x32x16_bf16 v[2:17], v[198:201], v[226:229], v[2:17]
	s_setprio 0
	s_waitcnt vmcnt(0)
	s_add_i32 s6, s6, -1
	s_add_i32 s92, s92, 64
	s_add_i32 s3, s3, 0x10000
	s_cmp_lg_u32 s6, 0
	s_waitcnt vmcnt(0) lgkmcnt(0)
	s_barrier
	s_cbranch_scc1 .LBB0_532
; DI f32x16 mfma(bf16x8 a, bf16x8 b, f32x16 c) { return __builtin_amdgcn_mfma_f32_32x32x16_bf16(a, b, c, 0, 0, 0); }
;     ...
;   for (int kt = 0; kt < nk; ++kt) {
;     char* cur = lds + (kt & 1) * STG; char* nxt = lds + ((kt + 1) & 1) * STG;
;     const bool more = kt + 1 < nk;
;     const bf16_t* An = Ag + (kt + 1) * BK; const bf16_t* Bn = Bg + (kt + 1) * BK;
;     if (!more) epi.pre(row0 + wm * 64, col0 + wn * (32 * NTW), lane, w, lds);
;     bf16x8 fa[2][2], fb[2][NTW];
; #pragma unroll
;     for (int mt = 0; mt < 2; ++mt) { int row = wm * 64 + mt * 32 + l31; fa[0][mt] = *(const bf16x8*)(cur + row * (BK * 2) + ((hh ^ swz<BK>(row)) << 4)); }
; #pragma unroll
;     for (int nt = 0; nt < NTW; ++nt) { int row = wn * (32 * NTW) + nt * 32 + l31; fb[0][nt] = *(const bf16x8*)(cur + ABYTES + row * (BK * 2) + ((hh ^ swz<BK>(row)) << 4)); }
; #pragma unroll
;     for (int kk = 0; kk < NKK; ++kk) {
;       if (kk + 1 < NKK) {
;         const int ch = (kk + 1) * 2 + hh;
; #pragma unroll
;         for (int mt = 0; mt < 2; ++mt) { int row = wm * 64 + mt * 32 + l31; fa[(kk + 1) & 1][mt] = *(const bf16x8*)(cur + row * (BK * 2) + ((ch ^ swz<BK>(row)) << 4)); }
; #pragma unroll
;         for (int nt = 0; nt < NTW; ++nt) { int row = wn * (32 * NTW) + nt * 32 + l31; fb[(kk + 1) & 1][nt] = *(const bf16x8*)(cur + ABYTES + row * (BK * 2) + ((ch ^ swz<BK>(row)) << 4)); }
;       }
;       if (more) {
; #pragma unroll
;         for (int q = 0; q < PPK; ++q) {
;           const int pi = kk * PPK + q;
;           if (pi < NPA) stage_piece<BM, BK>(An, lda, nxt, tid, pi, wv);
;           else if (pi < NP) stage_piece<BN, BK>(Bn, ldb, nxt + ABYTES, tid, pi - NPA, wv);
;         }
;       }
;       __builtin_amdgcn_s_setprio(1);
; #pragma unroll
;       for (int mt = 0; mt < 2; ++mt)
; #pragma unroll
;         for (int nt = 0; nt < NTW; ++nt) acc[mt][nt] = mfma(fa[kk & 1][mt], fb[kk & 1][nt], acc[mt][nt]);
;       __builtin_amdgcn_s_setprio(0);
;       __builtin_amdgcn_sched_barrier(0);
;     }
;     wait_vm0();
;     __syncthreads();
;   DI void xpass(int ps, int grow0, int gcol0, int lane, int w, char* lds) const {
;     char* xs = lds + (ps & 1) * 65536 + __builtin_amdgcn_readfirstlane(w) * 8192;
;     const float* xsrc = Xin + (size_t)(grow0 + (ps >> 1) * 32 + (ps & 1) * 16 + (lane >> 5)) * D_ + gcol0 + (lane & 31) * 4;
; #pragma unroll
;     for (int pc = 0; pc < 8; ++pc)
	v_readlane_b32 s3, v253, 9
	v_readlane_b32 s30, v253, 27
	v_readfirstlane_b32 s2, v134
	v_or_b32_e32 v130, s3, v135
	v_add_u32_e32 v130, v130, v169
	v_ashrrev_i32_e32 v131, 31, v130
	v_lshlrev_b64 v[130:131], 12, v[130:131]
	v_add_u32_e32 v132, s30, v161
	v_ashrrev_i32_e32 v133, 31, v132
	v_lshl_add_u64 v[130:131], s[10:11], 0, v[130:131]
	v_lshlrev_b32_e32 v0, 4, v0
	s_lshl_b32 s2, s2, 13
	v_lshl_add_u64 v[130:131], v[132:133], 2, v[130:131]
	v_and_b32_e32 v132, 0x1f0, v0
	v_mov_b32_e32 v133, v1
	v_lshl_add_u64 v[130:131], v[130:131], 0, v[132:133]
	s_mov_b32 m0, s2
	s_mov_b64 s[34:35], 0x2000
	global_load_lds_dwordx4 v[130:131], off
	v_lshl_add_u64 v[132:133], v[130:131], 0, s[34:35]
	s_or_b32 m0, s2, 0x400
	s_mov_b64 s[36:37], 0x4000
	global_load_lds_dwordx4 v[132:133], off
	v_lshl_add_u64 v[132:133], v[130:131], 0, s[36:37]
	s_or_b32 m0, s2, 0x800
	s_mov_b64 s[40:41], 0x6000
	global_load_lds_dwordx4 v[132:133], off
	v_lshl_add_u64 v[132:133], v[130:131], 0, s[40:41]
	s_or_b32 m0, s2, 0xc00
	s_mov_b64 s[44:45], 0x8000
	global_load_lds_dwordx4 v[132:133], off
	v_lshl_add_u64 v[132:133], v[130:131], 0, s[44:45]
	s_or_b32 m0, s2, 0x1000
	s_mov_b64 s[46:47], 0xa000
	global_load_lds_dwordx4 v[132:133], off
	v_lshl_add_u64 v[132:133], v[130:131], 0, s[46:47]
	s_or_b32 m0, s2, 0x1400
	s_mov_b64 s[52:53], 0xc000
	global_load_lds_dwordx4 v[132:133], off
	v_lshl_add_u64 v[132:133], v[130:131], 0, s[52:53]
	s_or_b32 m0, s2, 0x1800
	s_mov_b64 s[54:55], 0xe000
	global_load_lds_dwordx4 v[132:133], off
	v_lshl_add_u64 v[130:131], v[130:131], 0, s[54:55]
	s_or_b32 m0, s2, 0x1c00
	v_add_u32_e32 v0, s7, v136
	global_load_lds_dwordx4 v[130:131], off
	v_add_u32_e32 v134, s7, v144
	v_add_u32_e32 v130, v0, v143
	v_add_u32_e32 v135, v134, v146
	ds_read_b128 v[130:133], v130
	ds_read_b128 v[170:173], v135
	v_add_u32_e32 v135, s7, v145
	v_add_u32_e32 v136, v135, v149
	v_add_u32_e32 v143, s7, v150
	v_add_u32_e32 v144, v143, v155
	ds_read_b128 v[174:177], v136 offset:32768
	ds_read_b128 v[178:181], v144 offset:32768
	v_add_u32_e32 v136, s7, v156
	v_add_u32_e32 v144, v136, v157
	v_add_u32_e32 v149, s7, v158
	v_add_u32_e32 v145, v149, v168
	ds_read_b128 v[182:185], v144 offset:32768
	ds_read_b128 v[186:189], v145 offset:32768
	v_add_u32_e32 v144, v0, v166
	v_add_u32_e32 v145, v134, v167
	ds_read_b128 v[166:169], v144
	ds_read_b128 v[190:193], v145
	v_add_u32_e32 v144, v135, v163
	v_add_u32_e32 v145, v143, v164
	ds_read_b128 v[194:197], v144 offset:32768
	ds_read_b128 v[198:201], v145 offset:32768
	v_add_u32_e32 v144, v136, v159
	v_add_u32_e32 v145, v149, v160
	ds_read_b128 v[156:159], v144 offset:32768
	ds_read_b128 v[202:205], v145 offset:32768
	v_readlane_b32 s31, v253, 28
	s_setprio 1
	s_waitcnt lgkmcnt(0)
	v_mfma_f32_32x32x16_bf16 v[114:129], v[130:133], v[174:177], v[114:129]
	v_mfma_f32_32x32x16_bf16 v[98:113], v[130:133], v[178:181], v[98:113]
	v_mfma_f32_32x32x16_bf16 v[82:97], v[130:133], v[182:185], v[82:97]
	v_mfma_f32_32x32x16_bf16 v[66:81], v[130:133], v[186:189], v[66:81]
	v_mfma_f32_32x32x16_bf16 v[50:65], v[170:173], v[174:177], v[50:65]
	v_mfma_f32_32x32x16_bf16 v[34:49], v[170:173], v[178:181], v[34:49]
	v_mfma_f32_32x32x16_bf16 v[18:33], v[170:173], v[182:185], v[18:33]
	v_mfma_f32_32x32x16_bf16 v[2:17], v[170:173], v[186:189], v[2:17]
	s_setprio 0
	v_add_u32_e32 v130, v0, v153
	v_add_u32_e32 v144, v134, v154
	ds_read_b128 v[130:133], v130
	ds_read_b128 v[170:173], v144
	v_add_u32_e32 v144, v135, v151
	v_add_u32_e32 v145, v143, v152
	ds_read_b128 v[150:153], v144 offset:32768
	ds_read_b128 v[174:177], v145 offset:32768
	v_add_u32_e32 v144, v136, v147
	v_add_u32_e32 v148, v149, v148
	ds_read_b128 v[144:147], v144 offset:32768
	ds_read_b128 v[178:181], v148 offset:32768
	s_setprio 1
	v_mfma_f32_32x32x16_bf16 v[114:129], v[166:169], v[194:197], v[114:129]
	v_mfma_f32_32x32x16_bf16 v[98:113], v[166:169], v[198:201], v[98:113]
	v_mfma_f32_32x32x16_bf16 v[82:97], v[166:169], v[156:159], v[82:97]
	v_mfma_f32_32x32x16_bf16 v[66:81], v[166:169], v[202:205], v[66:81]
	v_mfma_f32_32x32x16_bf16 v[50:65], v[190:193], v[194:197], v[50:65]
	v_mfma_f32_32x32x16_bf16 v[34:49], v[190:193], v[198:201], v[34:49]
	v_mfma_f32_32x32x16_bf16 v[18:33], v[190:193], v[156:159], v[18:33]
	v_mfma_f32_32x32x16_bf16 v[2:17], v[190:193], v[202:205], v[2:17]
	s_setprio 0
	v_add_u32_e32 v0, v0, v141
	v_add_u32_e32 v134, v134, v142
	ds_read_b128 v[154:157], v0
	ds_read_b128 v[158:161], v134
	v_add_u32_e32 v0, v135, v139
	v_add_u32_e32 v134, v143, v140
	ds_read_b128 v[140:143], v0 offset:32768
	ds_read_b128 v[166:169], v134 offset:32768
	v_add_u32_e32 v0, v136, v137
	v_add_u32_e32 v138, v149, v138
	ds_read_b128 v[134:137], v0 offset:32768
	ds_read_b128 v[182:185], v138 offset:32768
	s_setprio 1
	s_waitcnt lgkmcnt(9)
	v_mfma_f32_32x32x16_bf16 v[114:129], v[130:133], v[150:153], v[114:129]
	s_waitcnt lgkmcnt(8)
	v_mfma_f32_32x32x16_bf16 v[98:113], v[130:133], v[174:177], v[98:113]
	s_waitcnt lgkmcnt(7)
	v_mfma_f32_32x32x16_bf16 v[82:97], v[130:133], v[144:147], v[82:97]
	s_waitcnt lgkmcnt(6)
	v_mfma_f32_32x32x16_bf16 v[66:81], v[130:133], v[178:181], v[66:81]
	v_mfma_f32_32x32x16_bf16 v[50:65], v[170:173], v[150:153], v[50:65]
	v_mfma_f32_32x32x16_bf16 v[34:49], v[170:173], v[174:177], v[34:49]
	v_mfma_f32_32x32x16_bf16 v[18:33], v[170:173], v[144:147], v[18:33]
	v_mfma_f32_32x32x16_bf16 v[2:17], v[170:173], v[178:181], v[2:17]
	s_setprio 0
	s_setprio 1
	s_waitcnt lgkmcnt(3)
	v_mfma_f32_32x32x16_bf16 v[114:129], v[154:157], v[140:143], v[114:129]
	s_waitcnt lgkmcnt(2)
	v_mfma_f32_32x32x16_bf16 v[98:113], v[154:157], v[166:169], v[98:113]
	s_waitcnt lgkmcnt(1)
	v_mfma_f32_32x32x16_bf16 v[82:97], v[154:157], v[134:137], v[82:97]
	s_waitcnt lgkmcnt(0)
	v_mfma_f32_32x32x16_bf16 v[66:81], v[154:157], v[182:185], v[66:81]
	v_mfma_f32_32x32x16_bf16 v[50:65], v[158:161], v[140:143], v[50:65]
	v_mfma_f32_32x32x16_bf16 v[34:49], v[158:161], v[166:169], v[34:49]
	v_mfma_f32_32x32x16_bf16 v[18:33], v[158:161], v[134:137], v[18:33]
	v_mfma_f32_32x32x16_bf16 v[2:17], v[158:161], v[182:185], v[2:17]
	s_setprio 0
	v_mov_b32_e32 v164, v216
	s_waitcnt vmcnt(0)
	s_barrier
;   DI void xpass(int ps, int grow0, int gcol0, int lane, int w, char* lds) const {
;     char* xs = lds + (ps & 1) * 65536 + __builtin_amdgcn_readfirstlane(w) * 8192;
;     const float* xsrc = Xin + (size_t)(grow0 + (ps >> 1) * 32 + (ps & 1) * 16 + (lane >> 5)) * D_ + gcol0 + (lane & 31) * 4;
; #pragma unroll
;     for (int pc = 0; pc < 8; ++pc)
;       __builtin_amdgcn_global_load_lds((const unsigned*)(xsrc + (size_t)(2 * pc) * D_), (__attribute__((address_space(3))) unsigned*)(xs + pc * 1024), 16, 0, 0);
;   }
;   DI void operator()(f32x16 (&acc)[2][4], int grow0, int gcol0, int lane, int w, char* lds) {
;     float* red = (float*)(lds + 131072); float* stat = (float*)lds;
;     const int l31 = lane & 31, hh = lane >> 5, tid = w * 64 + lane;
;     const int pm = grow0 >> 8, pn = gcol0 >> 8, wn = (gcol0 >> 7) & 1, lrow0 = grow0 & 255;
;     float bia[4], csc[4];
; #pragma unroll
;     for (int nt = 0; nt < 4; ++nt) { int c = gcol0 + nt * 32 + l31; bia[nt] = bias ? bias[c] : 0.f; csc[nt] = cscale ? cscale[c] : 1.f; }
;     float* redw = red + ((wn * 2 + ((lane >> 4) & 1)) * 256 + lrow0 + 4 * hh) * 2;
; #pragma unroll
;     for (int ps = 0; ps < 4; ++ps) {
;       const int mt = ps >> 1;
;       if (ps + 1 < 4) {
;         if (ps >= 1) asm volatile("s_waitcnt lgkmcnt(0)" ::: "memory");
;         xpass(ps + 1, grow0, gcol0, lane, w, lds);
;         if (ps >= 1) asm volatile("s_waitcnt vmcnt(8)" ::: "memory");
;       } else asm volatile("s_waitcnt vmcnt(0)" ::: "memory");
;       const char* xs = lds + (ps & 1) * 65536 + w * 8192;
; #pragma unroll
;       for (int qq = 0; qq < 2; ++qq)
; #pragma unroll
;         for (int e = 0; e < 4; ++e) {
;           const int i = 4 * (2 * (ps & 1) + qq) + e;
;           const float* xr = (const float*)(xs + (8 * qq + 4 * hh + e) * 512) + l31;
;           float s1 = 0.f, s2 = 0.f;
; #pragma unroll
;           for (int nt = 0; nt < 4; ++nt) {
;             float v = (acc[mt][nt][i] + bia[nt]) * csc[nt];
;             float z = ALPHA * xr[nt * 32] + hs * v;
;             acc[mt][nt][i] = z; s1 += z; s2 += z * z;
;           }
;           s1 = row16_sum(s1); s2 = row16_sum(s2);
;           if ((lane & 15) == 0) { f32x2 sv = {s1, s2}; *(f32x2*)(redw + (mt * 32 + (i & 3) + 8 * (i >> 2)) * 2) = sv; }
;         }
	v_mov_b32_e32 v133, v1
	v_ashrrev_i32_e32 v158, 6, v164
	v_lshrrev_b32_e32 v0, 30, v158
	v_add_u32_e32 v0, v158, v0
	v_ashrrev_i32_e32 v134, 2, v0
	v_mul_i32_i24_e32 v0, 4, v134
	v_sub_u32_e32 v0, v158, v0
	v_lshlrev_b32_e32 v135, 6, v0
	v_add_u32_e32 v163, s3, v135
	v_bfe_u32 v0, v164, 5, 1
	v_or_b32_e32 v159, v163, v0
	v_or_b32_e32 v130, 16, v159
	v_lshlrev_b32_e32 v200, 2, v164
	v_ashrrev_i32_e32 v131, 31, v130
	v_lshl_add_u32 v182, v134, 7, s30
	v_and_b32_e32 v0, 0x7c, v200
	v_lshlrev_b64 v[130:131], 12, v[130:131]
	v_ashrrev_i32_e32 v183, 31, v182
	v_readfirstlane_b32 s2, v158
	v_lshl_add_u64 v[130:131], s[10:11], 0, v[130:131]
	v_lshlrev_b32_e32 v0, 2, v0
	s_lshl_b32 s2, s2, 13
	v_lshl_add_u64 v[130:131], v[182:183], 2, v[130:131]
	v_mov_b32_e32 v132, v0
	s_add_i32 m0, s2, 0x10000
	v_lshl_add_u64 v[130:131], v[130:131], 0, v[132:133]
	global_load_lds_dwordx4 v[130:131], off
	v_lshl_add_u64 v[132:133], v[130:131], 0, s[34:35]
	s_add_i32 m0, s2, 0x10400
	v_and_b32_e32 v210, 0xc0, v135
	global_load_lds_dwordx4 v[132:133], off
	v_lshl_add_u64 v[132:133], v[130:131], 0, s[36:37]
	s_add_i32 m0, s2, 0x10800
	v_mov_b32_e32 v136, v114
	global_load_lds_dwordx4 v[132:133], off
	v_lshl_add_u64 v[132:133], v[130:131], 0, s[40:41]
	s_add_i32 m0, s2, 0x10c00
	v_mov_b32_e32 v137, v82
	global_load_lds_dwordx4 v[132:133], off
	v_lshl_add_u64 v[132:133], v[130:131], 0, s[44:45]
	s_add_i32 m0, s2, 0x11000
	v_mov_b32_e32 v140, v98
	global_load_lds_dwordx4 v[132:133], off
	v_lshl_add_u64 v[132:133], v[130:131], 0, s[46:47]
	s_add_i32 m0, s2, 0x11400
	v_mov_b32_e32 v141, v82
	global_load_lds_dwordx4 v[132:133], off
	v_lshl_add_u64 v[132:133], v[130:131], 0, s[52:53]
	s_add_i32 m0, s2, 0x11800
	v_lshl_add_u64 v[130:131], v[130:131], 0, s[54:55]
	global_load_lds_dwordx4 v[132:133], off
	s_add_i32 m0, s2, 0x11c00
	v_bfe_u32 v132, v164, 4, 1
	global_load_lds_dwordx4 v[130:131], off
	v_and_b32_e32 v130, 31, v164
	v_lshlrev_b32_e32 v131, 1, v134
	v_bfe_u32 v134, v164, 3, 3
	v_and_or_b32 v131, v131, 2, v132
	v_and_b32_e32 v132, 4, v134
	v_lshlrev_b32_e32 v130, 2, v130
	v_lshl_or_b32 v138, v158, 13, v130
	v_lshlrev_b32_e32 v154, 9, v132
	v_or_b32_e32 v133, v210, v132
	v_and_b32_e32 v130, 15, v164
	v_or_b32_e32 v132, v138, v154
	v_lshlrev_b32_e32 v135, 3, v133
	v_lshl_or_b32 v139, v131, 11, v221
	v_cmp_eq_u32_e32 vcc, 0, v130
	s_waitcnt vmcnt(8)
	ds_read2_b32 v[130:131], v132 offset1:32
	ds_read2_b32 v[132:133], v132 offset0:64 offset1:96
	v_pk_add_f32 v[136:137], v[136:137], 0 op_sel_hi:[1,0]
	v_pk_add_f32 v[140:141], v[140:141], 0 op_sel_hi:[1,0]
	s_mov_b32 s2, s67
	s_waitcnt lgkmcnt(0)
	v_mov_b32_e32 v142, v130
	v_mov_b32_e32 v143, v132
	v_mov_b32_e32 v130, v131
	v_mov_b32_e32 v131, v132
	v_pk_fma_f32 v[186:187], v[142:143], s[2:3], v[136:137] op_sel_hi:[1,0,1]
	v_pk_fma_f32 v[188:189], v[130:131], s[2:3], v[140:141] op_sel_hi:[1,0,1]
	v_pk_mul_f32 v[144:145], v[142:143], s[2:3] op_sel_hi:[1,0]
	v_pk_mul_f32 v[142:143], v[186:187], v[186:187]
	v_pk_mul_f32 v[130:131], v[188:189], v[188:189]
	v_pk_mov_b32 v[136:137], v[136:137], v[142:143] op_sel:[1,0]
	v_pk_mov_b32 v[130:131], v[144:145], v[130:131] op_sel:[1,0]
	v_add_f32_e32 v178, 0, v66
	v_pk_add_f32 v[130:131], v[136:137], v[130:131]
	v_pk_add_f32 v[136:137], v[186:187], v[188:189]
	v_pk_mul_f32 v[140:141], v[186:187], v[188:189]
	v_fmac_f32_e32 v178, 0x3fd744fd, v133
	v_mov_b32_e32 v137, v141
	v_pk_add_f32 v[130:131], v[136:137], v[130:131]
	v_mul_f32_e32 v179, v178, v178
	v_pk_add_f32 v[130:131], v[130:131], v[178:179]
	v_add_u32_e32 v179, v139, v135
	s_nop 0
	v_mov_b32_dpp v132, v130 quad_perm:[1,0,3,2] row_mask:0xf bank_mask:0xf bound_ctrl:1
	v_mov_b32_dpp v133, v131 quad_perm:[1,0,3,2] row_mask:0xf bank_mask:0xf bound_ctrl:1
	v_pk_add_f32 v[130:131], v[130:131], v[132:133]
	s_nop 1
	v_mov_b32_dpp v132, v130 quad_perm:[2,3,0,1] row_mask:0xf bank_mask:0xf bound_ctrl:1
	v_mov_b32_dpp v133, v131 quad_perm:[2,3,0,1] row_mask:0xf bank_mask:0xf bound_ctrl:1
	v_pk_add_f32 v[130:131], v[130:131], v[132:133]
	s_nop 1
	v_mov_b32_dpp v132, v130 row_half_mirror row_mask:0xf bank_mask:0xf bound_ctrl:1
	v_mov_b32_dpp v133, v131 row_half_mirror row_mask:0xf bank_mask:0xf bound_ctrl:1
	v_pk_add_f32 v[130:131], v[130:131], v[132:133]
	s_nop 1
	v_mov_b32_dpp v132, v130 row_mirror row_mask:0xf bank_mask:0xf bound_ctrl:1
	v_mov_b32_dpp v133, v131 row_mirror row_mask:0xf bank_mask:0xf bound_ctrl:1
	s_and_saveexec_b64 s[6:7], vcc
	v_pk_add_f32 v[130:131], v[130:131], v[132:133]
	ds_write_b64 v179, v[130:131]
	s_or_b64 exec, exec, s[6:7]
	v_add_u32_e32 v168, v138, v154
	ds_read2_b32 v[130:131], v168 offset0:128 offset1:160
	ds_read2_b32 v[132:133], v168 offset0:192 offset1:224
	v_mov_b32_e32 v82, v115
	v_add_f32_e32 v152, 0, v67
	v_pk_add_f32 v[66:67], v[82:83], 0 op_sel_hi:[1,0]
	v_mov_b32_e32 v82, v99
	v_pk_add_f32 v[82:83], v[82:83], 0 op_sel_hi:[1,0]
	s_waitcnt lgkmcnt(1)
	v_mov_b32_e32 v98, v130
	s_waitcnt lgkmcnt(0)
;   DI void operator()(f32x16 (&acc)[2][4], int grow0, int gcol0, int lane, int w, char* lds) {
;     ...
; #pragma unroll
;       for (int qq = 0; qq < 2; ++qq)
; #pragma unroll
;         for (int e = 0; e < 4; ++e) {
;           const int i = 4 * (2 * (ps & 1) + qq) + e;
;           const float* xr = (const float*)(xs + (8 * qq + 4 * hh + e) * 512) + l31;
;           float s1 = 0.f, s2 = 0.f;
; #pragma unroll
;           for (int nt = 0; nt < 4; ++nt) {
;             float v = (acc[mt][nt][i] + bia[nt]) * csc[nt];
;             float z = ALPHA * xr[nt * 32] + hs * v;
;             acc[mt][nt][i] = z; s1 += z; s2 += z * z;
;           }
;           s1 = row16_sum(s1); s2 = row16_sum(s2);
;           if ((lane & 15) == 0) { f32x2 sv = {s1, s2}; *(f32x2*)(redw + (mt * 32 + (i & 3) + 8 * (i >> 2)) * 2) = sv; }
;         }
	v_mov_b32_e32 v99, v132
	s_mov_b32 s2, s67
	v_mov_b32_e32 v130, v131
	v_mov_b32_e32 v131, v132
	v_pk_fma_f32 v[166:167], v[98:99], s[2:3], v[66:67] op_sel_hi:[1,0,1]
	v_pk_fma_f32 v[172:173], v[130:131], s[2:3], v[82:83] op_sel_hi:[1,0,1]
	v_pk_mul_f32 v[114:115], v[98:99], s[2:3] op_sel_hi:[1,0]
	v_pk_mul_f32 v[98:99], v[166:167], v[166:167]
	v_pk_mul_f32 v[82:83], v[172:173], v[172:173]
	v_pk_mov_b32 v[66:67], v[66:67], v[98:99] op_sel:[1,0]
	v_pk_mov_b32 v[82:83], v[114:115], v[82:83] op_sel:[1,0]
	v_pk_mul_f32 v[98:99], v[166:167], v[172:173]
	v_pk_add_f32 v[66:67], v[66:67], v[82:83]
	v_pk_add_f32 v[82:83], v[166:167], v[172:173]
	v_fmac_f32_e32 v152, 0x3fd744fd, v133
	v_mov_b32_e32 v83, v99
	v_pk_add_f32 v[66:67], v[82:83], v[66:67]
	v_mul_f32_e32 v153, v152, v152
	v_pk_add_f32 v[66:67], v[66:67], v[152:153]
	s_nop 1
	v_mov_b32_dpp v82, v66 quad_perm:[1,0,3,2] row_mask:0xf bank_mask:0xf bound_ctrl:1
	v_mov_b32_dpp v83, v67 quad_perm:[1,0,3,2] row_mask:0xf bank_mask:0xf bound_ctrl:1
	v_pk_add_f32 v[66:67], v[66:67], v[82:83]
	s_nop 1
	v_mov_b32_dpp v82, v66 quad_perm:[2,3,0,1] row_mask:0xf bank_mask:0xf bound_ctrl:1
	v_mov_b32_dpp v83, v67 quad_perm:[2,3,0,1] row_mask:0xf bank_mask:0xf bound_ctrl:1
	v_pk_add_f32 v[66:67], v[66:67], v[82:83]
	s_nop 1
	v_mov_b32_dpp v82, v66 row_half_mirror row_mask:0xf bank_mask:0xf bound_ctrl:1
	v_mov_b32_dpp v83, v67 row_half_mirror row_mask:0xf bank_mask:0xf bound_ctrl:1
	v_pk_add_f32 v[66:67], v[66:67], v[82:83]
	s_nop 1
	v_mov_b32_dpp v82, v66 row_mirror row_mask:0xf bank_mask:0xf bound_ctrl:1
	v_mov_b32_dpp v83, v67 row_mirror row_mask:0xf bank_mask:0xf bound_ctrl:1
	s_and_saveexec_b64 s[6:7], vcc
	v_readlane_b32 s63, v254, 51
	v_readlane_b32 s65, v254, 48
	v_readlane_b32 s70, v254, 52
	v_readlane_b32 s71, v255, 50
	v_pk_add_f32 v[66:67], v[66:67], v[82:83]
	ds_write_b64 v179, v[66:67] offset:8
	s_or_b64 exec, exec, s[6:7]
	v_add_u32_e32 v153, 0x400, v168
	ds_read2_b32 v[82:83], v153 offset1:32
	ds_read2_b32 v[98:99], v153 offset0:64 offset1:96
	v_mov_b32_e32 v114, v116
	v_mov_b32_e32 v115, v84
	v_mov_b32_e32 v130, v100
	v_mov_b32_e32 v131, v84
	v_pk_add_f32 v[114:115], v[114:115], 0 op_sel_hi:[1,0]
	v_pk_add_f32 v[130:131], v[130:131], 0 op_sel_hi:[1,0]
	s_waitcnt lgkmcnt(1)
	v_mov_b32_e32 v132, v82
	s_waitcnt lgkmcnt(0)
	v_mov_b32_e32 v133, v98
	s_mov_b32 s2, s67
	v_mov_b32_e32 v140, v83
	v_mov_b32_e32 v141, v98
	v_pk_fma_f32 v[82:83], v[132:133], s[2:3], v[114:115] op_sel_hi:[1,0,1]
	v_pk_fma_f32 v[150:151], v[140:141], s[2:3], v[130:131] op_sel_hi:[1,0,1]
	v_pk_mul_f32 v[136:137], v[132:133], s[2:3] op_sel_hi:[1,0]
	v_pk_mul_f32 v[132:133], v[82:83], v[82:83]
	v_pk_mul_f32 v[130:131], v[150:151], v[150:151]
	v_pk_mov_b32 v[114:115], v[114:115], v[132:133] op_sel:[1,0]
	v_pk_mov_b32 v[130:131], v[136:137], v[130:131] op_sel:[1,0]
	v_add_f32_e32 v66, 0, v68
	v_pk_add_f32 v[114:115], v[114:115], v[130:131]
	v_pk_add_f32 v[130:131], v[82:83], v[150:151]
	v_pk_mul_f32 v[132:133], v[82:83], v[150:151]
	v_fmac_f32_e32 v66, 0x3fd744fd, v99
	v_mov_b32_e32 v131, v133
	v_pk_add_f32 v[114:115], v[130:131], v[114:115]
	v_mul_f32_e32 v67, v66, v66
	v_pk_add_f32 v[98:99], v[114:115], v[66:67]
	s_nop 1
	v_mov_b32_dpp v114, v98 quad_perm:[1,0,3,2] row_mask:0xf bank_mask:0xf bound_ctrl:1
	v_mov_b32_dpp v115, v99 quad_perm:[1,0,3,2] row_mask:0xf bank_mask:0xf bound_ctrl:1
	v_pk_add_f32 v[98:99], v[98:99], v[114:115]
	s_nop 1
	v_mov_b32_dpp v114, v98 quad_perm:[2,3,0,1] row_mask:0xf bank_mask:0xf bound_ctrl:1
	v_mov_b32_dpp v115, v99 quad_perm:[2,3,0,1] row_mask:0xf bank_mask:0xf bound_ctrl:1
	v_pk_add_f32 v[98:99], v[98:99], v[114:115]
	s_nop 1
	v_mov_b32_dpp v114, v98 row_half_mirror row_mask:0xf bank_mask:0xf bound_ctrl:1
	v_mov_b32_dpp v115, v99 row_half_mirror row_mask:0xf bank_mask:0xf bound_ctrl:1
	v_pk_add_f32 v[98:99], v[98:99], v[114:115]
	s_nop 1
	v_mov_b32_dpp v114, v98 row_mirror row_mask:0xf bank_mask:0xf bound_ctrl:1
	v_mov_b32_dpp v115, v99 row_mirror row_mask:0xf bank_mask:0xf bound_ctrl:1
	s_and_saveexec_b64 s[6:7], vcc
	v_pk_add_f32 v[98:99], v[98:99], v[114:115]
	ds_write_b64 v179, v[98:99] offset:16
	s_or_b64 exec, exec, s[6:7]
	v_lshlrev_b32_e32 v139, 9, v134
	v_or_b32_e32 v146, 0x600, v139
	v_add_u32_e32 v151, v138, v146
	ds_read2_b32 v[98:99], v151 offset1:32
	ds_read2_b32 v[114:115], v151 offset0:64 offset1:96
	v_mov_b32_e32 v84, v117
	v_pk_add_f32 v[116:117], v[84:85], 0 op_sel_hi:[1,0]
	v_mov_b32_e32 v84, v101
	v_pk_add_f32 v[84:85], v[84:85], 0 op_sel_hi:[1,0]
	s_waitcnt lgkmcnt(1)
	v_mov_b32_e32 v100, v98
	s_waitcnt lgkmcnt(0)
;   DI void operator()(f32x16 (&acc)[2][4], int grow0, int gcol0, int lane, int w, char* lds) {
;     ...
; #pragma unroll
;       for (int qq = 0; qq < 2; ++qq)
; #pragma unroll
;         for (int e = 0; e < 4; ++e) {
;           const int i = 4 * (2 * (ps & 1) + qq) + e;
;           const float* xr = (const float*)(xs + (8 * qq + 4 * hh + e) * 512) + l31;
;           float s1 = 0.f, s2 = 0.f;
; #pragma unroll
;           for (int nt = 0; nt < 4; ++nt) {
;             float v = (acc[mt][nt][i] + bia[nt]) * csc[nt];
;             float z = ALPHA * xr[nt * 32] + hs * v;
;             acc[mt][nt][i] = z; s1 += z; s2 += z * z;
;           }
;           s1 = row16_sum(s1); s2 = row16_sum(s2);
;           if ((lane & 15) == 0) { f32x2 sv = {s1, s2}; *(f32x2*)(redw + (mt * 32 + (i & 3) + 8 * (i >> 2)) * 2) = sv; }
;         }
	v_mov_b32_e32 v101, v114
	s_mov_b32 s2, s67
	v_mov_b32_e32 v132, v99
	v_mov_b32_e32 v133, v114
	v_pk_mul_f32 v[130:131], v[100:101], s[2:3] op_sel_hi:[1,0]
	v_pk_fma_f32 v[98:99], v[100:101], s[2:3], v[116:117] op_sel_hi:[1,0,1]
	v_pk_fma_f32 v[100:101], v[132:133], s[2:3], v[84:85] op_sel_hi:[1,0,1]
	v_pk_mul_f32 v[134:135], v[98:99], v[98:99]
	v_pk_mul_f32 v[84:85], v[100:101], v[100:101]
	v_pk_mov_b32 v[116:117], v[116:117], v[134:135] op_sel:[1,0]
	v_pk_mov_b32 v[84:85], v[130:131], v[84:85] op_sel:[1,0]
	v_add_f32_e32 v68, 0, v69
	v_pk_add_f32 v[84:85], v[116:117], v[84:85]
	v_pk_add_f32 v[116:117], v[98:99], v[100:101]
	v_pk_mul_f32 v[130:131], v[98:99], v[100:101]
	v_fmac_f32_e32 v68, 0x3fd744fd, v115
	v_mov_b32_e32 v117, v131
	v_pk_add_f32 v[84:85], v[116:117], v[84:85]
	v_mul_f32_e32 v69, v68, v68
	v_pk_add_f32 v[84:85], v[84:85], v[68:69]
	s_nop 1
	v_mov_b32_dpp v114, v84 quad_perm:[1,0,3,2] row_mask:0xf bank_mask:0xf bound_ctrl:1
	v_mov_b32_dpp v115, v85 quad_perm:[1,0,3,2] row_mask:0xf bank_mask:0xf bound_ctrl:1
	v_pk_add_f32 v[84:85], v[84:85], v[114:115]
	s_nop 1
	v_mov_b32_dpp v114, v84 quad_perm:[2,3,0,1] row_mask:0xf bank_mask:0xf bound_ctrl:1
	v_mov_b32_dpp v115, v85 quad_perm:[2,3,0,1] row_mask:0xf bank_mask:0xf bound_ctrl:1
	v_pk_add_f32 v[84:85], v[84:85], v[114:115]
	s_nop 1
	v_mov_b32_dpp v114, v84 row_half_mirror row_mask:0xf bank_mask:0xf bound_ctrl:1
	v_mov_b32_dpp v115, v85 row_half_mirror row_mask:0xf bank_mask:0xf bound_ctrl:1
	v_pk_add_f32 v[84:85], v[84:85], v[114:115]
	s_nop 1
	v_mov_b32_dpp v114, v84 row_mirror row_mask:0xf bank_mask:0xf bound_ctrl:1
	v_mov_b32_dpp v115, v85 row_mirror row_mask:0xf bank_mask:0xf bound_ctrl:1
	s_and_saveexec_b64 s[6:7], vcc
	v_pk_add_f32 v[84:85], v[84:85], v[114:115]
	ds_write_b64 v179, v[84:85] offset:24
	s_or_b64 exec, exec, s[6:7]
	v_add_u32_e32 v67, 0x1000, v168
	ds_read2_b32 v[114:115], v67 offset1:32
	ds_read2_b32 v[130:131], v67 offset0:64 offset1:96
	v_mov_b32_e32 v116, v118
	v_mov_b32_e32 v117, v86
	v_pk_add_f32 v[132:133], v[116:117], 0 op_sel_hi:[1,0]
	v_mov_b32_e32 v116, v102
	v_pk_add_f32 v[116:117], v[116:117], 0 op_sel_hi:[1,0]
	s_waitcnt lgkmcnt(1)
	v_mov_b32_e32 v134, v114
	s_waitcnt lgkmcnt(0)
	v_mov_b32_e32 v135, v130
	s_mov_b32 s2, s67
	v_mov_b32_e32 v140, v115
	v_mov_b32_e32 v141, v130
	v_pk_fma_f32 v[114:115], v[134:135], s[2:3], v[132:133] op_sel_hi:[1,0,1]
	v_pk_fma_f32 v[116:117], v[140:141], s[2:3], v[116:117] op_sel_hi:[1,0,1]
	v_pk_mul_f32 v[136:137], v[134:135], s[2:3] op_sel_hi:[1,0]
	v_pk_mul_f32 v[134:135], v[114:115], v[114:115]
	v_pk_mul_f32 v[140:141], v[116:117], v[116:117]
	v_pk_mov_b32 v[132:133], v[132:133], v[134:135] op_sel:[1,0]
	v_pk_mov_b32 v[134:135], v[136:137], v[140:141] op_sel:[1,0]
	v_add_f32_e32 v84, 0, v70
	v_pk_add_f32 v[132:133], v[132:133], v[134:135]
	v_pk_add_f32 v[134:135], v[114:115], v[116:117]
	v_pk_mul_f32 v[136:137], v[114:115], v[116:117]
	v_fmac_f32_e32 v84, 0x3fd744fd, v131
	v_mov_b32_e32 v135, v137
	v_pk_add_f32 v[132:133], v[134:135], v[132:133]
	v_mul_f32_e32 v85, v84, v84
	v_pk_add_f32 v[130:131], v[132:133], v[84:85]
	s_nop 1
	v_mov_b32_dpp v132, v130 quad_perm:[1,0,3,2] row_mask:0xf bank_mask:0xf bound_ctrl:1
	v_mov_b32_dpp v133, v131 quad_perm:[1,0,3,2] row_mask:0xf bank_mask:0xf bound_ctrl:1
	v_pk_add_f32 v[130:131], v[130:131], v[132:133]
	s_nop 1
	v_mov_b32_dpp v132, v130 quad_perm:[2,3,0,1] row_mask:0xf bank_mask:0xf bound_ctrl:1
	v_mov_b32_dpp v133, v131 quad_perm:[2,3,0,1] row_mask:0xf bank_mask:0xf bound_ctrl:1
	v_pk_add_f32 v[130:131], v[130:131], v[132:133]
	s_nop 1
	v_mov_b32_dpp v132, v130 row_half_mirror row_mask:0xf bank_mask:0xf bound_ctrl:1
	v_mov_b32_dpp v133, v131 row_half_mirror row_mask:0xf bank_mask:0xf bound_ctrl:1
	v_pk_add_f32 v[130:131], v[130:131], v[132:133]
	s_nop 1
	v_mov_b32_dpp v132, v130 row_mirror row_mask:0xf bank_mask:0xf bound_ctrl:1
	v_mov_b32_dpp v133, v131 row_mirror row_mask:0xf bank_mask:0xf bound_ctrl:1
	s_and_saveexec_b64 s[6:7], vcc
	v_pk_add_f32 v[130:131], v[130:131], v[132:133]
	ds_write_b64 v179, v[130:131] offset:64
	s_or_b64 exec, exec, s[6:7]
	ds_read2_b32 v[130:131], v67 offset0:128 offset1:160
	ds_read2_b32 v[132:133], v67 offset0:192 offset1:224
	v_mov_b32_e32 v86, v119
	v_pk_add_f32 v[134:135], v[86:87], 0 op_sel_hi:[1,0]
	v_mov_b32_e32 v86, v103
	v_pk_add_f32 v[86:87], v[86:87], 0 op_sel_hi:[1,0]
	s_waitcnt lgkmcnt(1)
	v_mov_b32_e32 v102, v130
	s_waitcnt lgkmcnt(0)
	v_mov_b32_e32 v103, v132
	s_mov_b32 s2, s67
	v_mov_b32_e32 v118, v131
	v_mov_b32_e32 v119, v132
	v_pk_mul_f32 v[136:137], v[102:103], s[2:3] op_sel_hi:[1,0]
	v_pk_fma_f32 v[102:103], v[102:103], s[2:3], v[134:135] op_sel_hi:[1,0,1]
	v_pk_fma_f32 v[118:119], v[118:119], s[2:3], v[86:87] op_sel_hi:[1,0,1]
	v_pk_mul_f32 v[130:131], v[102:103], v[102:103]
	v_pk_mul_f32 v[86:87], v[118:119], v[118:119]
	v_pk_mov_b32 v[130:131], v[134:135], v[130:131] op_sel:[1,0]
	v_pk_mov_b32 v[86:87], v[136:137], v[86:87] op_sel:[1,0]
	v_add_f32_e32 v70, 0, v71
	v_pk_add_f32 v[86:87], v[130:131], v[86:87]
	v_pk_add_f32 v[130:131], v[102:103], v[118:119]
	v_pk_mul_f32 v[134:135], v[102:103], v[118:119]
	v_fmac_f32_e32 v70, 0x3fd744fd, v133
	v_mov_b32_e32 v131, v135
	v_pk_add_f32 v[86:87], v[130:131], v[86:87]
	v_mul_f32_e32 v71, v70, v70
	v_pk_add_f32 v[86:87], v[86:87], v[70:71]
	s_nop 1
	v_mov_b32_dpp v130, v86 quad_perm:[1,0,3,2] row_mask:0xf bank_mask:0xf bound_ctrl:1
	v_mov_b32_dpp v131, v87 quad_perm:[1,0,3,2] row_mask:0xf bank_mask:0xf bound_ctrl:1
	v_pk_add_f32 v[86:87], v[86:87], v[130:131]
	s_nop 1
	v_mov_b32_dpp v130, v86 quad_perm:[2,3,0,1] row_mask:0xf bank_mask:0xf bound_ctrl:1
	v_mov_b32_dpp v131, v87 quad_perm:[2,3,0,1] row_mask:0xf bank_mask:0xf bound_ctrl:1
	v_pk_add_f32 v[86:87], v[86:87], v[130:131]
	s_nop 1
	v_mov_b32_dpp v130, v86 row_half_mirror row_mask:0xf bank_mask:0xf bound_ctrl:1
	v_mov_b32_dpp v131, v87 row_half_mirror row_mask:0xf bank_mask:0xf bound_ctrl:1
	v_pk_add_f32 v[86:87], v[86:87], v[130:131]
	s_nop 1
	v_mov_b32_dpp v130, v86 row_mirror row_mask:0xf bank_mask:0xf bound_ctrl:1
	v_mov_b32_dpp v131, v87 row_mirror row_mask:0xf bank_mask:0xf bound_ctrl:1
	s_and_saveexec_b64 s[6:7], vcc
	v_pk_add_f32 v[86:87], v[86:87], v[130:131]
	ds_write_b64 v179, v[86:87] offset:72
	s_or_b64 exec, exec, s[6:7]
	v_add_u32_e32 v69, 0x1400, v168
	ds_read2_b32 v[130:131], v69 offset1:32
	ds_read2_b32 v[134:135], v69 offset0:64 offset1:96
	v_mov_b32_e32 v132, v120
	v_mov_b32_e32 v133, v88
	v_pk_add_f32 v[136:137], v[132:133], 0 op_sel_hi:[1,0]
	v_mov_b32_e32 v132, v104
	v_pk_add_f32 v[132:133], v[132:133], 0 op_sel_hi:[1,0]
	s_waitcnt lgkmcnt(1)
;   DI void xpass(int ps, int grow0, int gcol0, int lane, int w, char* lds) const {
;     char* xs = lds + (ps & 1) * 65536 + __builtin_amdgcn_readfirstlane(w) * 8192;
;     const float* xsrc = Xin + (size_t)(grow0 + (ps >> 1) * 32 + (ps & 1) * 16 + (lane >> 5)) * D_ + gcol0 + (lane & 31) * 4;
; #pragma unroll
;     for (int pc = 0; pc < 8; ++pc)
;       __builtin_amdgcn_global_load_lds((const unsigned*)(xsrc + (size_t)(2 * pc) * D_), (__attribute__((address_space(3))) unsigned*)(xs + pc * 1024), 16, 0, 0);
;   }
;   DI void operator()(f32x16 (&acc)[2][4], int grow0, int gcol0, int lane, int w, char* lds) {
;     ...
;     for (int ps = 0; ps < 4; ++ps) {
;       const int mt = ps >> 1;
;       if (ps + 1 < 4) {
;         if (ps >= 1) asm volatile("s_waitcnt lgkmcnt(0)" ::: "memory");
;         xpass(ps + 1, grow0, gcol0, lane, w, lds);
;         if (ps >= 1) asm volatile("s_waitcnt vmcnt(8)" ::: "memory");
;       } else asm volatile("s_waitcnt vmcnt(0)" ::: "memory");
;       const char* xs = lds + (ps & 1) * 65536 + w * 8192;
; #pragma unroll
;       for (int qq = 0; qq < 2; ++qq)
; #pragma unroll
;         for (int e = 0; e < 4; ++e) {
;           const int i = 4 * (2 * (ps & 1) + qq) + e;
;           const float* xr = (const float*)(xs + (8 * qq + 4 * hh + e) * 512) + l31;
;           float s1 = 0.f, s2 = 0.f;
; #pragma unroll
;           for (int nt = 0; nt < 4; ++nt) {
;             float v = (acc[mt][nt][i] + bia[nt]) * csc[nt];
;             float z = ALPHA * xr[nt * 32] + hs * v;
;             acc[mt][nt][i] = z; s1 += z; s2 += z * z;
;           }
;           s1 = row16_sum(s1); s2 = row16_sum(s2);
;           if ((lane & 15) == 0) { f32x2 sv = {s1, s2}; *(f32x2*)(redw + (mt * 32 + (i & 3) + 8 * (i >> 2)) * 2) = sv; }
;         }
	v_mov_b32_e32 v140, v130
	s_waitcnt lgkmcnt(0)
	v_mov_b32_e32 v141, v134
	s_mov_b32 s2, s67
	v_mov_b32_e32 v144, v131
	v_mov_b32_e32 v145, v134
	v_pk_fma_f32 v[130:131], v[140:141], s[2:3], v[136:137] op_sel_hi:[1,0,1]
	v_pk_fma_f32 v[132:133], v[144:145], s[2:3], v[132:133] op_sel_hi:[1,0,1]
	v_pk_mul_f32 v[142:143], v[140:141], s[2:3] op_sel_hi:[1,0]
	v_pk_mul_f32 v[140:141], v[130:131], v[130:131]
	v_pk_mul_f32 v[144:145], v[132:133], v[132:133]
	v_pk_mov_b32 v[136:137], v[136:137], v[140:141] op_sel:[1,0]
	v_pk_mov_b32 v[140:141], v[142:143], v[144:145] op_sel:[1,0]
	v_add_f32_e32 v86, 0, v72
	v_pk_add_f32 v[136:137], v[136:137], v[140:141]
	v_pk_add_f32 v[140:141], v[130:131], v[132:133]
	v_pk_mul_f32 v[142:143], v[130:131], v[132:133]
	v_fmac_f32_e32 v86, 0x3fd744fd, v135
	v_mov_b32_e32 v141, v143
	v_pk_add_f32 v[136:137], v[140:141], v[136:137]
	v_mul_f32_e32 v87, v86, v86
	v_pk_add_f32 v[134:135], v[136:137], v[86:87]
	s_nop 1
	v_mov_b32_dpp v136, v134 quad_perm:[1,0,3,2] row_mask:0xf bank_mask:0xf bound_ctrl:1
	v_mov_b32_dpp v137, v135 quad_perm:[1,0,3,2] row_mask:0xf bank_mask:0xf bound_ctrl:1
	v_pk_add_f32 v[134:135], v[134:135], v[136:137]
	s_nop 1
	v_mov_b32_dpp v136, v134 quad_perm:[2,3,0,1] row_mask:0xf bank_mask:0xf bound_ctrl:1
	v_mov_b32_dpp v137, v135 quad_perm:[2,3,0,1] row_mask:0xf bank_mask:0xf bound_ctrl:1
	v_pk_add_f32 v[134:135], v[134:135], v[136:137]
	s_nop 1
	v_mov_b32_dpp v136, v134 row_half_mirror row_mask:0xf bank_mask:0xf bound_ctrl:1
	v_mov_b32_dpp v137, v135 row_half_mirror row_mask:0xf bank_mask:0xf bound_ctrl:1
	v_pk_add_f32 v[134:135], v[134:135], v[136:137]
	s_nop 1
	v_mov_b32_dpp v136, v134 row_mirror row_mask:0xf bank_mask:0xf bound_ctrl:1
	v_mov_b32_dpp v137, v135 row_mirror row_mask:0xf bank_mask:0xf bound_ctrl:1
	s_and_saveexec_b64 s[6:7], vcc
	v_pk_add_f32 v[134:135], v[134:135], v[136:137]
	ds_write_b64 v179, v[134:135] offset:80
	s_or_b64 exec, exec, s[6:7]
	v_or_b32_e32 v101, 0x1600, v139
	v_add_u32_e32 v71, v138, v101
	ds_read2_b32 v[134:135], v71 offset1:32
	ds_read2_b32 v[136:137], v71 offset0:64 offset1:96
	v_mov_b32_e32 v88, v121
	v_pk_add_f32 v[120:121], v[88:89], 0 op_sel_hi:[1,0]
	v_mov_b32_e32 v88, v105
	v_pk_add_f32 v[104:105], v[88:89], 0 op_sel_hi:[1,0]
	s_waitcnt lgkmcnt(1)
	v_mov_b32_e32 v88, v134
	s_waitcnt lgkmcnt(0)
	v_mov_b32_e32 v89, v136
	s_mov_b32 s2, s67
	v_mov_b32_e32 v134, v135
	v_mov_b32_e32 v135, v136
	v_pk_mul_f32 v[140:141], v[88:89], s[2:3] op_sel_hi:[1,0]
	v_pk_fma_f32 v[88:89], v[88:89], s[2:3], v[120:121] op_sel_hi:[1,0,1]
	v_pk_fma_f32 v[104:105], v[134:135], s[2:3], v[104:105] op_sel_hi:[1,0,1]
	v_pk_mul_f32 v[142:143], v[88:89], v[88:89]
	v_pk_mul_f32 v[134:135], v[104:105], v[104:105]
	v_pk_mov_b32 v[120:121], v[120:121], v[142:143] op_sel:[1,0]
	v_pk_mov_b32 v[134:135], v[140:141], v[134:135] op_sel:[1,0]
	v_add_f32_e32 v72, 0, v73
	v_pk_add_f32 v[120:121], v[120:121], v[134:135]
	v_pk_add_f32 v[134:135], v[88:89], v[104:105]
	v_pk_mul_f32 v[140:141], v[88:89], v[104:105]
	v_fmac_f32_e32 v72, 0x3fd744fd, v137
	v_mov_b32_e32 v135, v141
	v_pk_add_f32 v[120:121], v[134:135], v[120:121]
	v_mul_f32_e32 v73, v72, v72
	v_pk_add_f32 v[120:121], v[120:121], v[72:73]
	s_nop 1
	v_mov_b32_dpp v134, v120 quad_perm:[1,0,3,2] row_mask:0xf bank_mask:0xf bound_ctrl:1
	v_mov_b32_dpp v135, v121 quad_perm:[1,0,3,2] row_mask:0xf bank_mask:0xf bound_ctrl:1
	v_pk_add_f32 v[120:121], v[120:121], v[134:135]
	s_nop 1
	v_mov_b32_dpp v134, v120 quad_perm:[2,3,0,1] row_mask:0xf bank_mask:0xf bound_ctrl:1
	v_mov_b32_dpp v135, v121 quad_perm:[2,3,0,1] row_mask:0xf bank_mask:0xf bound_ctrl:1
	v_pk_add_f32 v[120:121], v[120:121], v[134:135]
	s_nop 1
	v_mov_b32_dpp v134, v120 row_half_mirror row_mask:0xf bank_mask:0xf bound_ctrl:1
	v_mov_b32_dpp v135, v121 row_half_mirror row_mask:0xf bank_mask:0xf bound_ctrl:1
	v_pk_add_f32 v[120:121], v[120:121], v[134:135]
	s_nop 1
	v_mov_b32_dpp v134, v120 row_mirror row_mask:0xf bank_mask:0xf bound_ctrl:1
	v_mov_b32_dpp v135, v121 row_mirror row_mask:0xf bank_mask:0xf bound_ctrl:1
	s_and_saveexec_b64 s[6:7], vcc
	v_pk_add_f32 v[120:121], v[120:121], v[134:135]
	ds_write_b64 v179, v[120:121] offset:88
	s_or_b64 exec, exec, s[6:7]
	v_or_b32_e32 v120, 32, v159
	v_ashrrev_i32_e32 v121, 31, v120
	v_lshlrev_b64 v[120:121], 12, v[120:121]
	v_readfirstlane_b32 s2, v158
	v_lshl_add_u64 v[120:121], s[10:11], 0, v[120:121]
	s_lshl_b32 s2, s2, 13
	v_lshl_add_u64 v[120:121], v[182:183], 2, v[120:121]
	s_waitcnt lgkmcnt(0)
	v_lshl_add_u64 v[120:121], v[120:121], 0, v[0:1]
	s_mov_b32 m0, s2
	s_mov_b64 s[6:7], 0x2000
	global_load_lds_dwordx4 v[120:121], off
	v_lshl_add_u64 v[134:135], v[120:121], 0, s[6:7]
	s_or_b32 m0, s2, 0x400
	s_mov_b64 s[6:7], 0x4000
	global_load_lds_dwordx4 v[134:135], off
	v_lshl_add_u64 v[134:135], v[120:121], 0, s[6:7]
	s_or_b32 m0, s2, 0x800
	s_mov_b64 s[6:7], 0x6000
	global_load_lds_dwordx4 v[134:135], off
	v_lshl_add_u64 v[134:135], v[120:121], 0, s[6:7]
	s_or_b32 m0, s2, 0xc00
	s_mov_b64 s[6:7], 0x8000
	global_load_lds_dwordx4 v[134:135], off
	v_lshl_add_u64 v[134:135], v[120:121], 0, s[6:7]
	s_or_b32 m0, s2, 0x1000
	s_mov_b64 s[6:7], 0xa000
	global_load_lds_dwordx4 v[134:135], off
	v_lshl_add_u64 v[134:135], v[120:121], 0, s[6:7]
	s_or_b32 m0, s2, 0x1400
	s_mov_b64 s[6:7], 0xc000
	global_load_lds_dwordx4 v[134:135], off
	v_lshl_add_u64 v[134:135], v[120:121], 0, s[6:7]
	s_or_b32 m0, s2, 0x1800
	s_mov_b64 s[6:7], 0xe000
	global_load_lds_dwordx4 v[134:135], off
	v_lshl_add_u64 v[120:121], v[120:121], 0, s[6:7]
	s_or_b32 m0, s2, 0x1c00
	v_add_u32_e32 v105, 0x10000, v138
	global_load_lds_dwordx4 v[120:121], off
	s_waitcnt vmcnt(8)
;   DI void operator()(f32x16 (&acc)[2][4], int grow0, int gcol0, int lane, int w, char* lds) {
;     ...
; #pragma unroll
;       for (int qq = 0; qq < 2; ++qq)
; #pragma unroll
;         for (int e = 0; e < 4; ++e) {
;           const int i = 4 * (2 * (ps & 1) + qq) + e;
;           const float* xr = (const float*)(xs + (8 * qq + 4 * hh + e) * 512) + l31;
;           float s1 = 0.f, s2 = 0.f;
; #pragma unroll
;           for (int nt = 0; nt < 4; ++nt) {
;             float v = (acc[mt][nt][i] + bia[nt]) * csc[nt];
;             float z = ALPHA * xr[nt * 32] + hs * v;
;             acc[mt][nt][i] = z; s1 += z; s2 += z * z;
;           }
;           s1 = row16_sum(s1); s2 = row16_sum(s2);
;           if ((lane & 15) == 0) { f32x2 sv = {s1, s2}; *(f32x2*)(redw + (mt * 32 + (i & 3) + 8 * (i >> 2)) * 2) = sv; }
;         }
	v_add_u32_e32 v73, v105, v154
	ds_read2_b32 v[134:135], v73 offset1:32
	ds_read2_b32 v[138:139], v73 offset0:64 offset1:96
	v_mov_b32_e32 v136, v122
	v_mov_b32_e32 v137, v90
	v_pk_add_f32 v[140:141], v[136:137], 0 op_sel_hi:[1,0]
	v_mov_b32_e32 v136, v106
	v_pk_add_f32 v[136:137], v[136:137], 0 op_sel_hi:[1,0]
	s_waitcnt lgkmcnt(0)
	v_mov_b32_e32 v142, v134
	v_mov_b32_e32 v143, v138
	s_mov_b32 s2, s67
	v_mov_b32_e32 v148, v135
	v_mov_b32_e32 v149, v138
	v_pk_fma_f32 v[134:135], v[142:143], s[2:3], v[140:141] op_sel_hi:[1,0,1]
	v_pk_fma_f32 v[136:137], v[148:149], s[2:3], v[136:137] op_sel_hi:[1,0,1]
	v_pk_mul_f32 v[144:145], v[142:143], s[2:3] op_sel_hi:[1,0]
	v_pk_mul_f32 v[142:143], v[134:135], v[134:135]
	v_pk_mul_f32 v[148:149], v[136:137], v[136:137]
	v_pk_mov_b32 v[140:141], v[140:141], v[142:143] op_sel:[1,0]
	v_pk_mov_b32 v[142:143], v[144:145], v[148:149] op_sel:[1,0]
	v_add_f32_e32 v120, 0, v74
	v_pk_add_f32 v[140:141], v[140:141], v[142:143]
	v_pk_add_f32 v[142:143], v[134:135], v[136:137]
	v_pk_mul_f32 v[144:145], v[134:135], v[136:137]
	v_fmac_f32_e32 v120, 0x3fd744fd, v139
	v_mov_b32_e32 v143, v145
	v_pk_add_f32 v[140:141], v[142:143], v[140:141]
	v_mul_f32_e32 v121, v120, v120
	v_pk_add_f32 v[138:139], v[140:141], v[120:121]
	s_nop 1
	v_mov_b32_dpp v140, v138 quad_perm:[1,0,3,2] row_mask:0xf bank_mask:0xf bound_ctrl:1
	v_mov_b32_dpp v141, v139 quad_perm:[1,0,3,2] row_mask:0xf bank_mask:0xf bound_ctrl:1
	v_pk_add_f32 v[138:139], v[138:139], v[140:141]
	s_nop 1
	v_mov_b32_dpp v140, v138 quad_perm:[2,3,0,1] row_mask:0xf bank_mask:0xf bound_ctrl:1
	v_mov_b32_dpp v141, v139 quad_perm:[2,3,0,1] row_mask:0xf bank_mask:0xf bound_ctrl:1
	v_pk_add_f32 v[138:139], v[138:139], v[140:141]
	s_nop 1
	v_mov_b32_dpp v140, v138 row_half_mirror row_mask:0xf bank_mask:0xf bound_ctrl:1
	v_mov_b32_dpp v141, v139 row_half_mirror row_mask:0xf bank_mask:0xf bound_ctrl:1
	v_pk_add_f32 v[138:139], v[138:139], v[140:141]
	s_nop 1
	v_mov_b32_dpp v140, v138 row_mirror row_mask:0xf bank_mask:0xf bound_ctrl:1
	v_mov_b32_dpp v141, v139 row_mirror row_mask:0xf bank_mask:0xf bound_ctrl:1
	s_and_saveexec_b64 s[6:7], vcc
	v_pk_add_f32 v[138:139], v[138:139], v[140:141]
	ds_write_b64 v179, v[138:139] offset:128
	s_or_b64 exec, exec, s[6:7]
	v_or_b32_e32 v74, 0x200, v154
	v_add_u32_e32 v85, v105, v74
	ds_read2_b32 v[138:139], v85 offset1:32
	ds_read2_b32 v[140:141], v85 offset0:64 offset1:96
	v_mov_b32_e32 v90, v123
	v_pk_add_f32 v[142:143], v[90:91], 0 op_sel_hi:[1,0]
	v_mov_b32_e32 v90, v107
	v_pk_add_f32 v[90:91], v[90:91], 0 op_sel_hi:[1,0]
	s_waitcnt lgkmcnt(1)
	v_mov_b32_e32 v106, v138
	s_waitcnt lgkmcnt(0)
	v_mov_b32_e32 v107, v140
	s_mov_b32 s2, s67
	v_mov_b32_e32 v122, v139
	v_mov_b32_e32 v123, v140
	v_pk_mul_f32 v[144:145], v[106:107], s[2:3] op_sel_hi:[1,0]
	v_pk_fma_f32 v[106:107], v[106:107], s[2:3], v[142:143] op_sel_hi:[1,0,1]
	v_pk_fma_f32 v[122:123], v[122:123], s[2:3], v[90:91] op_sel_hi:[1,0,1]
	v_pk_mul_f32 v[138:139], v[106:107], v[106:107]
	v_pk_mul_f32 v[90:91], v[122:123], v[122:123]
	v_pk_mov_b32 v[138:139], v[142:143], v[138:139] op_sel:[1,0]
	v_pk_mov_b32 v[90:91], v[144:145], v[90:91] op_sel:[1,0]
	v_add_f32_e32 v74, 0, v75
	v_pk_add_f32 v[90:91], v[138:139], v[90:91]
	v_pk_add_f32 v[138:139], v[106:107], v[122:123]
	v_pk_mul_f32 v[142:143], v[106:107], v[122:123]
	v_fmac_f32_e32 v74, 0x3fd744fd, v141
	v_mov_b32_e32 v139, v143
	v_pk_add_f32 v[90:91], v[138:139], v[90:91]
	v_mul_f32_e32 v75, v74, v74
	v_pk_add_f32 v[90:91], v[90:91], v[74:75]
	s_nop 1
	v_mov_b32_dpp v138, v90 quad_perm:[1,0,3,2] row_mask:0xf bank_mask:0xf bound_ctrl:1
	v_mov_b32_dpp v139, v91 quad_perm:[1,0,3,2] row_mask:0xf bank_mask:0xf bound_ctrl:1
	v_pk_add_f32 v[90:91], v[90:91], v[138:139]
	s_nop 1
	v_mov_b32_dpp v138, v90 quad_perm:[2,3,0,1] row_mask:0xf bank_mask:0xf bound_ctrl:1
	v_mov_b32_dpp v139, v91 quad_perm:[2,3,0,1] row_mask:0xf bank_mask:0xf bound_ctrl:1
	v_pk_add_f32 v[90:91], v[90:91], v[138:139]
	s_nop 1
	v_mov_b32_dpp v138, v90 row_half_mirror row_mask:0xf bank_mask:0xf bound_ctrl:1
	v_mov_b32_dpp v139, v91 row_half_mirror row_mask:0xf bank_mask:0xf bound_ctrl:1
	v_pk_add_f32 v[90:91], v[90:91], v[138:139]
	s_nop 1
	v_mov_b32_dpp v138, v90 row_mirror row_mask:0xf bank_mask:0xf bound_ctrl:1
	v_mov_b32_dpp v139, v91 row_mirror row_mask:0xf bank_mask:0xf bound_ctrl:1
	s_and_saveexec_b64 s[6:7], vcc
	v_pk_add_f32 v[90:91], v[90:91], v[138:139]
	ds_write_b64 v179, v[90:91] offset:136
	s_or_b64 exec, exec, s[6:7]
	v_or_b32_e32 v75, 0x400, v154
	v_add_u32_e32 v75, v105, v75
	ds_read2_b32 v[138:139], v75 offset1:32
	ds_read2_b32 v[142:143], v75 offset0:64 offset1:96
	v_mov_b32_e32 v140, v124
	v_mov_b32_e32 v141, v92
	v_pk_add_f32 v[144:145], v[140:141], 0 op_sel_hi:[1,0]
	v_mov_b32_e32 v140, v108
	v_pk_add_f32 v[140:141], v[140:141], 0 op_sel_hi:[1,0]
	s_waitcnt lgkmcnt(1)
	v_mov_b32_e32 v148, v138
	s_waitcnt lgkmcnt(0)
;   DI void operator()(f32x16 (&acc)[2][4], int grow0, int gcol0, int lane, int w, char* lds) {
;     ...
; #pragma unroll
;       for (int qq = 0; qq < 2; ++qq)
; #pragma unroll
;         for (int e = 0; e < 4; ++e) {
;           const int i = 4 * (2 * (ps & 1) + qq) + e;
;           const float* xr = (const float*)(xs + (8 * qq + 4 * hh + e) * 512) + l31;
;           float s1 = 0.f, s2 = 0.f;
; #pragma unroll
;           for (int nt = 0; nt < 4; ++nt) {
;             float v = (acc[mt][nt][i] + bia[nt]) * csc[nt];
;             float z = ALPHA * xr[nt * 32] + hs * v;
;             acc[mt][nt][i] = z; s1 += z; s2 += z * z;
;           }
;           s1 = row16_sum(s1); s2 = row16_sum(s2);
;           if ((lane & 15) == 0) { f32x2 sv = {s1, s2}; *(f32x2*)(redw + (mt * 32 + (i & 3) + 8 * (i >> 2)) * 2) = sv; }
;         }
	v_mov_b32_e32 v149, v142
	s_mov_b32 s2, s67
	v_mov_b32_e32 v160, v139
	v_mov_b32_e32 v161, v142
	v_pk_fma_f32 v[138:139], v[148:149], s[2:3], v[144:145] op_sel_hi:[1,0,1]
	v_pk_fma_f32 v[140:141], v[160:161], s[2:3], v[140:141] op_sel_hi:[1,0,1]
	v_pk_mul_f32 v[156:157], v[148:149], s[2:3] op_sel_hi:[1,0]
	v_pk_mul_f32 v[148:149], v[138:139], v[138:139]
	v_pk_mul_f32 v[160:161], v[140:141], v[140:141]
	v_pk_mov_b32 v[144:145], v[144:145], v[148:149] op_sel:[1,0]
	v_pk_mov_b32 v[148:149], v[156:157], v[160:161] op_sel:[1,0]
	v_add_f32_e32 v90, 0, v76
	v_pk_add_f32 v[144:145], v[144:145], v[148:149]
	v_pk_add_f32 v[148:149], v[138:139], v[140:141]
	v_pk_mul_f32 v[156:157], v[138:139], v[140:141]
	v_fmac_f32_e32 v90, 0x3fd744fd, v143
	v_mov_b32_e32 v149, v157
	v_pk_add_f32 v[144:145], v[148:149], v[144:145]
	v_mul_f32_e32 v91, v90, v90
	v_pk_add_f32 v[142:143], v[144:145], v[90:91]
	s_nop 1
	v_mov_b32_dpp v144, v142 quad_perm:[1,0,3,2] row_mask:0xf bank_mask:0xf bound_ctrl:1
	v_mov_b32_dpp v145, v143 quad_perm:[1,0,3,2] row_mask:0xf bank_mask:0xf bound_ctrl:1
	v_pk_add_f32 v[142:143], v[142:143], v[144:145]
	s_nop 1
	v_mov_b32_dpp v144, v142 quad_perm:[2,3,0,1] row_mask:0xf bank_mask:0xf bound_ctrl:1
	v_mov_b32_dpp v145, v143 quad_perm:[2,3,0,1] row_mask:0xf bank_mask:0xf bound_ctrl:1
	v_pk_add_f32 v[142:143], v[142:143], v[144:145]
	s_nop 1
	v_mov_b32_dpp v144, v142 row_half_mirror row_mask:0xf bank_mask:0xf bound_ctrl:1
	v_mov_b32_dpp v145, v143 row_half_mirror row_mask:0xf bank_mask:0xf bound_ctrl:1
	v_pk_add_f32 v[142:143], v[142:143], v[144:145]
	s_nop 1
	v_mov_b32_dpp v144, v142 row_mirror row_mask:0xf bank_mask:0xf bound_ctrl:1
	v_mov_b32_dpp v145, v143 row_mirror row_mask:0xf bank_mask:0xf bound_ctrl:1
	s_and_saveexec_b64 s[6:7], vcc
	v_pk_add_f32 v[142:143], v[142:143], v[144:145]
	ds_write_b64 v179, v[142:143] offset:144
	s_or_b64 exec, exec, s[6:7]
	v_add_u32_e32 v87, v105, v146
	ds_read2_b32 v[142:143], v87 offset1:32
	ds_read2_b32 v[144:145], v87 offset0:64 offset1:96
	v_mov_b32_e32 v92, v125
	v_pk_add_f32 v[146:147], v[92:93], 0 op_sel_hi:[1,0]
	v_mov_b32_e32 v92, v109
	v_pk_add_f32 v[92:93], v[92:93], 0 op_sel_hi:[1,0]
	s_waitcnt lgkmcnt(1)
	v_mov_b32_e32 v108, v142
	s_waitcnt lgkmcnt(0)
	v_mov_b32_e32 v109, v144
	s_mov_b32 s2, s67
	v_mov_b32_e32 v124, v143
	v_mov_b32_e32 v125, v144
	v_pk_mul_f32 v[148:149], v[108:109], s[2:3] op_sel_hi:[1,0]
	v_pk_fma_f32 v[108:109], v[108:109], s[2:3], v[146:147] op_sel_hi:[1,0,1]
	v_pk_fma_f32 v[124:125], v[124:125], s[2:3], v[92:93] op_sel_hi:[1,0,1]
	v_pk_mul_f32 v[142:143], v[108:109], v[108:109]
	v_pk_mul_f32 v[92:93], v[124:125], v[124:125]
	v_pk_mov_b32 v[142:143], v[146:147], v[142:143] op_sel:[1,0]
	v_pk_mov_b32 v[92:93], v[148:149], v[92:93] op_sel:[1,0]
	v_add_f32_e32 v76, 0, v77
	v_pk_add_f32 v[92:93], v[142:143], v[92:93]
	v_pk_add_f32 v[142:143], v[108:109], v[124:125]
	v_pk_mul_f32 v[146:147], v[108:109], v[124:125]
	v_fmac_f32_e32 v76, 0x3fd744fd, v145
	v_mov_b32_e32 v143, v147
	v_pk_add_f32 v[92:93], v[142:143], v[92:93]
	v_mul_f32_e32 v77, v76, v76
	v_pk_add_f32 v[92:93], v[92:93], v[76:77]
	s_nop 1
	v_mov_b32_dpp v142, v92 quad_perm:[1,0,3,2] row_mask:0xf bank_mask:0xf bound_ctrl:1
	v_mov_b32_dpp v143, v93 quad_perm:[1,0,3,2] row_mask:0xf bank_mask:0xf bound_ctrl:1
	v_pk_add_f32 v[92:93], v[92:93], v[142:143]
	s_nop 1
	v_mov_b32_dpp v142, v92 quad_perm:[2,3,0,1] row_mask:0xf bank_mask:0xf bound_ctrl:1
	v_mov_b32_dpp v143, v93 quad_perm:[2,3,0,1] row_mask:0xf bank_mask:0xf bound_ctrl:1
	v_pk_add_f32 v[92:93], v[92:93], v[142:143]
	s_nop 1
	v_mov_b32_dpp v142, v92 row_half_mirror row_mask:0xf bank_mask:0xf bound_ctrl:1
	v_mov_b32_dpp v143, v93 row_half_mirror row_mask:0xf bank_mask:0xf bound_ctrl:1
	v_pk_add_f32 v[92:93], v[92:93], v[142:143]
	s_nop 1
	v_mov_b32_dpp v142, v92 row_mirror row_mask:0xf bank_mask:0xf bound_ctrl:1
	v_mov_b32_dpp v143, v93 row_mirror row_mask:0xf bank_mask:0xf bound_ctrl:1
	s_and_saveexec_b64 s[6:7], vcc
	v_pk_add_f32 v[92:93], v[92:93], v[142:143]
	ds_write_b64 v179, v[92:93] offset:152
	s_or_b64 exec, exec, s[6:7]
	v_or_b32_e32 v77, 0x1000, v154
	v_add_u32_e32 v77, v105, v77
	ds_read2_b32 v[142:143], v77 offset1:32
	ds_read2_b32 v[146:147], v77 offset0:64 offset1:96
	v_mov_b32_e32 v144, v126
	v_mov_b32_e32 v145, v94
	v_pk_add_f32 v[148:149], v[144:145], 0 op_sel_hi:[1,0]
	v_mov_b32_e32 v144, v110
	v_pk_add_f32 v[144:145], v[144:145], 0 op_sel_hi:[1,0]
	s_waitcnt lgkmcnt(1)
	v_mov_b32_e32 v156, v142
	s_waitcnt lgkmcnt(0)
	v_mov_b32_e32 v157, v146
	s_mov_b32 s2, s67
	v_mov_b32_e32 v170, v143
	v_mov_b32_e32 v171, v146
	v_pk_fma_f32 v[142:143], v[156:157], s[2:3], v[148:149] op_sel_hi:[1,0,1]
	v_pk_fma_f32 v[144:145], v[170:171], s[2:3], v[144:145] op_sel_hi:[1,0,1]
	v_pk_mul_f32 v[160:161], v[156:157], s[2:3] op_sel_hi:[1,0]
	v_pk_mul_f32 v[156:157], v[142:143], v[142:143]
	v_pk_mul_f32 v[170:171], v[144:145], v[144:145]
	v_pk_mov_b32 v[148:149], v[148:149], v[156:157] op_sel:[1,0]
	v_pk_mov_b32 v[156:157], v[160:161], v[170:171] op_sel:[1,0]
	v_add_f32_e32 v92, 0, v78
	v_pk_add_f32 v[148:149], v[148:149], v[156:157]
	v_pk_add_f32 v[156:157], v[142:143], v[144:145]
	v_pk_mul_f32 v[160:161], v[142:143], v[144:145]
	v_fmac_f32_e32 v92, 0x3fd744fd, v147
	v_mov_b32_e32 v157, v161
	v_pk_add_f32 v[148:149], v[156:157], v[148:149]
	v_mul_f32_e32 v93, v92, v92
	v_pk_add_f32 v[146:147], v[148:149], v[92:93]
	s_nop 1
	v_mov_b32_dpp v148, v146 quad_perm:[1,0,3,2] row_mask:0xf bank_mask:0xf bound_ctrl:1
	v_mov_b32_dpp v149, v147 quad_perm:[1,0,3,2] row_mask:0xf bank_mask:0xf bound_ctrl:1
	v_pk_add_f32 v[146:147], v[146:147], v[148:149]
	s_nop 1
	v_mov_b32_dpp v148, v146 quad_perm:[2,3,0,1] row_mask:0xf bank_mask:0xf bound_ctrl:1
	v_mov_b32_dpp v149, v147 quad_perm:[2,3,0,1] row_mask:0xf bank_mask:0xf bound_ctrl:1
	v_pk_add_f32 v[146:147], v[146:147], v[148:149]
	s_nop 1
	v_mov_b32_dpp v148, v146 row_half_mirror row_mask:0xf bank_mask:0xf bound_ctrl:1
	v_mov_b32_dpp v149, v147 row_half_mirror row_mask:0xf bank_mask:0xf bound_ctrl:1
	v_pk_add_f32 v[146:147], v[146:147], v[148:149]
	s_nop 1
	v_mov_b32_dpp v148, v146 row_mirror row_mask:0xf bank_mask:0xf bound_ctrl:1
	v_mov_b32_dpp v149, v147 row_mirror row_mask:0xf bank_mask:0xf bound_ctrl:1
	s_and_saveexec_b64 s[6:7], vcc
	v_pk_add_f32 v[146:147], v[146:147], v[148:149]
	ds_write_b64 v179, v[146:147] offset:192
	s_or_b64 exec, exec, s[6:7]
	v_or_b32_e32 v78, 0x1200, v154
	v_add_u32_e32 v91, v105, v78
	ds_read2_b32 v[146:147], v91 offset1:32
	ds_read2_b32 v[148:149], v91 offset0:64 offset1:96
	v_mov_b32_e32 v94, v127
	v_pk_add_f32 v[156:157], v[94:95], 0 op_sel_hi:[1,0]
	v_mov_b32_e32 v94, v111
	v_pk_add_f32 v[94:95], v[94:95], 0 op_sel_hi:[1,0]
	s_waitcnt lgkmcnt(1)
;   DI void operator()(f32x16 (&acc)[2][4], int grow0, int gcol0, int lane, int w, char* lds) {
;     ...
; #pragma unroll
;       for (int qq = 0; qq < 2; ++qq)
; #pragma unroll
;         for (int e = 0; e < 4; ++e) {
;           const int i = 4 * (2 * (ps & 1) + qq) + e;
;           const float* xr = (const float*)(xs + (8 * qq + 4 * hh + e) * 512) + l31;
;           float s1 = 0.f, s2 = 0.f;
; #pragma unroll
;           for (int nt = 0; nt < 4; ++nt) {
;             float v = (acc[mt][nt][i] + bia[nt]) * csc[nt];
;             float z = ALPHA * xr[nt * 32] + hs * v;
;             acc[mt][nt][i] = z; s1 += z; s2 += z * z;
;           }
;           s1 = row16_sum(s1); s2 = row16_sum(s2);
;           if ((lane & 15) == 0) { f32x2 sv = {s1, s2}; *(f32x2*)(redw + (mt * 32 + (i & 3) + 8 * (i >> 2)) * 2) = sv; }
;         }
	v_mov_b32_e32 v110, v146
	s_waitcnt lgkmcnt(0)
	v_mov_b32_e32 v111, v148
	s_mov_b32 s2, s67
	v_mov_b32_e32 v126, v147
	v_mov_b32_e32 v127, v148
	v_pk_mul_f32 v[160:161], v[110:111], s[2:3] op_sel_hi:[1,0]
	v_pk_fma_f32 v[110:111], v[110:111], s[2:3], v[156:157] op_sel_hi:[1,0,1]
	v_pk_fma_f32 v[126:127], v[126:127], s[2:3], v[94:95] op_sel_hi:[1,0,1]
	v_pk_mul_f32 v[146:147], v[110:111], v[110:111]
	v_pk_mul_f32 v[94:95], v[126:127], v[126:127]
	v_pk_mov_b32 v[146:147], v[156:157], v[146:147] op_sel:[1,0]
	v_pk_mov_b32 v[94:95], v[160:161], v[94:95] op_sel:[1,0]
	v_add_f32_e32 v78, 0, v79
	v_pk_add_f32 v[94:95], v[146:147], v[94:95]
	v_pk_add_f32 v[146:147], v[110:111], v[126:127]
	v_pk_mul_f32 v[156:157], v[110:111], v[126:127]
	v_fmac_f32_e32 v78, 0x3fd744fd, v149
	v_mov_b32_e32 v147, v157
	v_pk_add_f32 v[94:95], v[146:147], v[94:95]
	v_mul_f32_e32 v79, v78, v78
	v_pk_add_f32 v[94:95], v[94:95], v[78:79]
	s_nop 1
	v_mov_b32_dpp v146, v94 quad_perm:[1,0,3,2] row_mask:0xf bank_mask:0xf bound_ctrl:1
	v_mov_b32_dpp v147, v95 quad_perm:[1,0,3,2] row_mask:0xf bank_mask:0xf bound_ctrl:1
	v_pk_add_f32 v[94:95], v[94:95], v[146:147]
	s_nop 1
	v_mov_b32_dpp v146, v94 quad_perm:[2,3,0,1] row_mask:0xf bank_mask:0xf bound_ctrl:1
	v_mov_b32_dpp v147, v95 quad_perm:[2,3,0,1] row_mask:0xf bank_mask:0xf bound_ctrl:1
	v_pk_add_f32 v[94:95], v[94:95], v[146:147]
	s_nop 1
	v_mov_b32_dpp v146, v94 row_half_mirror row_mask:0xf bank_mask:0xf bound_ctrl:1
	v_mov_b32_dpp v147, v95 row_half_mirror row_mask:0xf bank_mask:0xf bound_ctrl:1
	v_pk_add_f32 v[94:95], v[94:95], v[146:147]
	s_nop 1
	v_mov_b32_dpp v146, v94 row_mirror row_mask:0xf bank_mask:0xf bound_ctrl:1
	v_mov_b32_dpp v147, v95 row_mirror row_mask:0xf bank_mask:0xf bound_ctrl:1
	s_and_saveexec_b64 s[6:7], vcc
	v_pk_add_f32 v[94:95], v[94:95], v[146:147]
	ds_write_b64 v179, v[94:95] offset:200
	s_or_b64 exec, exec, s[6:7]
	v_or_b32_e32 v79, 0x1400, v154
	v_add_u32_e32 v79, v105, v79
	ds_read2_b32 v[146:147], v79 offset1:32
	ds_read2_b32 v[154:155], v79 offset0:64 offset1:96
	v_mov_b32_e32 v148, v128
	v_mov_b32_e32 v149, v96
	v_pk_add_f32 v[156:157], v[148:149], 0 op_sel_hi:[1,0]
	v_mov_b32_e32 v148, v112
	v_pk_add_f32 v[148:149], v[148:149], 0 op_sel_hi:[1,0]
	s_waitcnt lgkmcnt(1)
	v_mov_b32_e32 v160, v146
	s_waitcnt lgkmcnt(0)
	v_mov_b32_e32 v161, v154
	s_mov_b32 s2, s67
	v_mov_b32_e32 v174, v147
	v_mov_b32_e32 v175, v154
	v_pk_fma_f32 v[146:147], v[160:161], s[2:3], v[156:157] op_sel_hi:[1,0,1]
	v_pk_fma_f32 v[148:149], v[174:175], s[2:3], v[148:149] op_sel_hi:[1,0,1]
	v_pk_mul_f32 v[170:171], v[160:161], s[2:3] op_sel_hi:[1,0]
	v_pk_mul_f32 v[160:161], v[146:147], v[146:147]
	v_pk_mul_f32 v[174:175], v[148:149], v[148:149]
	v_pk_mov_b32 v[156:157], v[156:157], v[160:161] op_sel:[1,0]
	v_pk_mov_b32 v[160:161], v[170:171], v[174:175] op_sel:[1,0]
	v_add_f32_e32 v94, 0, v80
	v_pk_add_f32 v[156:157], v[156:157], v[160:161]
	v_pk_add_f32 v[160:161], v[146:147], v[148:149]
	v_pk_mul_f32 v[170:171], v[146:147], v[148:149]
	v_fmac_f32_e32 v94, 0x3fd744fd, v155
	v_mov_b32_e32 v161, v171
	v_pk_add_f32 v[156:157], v[160:161], v[156:157]
	v_mul_f32_e32 v95, v94, v94
	v_pk_add_f32 v[154:155], v[156:157], v[94:95]
	s_nop 1
	v_mov_b32_dpp v156, v154 quad_perm:[1,0,3,2] row_mask:0xf bank_mask:0xf bound_ctrl:1
	v_mov_b32_dpp v157, v155 quad_perm:[1,0,3,2] row_mask:0xf bank_mask:0xf bound_ctrl:1
	v_pk_add_f32 v[154:155], v[154:155], v[156:157]
	s_nop 1
	v_mov_b32_dpp v156, v154 quad_perm:[2,3,0,1] row_mask:0xf bank_mask:0xf bound_ctrl:1
	v_mov_b32_dpp v157, v155 quad_perm:[2,3,0,1] row_mask:0xf bank_mask:0xf bound_ctrl:1
	v_pk_add_f32 v[154:155], v[154:155], v[156:157]
	s_nop 1
	v_mov_b32_dpp v156, v154 row_half_mirror row_mask:0xf bank_mask:0xf bound_ctrl:1
	v_mov_b32_dpp v157, v155 row_half_mirror row_mask:0xf bank_mask:0xf bound_ctrl:1
	v_pk_add_f32 v[154:155], v[154:155], v[156:157]
	s_nop 1
	v_mov_b32_dpp v156, v154 row_mirror row_mask:0xf bank_mask:0xf bound_ctrl:1
	v_mov_b32_dpp v157, v155 row_mirror row_mask:0xf bank_mask:0xf bound_ctrl:1
	s_and_saveexec_b64 s[6:7], vcc
	v_pk_add_f32 v[154:155], v[154:155], v[156:157]
	ds_write_b64 v179, v[154:155] offset:208
	s_or_b64 exec, exec, s[6:7]
	v_add_u32_e32 v93, v105, v101
	ds_read2_b32 v[154:155], v93 offset1:32
	ds_read2_b32 v[156:157], v93 offset0:64 offset1:96
	v_mov_b32_e32 v96, v129
	v_pk_add_f32 v[128:129], v[96:97], 0 op_sel_hi:[1,0]
	v_mov_b32_e32 v96, v113
	v_pk_add_f32 v[112:113], v[96:97], 0 op_sel_hi:[1,0]
	s_waitcnt lgkmcnt(1)
	v_mov_b32_e32 v96, v154
	s_waitcnt lgkmcnt(0)
	v_mov_b32_e32 v97, v156
	s_mov_b32 s2, s67
	v_mov_b32_e32 v154, v155
	v_mov_b32_e32 v155, v156
	v_pk_mul_f32 v[160:161], v[96:97], s[2:3] op_sel_hi:[1,0]
	v_pk_fma_f32 v[96:97], v[96:97], s[2:3], v[128:129] op_sel_hi:[1,0,1]
	v_pk_fma_f32 v[112:113], v[154:155], s[2:3], v[112:113] op_sel_hi:[1,0,1]
	v_pk_mul_f32 v[170:171], v[96:97], v[96:97]
	v_pk_mul_f32 v[154:155], v[112:113], v[112:113]
	v_pk_mov_b32 v[128:129], v[128:129], v[170:171] op_sel:[1,0]
	v_pk_mov_b32 v[154:155], v[160:161], v[154:155] op_sel:[1,0]
	v_add_f32_e32 v80, 0, v81
	v_pk_add_f32 v[128:129], v[128:129], v[154:155]
	v_pk_add_f32 v[154:155], v[96:97], v[112:113]
	v_pk_mul_f32 v[160:161], v[96:97], v[112:113]
	v_fmac_f32_e32 v80, 0x3fd744fd, v157
	v_mov_b32_e32 v155, v161
	v_pk_add_f32 v[128:129], v[154:155], v[128:129]
	v_mul_f32_e32 v81, v80, v80
	v_pk_add_f32 v[128:129], v[128:129], v[80:81]
	s_nop 1
	v_mov_b32_dpp v154, v128 quad_perm:[1,0,3,2] row_mask:0xf bank_mask:0xf bound_ctrl:1
	v_mov_b32_dpp v155, v129 quad_perm:[1,0,3,2] row_mask:0xf bank_mask:0xf bound_ctrl:1
	v_pk_add_f32 v[128:129], v[128:129], v[154:155]
	s_nop 1
	v_mov_b32_dpp v154, v128 quad_perm:[2,3,0,1] row_mask:0xf bank_mask:0xf bound_ctrl:1
	v_mov_b32_dpp v155, v129 quad_perm:[2,3,0,1] row_mask:0xf bank_mask:0xf bound_ctrl:1
	v_pk_add_f32 v[128:129], v[128:129], v[154:155]
	s_nop 1
	v_mov_b32_dpp v154, v128 row_half_mirror row_mask:0xf bank_mask:0xf bound_ctrl:1
	v_mov_b32_dpp v155, v129 row_half_mirror row_mask:0xf bank_mask:0xf bound_ctrl:1
	v_pk_add_f32 v[128:129], v[128:129], v[154:155]
	s_nop 1
	v_mov_b32_dpp v154, v128 row_mirror row_mask:0xf bank_mask:0xf bound_ctrl:1
	v_mov_b32_dpp v155, v129 row_mirror row_mask:0xf bank_mask:0xf bound_ctrl:1
	s_and_saveexec_b64 s[6:7], vcc
	v_pk_add_f32 v[128:129], v[128:129], v[154:155]
	ds_write_b64 v179, v[128:129] offset:216
	s_or_b64 exec, exec, s[6:7]
	v_or_b32_e32 v128, 48, v159
	v_ashrrev_i32_e32 v129, 31, v128
	v_lshlrev_b64 v[128:129], 12, v[128:129]
	v_readfirstlane_b32 s2, v158
	v_lshl_add_u64 v[128:129], s[10:11], 0, v[128:129]
	s_lshl_b32 s2, s2, 13
	v_lshl_add_u64 v[128:129], v[182:183], 2, v[128:129]
	s_waitcnt lgkmcnt(0)
;   DI void xpass(int ps, int grow0, int gcol0, int lane, int w, char* lds) const {
;     char* xs = lds + (ps & 1) * 65536 + __builtin_amdgcn_readfirstlane(w) * 8192;
;     const float* xsrc = Xin + (size_t)(grow0 + (ps >> 1) * 32 + (ps & 1) * 16 + (lane >> 5)) * D_ + gcol0 + (lane & 31) * 4;
; #pragma unroll
;     for (int pc = 0; pc < 8; ++pc)
;       __builtin_amdgcn_global_load_lds((const unsigned*)(xsrc + (size_t)(2 * pc) * D_), (__attribute__((address_space(3))) unsigned*)(xs + pc * 1024), 16, 0, 0);
;   }
;   DI void operator()(f32x16 (&acc)[2][4], int grow0, int gcol0, int lane, int w, char* lds) {
;     ...
;     for (int ps = 0; ps < 4; ++ps) {
;       const int mt = ps >> 1;
;       if (ps + 1 < 4) {
;         if (ps >= 1) asm volatile("s_waitcnt lgkmcnt(0)" ::: "memory");
;         xpass(ps + 1, grow0, gcol0, lane, w, lds);
;         if (ps >= 1) asm volatile("s_waitcnt vmcnt(8)" ::: "memory");
;       } else asm volatile("s_waitcnt vmcnt(0)" ::: "memory");
;       const char* xs = lds + (ps & 1) * 65536 + w * 8192;
; #pragma unroll
;       for (int qq = 0; qq < 2; ++qq)
; #pragma unroll
;         for (int e = 0; e < 4; ++e) {
;           const int i = 4 * (2 * (ps & 1) + qq) + e;
;           const float* xr = (const float*)(xs + (8 * qq + 4 * hh + e) * 512) + l31;
;           float s1 = 0.f, s2 = 0.f;
; #pragma unroll
;           for (int nt = 0; nt < 4; ++nt) {
;             float v = (acc[mt][nt][i] + bia[nt]) * csc[nt];
;             float z = ALPHA * xr[nt * 32] + hs * v;
;             acc[mt][nt][i] = z; s1 += z; s2 += z * z;
;           }
;           s1 = row16_sum(s1); s2 = row16_sum(s2);
;           if ((lane & 15) == 0) { f32x2 sv = {s1, s2}; *(f32x2*)(redw + (mt * 32 + (i & 3) + 8 * (i >> 2)) * 2) = sv; }
;         }
	s_add_i32 m0, s2, 0x10000
	v_lshl_add_u64 v[128:129], v[128:129], 0, v[0:1]
	s_mov_b64 s[6:7], 0x2000
	global_load_lds_dwordx4 v[128:129], off
	v_lshl_add_u64 v[154:155], v[128:129], 0, s[6:7]
	s_add_i32 m0, s2, 0x10400
	s_mov_b64 s[6:7], 0x4000
	global_load_lds_dwordx4 v[154:155], off
	v_lshl_add_u64 v[154:155], v[128:129], 0, s[6:7]
	s_add_i32 m0, s2, 0x10800
	s_mov_b64 s[6:7], 0x6000
	global_load_lds_dwordx4 v[154:155], off
	v_lshl_add_u64 v[154:155], v[128:129], 0, s[6:7]
	s_add_i32 m0, s2, 0x10c00
	s_mov_b64 s[6:7], 0x8000
	global_load_lds_dwordx4 v[154:155], off
	v_lshl_add_u64 v[154:155], v[128:129], 0, s[6:7]
	s_add_i32 m0, s2, 0x11000
	s_mov_b64 s[6:7], 0xa000
	global_load_lds_dwordx4 v[154:155], off
	v_lshl_add_u64 v[154:155], v[128:129], 0, s[6:7]
	s_add_i32 m0, s2, 0x11400
	s_mov_b64 s[6:7], 0xc000
	global_load_lds_dwordx4 v[154:155], off
	v_lshl_add_u64 v[154:155], v[128:129], 0, s[6:7]
	s_add_i32 m0, s2, 0x11800
	s_mov_b64 s[6:7], 0xe000
	global_load_lds_dwordx4 v[154:155], off
	v_lshl_add_u64 v[128:129], v[128:129], 0, s[6:7]
	s_add_i32 m0, s2, 0x11c00
	v_mov_b32_e32 v156, v50
	global_load_lds_dwordx4 v[128:129], off
	s_waitcnt vmcnt(8)
	ds_read2_b32 v[154:155], v168 offset1:32
	ds_read2_b32 v[158:159], v168 offset0:64 offset1:96
	v_mov_b32_e32 v157, v18
	v_pk_add_f32 v[160:161], v[156:157], 0 op_sel_hi:[1,0]
	v_mov_b32_e32 v156, v34
	v_pk_add_f32 v[156:157], v[156:157], 0 op_sel_hi:[1,0]
	s_waitcnt lgkmcnt(0)
	v_mov_b32_e32 v170, v154
	v_mov_b32_e32 v171, v158
	s_mov_b32 s2, s67
	v_mov_b32_e32 v176, v155
	v_mov_b32_e32 v177, v158
	v_pk_fma_f32 v[154:155], v[170:171], s[2:3], v[160:161] op_sel_hi:[1,0,1]
	v_pk_fma_f32 v[156:157], v[176:177], s[2:3], v[156:157] op_sel_hi:[1,0,1]
	v_pk_mul_f32 v[174:175], v[170:171], s[2:3] op_sel_hi:[1,0]
	v_pk_mul_f32 v[170:171], v[154:155], v[154:155]
	v_pk_mul_f32 v[176:177], v[156:157], v[156:157]
	v_pk_mov_b32 v[160:161], v[160:161], v[170:171] op_sel:[1,0]
	v_pk_mov_b32 v[170:171], v[174:175], v[176:177] op_sel:[1,0]
	v_add_f32_e32 v128, 0, v2
	v_pk_add_f32 v[160:161], v[160:161], v[170:171]
	v_pk_add_f32 v[170:171], v[154:155], v[156:157]
	v_pk_mul_f32 v[174:175], v[154:155], v[156:157]
	v_fmac_f32_e32 v128, 0x3fd744fd, v159
	v_mov_b32_e32 v171, v175
	v_pk_add_f32 v[160:161], v[170:171], v[160:161]
	v_mul_f32_e32 v129, v128, v128
	v_pk_add_f32 v[158:159], v[160:161], v[128:129]
	s_nop 1
	v_mov_b32_dpp v160, v158 quad_perm:[1,0,3,2] row_mask:0xf bank_mask:0xf bound_ctrl:1
	v_mov_b32_dpp v161, v159 quad_perm:[1,0,3,2] row_mask:0xf bank_mask:0xf bound_ctrl:1
	v_pk_add_f32 v[158:159], v[158:159], v[160:161]
	s_nop 1
	v_mov_b32_dpp v160, v158 quad_perm:[2,3,0,1] row_mask:0xf bank_mask:0xf bound_ctrl:1
	v_mov_b32_dpp v161, v159 quad_perm:[2,3,0,1] row_mask:0xf bank_mask:0xf bound_ctrl:1
	v_pk_add_f32 v[158:159], v[158:159], v[160:161]
	s_nop 1
	v_mov_b32_dpp v160, v158 row_half_mirror row_mask:0xf bank_mask:0xf bound_ctrl:1
	v_mov_b32_dpp v161, v159 row_half_mirror row_mask:0xf bank_mask:0xf bound_ctrl:1
	v_pk_add_f32 v[158:159], v[158:159], v[160:161]
	s_nop 1
	v_mov_b32_dpp v160, v158 row_mirror row_mask:0xf bank_mask:0xf bound_ctrl:1
	v_mov_b32_dpp v161, v159 row_mirror row_mask:0xf bank_mask:0xf bound_ctrl:1
	s_and_saveexec_b64 s[6:7], vcc
	v_pk_add_f32 v[158:159], v[158:159], v[160:161]
	ds_write_b64 v179, v[158:159] offset:256
	s_or_b64 exec, exec, s[6:7]
	ds_read2_b32 v[158:159], v168 offset0:128 offset1:160
	ds_read2_b32 v[160:161], v168 offset0:192 offset1:224
	v_mov_b32_e32 v18, v51
	v_pk_add_f32 v[168:169], v[18:19], 0 op_sel_hi:[1,0]
	v_mov_b32_e32 v18, v35
	v_pk_add_f32 v[18:19], v[18:19], 0 op_sel_hi:[1,0]
	s_waitcnt lgkmcnt(1)
	v_mov_b32_e32 v34, v158
	s_waitcnt lgkmcnt(0)
	v_mov_b32_e32 v35, v160
	s_mov_b32 s2, s67
	v_mov_b32_e32 v50, v159
	v_mov_b32_e32 v51, v160
	v_pk_mul_f32 v[170:171], v[34:35], s[2:3] op_sel_hi:[1,0]
	v_pk_fma_f32 v[34:35], v[34:35], s[2:3], v[168:169] op_sel_hi:[1,0,1]
	v_pk_fma_f32 v[50:51], v[50:51], s[2:3], v[18:19] op_sel_hi:[1,0,1]
	v_pk_mul_f32 v[158:159], v[34:35], v[34:35]
	v_pk_mul_f32 v[18:19], v[50:51], v[50:51]
	v_pk_mov_b32 v[158:159], v[168:169], v[158:159] op_sel:[1,0]
	v_pk_mov_b32 v[18:19], v[170:171], v[18:19] op_sel:[1,0]
	v_add_f32_e32 v2, 0, v3
	v_pk_add_f32 v[18:19], v[158:159], v[18:19]
	v_pk_add_f32 v[158:159], v[34:35], v[50:51]
	v_pk_mul_f32 v[168:169], v[34:35], v[50:51]
	v_fmac_f32_e32 v2, 0x3fd744fd, v161
	v_mov_b32_e32 v159, v169
	v_pk_add_f32 v[18:19], v[158:159], v[18:19]
	v_mul_f32_e32 v3, v2, v2
	v_pk_add_f32 v[18:19], v[18:19], v[2:3]
	s_nop 1
	v_mov_b32_dpp v158, v18 quad_perm:[1,0,3,2] row_mask:0xf bank_mask:0xf bound_ctrl:1
	v_mov_b32_dpp v159, v19 quad_perm:[1,0,3,2] row_mask:0xf bank_mask:0xf bound_ctrl:1
	v_pk_add_f32 v[18:19], v[18:19], v[158:159]
	s_nop 1
	v_mov_b32_dpp v158, v18 quad_perm:[2,3,0,1] row_mask:0xf bank_mask:0xf bound_ctrl:1
	v_mov_b32_dpp v159, v19 quad_perm:[2,3,0,1] row_mask:0xf bank_mask:0xf bound_ctrl:1
	v_pk_add_f32 v[18:19], v[18:19], v[158:159]
	s_nop 1
	v_mov_b32_dpp v158, v18 row_half_mirror row_mask:0xf bank_mask:0xf bound_ctrl:1
	v_mov_b32_dpp v159, v19 row_half_mirror row_mask:0xf bank_mask:0xf bound_ctrl:1
	v_pk_add_f32 v[18:19], v[18:19], v[158:159]
	s_nop 1
	v_mov_b32_dpp v158, v18 row_mirror row_mask:0xf bank_mask:0xf bound_ctrl:1
	v_mov_b32_dpp v159, v19 row_mirror row_mask:0xf bank_mask:0xf bound_ctrl:1
	s_and_saveexec_b64 s[6:7], vcc
	v_pk_add_f32 v[18:19], v[18:19], v[158:159]
	ds_write_b64 v179, v[18:19] offset:264
	s_or_b64 exec, exec, s[6:7]
	ds_read2_b32 v[158:159], v153 offset1:32
	ds_read2_b32 v[168:169], v153 offset0:64 offset1:96
	v_mov_b32_e32 v160, v52
	v_mov_b32_e32 v161, v20
	v_pk_add_f32 v[170:171], v[160:161], 0 op_sel_hi:[1,0]
	v_mov_b32_e32 v160, v36
	v_pk_add_f32 v[160:161], v[160:161], 0 op_sel_hi:[1,0]
	s_waitcnt lgkmcnt(1)
;   DI void operator()(f32x16 (&acc)[2][4], int grow0, int gcol0, int lane, int w, char* lds) {
;     ...
; #pragma unroll
;       for (int qq = 0; qq < 2; ++qq)
; #pragma unroll
;         for (int e = 0; e < 4; ++e) {
;           const int i = 4 * (2 * (ps & 1) + qq) + e;
;           const float* xr = (const float*)(xs + (8 * qq + 4 * hh + e) * 512) + l31;
;           float s1 = 0.f, s2 = 0.f;
; #pragma unroll
;           for (int nt = 0; nt < 4; ++nt) {
;             float v = (acc[mt][nt][i] + bia[nt]) * csc[nt];
;             float z = ALPHA * xr[nt * 32] + hs * v;
;             acc[mt][nt][i] = z; s1 += z; s2 += z * z;
;           }
;           s1 = row16_sum(s1); s2 = row16_sum(s2);
;           if ((lane & 15) == 0) { f32x2 sv = {s1, s2}; *(f32x2*)(redw + (mt * 32 + (i & 3) + 8 * (i >> 2)) * 2) = sv; }
;         }
	v_mov_b32_e32 v174, v158
	s_waitcnt lgkmcnt(0)
	v_mov_b32_e32 v175, v168
	s_mov_b32 s2, s67
	v_mov_b32_e32 v180, v159
	v_mov_b32_e32 v181, v168
	v_pk_fma_f32 v[158:159], v[174:175], s[2:3], v[170:171] op_sel_hi:[1,0,1]
	v_pk_fma_f32 v[160:161], v[180:181], s[2:3], v[160:161] op_sel_hi:[1,0,1]
	v_pk_mul_f32 v[176:177], v[174:175], s[2:3] op_sel_hi:[1,0]
	v_pk_mul_f32 v[174:175], v[158:159], v[158:159]
	v_pk_mul_f32 v[180:181], v[160:161], v[160:161]
	v_pk_mov_b32 v[170:171], v[170:171], v[174:175] op_sel:[1,0]
	v_pk_mov_b32 v[174:175], v[176:177], v[180:181] op_sel:[1,0]
	v_add_f32_e32 v18, 0, v4
	v_pk_add_f32 v[170:171], v[170:171], v[174:175]
	v_pk_add_f32 v[174:175], v[158:159], v[160:161]
	v_pk_mul_f32 v[176:177], v[158:159], v[160:161]
	v_fmac_f32_e32 v18, 0x3fd744fd, v169
	v_mov_b32_e32 v175, v177
	v_pk_add_f32 v[170:171], v[174:175], v[170:171]
	v_mul_f32_e32 v19, v18, v18
	v_pk_add_f32 v[168:169], v[170:171], v[18:19]
	s_nop 1
	v_mov_b32_dpp v170, v168 quad_perm:[1,0,3,2] row_mask:0xf bank_mask:0xf bound_ctrl:1
	v_mov_b32_dpp v171, v169 quad_perm:[1,0,3,2] row_mask:0xf bank_mask:0xf bound_ctrl:1
	v_pk_add_f32 v[168:169], v[168:169], v[170:171]
	s_nop 1
	v_mov_b32_dpp v170, v168 quad_perm:[2,3,0,1] row_mask:0xf bank_mask:0xf bound_ctrl:1
	v_mov_b32_dpp v171, v169 quad_perm:[2,3,0,1] row_mask:0xf bank_mask:0xf bound_ctrl:1
	v_pk_add_f32 v[168:169], v[168:169], v[170:171]
	s_nop 1
	v_mov_b32_dpp v170, v168 row_half_mirror row_mask:0xf bank_mask:0xf bound_ctrl:1
	v_mov_b32_dpp v171, v169 row_half_mirror row_mask:0xf bank_mask:0xf bound_ctrl:1
	v_pk_add_f32 v[168:169], v[168:169], v[170:171]
	s_nop 1
	v_mov_b32_dpp v170, v168 row_mirror row_mask:0xf bank_mask:0xf bound_ctrl:1
	v_mov_b32_dpp v171, v169 row_mirror row_mask:0xf bank_mask:0xf bound_ctrl:1
	s_and_saveexec_b64 s[6:7], vcc
	v_pk_add_f32 v[168:169], v[168:169], v[170:171]
	ds_write_b64 v179, v[168:169] offset:272
	s_or_b64 exec, exec, s[6:7]
	ds_read2_b32 v[168:169], v151 offset1:32
	ds_read2_b32 v[170:171], v151 offset0:64 offset1:96
	v_mov_b32_e32 v20, v53
	v_pk_add_f32 v[174:175], v[20:21], 0 op_sel_hi:[1,0]
	v_mov_b32_e32 v20, v37
	v_pk_add_f32 v[20:21], v[20:21], 0 op_sel_hi:[1,0]
	s_waitcnt lgkmcnt(1)
	v_mov_b32_e32 v36, v168
	s_waitcnt lgkmcnt(0)
	v_mov_b32_e32 v37, v170
	s_mov_b32 s2, s67
	v_mov_b32_e32 v52, v169
	v_mov_b32_e32 v53, v170
	v_pk_mul_f32 v[176:177], v[36:37], s[2:3] op_sel_hi:[1,0]
	v_pk_fma_f32 v[36:37], v[36:37], s[2:3], v[174:175] op_sel_hi:[1,0,1]
	v_pk_fma_f32 v[52:53], v[52:53], s[2:3], v[20:21] op_sel_hi:[1,0,1]
	v_pk_mul_f32 v[168:169], v[36:37], v[36:37]
	v_pk_mul_f32 v[20:21], v[52:53], v[52:53]
	v_pk_mov_b32 v[168:169], v[174:175], v[168:169] op_sel:[1,0]
	v_pk_mov_b32 v[20:21], v[176:177], v[20:21] op_sel:[1,0]
	v_add_f32_e32 v4, 0, v5
	v_pk_add_f32 v[20:21], v[168:169], v[20:21]
	v_pk_add_f32 v[168:169], v[36:37], v[52:53]
	v_pk_mul_f32 v[174:175], v[36:37], v[52:53]
	v_fmac_f32_e32 v4, 0x3fd744fd, v171
	v_mov_b32_e32 v169, v175
	v_pk_add_f32 v[20:21], v[168:169], v[20:21]
	v_mul_f32_e32 v5, v4, v4
	v_pk_add_f32 v[20:21], v[20:21], v[4:5]
	s_nop 1
	v_mov_b32_dpp v168, v20 quad_perm:[1,0,3,2] row_mask:0xf bank_mask:0xf bound_ctrl:1
	v_mov_b32_dpp v169, v21 quad_perm:[1,0,3,2] row_mask:0xf bank_mask:0xf bound_ctrl:1
	v_pk_add_f32 v[20:21], v[20:21], v[168:169]
	s_nop 1
	v_mov_b32_dpp v168, v20 quad_perm:[2,3,0,1] row_mask:0xf bank_mask:0xf bound_ctrl:1
	v_mov_b32_dpp v169, v21 quad_perm:[2,3,0,1] row_mask:0xf bank_mask:0xf bound_ctrl:1
	v_pk_add_f32 v[20:21], v[20:21], v[168:169]
	s_nop 1
	v_mov_b32_dpp v168, v20 row_half_mirror row_mask:0xf bank_mask:0xf bound_ctrl:1
	v_mov_b32_dpp v169, v21 row_half_mirror row_mask:0xf bank_mask:0xf bound_ctrl:1
	v_pk_add_f32 v[20:21], v[20:21], v[168:169]
	s_nop 1
	v_mov_b32_dpp v168, v20 row_mirror row_mask:0xf bank_mask:0xf bound_ctrl:1
	v_mov_b32_dpp v169, v21 row_mirror row_mask:0xf bank_mask:0xf bound_ctrl:1
	s_and_saveexec_b64 s[6:7], vcc
	v_pk_add_f32 v[20:21], v[20:21], v[168:169]
	ds_write_b64 v179, v[20:21] offset:280
	s_or_b64 exec, exec, s[6:7]
	ds_read2_b32 v[168:169], v67 offset1:32
	ds_read2_b32 v[174:175], v67 offset0:64 offset1:96
	v_mov_b32_e32 v170, v54
	v_mov_b32_e32 v171, v22
	v_pk_add_f32 v[176:177], v[170:171], 0 op_sel_hi:[1,0]
	v_mov_b32_e32 v170, v38
	v_pk_add_f32 v[170:171], v[170:171], 0 op_sel_hi:[1,0]
	s_waitcnt lgkmcnt(1)
	v_mov_b32_e32 v180, v168
	s_waitcnt lgkmcnt(0)
	v_mov_b32_e32 v181, v174
	s_mov_b32 s2, s67
	v_mov_b32_e32 v190, v169
	v_mov_b32_e32 v191, v174
	v_pk_fma_f32 v[168:169], v[180:181], s[2:3], v[176:177] op_sel_hi:[1,0,1]
	v_pk_fma_f32 v[170:171], v[190:191], s[2:3], v[170:171] op_sel_hi:[1,0,1]
	v_pk_mul_f32 v[184:185], v[180:181], s[2:3] op_sel_hi:[1,0]
	v_pk_mul_f32 v[180:181], v[168:169], v[168:169]
	v_pk_mul_f32 v[190:191], v[170:171], v[170:171]
	v_pk_mov_b32 v[176:177], v[176:177], v[180:181] op_sel:[1,0]
	v_pk_mov_b32 v[180:181], v[184:185], v[190:191] op_sel:[1,0]
	v_add_f32_e32 v20, 0, v6
	v_pk_add_f32 v[176:177], v[176:177], v[180:181]
	v_pk_add_f32 v[180:181], v[168:169], v[170:171]
	v_pk_mul_f32 v[184:185], v[168:169], v[170:171]
	v_fmac_f32_e32 v20, 0x3fd744fd, v175
	v_mov_b32_e32 v181, v185
	v_pk_add_f32 v[176:177], v[180:181], v[176:177]
	v_mul_f32_e32 v21, v20, v20
	v_pk_add_f32 v[174:175], v[176:177], v[20:21]
	s_nop 1
	v_mov_b32_dpp v176, v174 quad_perm:[1,0,3,2] row_mask:0xf bank_mask:0xf bound_ctrl:1
	v_mov_b32_dpp v177, v175 quad_perm:[1,0,3,2] row_mask:0xf bank_mask:0xf bound_ctrl:1
	v_pk_add_f32 v[174:175], v[174:175], v[176:177]
	s_nop 1
	v_mov_b32_dpp v176, v174 quad_perm:[2,3,0,1] row_mask:0xf bank_mask:0xf bound_ctrl:1
	v_mov_b32_dpp v177, v175 quad_perm:[2,3,0,1] row_mask:0xf bank_mask:0xf bound_ctrl:1
	v_pk_add_f32 v[174:175], v[174:175], v[176:177]
	s_nop 1
	v_mov_b32_dpp v176, v174 row_half_mirror row_mask:0xf bank_mask:0xf bound_ctrl:1
	v_mov_b32_dpp v177, v175 row_half_mirror row_mask:0xf bank_mask:0xf bound_ctrl:1
	v_pk_add_f32 v[174:175], v[174:175], v[176:177]
	s_nop 1
	v_mov_b32_dpp v176, v174 row_mirror row_mask:0xf bank_mask:0xf bound_ctrl:1
	v_mov_b32_dpp v177, v175 row_mirror row_mask:0xf bank_mask:0xf bound_ctrl:1
	s_and_saveexec_b64 s[6:7], vcc
	v_pk_add_f32 v[174:175], v[174:175], v[176:177]
	ds_write_b64 v179, v[174:175] offset:320
	s_or_b64 exec, exec, s[6:7]
	ds_read2_b32 v[174:175], v67 offset0:128 offset1:160
	ds_read2_b32 v[176:177], v67 offset0:192 offset1:224
	v_mov_b32_e32 v22, v55
	v_pk_add_f32 v[180:181], v[22:23], 0 op_sel_hi:[1,0]
	v_mov_b32_e32 v22, v39
	v_pk_add_f32 v[22:23], v[22:23], 0 op_sel_hi:[1,0]
	s_waitcnt lgkmcnt(1)
;   DI void operator()(f32x16 (&acc)[2][4], int grow0, int gcol0, int lane, int w, char* lds) {
;     ...
;       if (ps + 1 < 4) {
;         if (ps >= 1) asm volatile("s_waitcnt lgkmcnt(0)" ::: "memory");
;         xpass(ps + 1, grow0, gcol0, lane, w, lds);
;         if (ps >= 1) asm volatile("s_waitcnt vmcnt(8)" ::: "memory");
;       } else asm volatile("s_waitcnt vmcnt(0)" ::: "memory");
;       const char* xs = lds + (ps & 1) * 65536 + w * 8192;
; #pragma unroll
;       for (int qq = 0; qq < 2; ++qq)
; #pragma unroll
;         for (int e = 0; e < 4; ++e) {
;           const int i = 4 * (2 * (ps & 1) + qq) + e;
;           const float* xr = (const float*)(xs + (8 * qq + 4 * hh + e) * 512) + l31;
;           float s1 = 0.f, s2 = 0.f;
; #pragma unroll
;           for (int nt = 0; nt < 4; ++nt) {
;             float v = (acc[mt][nt][i] + bia[nt]) * csc[nt];
;             float z = ALPHA * xr[nt * 32] + hs * v;
;             acc[mt][nt][i] = z; s1 += z; s2 += z * z;
;           }
;           s1 = row16_sum(s1); s2 = row16_sum(s2);
;           if ((lane & 15) == 0) { f32x2 sv = {s1, s2}; *(f32x2*)(redw + (mt * 32 + (i & 3) + 8 * (i >> 2)) * 2) = sv; }
;         }
	v_mov_b32_e32 v38, v174
	s_waitcnt lgkmcnt(0)
	v_mov_b32_e32 v39, v176
	s_mov_b32 s2, s67
	v_mov_b32_e32 v54, v175
	v_mov_b32_e32 v55, v176
	v_pk_mul_f32 v[184:185], v[38:39], s[2:3] op_sel_hi:[1,0]
	v_pk_fma_f32 v[38:39], v[38:39], s[2:3], v[180:181] op_sel_hi:[1,0,1]
	v_pk_fma_f32 v[54:55], v[54:55], s[2:3], v[22:23] op_sel_hi:[1,0,1]
	v_pk_mul_f32 v[174:175], v[38:39], v[38:39]
	v_pk_mul_f32 v[22:23], v[54:55], v[54:55]
	v_pk_mov_b32 v[174:175], v[180:181], v[174:175] op_sel:[1,0]
	v_pk_mov_b32 v[22:23], v[184:185], v[22:23] op_sel:[1,0]
	v_add_f32_e32 v6, 0, v7
	v_pk_add_f32 v[22:23], v[174:175], v[22:23]
	v_pk_add_f32 v[174:175], v[38:39], v[54:55]
	v_pk_mul_f32 v[180:181], v[38:39], v[54:55]
	v_fmac_f32_e32 v6, 0x3fd744fd, v177
	v_mov_b32_e32 v175, v181
	v_pk_add_f32 v[22:23], v[174:175], v[22:23]
	v_mul_f32_e32 v7, v6, v6
	v_pk_add_f32 v[22:23], v[22:23], v[6:7]
	s_nop 1
	v_mov_b32_dpp v174, v22 quad_perm:[1,0,3,2] row_mask:0xf bank_mask:0xf bound_ctrl:1
	v_mov_b32_dpp v175, v23 quad_perm:[1,0,3,2] row_mask:0xf bank_mask:0xf bound_ctrl:1
	v_pk_add_f32 v[22:23], v[22:23], v[174:175]
	s_nop 1
	v_mov_b32_dpp v174, v22 quad_perm:[2,3,0,1] row_mask:0xf bank_mask:0xf bound_ctrl:1
	v_mov_b32_dpp v175, v23 quad_perm:[2,3,0,1] row_mask:0xf bank_mask:0xf bound_ctrl:1
	v_pk_add_f32 v[22:23], v[22:23], v[174:175]
	s_nop 1
	v_mov_b32_dpp v174, v22 row_half_mirror row_mask:0xf bank_mask:0xf bound_ctrl:1
	v_mov_b32_dpp v175, v23 row_half_mirror row_mask:0xf bank_mask:0xf bound_ctrl:1
	v_pk_add_f32 v[22:23], v[22:23], v[174:175]
	s_nop 1
	v_mov_b32_dpp v174, v22 row_mirror row_mask:0xf bank_mask:0xf bound_ctrl:1
	v_mov_b32_dpp v175, v23 row_mirror row_mask:0xf bank_mask:0xf bound_ctrl:1
	s_and_saveexec_b64 s[6:7], vcc
	v_pk_add_f32 v[22:23], v[22:23], v[174:175]
	ds_write_b64 v179, v[22:23] offset:328
	s_or_b64 exec, exec, s[6:7]
	ds_read2_b32 v[174:175], v69 offset1:32
	ds_read2_b32 v[180:181], v69 offset0:64 offset1:96
	v_mov_b32_e32 v176, v56
	v_mov_b32_e32 v177, v24
	v_pk_add_f32 v[184:185], v[176:177], 0 op_sel_hi:[1,0]
	v_mov_b32_e32 v176, v40
	v_pk_add_f32 v[176:177], v[176:177], 0 op_sel_hi:[1,0]
	s_waitcnt lgkmcnt(1)
	v_mov_b32_e32 v190, v174
	s_waitcnt lgkmcnt(0)
	v_mov_b32_e32 v191, v180
	s_mov_b32 s2, s67
	v_mov_b32_e32 v194, v175
	v_mov_b32_e32 v195, v180
	v_pk_fma_f32 v[174:175], v[190:191], s[2:3], v[184:185] op_sel_hi:[1,0,1]
	v_pk_fma_f32 v[176:177], v[194:195], s[2:3], v[176:177] op_sel_hi:[1,0,1]
	v_pk_mul_f32 v[192:193], v[190:191], s[2:3] op_sel_hi:[1,0]
	v_pk_mul_f32 v[190:191], v[174:175], v[174:175]
	v_pk_mul_f32 v[194:195], v[176:177], v[176:177]
	v_pk_mov_b32 v[184:185], v[184:185], v[190:191] op_sel:[1,0]
	v_pk_mov_b32 v[190:191], v[192:193], v[194:195] op_sel:[1,0]
	v_add_f32_e32 v22, 0, v8
	v_pk_add_f32 v[184:185], v[184:185], v[190:191]
	v_pk_add_f32 v[190:191], v[174:175], v[176:177]
	v_pk_mul_f32 v[192:193], v[174:175], v[176:177]
	v_fmac_f32_e32 v22, 0x3fd744fd, v181
	v_mov_b32_e32 v191, v193
	v_pk_add_f32 v[184:185], v[190:191], v[184:185]
	v_mul_f32_e32 v23, v22, v22
	v_pk_add_f32 v[180:181], v[184:185], v[22:23]
	s_nop 1
	v_mov_b32_dpp v184, v180 quad_perm:[1,0,3,2] row_mask:0xf bank_mask:0xf bound_ctrl:1
	v_mov_b32_dpp v185, v181 quad_perm:[1,0,3,2] row_mask:0xf bank_mask:0xf bound_ctrl:1
	v_pk_add_f32 v[180:181], v[180:181], v[184:185]
	s_nop 1
	v_mov_b32_dpp v184, v180 quad_perm:[2,3,0,1] row_mask:0xf bank_mask:0xf bound_ctrl:1
	v_mov_b32_dpp v185, v181 quad_perm:[2,3,0,1] row_mask:0xf bank_mask:0xf bound_ctrl:1
	v_pk_add_f32 v[180:181], v[180:181], v[184:185]
	s_nop 1
	v_mov_b32_dpp v184, v180 row_half_mirror row_mask:0xf bank_mask:0xf bound_ctrl:1
	v_mov_b32_dpp v185, v181 row_half_mirror row_mask:0xf bank_mask:0xf bound_ctrl:1
	v_pk_add_f32 v[180:181], v[180:181], v[184:185]
	s_nop 1
	v_mov_b32_dpp v184, v180 row_mirror row_mask:0xf bank_mask:0xf bound_ctrl:1
	v_mov_b32_dpp v185, v181 row_mirror row_mask:0xf bank_mask:0xf bound_ctrl:1
	s_and_saveexec_b64 s[6:7], vcc
	v_pk_add_f32 v[180:181], v[180:181], v[184:185]
	ds_write_b64 v179, v[180:181] offset:336
	s_or_b64 exec, exec, s[6:7]
	ds_read2_b32 v[180:181], v71 offset1:32
	ds_read2_b32 v[184:185], v71 offset0:64 offset1:96
	v_mov_b32_e32 v24, v57
	v_pk_add_f32 v[190:191], v[24:25], 0 op_sel_hi:[1,0]
	v_mov_b32_e32 v24, v41
	v_pk_add_f32 v[24:25], v[24:25], 0 op_sel_hi:[1,0]
	s_waitcnt lgkmcnt(1)
	v_mov_b32_e32 v40, v180
	s_waitcnt lgkmcnt(0)
	v_mov_b32_e32 v41, v184
	s_mov_b32 s2, s67
	v_mov_b32_e32 v56, v181
	v_mov_b32_e32 v57, v184
	v_pk_mul_f32 v[192:193], v[40:41], s[2:3] op_sel_hi:[1,0]
	v_pk_fma_f32 v[40:41], v[40:41], s[2:3], v[190:191] op_sel_hi:[1,0,1]
	v_pk_fma_f32 v[56:57], v[56:57], s[2:3], v[24:25] op_sel_hi:[1,0,1]
	v_pk_mul_f32 v[180:181], v[40:41], v[40:41]
	v_pk_mul_f32 v[24:25], v[56:57], v[56:57]
	v_pk_mov_b32 v[180:181], v[190:191], v[180:181] op_sel:[1,0]
	v_pk_mov_b32 v[24:25], v[192:193], v[24:25] op_sel:[1,0]
	v_add_f32_e32 v8, 0, v9
	v_pk_add_f32 v[24:25], v[180:181], v[24:25]
	v_pk_add_f32 v[180:181], v[40:41], v[56:57]
	v_pk_mul_f32 v[190:191], v[40:41], v[56:57]
	v_fmac_f32_e32 v8, 0x3fd744fd, v185
	v_mov_b32_e32 v181, v191
	v_pk_add_f32 v[24:25], v[180:181], v[24:25]
	v_mul_f32_e32 v9, v8, v8
	v_pk_add_f32 v[24:25], v[24:25], v[8:9]
	s_nop 1
	v_mov_b32_dpp v180, v24 quad_perm:[1,0,3,2] row_mask:0xf bank_mask:0xf bound_ctrl:1
	v_mov_b32_dpp v181, v25 quad_perm:[1,0,3,2] row_mask:0xf bank_mask:0xf bound_ctrl:1
	v_pk_add_f32 v[24:25], v[24:25], v[180:181]
	s_nop 1
	v_mov_b32_dpp v180, v24 quad_perm:[2,3,0,1] row_mask:0xf bank_mask:0xf bound_ctrl:1
	v_mov_b32_dpp v181, v25 quad_perm:[2,3,0,1] row_mask:0xf bank_mask:0xf bound_ctrl:1
	v_pk_add_f32 v[24:25], v[24:25], v[180:181]
	s_nop 1
	v_mov_b32_dpp v180, v24 row_half_mirror row_mask:0xf bank_mask:0xf bound_ctrl:1
	v_mov_b32_dpp v181, v25 row_half_mirror row_mask:0xf bank_mask:0xf bound_ctrl:1
	v_pk_add_f32 v[24:25], v[24:25], v[180:181]
	s_nop 1
	v_mov_b32_dpp v180, v24 row_mirror row_mask:0xf bank_mask:0xf bound_ctrl:1
	v_mov_b32_dpp v181, v25 row_mirror row_mask:0xf bank_mask:0xf bound_ctrl:1
	s_and_saveexec_b64 s[6:7], vcc
	v_pk_add_f32 v[24:25], v[24:25], v[180:181]
	ds_write_b64 v179, v[24:25] offset:344
	s_or_b64 exec, exec, s[6:7]
	s_waitcnt vmcnt(0)
;   DI void operator()(f32x16 (&acc)[2][4], int grow0, int gcol0, int lane, int w, char* lds) {
;     ...
; #pragma unroll
;       for (int qq = 0; qq < 2; ++qq)
; #pragma unroll
;         for (int e = 0; e < 4; ++e) {
;           const int i = 4 * (2 * (ps & 1) + qq) + e;
;           const float* xr = (const float*)(xs + (8 * qq + 4 * hh + e) * 512) + l31;
;           float s1 = 0.f, s2 = 0.f;
; #pragma unroll
;           for (int nt = 0; nt < 4; ++nt) {
;             float v = (acc[mt][nt][i] + bia[nt]) * csc[nt];
;             float z = ALPHA * xr[nt * 32] + hs * v;
;             acc[mt][nt][i] = z; s1 += z; s2 += z * z;
;           }
;           s1 = row16_sum(s1); s2 = row16_sum(s2);
;           if ((lane & 15) == 0) { f32x2 sv = {s1, s2}; *(f32x2*)(redw + (mt * 32 + (i & 3) + 8 * (i >> 2)) * 2) = sv; }
;         }
	ds_read2_b32 v[184:185], v73 offset1:32
	ds_read2_b32 v[192:193], v73 offset0:64 offset1:96
	v_add_f32_e32 v181, 0, v42
	v_mov_b32_e32 v190, v58
	v_mov_b32_e32 v191, v26
	s_waitcnt lgkmcnt(1)
	v_fmac_f32_e32 v181, 0x3fd744fd, v185
	v_pk_add_f32 v[194:195], v[190:191], 0 op_sel_hi:[1,0]
	s_waitcnt lgkmcnt(0)
	v_mov_b32_e32 v185, v192
	s_mov_b32 s2, s67
	v_pk_fma_f32 v[190:191], v[184:185], s[2:3], v[194:195] op_sel_hi:[1,0,1]
	v_mov_b32_e32 v180, v192
	v_pk_mul_f32 v[184:185], v[190:191], v[190:191]
	v_mov_b32_e32 v196, v165
	v_mov_b32_e32 v197, v181
	v_pk_mov_b32 v[184:185], v[194:195], v[184:185] op_sel:[1,0]
	v_add_f32_e32 v24, 0, v10
	v_pk_fma_f32 v[184:185], v[180:181], v[196:197], v[184:185]
	v_fmac_f32_e32 v24, 0x3fd744fd, v193
	v_pk_mov_b32 v[194:195], v[180:181], v[184:185] op_sel:[1,0]
	v_mul_f32_e32 v25, v24, v24
	v_pk_add_f32 v[196:197], v[190:191], v[194:195]
	v_pk_mul_f32 v[194:195], v[190:191], v[194:195]
	s_nop 0
	v_mov_b32_e32 v197, v195
	v_pk_add_f32 v[194:195], v[184:185], v[196:197]
	s_nop 0
	v_pk_add_f32 v[192:193], v[194:195], v[24:25]
	s_nop 1
	v_mov_b32_dpp v194, v192 quad_perm:[1,0,3,2] row_mask:0xf bank_mask:0xf bound_ctrl:1
	v_mov_b32_dpp v195, v193 quad_perm:[1,0,3,2] row_mask:0xf bank_mask:0xf bound_ctrl:1
	v_pk_add_f32 v[192:193], v[192:193], v[194:195]
	s_nop 1
	v_mov_b32_dpp v194, v192 quad_perm:[2,3,0,1] row_mask:0xf bank_mask:0xf bound_ctrl:1
	v_mov_b32_dpp v195, v193 quad_perm:[2,3,0,1] row_mask:0xf bank_mask:0xf bound_ctrl:1
	v_pk_add_f32 v[192:193], v[192:193], v[194:195]
	s_nop 1
	v_mov_b32_dpp v194, v192 row_half_mirror row_mask:0xf bank_mask:0xf bound_ctrl:1
	v_mov_b32_dpp v195, v193 row_half_mirror row_mask:0xf bank_mask:0xf bound_ctrl:1
	v_pk_add_f32 v[192:193], v[192:193], v[194:195]
	s_nop 1
	v_mov_b32_dpp v194, v192 row_mirror row_mask:0xf bank_mask:0xf bound_ctrl:1
	v_mov_b32_dpp v195, v193 row_mirror row_mask:0xf bank_mask:0xf bound_ctrl:1
	s_and_saveexec_b64 s[6:7], vcc
	v_pk_add_f32 v[192:193], v[192:193], v[194:195]
	ds_write_b64 v179, v[192:193] offset:384
	s_or_b64 exec, exec, s[6:7]
	ds_read2_b32 v[192:193], v85 offset1:32
	ds_read2_b32 v[194:195], v85 offset0:64 offset1:96
	v_mov_b32_e32 v26, v59
	v_pk_add_f32 v[196:197], v[26:27], 0 op_sel_hi:[1,0]
	v_mov_b32_e32 v26, v43
	v_pk_add_f32 v[26:27], v[26:27], 0 op_sel_hi:[1,0]
	s_waitcnt lgkmcnt(1)
	v_mov_b32_e32 v42, v192
	s_waitcnt lgkmcnt(0)
	v_mov_b32_e32 v43, v194
	s_mov_b32 s2, s67
	v_mov_b32_e32 v58, v193
	v_mov_b32_e32 v59, v194
	v_pk_mul_f32 v[198:199], v[42:43], s[2:3] op_sel_hi:[1,0]
	v_pk_fma_f32 v[42:43], v[42:43], s[2:3], v[196:197] op_sel_hi:[1,0,1]
	v_pk_fma_f32 v[58:59], v[58:59], s[2:3], v[26:27] op_sel_hi:[1,0,1]
	v_pk_mul_f32 v[192:193], v[42:43], v[42:43]
	v_pk_mul_f32 v[26:27], v[58:59], v[58:59]
	v_pk_mov_b32 v[192:193], v[196:197], v[192:193] op_sel:[1,0]
	v_pk_mov_b32 v[26:27], v[198:199], v[26:27] op_sel:[1,0]
	v_add_f32_e32 v10, 0, v11
	v_pk_add_f32 v[26:27], v[192:193], v[26:27]
	v_pk_add_f32 v[192:193], v[42:43], v[58:59]
	v_pk_mul_f32 v[196:197], v[42:43], v[58:59]
	v_fmac_f32_e32 v10, 0x3fd744fd, v195
	v_mov_b32_e32 v193, v197
	v_pk_add_f32 v[26:27], v[192:193], v[26:27]
	v_mul_f32_e32 v11, v10, v10
	v_pk_add_f32 v[26:27], v[26:27], v[10:11]
	s_nop 1
	v_mov_b32_dpp v192, v26 quad_perm:[1,0,3,2] row_mask:0xf bank_mask:0xf bound_ctrl:1
	v_mov_b32_dpp v193, v27 quad_perm:[1,0,3,2] row_mask:0xf bank_mask:0xf bound_ctrl:1
	v_pk_add_f32 v[26:27], v[26:27], v[192:193]
	s_nop 1
	v_mov_b32_dpp v192, v26 quad_perm:[2,3,0,1] row_mask:0xf bank_mask:0xf bound_ctrl:1
	v_mov_b32_dpp v193, v27 quad_perm:[2,3,0,1] row_mask:0xf bank_mask:0xf bound_ctrl:1
	v_pk_add_f32 v[26:27], v[26:27], v[192:193]
	s_nop 1
	v_mov_b32_dpp v192, v26 row_half_mirror row_mask:0xf bank_mask:0xf bound_ctrl:1
	v_mov_b32_dpp v193, v27 row_half_mirror row_mask:0xf bank_mask:0xf bound_ctrl:1
	v_pk_add_f32 v[26:27], v[26:27], v[192:193]
	s_nop 1
	v_mov_b32_dpp v192, v26 row_mirror row_mask:0xf bank_mask:0xf bound_ctrl:1
	v_mov_b32_dpp v193, v27 row_mirror row_mask:0xf bank_mask:0xf bound_ctrl:1
	s_and_saveexec_b64 s[6:7], vcc
	v_pk_add_f32 v[26:27], v[26:27], v[192:193]
	ds_write_b64 v179, v[26:27] offset:392
	s_or_b64 exec, exec, s[6:7]
	ds_read2_b32 v[192:193], v75 offset1:32
	ds_read2_b32 v[196:197], v75 offset0:64 offset1:96
	v_mov_b32_e32 v194, v60
	v_mov_b32_e32 v195, v28
	v_pk_add_f32 v[198:199], v[194:195], 0 op_sel_hi:[1,0]
	v_mov_b32_e32 v194, v44
	v_pk_add_f32 v[194:195], v[194:195], 0 op_sel_hi:[1,0]
	s_waitcnt lgkmcnt(1)
	v_mov_b32_e32 v202, v192
	s_waitcnt lgkmcnt(0)
	v_mov_b32_e32 v203, v196
	s_mov_b32 s2, s67
	v_mov_b32_e32 v206, v193
	v_mov_b32_e32 v207, v196
	v_pk_fma_f32 v[192:193], v[202:203], s[2:3], v[198:199] op_sel_hi:[1,0,1]
	v_pk_fma_f32 v[194:195], v[206:207], s[2:3], v[194:195] op_sel_hi:[1,0,1]
	v_pk_mul_f32 v[204:205], v[202:203], s[2:3] op_sel_hi:[1,0]
	v_pk_mul_f32 v[202:203], v[192:193], v[192:193]
	v_pk_mul_f32 v[206:207], v[194:195], v[194:195]
	v_pk_mov_b32 v[198:199], v[198:199], v[202:203] op_sel:[1,0]
	v_pk_mov_b32 v[202:203], v[204:205], v[206:207] op_sel:[1,0]
	v_add_f32_e32 v26, 0, v12
	v_pk_add_f32 v[198:199], v[198:199], v[202:203]
	v_pk_add_f32 v[202:203], v[192:193], v[194:195]
	v_pk_mul_f32 v[204:205], v[192:193], v[194:195]
	v_fmac_f32_e32 v26, 0x3fd744fd, v197
	v_mov_b32_e32 v203, v205
	v_pk_add_f32 v[198:199], v[202:203], v[198:199]
	v_mul_f32_e32 v27, v26, v26
	v_pk_add_f32 v[196:197], v[198:199], v[26:27]
	s_nop 1
	v_mov_b32_dpp v198, v196 quad_perm:[1,0,3,2] row_mask:0xf bank_mask:0xf bound_ctrl:1
	v_mov_b32_dpp v199, v197 quad_perm:[1,0,3,2] row_mask:0xf bank_mask:0xf bound_ctrl:1
	v_pk_add_f32 v[196:197], v[196:197], v[198:199]
	s_nop 1
	v_mov_b32_dpp v198, v196 quad_perm:[2,3,0,1] row_mask:0xf bank_mask:0xf bound_ctrl:1
	v_mov_b32_dpp v199, v197 quad_perm:[2,3,0,1] row_mask:0xf bank_mask:0xf bound_ctrl:1
	v_pk_add_f32 v[196:197], v[196:197], v[198:199]
	s_nop 1
	v_mov_b32_dpp v198, v196 row_half_mirror row_mask:0xf bank_mask:0xf bound_ctrl:1
	v_mov_b32_dpp v199, v197 row_half_mirror row_mask:0xf bank_mask:0xf bound_ctrl:1
	v_pk_add_f32 v[196:197], v[196:197], v[198:199]
	s_nop 1
	v_mov_b32_dpp v198, v196 row_mirror row_mask:0xf bank_mask:0xf bound_ctrl:1
	v_mov_b32_dpp v199, v197 row_mirror row_mask:0xf bank_mask:0xf bound_ctrl:1
	s_and_saveexec_b64 s[6:7], vcc
	v_pk_add_f32 v[196:197], v[196:197], v[198:199]
	ds_write_b64 v179, v[196:197] offset:400
	s_or_b64 exec, exec, s[6:7]
	ds_read2_b32 v[196:197], v87 offset1:32
	ds_read2_b32 v[198:199], v87 offset0:64 offset1:96
	v_mov_b32_e32 v28, v61
	v_pk_add_f32 v[202:203], v[28:29], 0 op_sel_hi:[1,0]
	v_mov_b32_e32 v28, v45
	v_pk_add_f32 v[28:29], v[28:29], 0 op_sel_hi:[1,0]
	s_waitcnt lgkmcnt(1)
;   DI void operator()(f32x16 (&acc)[2][4], int grow0, int gcol0, int lane, int w, char* lds) {
;     ...
; #pragma unroll
;       for (int qq = 0; qq < 2; ++qq)
; #pragma unroll
;         for (int e = 0; e < 4; ++e) {
;           const int i = 4 * (2 * (ps & 1) + qq) + e;
;           const float* xr = (const float*)(xs + (8 * qq + 4 * hh + e) * 512) + l31;
;           float s1 = 0.f, s2 = 0.f;
; #pragma unroll
;           for (int nt = 0; nt < 4; ++nt) {
;             float v = (acc[mt][nt][i] + bia[nt]) * csc[nt];
;             float z = ALPHA * xr[nt * 32] + hs * v;
;             acc[mt][nt][i] = z; s1 += z; s2 += z * z;
;           }
;           s1 = row16_sum(s1); s2 = row16_sum(s2);
;           if ((lane & 15) == 0) { f32x2 sv = {s1, s2}; *(f32x2*)(redw + (mt * 32 + (i & 3) + 8 * (i >> 2)) * 2) = sv; }
;         }
	v_mov_b32_e32 v44, v196
	s_waitcnt lgkmcnt(0)
	v_mov_b32_e32 v45, v198
	s_mov_b32 s2, s67
	v_mov_b32_e32 v60, v197
	v_mov_b32_e32 v61, v198
	v_pk_mul_f32 v[204:205], v[44:45], s[2:3] op_sel_hi:[1,0]
	v_pk_fma_f32 v[44:45], v[44:45], s[2:3], v[202:203] op_sel_hi:[1,0,1]
	v_pk_fma_f32 v[60:61], v[60:61], s[2:3], v[28:29] op_sel_hi:[1,0,1]
	v_pk_mul_f32 v[196:197], v[44:45], v[44:45]
	v_pk_mul_f32 v[28:29], v[60:61], v[60:61]
	v_pk_mov_b32 v[196:197], v[202:203], v[196:197] op_sel:[1,0]
	v_pk_mov_b32 v[28:29], v[204:205], v[28:29] op_sel:[1,0]
	v_add_f32_e32 v12, 0, v13
	v_pk_add_f32 v[28:29], v[196:197], v[28:29]
	v_pk_add_f32 v[196:197], v[44:45], v[60:61]
	v_pk_mul_f32 v[202:203], v[44:45], v[60:61]
	v_fmac_f32_e32 v12, 0x3fd744fd, v199
	v_mov_b32_e32 v197, v203
	v_pk_add_f32 v[28:29], v[196:197], v[28:29]
	v_mul_f32_e32 v13, v12, v12
	v_pk_add_f32 v[28:29], v[28:29], v[12:13]
	s_nop 1
	v_mov_b32_dpp v196, v28 quad_perm:[1,0,3,2] row_mask:0xf bank_mask:0xf bound_ctrl:1
	v_mov_b32_dpp v197, v29 quad_perm:[1,0,3,2] row_mask:0xf bank_mask:0xf bound_ctrl:1
	v_pk_add_f32 v[28:29], v[28:29], v[196:197]
	s_nop 1
	v_mov_b32_dpp v196, v28 quad_perm:[2,3,0,1] row_mask:0xf bank_mask:0xf bound_ctrl:1
	v_mov_b32_dpp v197, v29 quad_perm:[2,3,0,1] row_mask:0xf bank_mask:0xf bound_ctrl:1
	v_pk_add_f32 v[28:29], v[28:29], v[196:197]
	s_nop 1
	v_mov_b32_dpp v196, v28 row_half_mirror row_mask:0xf bank_mask:0xf bound_ctrl:1
	v_mov_b32_dpp v197, v29 row_half_mirror row_mask:0xf bank_mask:0xf bound_ctrl:1
	v_pk_add_f32 v[28:29], v[28:29], v[196:197]
	s_nop 1
	v_mov_b32_dpp v196, v28 row_mirror row_mask:0xf bank_mask:0xf bound_ctrl:1
	v_mov_b32_dpp v197, v29 row_mirror row_mask:0xf bank_mask:0xf bound_ctrl:1
	s_and_saveexec_b64 s[6:7], vcc
	v_pk_add_f32 v[28:29], v[28:29], v[196:197]
	ds_write_b64 v179, v[28:29] offset:408
	s_or_b64 exec, exec, s[6:7]
	ds_read2_b32 v[196:197], v77 offset1:32
	ds_read2_b32 v[202:203], v77 offset0:64 offset1:96
	v_mov_b32_e32 v198, v62
	v_mov_b32_e32 v199, v30
	v_pk_add_f32 v[204:205], v[198:199], 0 op_sel_hi:[1,0]
	v_mov_b32_e32 v198, v46
	v_pk_add_f32 v[198:199], v[198:199], 0 op_sel_hi:[1,0]
	s_waitcnt lgkmcnt(1)
	v_mov_b32_e32 v206, v196
	s_waitcnt lgkmcnt(0)
	v_mov_b32_e32 v207, v202
	s_mov_b32 s2, s67
	v_mov_b32_e32 v212, v197
	v_mov_b32_e32 v213, v202
	v_pk_fma_f32 v[196:197], v[206:207], s[2:3], v[204:205] op_sel_hi:[1,0,1]
	v_pk_fma_f32 v[198:199], v[212:213], s[2:3], v[198:199] op_sel_hi:[1,0,1]
	v_pk_mul_f32 v[208:209], v[206:207], s[2:3] op_sel_hi:[1,0]
	v_pk_mul_f32 v[206:207], v[196:197], v[196:197]
	v_pk_mul_f32 v[212:213], v[198:199], v[198:199]
	v_pk_mov_b32 v[204:205], v[204:205], v[206:207] op_sel:[1,0]
	v_pk_mov_b32 v[206:207], v[208:209], v[212:213] op_sel:[1,0]
	v_add_f32_e32 v28, 0, v14
	v_pk_add_f32 v[204:205], v[204:205], v[206:207]
	v_pk_add_f32 v[206:207], v[196:197], v[198:199]
	v_pk_mul_f32 v[208:209], v[196:197], v[198:199]
	v_fmac_f32_e32 v28, 0x3fd744fd, v203
	v_mov_b32_e32 v207, v209
	v_pk_add_f32 v[204:205], v[206:207], v[204:205]
	v_mul_f32_e32 v29, v28, v28
	v_pk_add_f32 v[202:203], v[204:205], v[28:29]
	s_nop 1
	v_mov_b32_dpp v204, v202 quad_perm:[1,0,3,2] row_mask:0xf bank_mask:0xf bound_ctrl:1
	v_mov_b32_dpp v205, v203 quad_perm:[1,0,3,2] row_mask:0xf bank_mask:0xf bound_ctrl:1
	v_pk_add_f32 v[202:203], v[202:203], v[204:205]
	s_nop 1
	v_mov_b32_dpp v204, v202 quad_perm:[2,3,0,1] row_mask:0xf bank_mask:0xf bound_ctrl:1
	v_mov_b32_dpp v205, v203 quad_perm:[2,3,0,1] row_mask:0xf bank_mask:0xf bound_ctrl:1
	v_pk_add_f32 v[202:203], v[202:203], v[204:205]
	s_nop 1
	v_mov_b32_dpp v204, v202 row_half_mirror row_mask:0xf bank_mask:0xf bound_ctrl:1
	v_mov_b32_dpp v205, v203 row_half_mirror row_mask:0xf bank_mask:0xf bound_ctrl:1
	v_pk_add_f32 v[202:203], v[202:203], v[204:205]
	s_nop 1
	v_mov_b32_dpp v204, v202 row_mirror row_mask:0xf bank_mask:0xf bound_ctrl:1
	v_mov_b32_dpp v205, v203 row_mirror row_mask:0xf bank_mask:0xf bound_ctrl:1
	s_and_saveexec_b64 s[6:7], vcc
	v_pk_add_f32 v[202:203], v[202:203], v[204:205]
	ds_write_b64 v179, v[202:203] offset:448
	s_or_b64 exec, exec, s[6:7]
	ds_read2_b32 v[202:203], v91 offset1:32
	ds_read2_b32 v[204:205], v91 offset0:64 offset1:96
	v_mov_b32_e32 v30, v63
	v_pk_add_f32 v[206:207], v[30:31], 0 op_sel_hi:[1,0]
	v_mov_b32_e32 v30, v47
	v_pk_add_f32 v[30:31], v[30:31], 0 op_sel_hi:[1,0]
	s_waitcnt lgkmcnt(1)
	v_mov_b32_e32 v46, v202
	s_waitcnt lgkmcnt(0)
	v_mov_b32_e32 v47, v204
	s_mov_b32 s2, s67
	v_mov_b32_e32 v62, v203
	v_mov_b32_e32 v63, v204
	v_pk_mul_f32 v[208:209], v[46:47], s[2:3] op_sel_hi:[1,0]
	v_pk_fma_f32 v[46:47], v[46:47], s[2:3], v[206:207] op_sel_hi:[1,0,1]
	v_pk_fma_f32 v[62:63], v[62:63], s[2:3], v[30:31] op_sel_hi:[1,0,1]
	v_pk_mul_f32 v[202:203], v[46:47], v[46:47]
	v_pk_mul_f32 v[30:31], v[62:63], v[62:63]
	v_pk_mov_b32 v[202:203], v[206:207], v[202:203] op_sel:[1,0]
	v_pk_mov_b32 v[30:31], v[208:209], v[30:31] op_sel:[1,0]
	v_add_f32_e32 v14, 0, v15
	v_pk_add_f32 v[30:31], v[202:203], v[30:31]
	v_pk_add_f32 v[202:203], v[46:47], v[62:63]
	v_pk_mul_f32 v[206:207], v[46:47], v[62:63]
	v_fmac_f32_e32 v14, 0x3fd744fd, v205
	v_mov_b32_e32 v203, v207
	v_pk_add_f32 v[30:31], v[202:203], v[30:31]
	v_mul_f32_e32 v15, v14, v14
	v_pk_add_f32 v[30:31], v[30:31], v[14:15]
	s_nop 1
	v_mov_b32_dpp v202, v30 quad_perm:[1,0,3,2] row_mask:0xf bank_mask:0xf bound_ctrl:1
	v_mov_b32_dpp v203, v31 quad_perm:[1,0,3,2] row_mask:0xf bank_mask:0xf bound_ctrl:1
	v_pk_add_f32 v[30:31], v[30:31], v[202:203]
	s_nop 1
	v_mov_b32_dpp v202, v30 quad_perm:[2,3,0,1] row_mask:0xf bank_mask:0xf bound_ctrl:1
	v_mov_b32_dpp v203, v31 quad_perm:[2,3,0,1] row_mask:0xf bank_mask:0xf bound_ctrl:1
	v_pk_add_f32 v[30:31], v[30:31], v[202:203]
	s_nop 1
	v_mov_b32_dpp v202, v30 row_half_mirror row_mask:0xf bank_mask:0xf bound_ctrl:1
	v_mov_b32_dpp v203, v31 row_half_mirror row_mask:0xf bank_mask:0xf bound_ctrl:1
	v_pk_add_f32 v[30:31], v[30:31], v[202:203]
	s_nop 1
	v_mov_b32_dpp v202, v30 row_mirror row_mask:0xf bank_mask:0xf bound_ctrl:1
	v_mov_b32_dpp v203, v31 row_mirror row_mask:0xf bank_mask:0xf bound_ctrl:1
	s_and_saveexec_b64 s[6:7], vcc
	v_pk_add_f32 v[30:31], v[30:31], v[202:203]
	ds_write_b64 v179, v[30:31] offset:456
	s_or_b64 exec, exec, s[6:7]
	ds_read2_b32 v[202:203], v79 offset1:32
	ds_read2_b32 v[206:207], v79 offset0:64 offset1:96
	v_mov_b32_e32 v204, v64
	v_mov_b32_e32 v205, v32
	v_pk_add_f32 v[208:209], v[204:205], 0 op_sel_hi:[1,0]
	v_mov_b32_e32 v204, v48
	v_pk_add_f32 v[204:205], v[204:205], 0 op_sel_hi:[1,0]
	s_waitcnt lgkmcnt(1)
; DI void ag_st64(u64_t* p, u64_t v) { __hip_atomic_store(p, v, __ATOMIC_RELAXED, __HIP_MEMORY_SCOPE_AGENT); }
;   DI void operator()(f32x16 (&acc)[2][4], int grow0, int gcol0, int lane, int w, char* lds) {
;     ...
; #pragma unroll
;       for (int qq = 0; qq < 2; ++qq)
; #pragma unroll
;         for (int e = 0; e < 4; ++e) {
;           const int i = 4 * (2 * (ps & 1) + qq) + e;
;           const float* xr = (const float*)(xs + (8 * qq + 4 * hh + e) * 512) + l31;
;           float s1 = 0.f, s2 = 0.f;
; #pragma unroll
;           for (int nt = 0; nt < 4; ++nt) {
;             float v = (acc[mt][nt][i] + bia[nt]) * csc[nt];
;             float z = ALPHA * xr[nt * 32] + hs * v;
;             acc[mt][nt][i] = z; s1 += z; s2 += z * z;
;           }
;           s1 = row16_sum(s1); s2 = row16_sum(s2);
;           if ((lane & 15) == 0) { f32x2 sv = {s1, s2}; *(f32x2*)(redw + (mt * 32 + (i & 3) + 8 * (i >> 2)) * 2) = sv; }
;         }
;     }
;     __syncthreads();
;     u64_t* myslots = xstat + ((size_t)pm * 256) * 4;
;     if (tid < 256) {
;       float s1 = (red[tid * 2] + red[(256 + tid) * 2]) + (red[(512 + tid) * 2] + red[(768 + tid) * 2]);
;       float s2 = (red[tid * 2 + 1] + red[(256 + tid) * 2 + 1]) + (red[(512 + tid) * 2 + 1] + red[(768 + tid) * 2 + 1]);
;       ag_st64(myslots + tid * 4 + pn, ((u64_t)__float_as_uint(s2) << 32) | (u64_t)__float_as_uint(s1));
;     }
	v_mov_b32_e32 v212, v202
	s_waitcnt lgkmcnt(0)
	v_mov_b32_e32 v213, v206
	s_mov_b32 s2, s67
	v_mov_b32_e32 v226, v203
	v_mov_b32_e32 v227, v206
	v_pk_fma_f32 v[202:203], v[212:213], s[2:3], v[208:209] op_sel_hi:[1,0,1]
	v_pk_fma_f32 v[204:205], v[226:227], s[2:3], v[204:205] op_sel_hi:[1,0,1]
	v_pk_mul_f32 v[214:215], v[212:213], s[2:3] op_sel_hi:[1,0]
	v_pk_mul_f32 v[212:213], v[202:203], v[202:203]
	v_pk_mul_f32 v[226:227], v[204:205], v[204:205]
	v_pk_mov_b32 v[208:209], v[208:209], v[212:213] op_sel:[1,0]
	v_pk_mov_b32 v[212:213], v[214:215], v[226:227] op_sel:[1,0]
	v_add_f32_e32 v30, 0, v16
	v_pk_add_f32 v[208:209], v[208:209], v[212:213]
	v_pk_add_f32 v[212:213], v[202:203], v[204:205]
	v_pk_mul_f32 v[214:215], v[202:203], v[204:205]
	v_fmac_f32_e32 v30, 0x3fd744fd, v207
	v_mov_b32_e32 v213, v215
	v_pk_add_f32 v[208:209], v[212:213], v[208:209]
	v_mul_f32_e32 v31, v30, v30
	v_pk_add_f32 v[206:207], v[208:209], v[30:31]
	s_nop 1
	v_mov_b32_dpp v208, v206 quad_perm:[1,0,3,2] row_mask:0xf bank_mask:0xf bound_ctrl:1
	v_mov_b32_dpp v209, v207 quad_perm:[1,0,3,2] row_mask:0xf bank_mask:0xf bound_ctrl:1
	v_pk_add_f32 v[206:207], v[206:207], v[208:209]
	s_nop 1
	v_mov_b32_dpp v208, v206 quad_perm:[2,3,0,1] row_mask:0xf bank_mask:0xf bound_ctrl:1
	v_mov_b32_dpp v209, v207 quad_perm:[2,3,0,1] row_mask:0xf bank_mask:0xf bound_ctrl:1
	v_pk_add_f32 v[206:207], v[206:207], v[208:209]
	s_nop 1
	v_mov_b32_dpp v208, v206 row_half_mirror row_mask:0xf bank_mask:0xf bound_ctrl:1
	v_mov_b32_dpp v209, v207 row_half_mirror row_mask:0xf bank_mask:0xf bound_ctrl:1
	v_pk_add_f32 v[206:207], v[206:207], v[208:209]
	s_nop 1
	v_mov_b32_dpp v208, v206 row_mirror row_mask:0xf bank_mask:0xf bound_ctrl:1
	v_mov_b32_dpp v209, v207 row_mirror row_mask:0xf bank_mask:0xf bound_ctrl:1
	s_and_saveexec_b64 s[6:7], vcc
	v_pk_add_f32 v[206:207], v[206:207], v[208:209]
	ds_write_b64 v179, v[206:207] offset:464
	s_or_b64 exec, exec, s[6:7]
	ds_read2_b32 v[206:207], v93 offset1:32
	ds_read2_b32 v[208:209], v93 offset0:64 offset1:96
	v_mov_b32_e32 v32, v65
	v_pk_add_f32 v[64:65], v[32:33], 0 op_sel_hi:[1,0]
	v_mov_b32_e32 v32, v49
	v_pk_add_f32 v[48:49], v[32:33], 0 op_sel_hi:[1,0]
	s_waitcnt lgkmcnt(1)
	v_mov_b32_e32 v32, v206
	s_waitcnt lgkmcnt(0)
	v_mov_b32_e32 v33, v208
	s_mov_b32 s2, s67
	v_mov_b32_e32 v206, v207
	v_mov_b32_e32 v207, v208
	v_pk_mul_f32 v[212:213], v[32:33], s[2:3] op_sel_hi:[1,0]
	v_pk_fma_f32 v[32:33], v[32:33], s[2:3], v[64:65] op_sel_hi:[1,0,1]
	v_pk_fma_f32 v[48:49], v[206:207], s[2:3], v[48:49] op_sel_hi:[1,0,1]
	v_pk_mul_f32 v[214:215], v[32:33], v[32:33]
	v_pk_mul_f32 v[206:207], v[48:49], v[48:49]
	v_pk_mov_b32 v[64:65], v[64:65], v[214:215] op_sel:[1,0]
	v_pk_mov_b32 v[206:207], v[212:213], v[206:207] op_sel:[1,0]
	v_add_f32_e32 v16, 0, v17
	v_pk_add_f32 v[64:65], v[64:65], v[206:207]
	v_pk_add_f32 v[206:207], v[32:33], v[48:49]
	v_pk_mul_f32 v[212:213], v[32:33], v[48:49]
	v_fmac_f32_e32 v16, 0x3fd744fd, v209
	v_mov_b32_e32 v207, v213
	v_pk_add_f32 v[64:65], v[206:207], v[64:65]
	v_mul_f32_e32 v17, v16, v16
	v_pk_add_f32 v[64:65], v[64:65], v[16:17]
	s_nop 1
	v_mov_b32_dpp v206, v64 quad_perm:[1,0,3,2] row_mask:0xf bank_mask:0xf bound_ctrl:1
	v_mov_b32_dpp v207, v65 quad_perm:[1,0,3,2] row_mask:0xf bank_mask:0xf bound_ctrl:1
	v_pk_add_f32 v[64:65], v[64:65], v[206:207]
	s_nop 1
	v_mov_b32_dpp v206, v64 quad_perm:[2,3,0,1] row_mask:0xf bank_mask:0xf bound_ctrl:1
	v_mov_b32_dpp v207, v65 quad_perm:[2,3,0,1] row_mask:0xf bank_mask:0xf bound_ctrl:1
	v_pk_add_f32 v[64:65], v[64:65], v[206:207]
	s_nop 1
	v_mov_b32_dpp v206, v64 row_half_mirror row_mask:0xf bank_mask:0xf bound_ctrl:1
	v_mov_b32_dpp v207, v65 row_half_mirror row_mask:0xf bank_mask:0xf bound_ctrl:1
	v_pk_add_f32 v[64:65], v[64:65], v[206:207]
	s_nop 1
	v_mov_b32_dpp v206, v64 row_mirror row_mask:0xf bank_mask:0xf bound_ctrl:1
	v_mov_b32_dpp v207, v65 row_mirror row_mask:0xf bank_mask:0xf bound_ctrl:1
	s_and_saveexec_b64 s[6:7], vcc
	v_pk_add_f32 v[64:65], v[64:65], v[206:207]
	ds_write_b64 v179, v[64:65] offset:472
	s_or_b64 exec, exec, s[6:7]
	v_ashrrev_i32_e32 v206, 8, v163
	v_ashrrev_i32_e32 v207, 31, v206
	v_lshlrev_b64 v[64:65], 13, v[206:207]
	v_lshl_add_u64 v[64:65], s[8:9], 0, v[64:65]
	v_cmp_gt_i32_e64 s[40:41], s60, v164
	v_ashrrev_i32_e32 v201, 31, v200
	s_waitcnt lgkmcnt(0)
	s_barrier
	s_and_saveexec_b64 s[6:7], s[40:41]
	s_cbranch_execz .LBB0_599
	v_lshl_add_u32 v0, v164, 3, v221
	ds_read2st64_b64 v[212:215], v0 offset1:4
	ds_read2st64_b64 v[226:229], v0 offset0:8 offset1:12
	v_ashrrev_i32_e32 v208, 8, v182
	v_ashrrev_i32_e32 v209, 31, v208
	s_waitcnt lgkmcnt(1)
	v_mov_b32_e32 v230, v212
	s_waitcnt lgkmcnt(0)
	v_mov_b32_e32 v231, v226
	v_mov_b32_e32 v232, v214
	v_mov_b32_e32 v233, v228
	v_mov_b32_e32 v226, v213
	v_mov_b32_e32 v228, v215
	v_pk_add_f32 v[230:231], v[230:231], v[232:233]
	v_pk_add_f32 v[212:213], v[226:227], v[228:229]
	v_pk_add_f32 v[230:231], v[230:231], v[230:231] op_sel:[0,1] op_sel_hi:[1,0]
	v_pk_add_f32 v[212:213], v[212:213], v[212:213] op_sel:[0,1] op_sel_hi:[1,0]
	v_lshl_add_u64 v[214:215], v[200:201], 3, v[64:65]
	v_lshl_add_u64 v[208:209], v[208:209], 3, v[214:215]
	v_mov_b32_e32 v231, v212
	global_store_dwordx2 v[208:209], v[230:231], off sc1

; template <int BK> DI int swz(int row) { constexpr int CPR = BK / 8; return (row / (16 / CPR)) % CPR; }
; DI void wait_vm0() { asm volatile("s_waitcnt vmcnt(0)" ::: "memory"); }
;   DI void pre(int grow0, int gcol0, int lane, int w, char* lds) { xpass(0, grow0, gcol0, lane, w, lds); }
; template <int ROWS, int BK>
; DI void stage_tile(const bf16_t* g, int ld, char* l, int tid) {
;   constexpr int CPR = BK / 8, TOT = ROWS * CPR, N = (TOT + NT - 1) / NT;
;   const int row0 = tid / CPR, pc = tid % CPR; const int c = pc ^ swz<BK>(row0);
;   const unsigned voff = (unsigned)(row0 * ld + c * 8) * 2u;
; #pragma unroll
;   for (int i = 0; i < N; ++i) {
;     if (TOT % NT == 0 || tid + i * NT < TOT) {
;       const char* gb = (const char*)g + (size_t)i * (NT / CPR) * ld * 2;
;       __builtin_amdgcn_global_load_lds((const unsigned*)(gb + voff), (__attribute__((address_space(3))) unsigned*)(l + i * NT * 16 + __builtin_amdgcn_readfirstlane(tid >> 6) * 1024), 16, 0, 0);
;     }
;   }
; }
;     ...
;   const bf16_t* Ag = A + (size_t)row0 * lda; const bf16_t* Bg = Bt + (size_t)col0 * ldb;
;   const int wv = __builtin_amdgcn_readfirstlane(tid >> 6);
;   __syncthreads();
;   if (!pre) { stage_tile<BM, BK>(Ag, lda, lds, tid); stage_tile<BN, BK>(Bg, ldb, lds + ABYTES, tid); }
;   wait_vm0();
;   __syncthreads();
;   const int nk = K / BK;
;   for (int kt = 0; kt < nk; ++kt) {
;     char* cur = lds + (kt & 1) * STG; char* nxt = lds + ((kt + 1) & 1) * STG;
;     const bool more = kt + 1 < nk;
;     const bf16_t* An = Ag + (kt + 1) * BK; const bf16_t* Bn = Bg + (kt + 1) * BK;
;     if (!more) epi.pre(row0 + wm * 64, col0 + wn * (32 * NTW), lane, w, lds);
;     bf16x8 fa[2][2], fb[2][NTW];
; #pragma unroll
;     for (int mt = 0; mt < 2; ++mt) { int row = wm * 64 + mt * 32 + l31; fa[0][mt] = *(const bf16x8*)(cur + row * (BK * 2) + ((hh ^ swz<BK>(row)) << 4)); }
; #pragma unroll
;     for (int nt = 0; nt < NTW; ++nt) { int row = wn * (32 * NTW) + nt * 32 + l31; fb[0][nt] = *(const bf16x8*)(cur + ABYTES + row * (BK * 2) + ((hh ^ swz<BK>(row)) << 4)); }
.LBB0_615:
	s_and_b64 vcc, exec, s[6:7]
	s_cbranch_vccz .LBB0_618
	s_waitcnt vmcnt(0)
	v_mov_b32_e32 v136, v216
	v_readlane_b32 s2, v253, 29
	v_ashrrev_i32_e32 v0, 31, v136
	v_lshrrev_b32_e32 v2, 29, v0
	v_lshrrev_b32_e32 v0, 28, v0
	v_add_u32_e32 v0, v136, v0
	v_ashrrev_i32_e32 v0, 4, v0
	v_readlane_b32 s3, v253, 30
	s_waitcnt lgkmcnt(0)
	s_add_u32 s2, s42, s2
	v_lshrrev_b32_e32 v6, 29, v0
	s_addc_u32 s3, s43, s3
	v_readlane_b32 s6, v253, 13
	v_add_u32_e32 v2, v136, v2
	v_add_u32_e32 v6, v0, v6
	v_readlane_b32 s7, v253, 14
	s_add_u32 s6, s2, s6
	v_and_b32_e32 v3, 0xffffff8, v2
	v_and_b32_e32 v6, 0xffffff8, v6
	s_addc_u32 s7, s3, s7
	v_sub_u32_e32 v3, v136, v3
	v_sub_u32_e32 v0, v0, v6
	v_lshlrev_b32_e32 v2, 8, v2
	v_readfirstlane_b32 s3, v136
	v_xor_b32_e32 v0, v0, v3
	v_and_b32_e32 v2, 0xfffff800, v2
	v_readlane_b32 s30, v253, 31
	s_lshl_b32 s3, s3, 4
	v_lshl_add_u32 v0, v0, 4, v2
	v_readlane_b32 s31, v253, 32
	s_and_b32 s3, s3, 0xfffffc00
	s_mov_b32 m0, s3
	v_lshl_add_u64 v[132:133], s[30:31], 0, v[0:1]
	s_barrier
	s_nop 0
	global_load_lds_dwordx4 v0, s[30:31]
	v_lshl_add_u64 v[2:3], v[132:133], 0, s[58:59]
	s_add_i32 m0, s3, 0x2000
	v_lshl_add_u64 v[130:131], s[6:7], 0, v[0:1]
	global_load_lds_dwordx4 v[2:3], off
	v_lshl_add_u64 v[2:3], v[132:133], 0, s[48:49]
	s_add_i32 m0, s3, 0x4000
	v_ashrrev_i32_e32 v4, 6, v136
	global_load_lds_dwordx4 v[2:3], off
	v_lshl_add_u64 v[2:3], v[132:133], 0, s[50:51]
	s_add_i32 m0, s3, 0x6000
	v_readfirstlane_b32 s2, v4
	global_load_lds_dwordx4 v[2:3], off
	s_add_i32 m0, s3, 0x8000
	v_lshl_add_u64 v[2:3], v[130:131], 0, s[58:59]
	global_load_lds_dwordx4 v0, s[6:7]
	s_add_i32 m0, s3, 0xa000
	v_lshrrev_b32_e32 v0, 30, v4
	global_load_lds_dwordx4 v[2:3], off
	v_lshl_add_u64 v[2:3], v[130:131], 0, s[48:49]
	s_add_i32 m0, s3, 0xc000
	v_lshrrev_b32_e32 v5, 5, v136
	global_load_lds_dwordx4 v[2:3], off
	v_lshl_add_u64 v[2:3], v[130:131], 0, s[50:51]
	s_add_i32 m0, s3, 0xe000
	v_bfe_u32 v20, v136, 5, 1
	global_load_lds_dwordx4 v[2:3], off
	v_add_u32_e32 v2, v4, v0
	v_ashrrev_i32_e32 v0, 2, v2
	v_mul_i32_i24_e32 v6, 4, v0
	v_sub_u32_e32 v4, v4, v6
	v_and_b32_e32 v3, 31, v136
	v_lshlrev_b32_e32 v21, 6, v4
	v_or_b32_e32 v6, v21, v3
	v_bfe_u32 v4, v4, 25, 1
	v_lshlrev_b32_e32 v137, 7, v6
	v_add_u32_e32 v7, v6, v4
	v_or_b32_e32 v6, 32, v6
	v_add_u32_e32 v4, v6, v4
	v_lshlrev_b32_e32 v164, 7, v6
	v_ashrrev_i32_e32 v6, 1, v4
	v_ashrrev_i32_e32 v4, 31, v4
	v_lshrrev_b32_e32 v4, 29, v4
	v_add_u32_e32 v4, v6, v4
	v_and_b32_e32 v4, -8, v4
	v_lshlrev_b32_e32 v0, 7, v0
	v_sub_u32_e32 v23, v6, v4
	v_or_b32_e32 v3, v0, v3
	v_bitop3_b32 v4, v23, v5, 1 bitop3:0x78
	v_lshrrev_b32_e32 v2, 31, v2
	v_lshlrev_b32_e32 v194, 4, v4
	v_add_u32_e32 v4, v3, v2
	v_ashrrev_i32_e32 v6, 1, v4
	v_ashrrev_i32_e32 v4, 31, v4
	v_lshrrev_b32_e32 v4, 29, v4
	v_add_u32_e32 v4, v6, v4
	v_and_b32_e32 v4, -8, v4
	v_sub_u32_e32 v24, v6, v4
	v_bitop3_b32 v4, v24, v5, 1 bitop3:0x78
	v_lshlrev_b32_e32 v196, 4, v4
	v_or_b32_e32 v4, 32, v3
	v_lshlrev_b32_e32 v197, 7, v4
	v_add_u32_e32 v4, v4, v2
	v_ashrrev_i32_e32 v6, 1, v4
	v_ashrrev_i32_e32 v4, 31, v4
	v_lshrrev_b32_e32 v4, 29, v4
	v_add_u32_e32 v4, v6, v4
	v_and_b32_e32 v4, -8, v4
	v_sub_u32_e32 v25, v6, v4
	v_bitop3_b32 v4, v25, v5, 1 bitop3:0x78
	v_lshlrev_b32_e32 v195, 7, v3
	v_lshlrev_b32_e32 v198, 4, v4
	v_or_b32_e32 v4, 64, v3
	v_or_b32_e32 v3, 0x60, v3
	v_lshlrev_b32_e32 v199, 7, v4
	v_add_u32_e32 v4, v4, v2
	v_add_u32_e32 v2, v3, v2
	v_lshlrev_b32_e32 v201, 7, v3
	v_ashrrev_i32_e32 v3, 1, v2
	v_ashrrev_i32_e32 v2, 31, v2
	v_ashrrev_i32_e32 v8, 1, v7
	v_ashrrev_i32_e32 v7, 31, v7
	v_lshrrev_b32_e32 v2, 29, v2
	v_lshrrev_b32_e32 v7, 29, v7
	v_add_u32_e32 v2, v3, v2
	v_add_u32_e32 v7, v8, v7
	v_and_b32_e32 v2, -8, v2
	v_and_b32_e32 v7, -8, v7
	v_sub_u32_e32 v27, v3, v2
	v_sub_u32_e32 v22, v8, v7
	v_ashrrev_i32_e32 v6, 1, v4
	v_ashrrev_i32_e32 v4, 31, v4
	v_bitop3_b32 v2, v27, v5, 1 bitop3:0x78
	v_lshrrev_b32_e32 v4, 29, v4
	v_lshlrev_b32_e32 v202, 4, v2
	v_bitop3_b32 v2, v22, v20, 2 bitop3:0x1e
	v_add_u32_e32 v4, v6, v4
	v_lshlrev_b32_e32 v203, 4, v2
	v_bitop3_b32 v2, v23, v20, 2 bitop3:0x1e
	v_and_b32_e32 v4, -8, v4
	v_lshlrev_b32_e32 v204, 4, v2
	v_bitop3_b32 v2, v24, v20, 2 bitop3:0x1e
	v_sub_u32_e32 v26, v6, v4
	v_lshlrev_b32_e32 v205, 4, v2
	v_bitop3_b32 v2, v25, v20, 2 bitop3:0x1e
	s_lshl_b32 s3, s2, 10
	v_bitop3_b32 v7, v22, v5, 1 bitop3:0x78
	v_bitop3_b32 v4, v26, v5, 1 bitop3:0x78
	v_lshlrev_b32_e32 v206, 4, v2
	v_bitop3_b32 v2, v26, v20, 2 bitop3:0x1e
	v_lshlrev_b32_e32 v163, 4, v7
	v_lshlrev_b32_e32 v200, 4, v4
	v_lshlrev_b32_e32 v207, 4, v2
	v_bitop3_b32 v2, v27, v20, 2 bitop3:0x1e
	s_add_i32 s30, s3, 0x10000
	v_lshlrev_b32_e32 v208, 4, v2
	v_add_u32_e32 v209, v137, v163
	v_add_u32_e32 v211, v195, v196
	v_add_u32_e32 v213, v199, v200
	v_lshl_add_u64 v[18:19], v[132:133], 0, s[28:29]
	v_add_u32_e32 v215, v137, v203
	v_add_u32_e32 v227, v195, v205
	v_add_u32_e32 v229, v199, v207
	s_mov_b32 m0, s30
	s_add_i32 s7, s3, 0x12000
	s_waitcnt vmcnt(0)
	s_waitcnt vmcnt(0) lgkmcnt(0)
	s_barrier
; DI f32x16 mfma(bf16x8 a, bf16x8 b, f32x16 c) { return __builtin_amdgcn_mfma_f32_32x32x16_bf16(a, b, c, 0, 0, 0); }
; template <int BK> DI int swz(int row) { constexpr int CPR = BK / 8; return (row / (16 / CPR)) % CPR; }
;   DI void pre(int grow0, int gcol0, int lane, int w, char* lds) { xpass(0, grow0, gcol0, lane, w, lds); }
;     ...
;   for (int kt = 0; kt < nk; ++kt) {
;     char* cur = lds + (kt & 1) * STG; char* nxt = lds + ((kt + 1) & 1) * STG;
;     const bool more = kt + 1 < nk;
;     const bf16_t* An = Ag + (kt + 1) * BK; const bf16_t* Bn = Bg + (kt + 1) * BK;
;     if (!more) epi.pre(row0 + wm * 64, col0 + wn * (32 * NTW), lane, w, lds);
;     bf16x8 fa[2][2], fb[2][NTW];
; #pragma unroll
;     for (int mt = 0; mt < 2; ++mt) { int row = wm * 64 + mt * 32 + l31; fa[0][mt] = *(const bf16x8*)(cur + row * (BK * 2) + ((hh ^ swz<BK>(row)) << 4)); }
; #pragma unroll
;     for (int nt = 0; nt < NTW; ++nt) { int row = wn * (32 * NTW) + nt * 32 + l31; fb[0][nt] = *(const bf16x8*)(cur + ABYTES + row * (BK * 2) + ((hh ^ swz<BK>(row)) << 4)); }
; #pragma unroll
;     for (int kk = 0; kk < NKK; ++kk) {
;       if (kk + 1 < NKK) {
;         const int ch = (kk + 1) * 2 + hh;
; #pragma unroll
;         for (int mt = 0; mt < 2; ++mt) { int row = wm * 64 + mt * 32 + l31; fa[(kk + 1) & 1][mt] = *(const bf16x8*)(cur + row * (BK * 2) + ((ch ^ swz<BK>(row)) << 4)); }
; #pragma unroll
;         for (int nt = 0; nt < NTW; ++nt) { int row = wn * (32 * NTW) + nt * 32 + l31; fb[(kk + 1) & 1][nt] = *(const bf16x8*)(cur + ABYTES + row * (BK * 2) + ((ch ^ swz<BK>(row)) << 4)); }
;       }
;       if (more) {
; #pragma unroll
;         for (int q = 0; q < PPK; ++q) {
;           const int pi = kk * PPK + q;
;           if (pi < NPA) stage_piece<BM, BK>(An, lda, nxt, tid, pi, wv);
;           else if (pi < NP) stage_piece<BN, BK>(Bn, ldb, nxt + ABYTES, tid, pi - NPA, wv);
;         }
;       }
;       __builtin_amdgcn_s_setprio(1);
; #pragma unroll
;       for (int mt = 0; mt < 2; ++mt)
; #pragma unroll
;         for (int nt = 0; nt < NTW; ++nt) acc[mt][nt] = mfma(fa[kk & 1][mt], fb[kk & 1][nt], acc[mt][nt]);
;       __builtin_amdgcn_s_setprio(0);
;       __builtin_amdgcn_sched_barrier(0);
;     }
	v_add_u32_e32 v210, v164, v194
	ds_read_b128 v[2:5], v209
	ds_read_b128 v[34:37], v210
	v_add_u32_e32 v212, v197, v198
	ds_read_b128 v[6:9], v211 offset:32768
	ds_read_b128 v[10:13], v212 offset:32768
	v_add_u32_e32 v214, v201, v202
	ds_read_b128 v[14:17], v213 offset:32768
	ds_read_b128 v[38:41], v214 offset:32768
	v_add_u32_e32 v226, v164, v204
	ds_read_b128 v[138:141], v215
	ds_read_b128 v[142:145], v226
	v_add_u32_e32 v228, v197, v206
	ds_read_b128 v[146:149], v227 offset:32768
	ds_read_b128 v[150:153], v228 offset:32768
	v_add_u32_e32 v230, v201, v208
	ds_read_b128 v[154:157], v229 offset:32768
	ds_read_b128 v[158:161], v230 offset:32768
	global_load_lds_dwordx4 v[18:19], off
	v_lshl_add_u64 v[18:19], v[132:133], 0, s[24:25]
	s_mov_b32 m0, s7
	v_readlane_b32 s6, v253, 9
	global_load_lds_dwordx4 v[18:19], off
	s_nop 0
	v_or_b32_e32 v18, s6, v20
	v_add_u32_e32 v18, v18, v21
	v_ashrrev_i32_e32 v19, 31, v18
	v_lshlrev_b64 v[134:135], 12, v[18:19]
	v_bitop3_b32 v18, v22, v20, 4 bitop3:0x1e
	v_lshlrev_b32_e32 v231, 4, v18
	v_bitop3_b32 v18, v23, v20, 4 bitop3:0x1e
	v_lshlrev_b32_e32 v232, 4, v18
	v_bitop3_b32 v18, v24, v20, 4 bitop3:0x1e
	v_lshlrev_b32_e32 v233, 4, v18
	v_bitop3_b32 v18, v25, v20, 4 bitop3:0x1e
	v_lshlrev_b32_e32 v234, 4, v18
	v_bitop3_b32 v18, v26, v20, 4 bitop3:0x1e
	v_lshlrev_b32_e32 v235, 4, v18
	v_bitop3_b32 v18, v27, v20, 4 bitop3:0x1e
	v_lshlrev_b32_e32 v236, 4, v18
	v_bitop3_b32 v18, v22, v20, 6 bitop3:0x1e
	v_lshlrev_b32_e32 v237, 4, v18
	v_bitop3_b32 v18, v23, v20, 6 bitop3:0x1e
	v_lshlrev_b32_e32 v238, 4, v18
	v_bitop3_b32 v18, v24, v20, 6 bitop3:0x1e
	v_lshlrev_b32_e32 v239, 4, v18
	v_bitop3_b32 v18, v25, v20, 6 bitop3:0x1e
	v_lshlrev_b32_e32 v240, 4, v18
	v_bitop3_b32 v18, v26, v20, 6 bitop3:0x1e
	v_lshlrev_b32_e32 v241, 4, v18
	v_bitop3_b32 v18, v27, v20, 6 bitop3:0x1e
	v_lshlrev_b32_e32 v242, 4, v18
	v_lshl_add_u64 v[190:191], v[130:131], 0, s[28:29]
	s_add_i32 s6, s3, 0x18000
	s_setprio 1
	s_waitcnt lgkmcnt(0)
	v_mfma_f32_32x32x16_bf16 v[114:129], v[2:5], v[6:9], 0
	v_mfma_f32_32x32x16_bf16 v[82:97], v[2:5], v[10:13], 0
	v_mfma_f32_32x32x16_bf16 v[66:81], v[2:5], v[14:17], 0
	v_mfma_f32_32x32x16_bf16 v[98:113], v[2:5], v[38:41], 0
	v_mfma_f32_32x32x16_bf16 v[50:65], v[34:37], v[6:9], 0
	v_mfma_f32_32x32x16_bf16 v[18:33], v[34:37], v[10:13], 0
	v_mfma_f32_32x32x16_bf16 v[2:17], v[34:37], v[14:17], 0
	v_mfma_f32_32x32x16_bf16 v[34:49], v[34:37], v[38:41], 0
	s_setprio 0
	s_add_i32 s34, s3, 0x14000
	v_add_u32_e32 v243, v137, v231
	v_add_u32_e32 v245, v195, v233
	v_add_u32_e32 v247, v199, v235
	v_lshl_add_u64 v[192:193], v[132:133], 0, s[26:27]
	s_mov_b32 m0, s34
	s_add_i32 s31, s3, 0x16000
	v_add_u32_e32 v244, v164, v232
	ds_read_b128 v[166:169], v243
	ds_read_b128 v[170:173], v244
	v_add_u32_e32 v246, v197, v234
	ds_read_b128 v[174:177], v245 offset:32768
	ds_read_b128 v[178:181], v246 offset:32768
	v_add_u32_e32 v248, v201, v236
	ds_read_b128 v[182:185], v247 offset:32768
	ds_read_b128 v[186:189], v248 offset:32768
	global_load_lds_dwordx4 v[192:193], off
	v_lshl_add_u64 v[192:193], v[132:133], 0, s[38:39]
	s_mov_b32 m0, s31
	s_nop 0
	global_load_lds_dwordx4 v[192:193], off
	s_setprio 1
	v_mfma_f32_32x32x16_bf16 v[114:129], v[138:141], v[146:149], v[114:129]
	v_mfma_f32_32x32x16_bf16 v[82:97], v[138:141], v[150:153], v[82:97]
	v_mfma_f32_32x32x16_bf16 v[66:81], v[138:141], v[154:157], v[66:81]
	v_mfma_f32_32x32x16_bf16 v[98:113], v[138:141], v[158:161], v[98:113]
	v_mfma_f32_32x32x16_bf16 v[50:65], v[142:145], v[146:149], v[50:65]
	v_mfma_f32_32x32x16_bf16 v[18:33], v[142:145], v[150:153], v[18:33]
	v_mfma_f32_32x32x16_bf16 v[2:17], v[142:145], v[154:157], v[2:17]
	v_mfma_f32_32x32x16_bf16 v[34:49], v[142:145], v[158:161], v[34:49]
	s_setprio 0
	s_mov_b32 m0, s6
	v_add_u32_e32 v249, v137, v237
	v_add_u32_e32 v251, v195, v239
	v_add_u32_e32 v217, v199, v241
	s_add_i32 s35, s3, 0x1a000
	v_add_u32_e32 v250, v164, v238
	ds_read_b128 v[138:141], v249
	ds_read_b128 v[142:145], v250
	v_add_u32_e32 v252, v197, v240
	ds_read_b128 v[146:149], v251 offset:32768
	ds_read_b128 v[150:153], v252 offset:32768
	v_add_u32_e32 v219, v201, v242
	ds_read_b128 v[154:157], v217 offset:32768
	ds_read_b128 v[158:161], v219 offset:32768
	global_load_lds_dwordx4 v[190:191], off
	v_lshl_add_u64 v[190:191], v[130:131], 0, s[24:25]
	s_mov_b32 m0, s35
	s_nop 0
	global_load_lds_dwordx4 v[190:191], off
	s_setprio 1
	s_waitcnt lgkmcnt(0)
	v_mfma_f32_32x32x16_bf16 v[114:129], v[166:169], v[174:177], v[114:129]
	v_mfma_f32_32x32x16_bf16 v[82:97], v[166:169], v[178:181], v[82:97]
	v_mfma_f32_32x32x16_bf16 v[66:81], v[166:169], v[182:185], v[66:81]
	v_mfma_f32_32x32x16_bf16 v[98:113], v[166:169], v[186:189], v[98:113]
	v_mfma_f32_32x32x16_bf16 v[50:65], v[170:173], v[174:177], v[50:65]
	v_mfma_f32_32x32x16_bf16 v[18:33], v[170:173], v[178:181], v[18:33]
	v_mfma_f32_32x32x16_bf16 v[2:17], v[170:173], v[182:185], v[2:17]
	v_mfma_f32_32x32x16_bf16 v[34:49], v[170:173], v[186:189], v[34:49]
	s_setprio 0
	s_add_i32 s37, s3, 0x1c000
	v_lshl_add_u64 v[166:167], v[130:131], 0, s[26:27]
	s_mov_b32 m0, s37
	s_add_i32 s36, s3, 0x1e000
	global_load_lds_dwordx4 v[166:167], off
	v_lshl_add_u64 v[166:167], v[130:131], 0, s[38:39]
	s_mov_b32 m0, s36
	s_nop 0
	global_load_lds_dwordx4 v[166:167], off
	s_setprio 1
	v_mfma_f32_32x32x16_bf16 v[114:129], v[138:141], v[146:149], v[114:129]
	v_mfma_f32_32x32x16_bf16 v[82:97], v[138:141], v[150:153], v[82:97]
	v_mfma_f32_32x32x16_bf16 v[66:81], v[138:141], v[154:157], v[66:81]
	v_mfma_f32_32x32x16_bf16 v[98:113], v[138:141], v[158:161], v[98:113]
	v_mfma_f32_32x32x16_bf16 v[50:65], v[142:145], v[146:149], v[50:65]
	v_mfma_f32_32x32x16_bf16 v[18:33], v[142:145], v[150:153], v[18:33]
	v_mfma_f32_32x32x16_bf16 v[2:17], v[142:145], v[154:157], v[2:17]
	v_mfma_f32_32x32x16_bf16 v[34:49], v[142:145], v[158:161], v[34:49]
	s_setprio 0
	v_add_u32_e32 v137, 0x10000, v137
	v_add_u32_e32 v195, 0x18000, v195
	v_add_u32_e32 v199, 0x18000, v199
	s_mov_b64 s[40:41], 0x100
	s_mov_b32 m0, s3
	v_add_u32_e32 v163, v137, v163
	v_add_u32_e32 v164, 0x10000, v164
	v_add_u32_e32 v196, v195, v196
	v_add_u32_e32 v197, 0x18000, v197
	v_add_u32_e32 v200, v199, v200
	v_add_u32_e32 v201, 0x18000, v201
	v_lshl_add_u64 v[190:191], v[132:133], 0, s[40:41]
	v_add_u32_e32 v203, v137, v203
	v_add_u32_e32 v205, v195, v205
	v_add_u32_e32 v207, v199, v207
	s_mov_b64 s[42:43], 0x20100
	s_waitcnt vmcnt(0)
	s_waitcnt vmcnt(0) lgkmcnt(0)
	s_barrier
; DI f32x16 mfma(bf16x8 a, bf16x8 b, f32x16 c) { return __builtin_amdgcn_mfma_f32_32x32x16_bf16(a, b, c, 0, 0, 0); }
; template <int BK> DI int swz(int row) { constexpr int CPR = BK / 8; return (row / (16 / CPR)) % CPR; }
;   DI void pre(int grow0, int gcol0, int lane, int w, char* lds) { xpass(0, grow0, gcol0, lane, w, lds); }
;     ...
;   for (int kt = 0; kt < nk; ++kt) {
;     char* cur = lds + (kt & 1) * STG; char* nxt = lds + ((kt + 1) & 1) * STG;
;     const bool more = kt + 1 < nk;
;     const bf16_t* An = Ag + (kt + 1) * BK; const bf16_t* Bn = Bg + (kt + 1) * BK;
;     if (!more) epi.pre(row0 + wm * 64, col0 + wn * (32 * NTW), lane, w, lds);
;     bf16x8 fa[2][2], fb[2][NTW];
; #pragma unroll
;     for (int mt = 0; mt < 2; ++mt) { int row = wm * 64 + mt * 32 + l31; fa[0][mt] = *(const bf16x8*)(cur + row * (BK * 2) + ((hh ^ swz<BK>(row)) << 4)); }
; #pragma unroll
;     for (int nt = 0; nt < NTW; ++nt) { int row = wn * (32 * NTW) + nt * 32 + l31; fb[0][nt] = *(const bf16x8*)(cur + ABYTES + row * (BK * 2) + ((hh ^ swz<BK>(row)) << 4)); }
; #pragma unroll
;     for (int kk = 0; kk < NKK; ++kk) {
;       if (kk + 1 < NKK) {
;         const int ch = (kk + 1) * 2 + hh;
; #pragma unroll
;         for (int mt = 0; mt < 2; ++mt) { int row = wm * 64 + mt * 32 + l31; fa[(kk + 1) & 1][mt] = *(const bf16x8*)(cur + row * (BK * 2) + ((ch ^ swz<BK>(row)) << 4)); }
; #pragma unroll
;         for (int nt = 0; nt < NTW; ++nt) { int row = wn * (32 * NTW) + nt * 32 + l31; fb[(kk + 1) & 1][nt] = *(const bf16x8*)(cur + ABYTES + row * (BK * 2) + ((ch ^ swz<BK>(row)) << 4)); }
;       }
;       if (more) {
; #pragma unroll
;         for (int q = 0; q < PPK; ++q) {
;           const int pi = kk * PPK + q;
;           if (pi < NPA) stage_piece<BM, BK>(An, lda, nxt, tid, pi, wv);
;           else if (pi < NP) stage_piece<BN, BK>(Bn, ldb, nxt + ABYTES, tid, pi - NPA, wv);
;         }
;       }
;       __builtin_amdgcn_s_setprio(1);
; #pragma unroll
;       for (int mt = 0; mt < 2; ++mt)
; #pragma unroll
;         for (int nt = 0; nt < NTW; ++nt) acc[mt][nt] = mfma(fa[kk & 1][mt], fb[kk & 1][nt], acc[mt][nt]);
;       __builtin_amdgcn_s_setprio(0);
;       __builtin_amdgcn_sched_barrier(0);
;     }
	v_add_u32_e32 v194, v164, v194
	ds_read_b128 v[138:141], v163
	ds_read_b128 v[142:145], v194
	v_add_u32_e32 v198, v197, v198
	ds_read_b128 v[146:149], v196
	ds_read_b128 v[150:153], v198
	v_add_u32_e32 v202, v201, v202
	ds_read_b128 v[154:157], v200
	ds_read_b128 v[158:161], v202
	v_add_u32_e32 v204, v164, v204
	ds_read_b128 v[166:169], v203
	ds_read_b128 v[170:173], v204
	v_add_u32_e32 v206, v197, v206
	ds_read_b128 v[174:177], v205
	ds_read_b128 v[178:181], v206
	v_add_u32_e32 v208, v201, v208
	ds_read_b128 v[182:185], v207
	ds_read_b128 v[186:189], v208
	global_load_lds_dwordx4 v[190:191], off
	v_lshl_add_u64 v[190:191], v[132:133], 0, s[42:43]
	s_add_i32 m0, s3, 0x2000
	s_nop 0
	global_load_lds_dwordx4 v[190:191], off
	v_lshl_add_u64 v[190:191], v[130:131], 0, s[40:41]
	s_add_i32 s40, s3, 0x8000
	s_setprio 1
	s_waitcnt lgkmcnt(0)
	v_mfma_f32_32x32x16_bf16 v[114:129], v[138:141], v[146:149], v[114:129]
	v_mfma_f32_32x32x16_bf16 v[82:97], v[138:141], v[150:153], v[82:97]
	v_mfma_f32_32x32x16_bf16 v[66:81], v[138:141], v[154:157], v[66:81]
	v_mfma_f32_32x32x16_bf16 v[98:113], v[138:141], v[158:161], v[98:113]
	v_mfma_f32_32x32x16_bf16 v[50:65], v[142:145], v[146:149], v[50:65]
	v_mfma_f32_32x32x16_bf16 v[18:33], v[142:145], v[150:153], v[18:33]
	v_mfma_f32_32x32x16_bf16 v[2:17], v[142:145], v[154:157], v[2:17]
	v_mfma_f32_32x32x16_bf16 v[34:49], v[142:145], v[158:161], v[34:49]
	s_setprio 0
	s_mov_b64 s[44:45], 0x40100
	v_add_u32_e32 v231, v137, v231
	v_add_u32_e32 v233, v195, v233
	v_add_u32_e32 v235, v199, v235
	v_lshl_add_u64 v[192:193], v[132:133], 0, s[44:45]
	s_add_i32 m0, s3, 0x4000
	s_mov_b64 s[46:47], 0x60100
	v_add_u32_e32 v232, v164, v232
	ds_read_b128 v[138:141], v231
	ds_read_b128 v[142:145], v232
	v_add_u32_e32 v234, v197, v234
	ds_read_b128 v[146:149], v233
	ds_read_b128 v[150:153], v234
	v_add_u32_e32 v236, v201, v236
	ds_read_b128 v[154:157], v235
	ds_read_b128 v[158:161], v236
	global_load_lds_dwordx4 v[192:193], off
	v_lshl_add_u64 v[192:193], v[132:133], 0, s[46:47]
	s_add_i32 m0, s3, 0x6000
	s_nop 0
	global_load_lds_dwordx4 v[192:193], off
	s_setprio 1
	v_mfma_f32_32x32x16_bf16 v[114:129], v[166:169], v[174:177], v[114:129]
	v_mfma_f32_32x32x16_bf16 v[82:97], v[166:169], v[178:181], v[82:97]
	v_mfma_f32_32x32x16_bf16 v[66:81], v[166:169], v[182:185], v[66:81]
	v_mfma_f32_32x32x16_bf16 v[98:113], v[166:169], v[186:189], v[98:113]
	v_mfma_f32_32x32x16_bf16 v[50:65], v[170:173], v[174:177], v[50:65]
	v_mfma_f32_32x32x16_bf16 v[18:33], v[170:173], v[178:181], v[18:33]
	v_mfma_f32_32x32x16_bf16 v[2:17], v[170:173], v[182:185], v[2:17]
	v_mfma_f32_32x32x16_bf16 v[34:49], v[170:173], v[186:189], v[34:49]
	s_setprio 0
	s_mov_b32 m0, s40
	v_add_u32_e32 v237, v137, v237
	v_add_u32_e32 v195, v195, v239
	v_add_u32_e32 v199, v199, v241
	v_add_u32_e32 v164, v164, v238
	ds_read_b128 v[166:169], v237
	ds_read_b128 v[170:173], v164
	v_add_u32_e32 v197, v197, v240
	ds_read_b128 v[174:177], v195
	ds_read_b128 v[178:181], v197
	v_add_u32_e32 v201, v201, v242
	ds_read_b128 v[182:185], v199
	ds_read_b128 v[186:189], v201
	global_load_lds_dwordx4 v[190:191], off
	v_lshl_add_u64 v[190:191], v[130:131], 0, s[42:43]
	s_add_i32 m0, s3, 0xa000
	s_nop 0
	global_load_lds_dwordx4 v[190:191], off
	s_setprio 1
	s_waitcnt lgkmcnt(0)
	v_mfma_f32_32x32x16_bf16 v[114:129], v[138:141], v[146:149], v[114:129]
	v_mfma_f32_32x32x16_bf16 v[82:97], v[138:141], v[150:153], v[82:97]
	v_mfma_f32_32x32x16_bf16 v[66:81], v[138:141], v[154:157], v[66:81]
	v_mfma_f32_32x32x16_bf16 v[98:113], v[138:141], v[158:161], v[98:113]
	v_mfma_f32_32x32x16_bf16 v[50:65], v[142:145], v[146:149], v[50:65]
	v_mfma_f32_32x32x16_bf16 v[18:33], v[142:145], v[150:153], v[18:33]
	v_mfma_f32_32x32x16_bf16 v[2:17], v[142:145], v[154:157], v[2:17]
	v_mfma_f32_32x32x16_bf16 v[34:49], v[142:145], v[158:161], v[34:49]
	s_setprio 0
	v_lshl_add_u64 v[138:139], v[130:131], 0, s[44:45]
	s_add_i32 m0, s3, 0xc000
	s_nop 0
	global_load_lds_dwordx4 v[138:139], off
	v_lshl_add_u64 v[138:139], v[130:131], 0, s[46:47]
	s_add_i32 m0, s3, 0xe000
	s_nop 0
	global_load_lds_dwordx4 v[138:139], off
	s_setprio 1
	v_mfma_f32_32x32x16_bf16 v[114:129], v[166:169], v[174:177], v[114:129]
	v_mfma_f32_32x32x16_bf16 v[82:97], v[166:169], v[178:181], v[82:97]
	v_mfma_f32_32x32x16_bf16 v[66:81], v[166:169], v[182:185], v[66:81]
	v_mfma_f32_32x32x16_bf16 v[98:113], v[166:169], v[186:189], v[98:113]
	v_mfma_f32_32x32x16_bf16 v[50:65], v[170:173], v[174:177], v[50:65]
	v_mfma_f32_32x32x16_bf16 v[18:33], v[170:173], v[178:181], v[18:33]
	v_mfma_f32_32x32x16_bf16 v[2:17], v[170:173], v[182:185], v[2:17]
	v_mfma_f32_32x32x16_bf16 v[34:49], v[170:173], v[186:189], v[34:49]
	s_setprio 0
	s_mov_b64 s[40:41], 0x180
	s_mov_b32 m0, s30
	v_lshl_add_u64 v[190:191], v[132:133], 0, s[40:41]
	s_mov_b64 s[42:43], 0x20180
	s_waitcnt vmcnt(0)
	s_waitcnt vmcnt(0) lgkmcnt(0)
	s_barrier
; DI f32x16 mfma(bf16x8 a, bf16x8 b, f32x16 c) { return __builtin_amdgcn_mfma_f32_32x32x16_bf16(a, b, c, 0, 0, 0); }
;     ...
;   for (int kt = 0; kt < nk; ++kt) {
;     char* cur = lds + (kt & 1) * STG; char* nxt = lds + ((kt + 1) & 1) * STG;
;     const bool more = kt + 1 < nk;
;     const bf16_t* An = Ag + (kt + 1) * BK; const bf16_t* Bn = Bg + (kt + 1) * BK;
;     if (!more) epi.pre(row0 + wm * 64, col0 + wn * (32 * NTW), lane, w, lds);
;     bf16x8 fa[2][2], fb[2][NTW];
; #pragma unroll
;     for (int mt = 0; mt < 2; ++mt) { int row = wm * 64 + mt * 32 + l31; fa[0][mt] = *(const bf16x8*)(cur + row * (BK * 2) + ((hh ^ swz<BK>(row)) << 4)); }
; #pragma unroll
;     for (int nt = 0; nt < NTW; ++nt) { int row = wn * (32 * NTW) + nt * 32 + l31; fb[0][nt] = *(const bf16x8*)(cur + ABYTES + row * (BK * 2) + ((hh ^ swz<BK>(row)) << 4)); }
; #pragma unroll
;     for (int kk = 0; kk < NKK; ++kk) {
;       if (kk + 1 < NKK) {
;         const int ch = (kk + 1) * 2 + hh;
; #pragma unroll
;         for (int mt = 0; mt < 2; ++mt) { int row = wm * 64 + mt * 32 + l31; fa[(kk + 1) & 1][mt] = *(const bf16x8*)(cur + row * (BK * 2) + ((ch ^ swz<BK>(row)) << 4)); }
; #pragma unroll
;         for (int nt = 0; nt < NTW; ++nt) { int row = wn * (32 * NTW) + nt * 32 + l31; fb[(kk + 1) & 1][nt] = *(const bf16x8*)(cur + ABYTES + row * (BK * 2) + ((ch ^ swz<BK>(row)) << 4)); }
;       }
;       if (more) {
; #pragma unroll
;         for (int q = 0; q < PPK; ++q) {
;           const int pi = kk * PPK + q;
;           if (pi < NPA) stage_piece<BM, BK>(An, lda, nxt, tid, pi, wv);
;           else if (pi < NP) stage_piece<BN, BK>(Bn, ldb, nxt + ABYTES, tid, pi - NPA, wv);
;         }
;       }
;       __builtin_amdgcn_s_setprio(1);
; #pragma unroll
;       for (int mt = 0; mt < 2; ++mt)
; #pragma unroll
;         for (int nt = 0; nt < NTW; ++nt) acc[mt][nt] = mfma(fa[kk & 1][mt], fb[kk & 1][nt], acc[mt][nt]);
;       __builtin_amdgcn_s_setprio(0);
;       __builtin_amdgcn_sched_barrier(0);
;     }
;     wait_vm0();
;     __syncthreads();
;   DI void xpass(int ps, int grow0, int gcol0, int lane, int w, char* lds) const {
;     char* xs = lds + (ps & 1) * 65536 + __builtin_amdgcn_readfirstlane(w) * 8192;
;     const float* xsrc = Xin + (size_t)(grow0 + (ps >> 1) * 32 + (ps & 1) * 16 + (lane >> 5)) * D_ + gcol0 + (lane & 31) * 4;
; #pragma unroll
;     for (int pc = 0; pc < 8; ++pc)
	ds_read_b128 v[138:141], v209
	ds_read_b128 v[142:145], v210
	ds_read_b128 v[146:149], v211 offset:32768
	ds_read_b128 v[150:153], v212 offset:32768
	ds_read_b128 v[154:157], v213 offset:32768
	ds_read_b128 v[158:161], v214 offset:32768
	ds_read_b128 v[166:169], v215
	ds_read_b128 v[170:173], v226
	ds_read_b128 v[174:177], v227 offset:32768
	ds_read_b128 v[178:181], v228 offset:32768
	ds_read_b128 v[182:185], v229 offset:32768
	ds_read_b128 v[186:189], v230 offset:32768
	global_load_lds_dwordx4 v[190:191], off
	v_lshl_add_u64 v[190:191], v[132:133], 0, s[42:43]
	s_mov_b32 m0, s7
	s_nop 0
	global_load_lds_dwordx4 v[190:191], off
	v_lshl_add_u64 v[190:191], v[130:131], 0, s[40:41]
	s_setprio 1
	s_waitcnt lgkmcnt(0)
	v_mfma_f32_32x32x16_bf16 v[114:129], v[138:141], v[146:149], v[114:129]
	v_mfma_f32_32x32x16_bf16 v[82:97], v[138:141], v[150:153], v[82:97]
	v_mfma_f32_32x32x16_bf16 v[66:81], v[138:141], v[154:157], v[66:81]
	v_mfma_f32_32x32x16_bf16 v[98:113], v[138:141], v[158:161], v[98:113]
	v_mfma_f32_32x32x16_bf16 v[50:65], v[142:145], v[146:149], v[50:65]
	v_mfma_f32_32x32x16_bf16 v[18:33], v[142:145], v[150:153], v[18:33]
	v_mfma_f32_32x32x16_bf16 v[2:17], v[142:145], v[154:157], v[2:17]
	v_mfma_f32_32x32x16_bf16 v[34:49], v[142:145], v[158:161], v[34:49]
	s_setprio 0
	s_mov_b64 s[40:41], 0x40180
	s_mov_b32 m0, s34
	v_lshl_add_u64 v[192:193], v[132:133], 0, s[40:41]
	s_mov_b64 s[44:45], 0x60180
	ds_read_b128 v[138:141], v243
	ds_read_b128 v[142:145], v244
	ds_read_b128 v[146:149], v245 offset:32768
	ds_read_b128 v[150:153], v246 offset:32768
	ds_read_b128 v[154:157], v247 offset:32768
	ds_read_b128 v[158:161], v248 offset:32768
	global_load_lds_dwordx4 v[192:193], off
	v_lshl_add_u64 v[132:133], v[132:133], 0, s[44:45]
	s_mov_b32 m0, s31
	s_nop 0
	global_load_lds_dwordx4 v[132:133], off
	s_setprio 1
	v_mfma_f32_32x32x16_bf16 v[114:129], v[166:169], v[174:177], v[114:129]
	v_mfma_f32_32x32x16_bf16 v[82:97], v[166:169], v[178:181], v[82:97]
	v_mfma_f32_32x32x16_bf16 v[66:81], v[166:169], v[182:185], v[66:81]
	v_mfma_f32_32x32x16_bf16 v[98:113], v[166:169], v[186:189], v[98:113]
	v_mfma_f32_32x32x16_bf16 v[50:65], v[170:173], v[174:177], v[50:65]
	v_mfma_f32_32x32x16_bf16 v[18:33], v[170:173], v[178:181], v[18:33]
	v_mfma_f32_32x32x16_bf16 v[2:17], v[170:173], v[182:185], v[2:17]
	v_mfma_f32_32x32x16_bf16 v[34:49], v[170:173], v[186:189], v[34:49]
	s_setprio 0
	s_mov_b32 m0, s6
	ds_read_b128 v[166:169], v249
	ds_read_b128 v[170:173], v250
	ds_read_b128 v[174:177], v251 offset:32768
	ds_read_b128 v[178:181], v252 offset:32768
	ds_read_b128 v[182:185], v217 offset:32768
	ds_read_b128 v[186:189], v219 offset:32768
	global_load_lds_dwordx4 v[190:191], off
	v_lshl_add_u64 v[132:133], v[130:131], 0, s[42:43]
	s_mov_b32 m0, s35
	s_nop 0
	global_load_lds_dwordx4 v[132:133], off
	s_setprio 1
	s_waitcnt lgkmcnt(0)
	v_mfma_f32_32x32x16_bf16 v[114:129], v[138:141], v[146:149], v[114:129]
	v_mfma_f32_32x32x16_bf16 v[82:97], v[138:141], v[150:153], v[82:97]
	v_mfma_f32_32x32x16_bf16 v[66:81], v[138:141], v[154:157], v[66:81]
	v_mfma_f32_32x32x16_bf16 v[98:113], v[138:141], v[158:161], v[98:113]
	v_mfma_f32_32x32x16_bf16 v[50:65], v[142:145], v[146:149], v[50:65]
	v_mfma_f32_32x32x16_bf16 v[18:33], v[142:145], v[150:153], v[18:33]
	v_mfma_f32_32x32x16_bf16 v[2:17], v[142:145], v[154:157], v[2:17]
	v_mfma_f32_32x32x16_bf16 v[34:49], v[142:145], v[158:161], v[34:49]
	s_setprio 0
	s_mov_b32 m0, s37
	v_lshl_add_u64 v[132:133], v[130:131], 0, s[40:41]
	global_load_lds_dwordx4 v[132:133], off
	v_lshl_add_u64 v[130:131], v[130:131], 0, s[44:45]
	s_mov_b32 m0, s36
	s_nop 0
	global_load_lds_dwordx4 v[130:131], off
	s_setprio 1
	v_mfma_f32_32x32x16_bf16 v[114:129], v[166:169], v[174:177], v[114:129]
	v_mfma_f32_32x32x16_bf16 v[82:97], v[166:169], v[178:181], v[82:97]
	v_mfma_f32_32x32x16_bf16 v[66:81], v[166:169], v[182:185], v[66:81]
	v_mfma_f32_32x32x16_bf16 v[98:113], v[166:169], v[186:189], v[98:113]
	v_mfma_f32_32x32x16_bf16 v[50:65], v[170:173], v[174:177], v[50:65]
	v_mfma_f32_32x32x16_bf16 v[18:33], v[170:173], v[178:181], v[18:33]
	v_mfma_f32_32x32x16_bf16 v[2:17], v[170:173], v[182:185], v[2:17]
	v_mfma_f32_32x32x16_bf16 v[34:49], v[170:173], v[186:189], v[34:49]
	s_setprio 0
	v_readlane_b32 s6, v253, 27
	v_lshl_add_u64 v[132:133], s[10:11], 0, v[134:135]
	s_lshl_b32 s2, s2, 13
	v_add_u32_e32 v130, s6, v0
	v_ashrrev_i32_e32 v131, 31, v130
	v_lshlrev_b32_e32 v0, 4, v136
	v_lshl_add_u64 v[130:131], v[130:131], 2, v[132:133]
	v_and_b32_e32 v0, 0x1f0, v0
	v_lshl_add_u64 v[130:131], v[130:131], 0, v[0:1]
	s_mov_b32 m0, s2
	s_mov_b64 s[30:31], 0x2000
	s_waitcnt vmcnt(0)
	s_waitcnt vmcnt(0) lgkmcnt(0)
	s_barrier
; DI void wait_vm0() { asm volatile("s_waitcnt vmcnt(0)" ::: "memory"); }
;     ...
;     if (!more) epi.pre(row0 + wm * 64, col0 + wn * (32 * NTW), lane, w, lds);
;     bf16x8 fa[2][2], fb[2][NTW];
; #pragma unroll
;     for (int mt = 0; mt < 2; ++mt) { int row = wm * 64 + mt * 32 + l31; fa[0][mt] = *(const bf16x8*)(cur + row * (BK * 2) + ((hh ^ swz<BK>(row)) << 4)); }
; #pragma unroll
;     for (int nt = 0; nt < NTW; ++nt) { int row = wn * (32 * NTW) + nt * 32 + l31; fb[0][nt] = *(const bf16x8*)(cur + ABYTES + row * (BK * 2) + ((hh ^ swz<BK>(row)) << 4)); }
; #pragma unroll
;     for (int kk = 0; kk < NKK; ++kk) {
;       if (kk + 1 < NKK) {
;         const int ch = (kk + 1) * 2 + hh;
; #pragma unroll
;         for (int mt = 0; mt < 2; ++mt) { int row = wm * 64 + mt * 32 + l31; fa[(kk + 1) & 1][mt] = *(const bf16x8*)(cur + row * (BK * 2) + ((ch ^ swz<BK>(row)) << 4)); }
; #pragma unroll
;         for (int nt = 0; nt < NTW; ++nt) { int row = wn * (32 * NTW) + nt * 32 + l31; fb[(kk + 1) & 1][nt] = *(const bf16x8*)(cur + ABYTES + row * (BK * 2) + ((ch ^ swz<BK>(row)) << 4)); }
;       }
;       if (more) {
; #pragma unroll
;         for (int q = 0; q < PPK; ++q) {
;           const int pi = kk * PPK + q;
;           if (pi < NPA) stage_piece<BM, BK>(An, lda, nxt, tid, pi, wv);
;           else if (pi < NP) stage_piece<BN, BK>(Bn, ldb, nxt + ABYTES, tid, pi - NPA, wv);
;         }
;       }
;       __builtin_amdgcn_s_setprio(1);
; #pragma unroll
;       for (int mt = 0; mt < 2; ++mt)
; #pragma unroll
;         for (int nt = 0; nt < NTW; ++nt) acc[mt][nt] = mfma(fa[kk & 1][mt], fb[kk & 1][nt], acc[mt][nt]);
;       __builtin_amdgcn_s_setprio(0);
;       __builtin_amdgcn_sched_barrier(0);
;     }
;     wait_vm0();
;     __syncthreads();
;   DI void xpass(int ps, int grow0, int gcol0, int lane, int w, char* lds) const {
;     char* xs = lds + (ps & 1) * 65536 + __builtin_amdgcn_readfirstlane(w) * 8192;
;     const float* xsrc = Xin + (size_t)(grow0 + (ps >> 1) * 32 + (ps & 1) * 16 + (lane >> 5)) * D_ + gcol0 + (lane & 31) * 4;
; #pragma unroll
;     for (int pc = 0; pc < 8; ++pc)
;       __builtin_amdgcn_global_load_lds((const unsigned*)(xsrc + (size_t)(2 * pc) * D_), (__attribute__((address_space(3))) unsigned*)(xs + pc * 1024), 16, 0, 0);
;   }
;   DI void pre(int grow0, int gcol0, int lane, int w, char* lds) { xpass(0, grow0, gcol0, lane, w, lds); }
	global_load_lds_dwordx4 v[130:131], off
	v_lshl_add_u64 v[132:133], v[130:131], 0, s[30:31]
	s_or_b32 m0, s2, 0x400
	s_mov_b64 s[30:31], 0x4000
	global_load_lds_dwordx4 v[132:133], off
	v_lshl_add_u64 v[132:133], v[130:131], 0, s[30:31]
	s_or_b32 m0, s2, 0x800
	s_mov_b64 s[30:31], 0x6000
	global_load_lds_dwordx4 v[132:133], off
	v_lshl_add_u64 v[132:133], v[130:131], 0, s[30:31]
	s_or_b32 m0, s2, 0xc00
	s_mov_b64 s[30:31], 0x8000
	global_load_lds_dwordx4 v[132:133], off
	v_lshl_add_u64 v[132:133], v[130:131], 0, s[30:31]
	s_or_b32 m0, s2, 0x1000
	s_mov_b64 s[30:31], 0xa000
	global_load_lds_dwordx4 v[132:133], off
	v_lshl_add_u64 v[132:133], v[130:131], 0, s[30:31]
	s_or_b32 m0, s2, 0x1400
	s_mov_b64 s[30:31], 0xc000
	global_load_lds_dwordx4 v[132:133], off
	v_lshl_add_u64 v[132:133], v[130:131], 0, s[30:31]
	s_or_b32 m0, s2, 0x1800
	s_mov_b64 s[30:31], 0xe000
	global_load_lds_dwordx4 v[132:133], off
	v_lshl_add_u64 v[130:131], v[130:131], 0, s[30:31]
	s_or_b32 m0, s2, 0x1c00
	v_readlane_b32 s7, v253, 28
	global_load_lds_dwordx4 v[130:131], off
	ds_read_b128 v[130:133], v163
	ds_read_b128 v[134:137], v194
	ds_read_b128 v[138:141], v196
	ds_read_b128 v[142:145], v198
	ds_read_b128 v[146:149], v200
	ds_read_b128 v[150:153], v202
	ds_read_b128 v[154:157], v203
	ds_read_b128 v[158:161], v204
	ds_read_b128 v[166:169], v205
	ds_read_b128 v[170:173], v206
	ds_read_b128 v[174:177], v207
	ds_read_b128 v[178:181], v208
	s_setprio 1
	s_waitcnt lgkmcnt(0)
	v_mfma_f32_32x32x16_bf16 v[114:129], v[130:133], v[138:141], v[114:129]
	v_mfma_f32_32x32x16_bf16 v[82:97], v[130:133], v[142:145], v[82:97]
	v_mfma_f32_32x32x16_bf16 v[66:81], v[130:133], v[146:149], v[66:81]
	v_mfma_f32_32x32x16_bf16 v[98:113], v[130:133], v[150:153], v[98:113]
	v_mfma_f32_32x32x16_bf16 v[50:65], v[134:137], v[138:141], v[50:65]
	v_mfma_f32_32x32x16_bf16 v[18:33], v[134:137], v[142:145], v[18:33]
	v_mfma_f32_32x32x16_bf16 v[2:17], v[134:137], v[146:149], v[2:17]
	v_mfma_f32_32x32x16_bf16 v[34:49], v[134:137], v[150:153], v[34:49]
	s_setprio 0
	ds_read_b128 v[130:133], v231
	ds_read_b128 v[134:137], v232
	ds_read_b128 v[138:141], v233
	ds_read_b128 v[142:145], v234
	ds_read_b128 v[146:149], v235
	ds_read_b128 v[150:153], v236
	s_setprio 1
	v_mfma_f32_32x32x16_bf16 v[114:129], v[154:157], v[166:169], v[114:129]
	v_mfma_f32_32x32x16_bf16 v[82:97], v[154:157], v[170:173], v[82:97]
	v_mfma_f32_32x32x16_bf16 v[66:81], v[154:157], v[174:177], v[66:81]
	v_mfma_f32_32x32x16_bf16 v[98:113], v[154:157], v[178:181], v[98:113]
	v_mfma_f32_32x32x16_bf16 v[50:65], v[158:161], v[166:169], v[50:65]
	v_mfma_f32_32x32x16_bf16 v[18:33], v[158:161], v[170:173], v[18:33]
	v_mfma_f32_32x32x16_bf16 v[2:17], v[158:161], v[174:177], v[2:17]
	v_mfma_f32_32x32x16_bf16 v[34:49], v[158:161], v[178:181], v[34:49]
	s_setprio 0
	ds_read_b128 v[154:157], v237
	ds_read_b128 v[158:161], v164
	ds_read_b128 v[166:169], v195
	ds_read_b128 v[170:173], v197
	ds_read_b128 v[174:177], v199
	ds_read_b128 v[178:181], v201
	s_setprio 1
	s_waitcnt lgkmcnt(9)
	v_mfma_f32_32x32x16_bf16 v[114:129], v[130:133], v[138:141], v[114:129]
	s_waitcnt lgkmcnt(8)
	v_mfma_f32_32x32x16_bf16 v[82:97], v[130:133], v[142:145], v[82:97]
	s_waitcnt lgkmcnt(7)
	v_mfma_f32_32x32x16_bf16 v[66:81], v[130:133], v[146:149], v[66:81]
	s_waitcnt lgkmcnt(6)
	v_mfma_f32_32x32x16_bf16 v[98:113], v[130:133], v[150:153], v[98:113]
	v_mfma_f32_32x32x16_bf16 v[50:65], v[134:137], v[138:141], v[50:65]
	v_mfma_f32_32x32x16_bf16 v[18:33], v[134:137], v[142:145], v[18:33]
	v_mfma_f32_32x32x16_bf16 v[2:17], v[134:137], v[146:149], v[2:17]
	v_mfma_f32_32x32x16_bf16 v[34:49], v[134:137], v[150:153], v[34:49]
	s_setprio 0
	s_setprio 1
	s_waitcnt lgkmcnt(3)
	v_mfma_f32_32x32x16_bf16 v[114:129], v[154:157], v[166:169], v[114:129]
	s_waitcnt lgkmcnt(2)
	v_mfma_f32_32x32x16_bf16 v[82:97], v[154:157], v[170:173], v[82:97]
	s_waitcnt lgkmcnt(1)
	v_mfma_f32_32x32x16_bf16 v[66:81], v[154:157], v[174:177], v[66:81]
	s_waitcnt lgkmcnt(0)
	v_mfma_f32_32x32x16_bf16 v[98:113], v[154:157], v[178:181], v[98:113]
	v_mfma_f32_32x32x16_bf16 v[50:65], v[158:161], v[166:169], v[50:65]
	v_mfma_f32_32x32x16_bf16 v[18:33], v[158:161], v[170:173], v[18:33]
	v_mfma_f32_32x32x16_bf16 v[2:17], v[158:161], v[174:177], v[2:17]
	v_mfma_f32_32x32x16_bf16 v[34:49], v[158:161], v[178:181], v[34:49]
	s_setprio 0
	v_mov_b32_e32 v163, v216
	s_waitcnt vmcnt(0)
	s_barrier
	v_readlane_b32 s2, v253, 33
	v_ashrrev_i32_e32 v176, 6, v163
	v_lshrrev_b32_e32 v0, 30, v176
	v_add_u32_e32 v0, v176, v0
	v_ashrrev_i32_e32 v0, 2, v0
	v_lshlrev_b32_e32 v133, 7, v0
	v_add_u32_e32 v142, s6, v133
	v_and_b32_e32 v132, 31, v163
	v_readlane_b32 s3, v253, 34
	v_or_b32_e32 v130, v142, v132
	s_andn2_b64 vcc, exec, s[2:3]
	v_cndmask_b32_e64 v131, 0, 1, s[2:3]
	v_cmp_ne_u32_e64 s[40:41], 1, v131
	v_ashrrev_i32_e32 v131, 31, v130
	s_cbranch_vccnz .LBB0_680
	s_load_dwordx16 s[44:59], s[0:1], 0x18
	s_waitcnt lgkmcnt(0)
	v_lshl_add_u64 v[134:135], v[130:131], 2, s[54:55]
	global_load_dword v169, v[134:135], off
	s_branch .LBB0_681
